# x3 plus row-major XOR-swizzled LDS tiles so each LDS-DMA piece is 8 full 128B lines (8 main GEMM loops); B-fragment read bases folded into offsets (no VALU in load segments)
# speedup vs baseline: 1.0096x; 1.0096x over previous
; #define PG8_STAGE(bufoff, gbase, voff) do { _Pragma("unroll") for (int _i = 0; _i < 2; ++_i) \
;         __builtin_amdgcn_global_load_lds((const unsigned*)((const char*)(gbase) + (voff)[_i]), (LAS unsigned*)(lds + (bufoff) + ldsw + _i * 8192), 16, 0, 0); } while (0)
; #define PG8_WAIT_V(n) asm volatile("s_waitcnt vmcnt(" #n ")" ::: "memory")
; #define PG8_BAR __builtin_amdgcn_s_barrier()
; template <class Epi, bool ALIGN_EPI = true>
; __device__ __forceinline__ void gemm_phase(LAS unsigned char* lds, const Gemm g, const Sched& S, const Epi& E) {
;     ...
;     for (int i = 0; i < 2; ++i) { int R, C; stage_rc(tid * 16 + i * 8192, R, C); const int Rb = (R & ~31) + perm32(R & 31);
;         voffA[i] = (unsigned)(R * g.lda + C) * 2u; voffB[i] = (unsigned)(Rb * g.ldb + C) * 2u; }
;     ...
;     PG8_STAGE(PG8_SB(0, 0), cB, voffB); PG8_STAGE(PG8_SB(0, 1), cB + hstepB, voffB); PG8_STAGE(PG8_SA(0, 0), cA, voffA); PG8_STAGE(PG8_SA(0, 1), cA + hstepA, voffA);
;     if (wr == 1) PG8_BAR;
;     PG8_WAIT_V(2); PG8_BAR;
;     PG8_STAGE(PG8_SB(1, 0), cB + kstep, voffB); PG8_STAGE(PG8_SA(1, 0), cA + kstep, voffA); PG8_STAGE(PG8_SB(1, 1), cB + hstepB + kstep, voffB);
.LBB0_490:
	s_or_b64 exec, exec, s[26:27]
	v_bfe_i32 v5, v12, 27, 1
	v_lshlrev_b32_e32 v4, 4, v12
	v_lshrrev_b32_e32 v5, 22, v5
	v_add_u32_e32 v5, v4, v5
	v_and_b32_e32 v5, 0xfffffc00, v5
	v_sub_u32_e32 v5, v4, v5
	v_lshrrev_b32_e32 v6, 4, v5
	v_ashrrev_i32_e32 v2, 31, v12
	v_bitop3_b32 v5, v6, v5, 32 bitop3:0x6c
	v_lshrrev_b32_e32 v2, 26, v2
	v_ashrrev_i32_e32 v7, 31, v5
	v_add_u32_e32 v2, v12, v2
	v_lshrrev_b32_e32 v7, 26, v7
	v_ashrrev_i32_e32 v2, 6, v2
	v_add_u32_e32 v7, v5, v7
	v_lshlrev_b32_e32 v6, 3, v2
	v_ashrrev_i32_e32 v13, 6, v7
	v_and_b32_e32 v7, 0xc0, v7
	v_and_b32_e32 v6, -16, v6
	v_sub_u32_e32 v5, v5, v7
	v_add_u32_e32 v6, v13, v6
	v_ashrrev_i16_sdwa v5, v213, sext(v5) dst_sel:DWORD dst_unused:UNUSED_PAD src0_sel:DWORD src1_sel:BYTE_0
	s_add_u32 s57, s54, s0
	v_lshlrev_b32_e32 v8, 5, v2
	v_bfe_i32 v14, v5, 0, 16
	v_lshlrev_b32_e32 v5, 1, v6
	v_lshrrev_b32_e32 v7, 2, v6
	v_and_b32_e32 v9, 3, v13
	s_mov_b32 s0, 0xfffe0
	v_and_b32_e32 v8, 32, v8
	v_and_b32_e32 v5, 24, v5
	v_and_b32_e32 v7, 4, v7
	v_and_or_b32 v9, v6, s0, v9
	v_or3_b32 v5, v9, v7, v5
	v_add_lshl_u32 v7, v8, v14, 1
	v_add_u32_e32 v4, 0x2000, v4
	v_lshl_add_u32 v152, v5, 12, v7
	v_lshrrev_b32_e32 v247, 3, v0
	v_xor_b32_e32 v247, v247, v0
	v_and_b32_e32 v247, 7, v247
	v_lshl_add_u32 v152, v247, 4, v152
	v_and_b32_e32 v247, 64, v0
	v_sub_u32_e32 v152, v152, v247
	v_lshrrev_b32_e32 v247, 4, v0
	v_and_b32_e32 v247, 2, v247
	v_xor_b32_e32 v247, v247, v0
	v_and_b32_e32 v247, 3, v247
	v_lshlrev_b32_e32 v247, 4, v247
	v_sub_u32_e32 v152, v152, v247
	v_and_b32_e32 v247, 64, v0
	v_mul_u32_u24_e32 v247, 0x400, v247
	v_add_u32_e32 v152, v152, v247
	v_and_b32_e32 v247, 32, v0
	v_mul_u32_u24_e32 v247, 0x400, v247
	v_sub_u32_e32 v152, v152, v247
	v_and_b32_e32 v247, 16, v0
	v_mul_u32_u24_e32 v247, 0x600, v247
	v_sub_u32_e32 v152, v152, v247
	v_and_b32_e32 v247, 8, v0
	v_mul_u32_u24_e32 v247, 0x200, v247
	v_sub_u32_e32 v152, v152, v247
	v_and_b32_e32 v247, 4, v0
	v_mul_u32_u24_e32 v247, 0x400, v247
	v_sub_u32_e32 v152, v152, v247
	v_ashrrev_i32_e32 v5, 31, v4
	v_lshrrev_b32_e32 v5, 22, v5
	v_add_u32_e32 v5, v4, v5
	v_ashrrev_i32_e32 v15, 10, v5
	v_mul_i32_i24_e32 v5, 0x400, v15
	v_sub_u32_e32 v4, v4, v5
	v_lshrrev_b32_e32 v5, 4, v4
	v_bitop3_b32 v4, v5, v4, 32 bitop3:0x6c
	v_lshl_add_u32 v150, v6, 12, v7
	v_lshrrev_b32_e32 v247, 3, v0
	v_xor_b32_e32 v247, v247, v0
	v_and_b32_e32 v247, 7, v247
	v_lshl_add_u32 v150, v247, 4, v150
	v_and_b32_e32 v247, 64, v0
	v_sub_u32_e32 v150, v150, v247
	v_lshrrev_b32_e32 v247, 4, v0
	v_and_b32_e32 v247, 2, v247
	v_xor_b32_e32 v247, v247, v0
	v_and_b32_e32 v247, 3, v247
	v_lshlrev_b32_e32 v247, 4, v247
	v_sub_u32_e32 v150, v150, v247
	v_bfe_u32 v247, v0, 2, 4
	v_add_u32_e32 v247, 1, v247
	v_lshrrev_b32_e32 v247, 1, v247
	v_mul_u32_u24_e32 v247, 0x1000, v247
	v_sub_u32_e32 v150, v150, v247
	v_and_b32_e32 v247, 64, v0
	v_mul_u32_u24_e32 v247, 0x200, v247
	v_add_u32_e32 v150, v150, v247
	v_ashrrev_i32_e32 v6, 31, v4
	v_lshrrev_b32_e32 v6, 26, v6
	v_lshlrev_b32_e32 v5, 3, v15
	v_add_u32_e32 v6, v4, v6
	v_and_b32_e32 v5, -16, v5
	v_ashrrev_i32_e32 v16, 6, v6
	s_addc_u32 s26, s55, s1
	s_ashr_i32 s40, s47, 6
	v_add_u32_e32 v5, v16, v5
	v_and_b32_e32 v6, 0xc0, v6
	v_and_b32_e32 v8, 3, v16
	s_ashr_i32 s41, s47, 8
	v_sub_u32_e32 v4, v4, v6
	v_and_or_b32 v8, v5, s0, v8
	s_lshl_b32 s27, s40, 10
	v_readlane_b32 s0, v244, 48
	v_readlane_b32 s10, v242, 27
	v_ashrrev_i16_sdwa v4, v213, sext(v4) dst_sel:DWORD dst_unused:UNUSED_PAD src0_sel:DWORD src1_sel:BYTE_0
	v_readlane_b32 s1, v244, 49
	s_add_u32 s54, s10, s0
	v_readlane_b32 s0, v242, 28
	v_lshlrev_b32_e32 v7, 5, v15
	s_waitcnt lgkmcnt(0)
	v_bfe_i32 v17, v4, 0, 16
	v_lshlrev_b32_e32 v4, 1, v5
	v_lshrrev_b32_e32 v6, 2, v5
	s_addc_u32 s55, s0, s1
	s_add_i32 s50, s27, 0
	v_and_b32_e32 v7, 32, v7
	v_and_b32_e32 v4, 24, v4
	v_and_b32_e32 v6, 4, v6
	s_waitcnt lgkmcnt(0)
	s_barrier
	s_add_i32 m0, s50, 0x10000
	v_or3_b32 v4, v8, v6, v4
	v_add_lshl_u32 v6, v7, v17, 1
	global_load_lds_dwordx4 v152, s[54:55]
	s_add_i32 m0, s50, 0x12000
	v_lshl_add_u32 v156, v4, 12, v6
	v_lshrrev_b32_e32 v247, 3, v0
	v_xor_b32_e32 v247, v247, v0
	v_and_b32_e32 v247, 7, v247
	v_lshl_add_u32 v156, v247, 4, v156
	v_and_b32_e32 v247, 64, v0
	v_sub_u32_e32 v156, v156, v247
	v_lshrrev_b32_e32 v247, 4, v0
	v_and_b32_e32 v247, 2, v247
	v_xor_b32_e32 v247, v247, v0
	v_and_b32_e32 v247, 3, v247
	v_lshlrev_b32_e32 v247, 4, v247
	v_sub_u32_e32 v156, v156, v247
	v_and_b32_e32 v247, 64, v0
	v_mul_u32_u24_e32 v247, 0x400, v247
	v_add_u32_e32 v156, v156, v247
	v_and_b32_e32 v247, 32, v0
	v_mul_u32_u24_e32 v247, 0x400, v247
	v_sub_u32_e32 v156, v156, v247
	v_and_b32_e32 v247, 16, v0
	v_mul_u32_u24_e32 v247, 0x600, v247
	v_sub_u32_e32 v156, v156, v247
	v_and_b32_e32 v247, 8, v0
	v_mul_u32_u24_e32 v247, 0x200, v247
	v_sub_u32_e32 v156, v156, v247
	v_and_b32_e32 v247, 4, v0
	v_mul_u32_u24_e32 v247, 0x400, v247
	v_sub_u32_e32 v156, v156, v247
	s_add_u32 s0, s54, 0x80000
	global_load_lds_dwordx4 v156, s[54:55]
	s_addc_u32 s1, s55, 0
	s_add_i32 m0, s50, 0x14000
	v_lshl_add_u32 v154, v5, 12, v6
	v_lshrrev_b32_e32 v247, 3, v0
	v_xor_b32_e32 v247, v247, v0
	v_and_b32_e32 v247, 7, v247
	v_lshl_add_u32 v154, v247, 4, v154
	v_and_b32_e32 v247, 64, v0
	v_sub_u32_e32 v154, v154, v247
	v_lshrrev_b32_e32 v247, 4, v0
	v_and_b32_e32 v247, 2, v247
	v_xor_b32_e32 v247, v247, v0
	v_and_b32_e32 v247, 3, v247
	v_lshlrev_b32_e32 v247, 4, v247
	v_sub_u32_e32 v154, v154, v247
	v_bfe_u32 v247, v0, 2, 4
	v_add_u32_e32 v247, 1, v247
	v_lshrrev_b32_e32 v247, 1, v247
	v_mul_u32_u24_e32 v247, 0x1000, v247
	v_sub_u32_e32 v154, v154, v247
	v_and_b32_e32 v247, 64, v0
	v_mul_u32_u24_e32 v247, 0x200, v247
	v_add_u32_e32 v154, v154, v247
	global_load_lds_dwordx4 v152, s[0:1]
	s_add_i32 m0, s50, 0x16000
	v_mov_b32_e32 v153, v3
	global_load_lds_dwordx4 v156, s[0:1]
	v_readlane_b32 s0, v244, 44
	v_readlane_b32 s1, v244, 45
	s_add_u32 s0, s57, s0
	s_addc_u32 s1, s26, s1
	s_add_i32 s51, s50, 0x2000
	s_mov_b32 m0, s50
	s_add_u32 s30, s0, 0x80000
	global_load_lds_dwordx4 v150, s[0:1]
	s_mov_b32 m0, s51
	s_addc_u32 s31, s1, 0
	s_add_i32 s36, s50, 0x4000
	global_load_lds_dwordx4 v154, s[0:1]
	s_mov_b32 m0, s36
	s_add_i32 s37, s50, 0x6000
	global_load_lds_dwordx4 v150, s[30:31]
	s_mov_b32 m0, s37
	v_mov_b32_e32 v157, v3
	global_load_lds_dwordx4 v154, s[30:31]
	v_mov_b32_e32 v151, v3
	v_mov_b32_e32 v155, v3
	s_cmp_eq_u32 s41, 1
	v_lshl_add_u64 v[10:11], s[54:55], 0, v[152:153]
	v_lshl_add_u64 v[8:9], s[54:55], 0, v[156:157]
	v_lshl_add_u64 v[4:5], s[0:1], 0, v[150:151]
	s_cselect_b64 s[42:43], -1, 0
	s_cmp_lg_u32 s41, 1
	v_lshl_add_u64 v[6:7], s[0:1], 0, v[154:155]
	s_cbranch_scc1 .LBB0_492
	s_barrier
; #define PG8_STAGE(bufoff, gbase, voff) do { _Pragma("unroll") for (int _i = 0; _i < 2; ++_i) \
;         __builtin_amdgcn_global_load_lds((const unsigned*)((const char*)(gbase) + (voff)[_i]), (LAS unsigned*)(lds + (bufoff) + ldsw + _i * 8192), 16, 0, 0); } while (0)
; #define PG8_WAIT_V(n) asm volatile("s_waitcnt vmcnt(" #n ")" ::: "memory")
; #define PG8_BAR __builtin_amdgcn_s_barrier()
; template <class Epi, bool ALIGN_EPI = true>
; __device__ __forceinline__ void gemm_phase(LAS unsigned char* lds, const Gemm g, const Sched& S, const Epi& E) {
;     ...
;     for (int i = 0; i < 2; ++i) { int R, C; stage_rc(tid * 16 + i * 8192, R, C); const int Rb = (R & ~31) + perm32(R & 31);
;         voffA[i] = (unsigned)(R * g.lda + C) * 2u; voffB[i] = (unsigned)(Rb * g.ldb + C) * 2u; }
;     const size_t kstep = (size_t)(BK * 2);
;     const size_t hstepA = (size_t)HALF * g.lda * 2, hstepB = (size_t)HALF * g.ldb * 2;
;     const unsigned ldsw = (unsigned)wid * 1024u;
;     const int aoff = lds_byte(wr * 64 + fr, fq * 8), boff = lds_byte(wc * 32 + fr, fq * 8);
;     ...
;     f32x4 acc[2][2][4][2];
; #pragma unroll
;     for (int a = 0; a < 2; ++a)
; #pragma unroll
;         for (int b = 0; b < 2; ++b)
; #pragma unroll
;             for (int m = 0; m < 4; ++m)
; #pragma unroll
;                 for (int n = 0; n < 2; ++n) acc[a][b][m][n] = (f32x4){0.f, 0.f, 0.f, 0.f};
;     bf16x8 At[4][2], B0[2][2], B1[2][2];
;     const char* cA = (const char*)g.A + cur.aoff; const char* cB = (const char*)g.Bt + cur.boff;
;     PG8_STAGE(PG8_SB(0, 0), cB, voffB); PG8_STAGE(PG8_SB(0, 1), cB + hstepB, voffB); PG8_STAGE(PG8_SA(0, 0), cA, voffA); PG8_STAGE(PG8_SA(0, 1), cA + hstepA, voffA);
;     if (wr == 1) PG8_BAR;
;     PG8_WAIT_V(2); PG8_BAR;
;     PG8_STAGE(PG8_SB(1, 0), cB + kstep, voffB); PG8_STAGE(PG8_SA(1, 0), cA + kstep, voffA); PG8_STAGE(PG8_SB(1, 1), cB + hstepB + kstep, voffB);
;     PG8_WAIT_V(6); PG8_BAR;
.LBB0_492:
	v_readlane_b32 s60, v246, 42
	v_readlane_b32 s62, v246, 44
	v_readlane_b32 s63, v246, 45
	s_add_u32 s44, s62, s44
	s_addc_u32 s45, s63, s45
	s_add_u32 s24, s62, s24
	s_addc_u32 s25, s63, s25
	s_add_u32 s31, s62, s20
	s_addc_u32 s34, s63, s21
	s_add_u32 s20, s62, s22
	s_addc_u32 s21, s63, s23
	s_add_u32 s18, s62, s18
	v_writelane_b32 v242, s20, 29
	s_addc_u32 s19, s63, s19
	s_add_u32 s16, s62, s16
	v_writelane_b32 v242, s21, 30
	v_writelane_b32 v242, s18, 31
	s_addc_u32 s17, s63, s17
	s_add_u32 s6, s62, s6
	v_writelane_b32 v242, s19, 32
	v_writelane_b32 v242, s16, 33
	s_addc_u32 s7, s63, s7
	s_add_u32 s33, s62, s4
	v_writelane_b32 v242, s17, 34
	v_writelane_b32 v242, s6, 35
	s_addc_u32 s30, s63, s5
	v_lshl_add_u64 v[10:11], v[10:11], 0, s[8:9]
	v_writelane_b32 v242, s7, 36
	s_add_u32 s6, s62, s14
	s_addc_u32 s7, s63, s15
	s_lshl_b32 s94, s38, 10
	s_lshl_b64 s[4:5], s[94:95], 2
	s_add_u32 s84, s6, s4
	s_addc_u32 s85, s7, s5
	s_ashr_i32 s4, s48, 31
	s_lshr_b32 s4, s4, 26
	s_add_i32 s4, s48, s4
	s_ashr_i32 s46, s4, 6
	s_lshl_b32 s4, s40, 5
	s_and_b32 s89, s4, 0x60
	s_add_i32 m0, s50, 0x18000
	s_lshl_b32 s88, s41, 6
	s_lshl_b32 s6, s41, 13
	s_lshl_b32 s7, s89, 7
	s_waitcnt vmcnt(2)
	s_barrier
	global_load_lds_dwordx4 v[10:11], off
	v_lshl_add_u64 v[8:9], v[8:9], 0, s[8:9]
	s_add_i32 m0, s50, 0x1a000
	s_add_i32 s92, s50, 0x8000
	s_add_i32 s93, s50, 0xa000
	global_load_lds_dwordx4 v[8:9], off
	v_lshl_add_u64 v[4:5], v[4:5], 0, s[8:9]
	s_mov_b32 m0, s92
	s_add_u32 s4, s54, 0x80080
	global_load_lds_dwordx4 v[4:5], off
	v_lshl_add_u64 v[4:5], v[6:7], 0, s[8:9]
	s_mov_b32 m0, s93
	s_addc_u32 s5, s55, 0
	global_load_lds_dwordx4 v[4:5], off
	s_add_i32 m0, s50, 0x1c000
	v_lshl_add_u64 v[4:5], s[4:5], 0, v[152:153]
	global_load_lds_dwordx4 v[4:5], off
	v_lshl_add_u64 v[4:5], s[4:5], 0, v[156:157]
	s_add_i32 m0, s50, 0x1e000
	s_movk_i32 s4, 0x3c0
	global_load_lds_dwordx4 v[4:5], off
	v_and_b32_e32 v4, 48, v12
	v_lshlrev_b32_e32 v5, 6, v12
	v_and_or_b32 v4, v5, s4, v4
	v_lshlrev_b32_e32 v5, 2, v12
	v_and_b32_e32 v5, 32, v5
	v_bitop3_b32 v6, v4, s6, v5 bitop3:0xde
	v_bitop3_b32 v185, s7, v4, v5 bitop3:0xf6
	v_bfe_u32 v185, v0, 4, 2
	v_xor_b32_e32 v185, v185, v0
	v_and_b32_e32 v185, 7, v185
	v_lshlrev_b32_e32 v185, 4, v185
	v_and_b32_e32 v247, 15, v0
	v_lshl_or_b32 v185, v247, 7, v185
	v_and_b32_e32 v247, 0xc0, v0
	v_lshl_or_b32 v185, v247, 6, v185
	v_or_b32_e32 v185, 0x10000, v185
	v_lshlrev_b32_e32 v4, 15, v2
	v_and_b32_e32 v4, 0xffff0000, v4
	v_lshl_add_u32 v4, v13, 12, v4
	v_and_b32_e32 v2, 1, v2
	v_lshl_or_b32 v2, v2, 6, v4
	v_readlane_b32 s61, v246, 43
	s_cmp_gt_i32 s48, 63
	v_lshl_add_u32 v158, v14, 1, v2
	v_lshrrev_b32_e32 v247, 3, v0
	v_xor_b32_e32 v247, v247, v0
	v_and_b32_e32 v247, 7, v247
	v_lshl_add_u32 v158, v247, 4, v158
	v_and_b32_e32 v247, 64, v0
	v_sub_u32_e32 v158, v158, v247
	v_lshrrev_b32_e32 v247, 4, v0
	v_and_b32_e32 v247, 2, v247
	v_xor_b32_e32 v247, v247, v0
	v_and_b32_e32 v247, 3, v247
	v_lshlrev_b32_e32 v247, 4, v247
	v_sub_u32_e32 v158, v158, v247
	v_bfe_u32 v247, v0, 2, 4
	v_add_u32_e32 v247, 1, v247
	v_lshrrev_b32_e32 v247, 1, v247
	v_mul_u32_u24_e32 v247, 0x1000, v247
	v_sub_u32_e32 v158, v158, v247
	v_and_b32_e32 v247, 64, v0
	v_mul_u32_u24_e32 v247, 0x200, v247
	v_add_u32_e32 v158, v158, v247
	v_lshlrev_b32_e32 v2, 15, v15
	s_cselect_b64 s[60:61], -1, 0
	s_add_i32 s94, s46, -2
	v_and_b32_e32 v2, 0xffff0000, v2
	s_cmpk_lt_u32 s47, 0x100
	v_lshl_add_u32 v2, v16, 12, v2
	v_and_b32_e32 v4, 1, v15
	s_waitcnt vmcnt(6)
	s_cselect_b64 s[62:63], -1, 0
	s_and_b32 s4, s47, 0xffffff00
	v_lshl_or_b32 v2, v4, 6, v2
	v_mov_b32_e32 v4, v3
	v_mov_b32_e32 v5, v3
	v_and_b32_e32 v184, 63, v12
	s_add_i32 s47, s4, 0
	v_lshl_add_u32 v160, v17, 1, v2
	v_lshrrev_b32_e32 v247, 3, v0
	v_xor_b32_e32 v247, v247, v0
	v_and_b32_e32 v247, 7, v247
	v_lshl_add_u32 v160, v247, 4, v160
	v_and_b32_e32 v247, 64, v0
	v_sub_u32_e32 v160, v160, v247
	v_lshrrev_b32_e32 v247, 4, v0
	v_and_b32_e32 v247, 2, v247
	v_xor_b32_e32 v247, v247, v0
	v_and_b32_e32 v247, 3, v247
	v_lshlrev_b32_e32 v247, 4, v247
	v_sub_u32_e32 v160, v160, v247
	v_bfe_u32 v247, v0, 2, 4
	v_add_u32_e32 v247, 1, v247
	v_lshrrev_b32_e32 v247, 1, v247
	v_mul_u32_u24_e32 v247, 0x1000, v247
	v_sub_u32_e32 v160, v160, v247
	v_and_b32_e32 v247, 64, v0
	v_mul_u32_u24_e32 v247, 0x200, v247
	v_add_u32_e32 v160, v160, v247
	v_mov_b32_e32 v2, v3
	v_add_u32_e32 v186, 0, v6
	v_bfe_u32 v186, v0, 4, 2
	v_xor_b32_e32 v186, v186, v0
	v_and_b32_e32 v186, 7, v186
	v_lshlrev_b32_e32 v186, 4, v186
	v_and_b32_e32 v247, 15, v0
	v_lshl_or_b32 v186, v247, 7, v186
	v_and_b32_e32 v247, 0x100, v0
	v_lshl_or_b32 v186, v247, 5, v186
	v_mov_b64_e32 v[8:9], v[4:5]
	v_mov_b64_e32 v[12:13], v[4:5]
	v_mov_b64_e32 v[16:17], v[4:5]
	v_mov_b64_e32 v[20:21], v[4:5]
	v_mov_b64_e32 v[24:25], v[4:5]
	v_mov_b64_e32 v[28:29], v[4:5]
	v_mov_b64_e32 v[32:33], v[4:5]
	v_mov_b64_e32 v[36:37], v[4:5]
	v_mov_b64_e32 v[40:41], v[4:5]
	v_mov_b64_e32 v[44:45], v[4:5]
	v_mov_b64_e32 v[48:49], v[4:5]
	v_mov_b64_e32 v[52:53], v[4:5]
	v_mov_b64_e32 v[56:57], v[4:5]
	v_mov_b64_e32 v[60:61], v[4:5]
	v_mov_b64_e32 v[64:65], v[4:5]
	v_mov_b64_e32 v[68:69], v[4:5]
	v_mov_b64_e32 v[72:73], v[4:5]
	v_mov_b64_e32 v[76:77], v[4:5]
	v_mov_b64_e32 v[80:81], v[4:5]
	v_mov_b64_e32 v[84:85], v[4:5]
	v_mov_b64_e32 v[88:89], v[4:5]
	v_mov_b64_e32 v[92:93], v[4:5]
	v_mov_b64_e32 v[96:97], v[4:5]
	v_mov_b64_e32 v[100:101], v[4:5]
	v_mov_b64_e32 v[104:105], v[4:5]
	v_mov_b64_e32 v[108:109], v[4:5]
	v_mov_b64_e32 v[112:113], v[4:5]
	v_mov_b64_e32 v[116:117], v[4:5]
	v_mov_b64_e32 v[120:121], v[4:5]
	v_mov_b64_e32 v[124:125], v[4:5]
	v_mov_b64_e32 v[128:129], v[4:5]
	v_mov_b64_e32 v[132:133], v[4:5]
	s_mov_b64 s[38:39], s[24:25]
	s_add_i32 s47, s47, 0x20000
	v_mov_b32_e32 v159, v3
	v_mov_b32_e32 v161, v3
	s_mov_b32 s96, 0
	v_mov_b64_e32 v[6:7], v[2:3]
	v_mov_b64_e32 v[10:11], v[2:3]
	v_mov_b64_e32 v[14:15], v[2:3]
	v_mov_b64_e32 v[18:19], v[2:3]
	v_mov_b64_e32 v[22:23], v[2:3]
	v_mov_b64_e32 v[26:27], v[2:3]
	v_mov_b64_e32 v[30:31], v[2:3]
	v_mov_b64_e32 v[34:35], v[2:3]
	v_mov_b64_e32 v[38:39], v[2:3]
	v_mov_b64_e32 v[42:43], v[2:3]
	v_mov_b64_e32 v[46:47], v[2:3]
	v_mov_b64_e32 v[50:51], v[2:3]
	v_mov_b64_e32 v[54:55], v[2:3]
	v_mov_b64_e32 v[58:59], v[2:3]
	v_mov_b64_e32 v[62:63], v[2:3]
	v_mov_b64_e32 v[66:67], v[2:3]
	v_mov_b64_e32 v[70:71], v[2:3]
	v_mov_b64_e32 v[74:75], v[2:3]
	v_mov_b64_e32 v[78:79], v[2:3]
	v_mov_b64_e32 v[82:83], v[2:3]
	v_mov_b64_e32 v[86:87], v[2:3]
	v_mov_b64_e32 v[90:91], v[2:3]
	v_mov_b64_e32 v[94:95], v[2:3]
	v_mov_b64_e32 v[98:99], v[2:3]
	v_mov_b64_e32 v[102:103], v[2:3]
	v_mov_b64_e32 v[106:107], v[2:3]
	v_mov_b64_e32 v[110:111], v[2:3]
	v_mov_b64_e32 v[114:115], v[2:3]
	v_mov_b64_e32 v[118:119], v[2:3]
	v_mov_b64_e32 v[122:123], v[2:3]
	v_mov_b64_e32 v[126:127], v[2:3]
	v_mov_b64_e32 v[130:131], v[2:3]
	s_barrier
	s_branch .LBB0_495

; #define PG8_STAGE(bufoff, gbase, voff) do { _Pragma("unroll") for (int _i = 0; _i < 2; ++_i) \
;         __builtin_amdgcn_global_load_lds((const unsigned*)((const char*)(gbase) + (voff)[_i]), (LAS unsigned*)(lds + (bufoff) + ldsw + _i * 8192), 16, 0, 0); } while (0)
; #define PG8_LDA(dst, b, h) do { _Pragma("unroll") for (int m = 0; m < 4; ++m) _Pragma("unroll") for (int k = 0; k < 2; ++k) dst[m][k] = *(const LAS bf16x8*)(lds + PG8_SA(b, h) + aoff + m * 2048 + k * 1024); } while (0)
; #define PG8_LDB(dst, b, h) do { _Pragma("unroll") for (int n = 0; n < 2; ++n) _Pragma("unroll") for (int k = 0; k < 2; ++k) dst[n][k] = *(const LAS bf16x8*)(lds + PG8_SB(b, h) + boff + n * 2048 + k * 1024); } while (0)
; #define PG8_WAIT_V(n) asm volatile("s_waitcnt vmcnt(" #n ")" ::: "memory")
; #define PG8_WAIT_L(n) asm volatile("s_waitcnt lgkmcnt(" #n ")" ::: "memory")
; #define PG8_BAR __builtin_amdgcn_s_barrier()
; template <class Epi, bool ALIGN_EPI = true>
; __device__ __forceinline__ void gemm_phase(LAS unsigned char* lds, const Gemm g, const Sched& S, const Epi& E) {
;     ...
;         const bool has_next = S.next(ui + 1, nxt);
;         const char* nA = has_next ? (const char*)g.A + nxt.aoff : cA; const char* nB = has_next ? (const char*)g.Bt + nxt.boff : cB;
;         for (int hh = 0; hh < (Epi::HAS_MID ? 2 : 1); ++hh) {
;         if constexpr (Epi::HAS_MID) { if (hh == 1) { int le = lane; asm volatile("" : "+v"(le)); E.mid(acc, cur, wr, wc, le & 15, le >> 4); } }
;         const int t_lo = Epi::HAS_MID ? hh * (nt >> 1) : 0, t_hi = Epi::HAS_MID ? (hh + 1) * (nt >> 1) : nt;
;         for (int t = t_lo; t < t_hi; t += 2) {
;             const bool last = (t == nt - 2);
;             const char* a1 = cA + (size_t)(t + 1) * kstep;
;             const char* a2 = last ? nA : cA + (size_t)(t + 2) * kstep; const char* b2 = last ? nB : cB + (size_t)(t + 2) * kstep;
;             const char* a3 = a2 + kstep; const char* b3 = b2 + kstep;
;             const int rflag = __builtin_amdgcn_readfirstlane(t | (int)(ui == 0));
;             PG8_LDB(B0, 0, 0); PG8_LDB(B1, 0, 1); PG8_SCHED; PG8_LDA(At, 0, 0); PG8_STAGE(PG8_SA(1, 1), a1 + hstepA, voffA);
;             if constexpr (Epi::NSTORES > 0) PG8_WAIT_RELAX(rflag, 8 + Epi::NSTORES); else PG8_WAIT_V(8);
;             PG8_WAIT_L(0); PG8_BAR; PG8_MMA(0, 0, At, B0); PG8_MMA(0, 1, At, B1); PG8_BAR; PG8_SCHED;
.LBB0_498:
	s_add_u32 s48, s57, s70
	s_addc_u32 s49, s26, s71
	v_readlane_b32 s4, v242, 27
	s_add_u32 s40, s4, s90
	v_readlane_b32 s4, v242, 28
	s_addc_u32 s41, s4, s91
	s_andn2_b64 vcc, exec, s[60:61]
	s_cbranch_vccnz .LBB0_501
	s_and_b64 s[4:5], s[72:73], exec
	s_cselect_b32 s16, s49, s1
	s_cselect_b32 s17, s48, s0
	s_cselect_b32 s18, s41, s55
	s_cselect_b32 s19, s40, s54
	s_cmp_eq_u32 s96, 0
	s_cselect_b64 s[4:5], -1, 0
	v_cndmask_b32_e64 v2, 0, 1, s[4:5]
	s_add_u32 s4, s0, 0x80080
	s_addc_u32 s5, s1, 0
	s_add_u32 s20, s54, 0x100
	s_mov_b32 s6, 0
	s_addc_u32 s21, s55, 0
	v_xor_b32_e32 v210, 64, v186
	v_xor_b32_e32 v211, 64, v185
.LBB0_500:
	s_add_i32 s22, s6, 2
	s_add_u32 s7, s4, 0xfff80080
	s_addc_u32 s14, s5, -1
	s_add_i32 s23, 0, 0x10000
	s_cmp_eq_u32 s94, s6
	v_add_u32_e32 v182, s6, v2
	s_cselect_b32 s15, s16, s14
	s_cselect_b32 s14, s17, s7
	s_waitcnt lgkmcnt(0)
	s_cselect_b32 s7, s18, s21
	s_cselect_b32 s6, s19, s20
	s_add_i32 s52, 0, 0x14000
	ds_read_b128 v[134:137], v185
	ds_read_b128 v[138:141], v211
	ds_read_b128 v[142:145], v185 offset:2048
	ds_read_b128 v[146:149], v211 offset:2048
	ds_read_b128 v[162:165], v185 offset:16384
	ds_read_b128 v[166:169], v211 offset:16384
	ds_read_b128 v[170:173], v185 offset:18432
	ds_read_b128 v[174:177], v211 offset:18432
	s_add_i32 m0, s50, 0xc000
	ds_read_b128 v[178:181], v186
	ds_read_b128 v[188:191], v210
	ds_read_b128 v[192:195], v186 offset:2048
	ds_read_b128 v[206:209], v210 offset:2048
	ds_read_b128 v[224:227], v186 offset:4096
	ds_read_b128 v[228:231], v210 offset:4096
	ds_read_b128 v[232:235], v186 offset:6144
	ds_read_b128 v[236:239], v210 offset:6144
	s_add_u32 s100, s4, 0xfff80000
	s_addc_u32 s101, s5, -1
	s_mov_b32 m0, s92
	s_nop 0
	global_load_lds_dwordx4 v158, s[100:101]
	s_mov_b32 m0, s93
	s_nop 0
	global_load_lds_dwordx4 v160, s[100:101]
	s_add_i32 m0, s50, 0xc000
	s_nop 0
	global_load_lds_dwordx4 v158, s[4:5]
	s_add_i32 m0, s50, 0xe000
	v_readfirstlane_b32 s53, v182
	global_load_lds_dwordx4 v160, s[4:5]
	s_cmp_eq_u32 s53, 0
	s_cbranch_scc1 .Lrw6
	s_waitcnt vmcnt(8)
.Lrw6:
	s_waitcnt vmcnt(24)
	s_waitcnt lgkmcnt(0)
	s_barrier
	s_setprio 1
	s_waitcnt lgkmcnt(0)
	v_mfma_f32_16x16x32_bf16 v[130:133], v[134:137], v[178:181], v[130:133]
	v_mfma_f32_16x16x32_bf16 v[126:129], v[142:145], v[178:181], v[126:129]
	v_mfma_f32_16x16x32_bf16 v[122:125], v[134:137], v[192:195], v[122:125]
	v_mfma_f32_16x16x32_bf16 v[118:121], v[142:145], v[192:195], v[118:121]
	v_mfma_f32_16x16x32_bf16 v[114:117], v[134:137], v[224:227], v[114:117]
	v_mfma_f32_16x16x32_bf16 v[110:113], v[142:145], v[224:227], v[110:113]
	v_mfma_f32_16x16x32_bf16 v[106:109], v[134:137], v[232:235], v[106:109]
	v_mfma_f32_16x16x32_bf16 v[102:105], v[142:145], v[232:235], v[102:105]
	v_mfma_f32_16x16x32_bf16 v[130:133], v[138:141], v[188:191], v[130:133]
	v_mfma_f32_16x16x32_bf16 v[126:129], v[146:149], v[188:191], v[126:129]
	v_mfma_f32_16x16x32_bf16 v[122:125], v[138:141], v[206:209], v[122:125]
	v_mfma_f32_16x16x32_bf16 v[118:121], v[146:149], v[206:209], v[118:121]
	v_mfma_f32_16x16x32_bf16 v[114:117], v[138:141], v[228:231], v[114:117]
	v_mfma_f32_16x16x32_bf16 v[110:113], v[146:149], v[228:231], v[110:113]
	v_mfma_f32_16x16x32_bf16 v[106:109], v[138:141], v[236:239], v[106:109]
	v_mfma_f32_16x16x32_bf16 v[102:105], v[146:149], v[236:239], v[102:105]
	s_setprio 0
	s_setprio 1
	v_mfma_f32_16x16x32_bf16 v[98:101], v[162:165], v[178:181], v[98:101]
	v_mfma_f32_16x16x32_bf16 v[94:97], v[170:173], v[178:181], v[94:97]
	v_mfma_f32_16x16x32_bf16 v[90:93], v[162:165], v[192:195], v[90:93]
	v_mfma_f32_16x16x32_bf16 v[86:89], v[170:173], v[192:195], v[86:89]
	v_mfma_f32_16x16x32_bf16 v[82:85], v[162:165], v[224:227], v[82:85]
	v_mfma_f32_16x16x32_bf16 v[78:81], v[170:173], v[224:227], v[78:81]
	v_mfma_f32_16x16x32_bf16 v[74:77], v[162:165], v[232:235], v[74:77]
	v_mfma_f32_16x16x32_bf16 v[70:73], v[170:173], v[232:235], v[70:73]
	v_mfma_f32_16x16x32_bf16 v[98:101], v[166:169], v[188:191], v[98:101]
	v_mfma_f32_16x16x32_bf16 v[94:97], v[174:177], v[188:191], v[94:97]
	v_mfma_f32_16x16x32_bf16 v[90:93], v[166:169], v[206:209], v[90:93]
	v_mfma_f32_16x16x32_bf16 v[86:89], v[174:177], v[206:209], v[86:89]
	v_mfma_f32_16x16x32_bf16 v[82:85], v[166:169], v[228:231], v[82:85]
	v_mfma_f32_16x16x32_bf16 v[78:81], v[174:177], v[228:231], v[78:81]
	v_mfma_f32_16x16x32_bf16 v[74:77], v[166:169], v[236:239], v[74:77]
	v_mfma_f32_16x16x32_bf16 v[70:73], v[174:177], v[236:239], v[70:73]
	s_setprio 0
	s_barrier
	s_add_i32 s23, s23, s27
	s_mov_b32 m0, s23
	ds_read_b128 v[178:181], v186 offset:16384
	ds_read_b128 v[188:191], v210 offset:16384
	ds_read_b128 v[192:195], v186 offset:18432
	ds_read_b128 v[206:209], v210 offset:18432
	ds_read_b128 v[224:227], v186 offset:20480
	ds_read_b128 v[228:231], v210 offset:20480
	ds_read_b128 v[232:235], v186 offset:22528
	ds_read_b128 v[236:239], v210 offset:22528
	global_load_lds_dwordx4 v152, s[6:7]
	s_add_i32 m0, s23, 0x2000
	s_add_u32 s24, s6, 0x80000
	s_addc_u32 s25, s7, 0
	s_add_i32 s23, s52, s27
	global_load_lds_dwordx4 v156, s[6:7]
	s_mov_b32 m0, s23
	s_nop 0
	global_load_lds_dwordx4 v152, s[24:25]
	s_add_i32 m0, s23, 0x2000
	s_nop 0
	global_load_lds_dwordx4 v156, s[24:25]
	s_cmp_eq_u32 s53, 0
	s_cbranch_scc1 .Lrw7
	s_waitcnt vmcnt(6)
; #define PG8_STAGE(bufoff, gbase, voff) do { _Pragma("unroll") for (int _i = 0; _i < 2; ++_i) \
;         __builtin_amdgcn_global_load_lds((const unsigned*)((const char*)(gbase) + (voff)[_i]), (LAS unsigned*)(lds + (bufoff) + ldsw + _i * 8192), 16, 0, 0); } while (0)
; #define PG8_LDA(dst, b, h) do { _Pragma("unroll") for (int m = 0; m < 4; ++m) _Pragma("unroll") for (int k = 0; k < 2; ++k) dst[m][k] = *(const LAS bf16x8*)(lds + PG8_SA(b, h) + aoff + m * 2048 + k * 1024); } while (0)
; #define PG8_LDB(dst, b, h) do { _Pragma("unroll") for (int n = 0; n < 2; ++n) _Pragma("unroll") for (int k = 0; k < 2; ++k) dst[n][k] = *(const LAS bf16x8*)(lds + PG8_SB(b, h) + boff + n * 2048 + k * 1024); } while (0)
; #define PG8_MMA(ai, bj, At, Bt) do { __builtin_amdgcn_s_setprio(1); _Pragma("unroll") for (int m = 0; m < 4; ++m) _Pragma("unroll") for (int n = 0; n < 2; ++n) _Pragma("unroll") for (int k = 0; k < 2; ++k) \
;         acc[ai][bj][m][n] = __builtin_amdgcn_mfma_f32_16x16x32_bf16(Bt[n][k], At[m][k], acc[ai][bj][m][n], 0, 0, 0); __builtin_amdgcn_s_setprio(0); } while (0)
; #define PG8_WAIT_V(n) asm volatile("s_waitcnt vmcnt(" #n ")" ::: "memory")
; #define PG8_WAIT_L(n) asm volatile("s_waitcnt lgkmcnt(" #n ")" ::: "memory")
; #define PG8_BAR __builtin_amdgcn_s_barrier()
; #define PG8_WAIT_RELAX(flag, n) asm volatile("s_cmp_eq_u32 %0, 0\n\ts_cbranch_scc1 .Lrw%=\n\ts_waitcnt vmcnt(8)\n.Lrw%=:\n\ts_waitcnt vmcnt(%1)" :: "s"(flag), "n"(n) : "scc", "memory")
; #define PG8_SCHED __builtin_amdgcn_sched_barrier(0)
; template <class Epi, bool ALIGN_EPI = true>
; __device__ __forceinline__ void gemm_phase(LAS unsigned char* lds, const Gemm g, const Sched& S, const Epi& E) {
;     ...
;             PG8_WAIT_L(0); PG8_BAR; PG8_MMA(0, 0, At, B0); PG8_MMA(0, 1, At, B1); PG8_BAR; PG8_SCHED;
;             PG8_LDA(At, 0, 1); PG8_STAGE(PG8_SB(0, 0), b2, voffB); PG8_STAGE(PG8_SB(0, 1), b2 + hstepB, voffB); PG8_STAGE(PG8_SA(0, 0), a2, voffA);
;             if constexpr (Epi::NSTORES > 0) PG8_WAIT_RELAX(rflag, 8 + Epi::NSTORES); else PG8_WAIT_V(8);
;             PG8_WAIT_L(0); PG8_BAR; PG8_MMA(1, 0, At, B0); PG8_MMA(1, 1, At, B1); PG8_BAR; PG8_SCHED;
;             PG8_LDB(B0, 1, 0); PG8_LDB(B1, 1, 1); PG8_SCHED; PG8_LDA(At, 1, 0); PG8_STAGE(PG8_SA(0, 1), a2 + hstepA, voffA);
.Lrw7:
	s_waitcnt vmcnt(6)
	s_waitcnt lgkmcnt(0)
	s_barrier
	s_setprio 1
	s_waitcnt lgkmcnt(0)
	v_mfma_f32_16x16x32_bf16 v[66:69], v[134:137], v[178:181], v[66:69]
	v_mfma_f32_16x16x32_bf16 v[62:65], v[142:145], v[178:181], v[62:65]
	v_mfma_f32_16x16x32_bf16 v[58:61], v[134:137], v[192:195], v[58:61]
	v_mfma_f32_16x16x32_bf16 v[54:57], v[142:145], v[192:195], v[54:57]
	v_mfma_f32_16x16x32_bf16 v[50:53], v[134:137], v[224:227], v[50:53]
	v_mfma_f32_16x16x32_bf16 v[46:49], v[142:145], v[224:227], v[46:49]
	v_mfma_f32_16x16x32_bf16 v[42:45], v[134:137], v[232:235], v[42:45]
	v_mfma_f32_16x16x32_bf16 v[38:41], v[142:145], v[232:235], v[38:41]
	v_mfma_f32_16x16x32_bf16 v[66:69], v[138:141], v[188:191], v[66:69]
	v_mfma_f32_16x16x32_bf16 v[62:65], v[146:149], v[188:191], v[62:65]
	v_mfma_f32_16x16x32_bf16 v[58:61], v[138:141], v[206:209], v[58:61]
	v_mfma_f32_16x16x32_bf16 v[54:57], v[146:149], v[206:209], v[54:57]
	v_mfma_f32_16x16x32_bf16 v[50:53], v[138:141], v[228:231], v[50:53]
	v_mfma_f32_16x16x32_bf16 v[46:49], v[146:149], v[228:231], v[46:49]
	v_mfma_f32_16x16x32_bf16 v[42:45], v[138:141], v[236:239], v[42:45]
	v_mfma_f32_16x16x32_bf16 v[38:41], v[146:149], v[236:239], v[38:41]
	s_setprio 0
	s_setprio 1
	v_mfma_f32_16x16x32_bf16 v[34:37], v[162:165], v[178:181], v[34:37]
	v_mfma_f32_16x16x32_bf16 v[30:33], v[170:173], v[178:181], v[30:33]
	v_mfma_f32_16x16x32_bf16 v[26:29], v[162:165], v[192:195], v[26:29]
	v_mfma_f32_16x16x32_bf16 v[22:25], v[170:173], v[192:195], v[22:25]
	v_mfma_f32_16x16x32_bf16 v[18:21], v[162:165], v[224:227], v[18:21]
	v_mfma_f32_16x16x32_bf16 v[14:17], v[170:173], v[224:227], v[14:17]
	v_mfma_f32_16x16x32_bf16 v[10:13], v[162:165], v[232:235], v[10:13]
	v_mfma_f32_16x16x32_bf16 v[4:7], v[170:173], v[232:235], v[6:9]
	v_mfma_f32_16x16x32_bf16 v[34:37], v[166:169], v[188:191], v[34:37]
	v_mfma_f32_16x16x32_bf16 v[30:33], v[174:177], v[188:191], v[30:33]
	v_mfma_f32_16x16x32_bf16 v[26:29], v[166:169], v[206:209], v[26:29]
	v_mfma_f32_16x16x32_bf16 v[22:25], v[174:177], v[206:209], v[22:25]
	v_mfma_f32_16x16x32_bf16 v[18:21], v[166:169], v[228:231], v[18:21]
	v_mfma_f32_16x16x32_bf16 v[14:17], v[174:177], v[228:231], v[14:17]
	v_mfma_f32_16x16x32_bf16 v[10:13], v[166:169], v[236:239], v[10:13]
	v_mfma_f32_16x16x32_bf16 v[4:7], v[174:177], v[236:239], v[4:7]
	s_setprio 0
	s_barrier
	s_add_i32 s23, 0, 0x18000
	s_add_i32 s24, 0, 0x1c000
	ds_read_b128 v[134:137], v185 offset:32768
	ds_read_b128 v[138:141], v211 offset:32768
	ds_read_b128 v[142:145], v185 offset:34816
	ds_read_b128 v[146:149], v211 offset:34816
	ds_read_b128 v[162:165], v185 offset:49152
	ds_read_b128 v[166:169], v211 offset:49152
	ds_read_b128 v[170:173], v185 offset:51200
	ds_read_b128 v[174:177], v211 offset:51200
	s_add_u32 s14, s14, 0x80000
	s_addc_u32 s15, s15, 0
	s_mov_b32 m0, s36
	ds_read_b128 v[178:181], v186 offset:32768
	ds_read_b128 v[188:191], v210 offset:32768
	ds_read_b128 v[192:195], v186 offset:34816
	ds_read_b128 v[206:209], v210 offset:34816
	ds_read_b128 v[224:227], v186 offset:36864
	ds_read_b128 v[228:231], v210 offset:36864
	ds_read_b128 v[232:235], v186 offset:38912
	ds_read_b128 v[236:239], v210 offset:38912
	s_add_u32 s100, s14, 0xfff80000
	s_addc_u32 s101, s15, -1
	s_mov_b32 m0, s50
	s_nop 0
	global_load_lds_dwordx4 v150, s[100:101]
	s_mov_b32 m0, s51
	s_nop 0
	global_load_lds_dwordx4 v154, s[100:101]
	s_mov_b32 m0, s36
	s_nop 0
	global_load_lds_dwordx4 v150, s[14:15]
	s_mov_b32 m0, s37
	s_nop 0
	global_load_lds_dwordx4 v154, s[14:15]
	s_waitcnt vmcnt(8)
	s_waitcnt lgkmcnt(0)
	s_barrier
; #define PG8_STAGE(bufoff, gbase, voff) do { _Pragma("unroll") for (int _i = 0; _i < 2; ++_i) \
;         __builtin_amdgcn_global_load_lds((const unsigned*)((const char*)(gbase) + (voff)[_i]), (LAS unsigned*)(lds + (bufoff) + ldsw + _i * 8192), 16, 0, 0); } while (0)
; #define PG8_LDA(dst, b, h) do { _Pragma("unroll") for (int m = 0; m < 4; ++m) _Pragma("unroll") for (int k = 0; k < 2; ++k) dst[m][k] = *(const LAS bf16x8*)(lds + PG8_SA(b, h) + aoff + m * 2048 + k * 1024); } while (0)
; #define PG8_LDB(dst, b, h) do { _Pragma("unroll") for (int n = 0; n < 2; ++n) _Pragma("unroll") for (int k = 0; k < 2; ++k) dst[n][k] = *(const LAS bf16x8*)(lds + PG8_SB(b, h) + boff + n * 2048 + k * 1024); } while (0)
; #define PG8_MMA(ai, bj, At, Bt) do { __builtin_amdgcn_s_setprio(1); _Pragma("unroll") for (int m = 0; m < 4; ++m) _Pragma("unroll") for (int n = 0; n < 2; ++n) _Pragma("unroll") for (int k = 0; k < 2; ++k) \
;         acc[ai][bj][m][n] = __builtin_amdgcn_mfma_f32_16x16x32_bf16(Bt[n][k], At[m][k], acc[ai][bj][m][n], 0, 0, 0); __builtin_amdgcn_s_setprio(0); } while (0)
; #define PG8_WAIT_V(n) asm volatile("s_waitcnt vmcnt(" #n ")" ::: "memory")
; #define PG8_WAIT_L(n) asm volatile("s_waitcnt lgkmcnt(" #n ")" ::: "memory")
; #define PG8_BAR __builtin_amdgcn_s_barrier()
; #define PG8_SCHED __builtin_amdgcn_sched_barrier(0)
; template <class Epi, bool ALIGN_EPI = true>
; __device__ __forceinline__ void gemm_phase(LAS unsigned char* lds, const Gemm g, const Sched& S, const Epi& E) {
;     ...
;             PG8_LDB(B0, 1, 0); PG8_LDB(B1, 1, 1); PG8_SCHED; PG8_LDA(At, 1, 0); PG8_STAGE(PG8_SA(0, 1), a2 + hstepA, voffA);
;             PG8_WAIT_V(8); PG8_WAIT_L(0); PG8_BAR; PG8_MMA(0, 0, At, B0); PG8_MMA(0, 1, At, B1); PG8_BAR; PG8_SCHED;
;             PG8_LDA(At, 1, 1); PG8_STAGE(PG8_SB(1, 0), b3, voffB); PG8_STAGE(PG8_SB(1, 1), b3 + hstepB, voffB); PG8_STAGE(PG8_SA(1, 0), a3, voffA);
;             PG8_WAIT_V(8); PG8_WAIT_L(0); PG8_BAR; PG8_MMA(1, 0, At, B0); PG8_MMA(1, 1, At, B1); PG8_BAR; PG8_SCHED;
	s_setprio 1
	s_waitcnt lgkmcnt(0)
	v_mfma_f32_16x16x32_bf16 v[130:133], v[134:137], v[178:181], v[130:133]
	v_mfma_f32_16x16x32_bf16 v[126:129], v[142:145], v[178:181], v[126:129]
	v_mfma_f32_16x16x32_bf16 v[122:125], v[134:137], v[192:195], v[122:125]
	v_mfma_f32_16x16x32_bf16 v[118:121], v[142:145], v[192:195], v[118:121]
	v_mfma_f32_16x16x32_bf16 v[114:117], v[134:137], v[224:227], v[114:117]
	v_mfma_f32_16x16x32_bf16 v[110:113], v[142:145], v[224:227], v[110:113]
	v_mfma_f32_16x16x32_bf16 v[106:109], v[134:137], v[232:235], v[106:109]
	v_mfma_f32_16x16x32_bf16 v[102:105], v[142:145], v[232:235], v[102:105]
	v_mfma_f32_16x16x32_bf16 v[130:133], v[138:141], v[188:191], v[130:133]
	v_mfma_f32_16x16x32_bf16 v[126:129], v[146:149], v[188:191], v[126:129]
	v_mfma_f32_16x16x32_bf16 v[122:125], v[138:141], v[206:209], v[122:125]
	v_mfma_f32_16x16x32_bf16 v[118:121], v[146:149], v[206:209], v[118:121]
	v_mfma_f32_16x16x32_bf16 v[114:117], v[138:141], v[228:231], v[114:117]
	v_mfma_f32_16x16x32_bf16 v[110:113], v[146:149], v[228:231], v[110:113]
	v_mfma_f32_16x16x32_bf16 v[106:109], v[138:141], v[236:239], v[106:109]
	v_mfma_f32_16x16x32_bf16 v[102:105], v[146:149], v[236:239], v[102:105]
	s_setprio 0
	s_setprio 1
	v_mfma_f32_16x16x32_bf16 v[98:101], v[162:165], v[178:181], v[98:101]
	v_mfma_f32_16x16x32_bf16 v[94:97], v[170:173], v[178:181], v[94:97]
	v_mfma_f32_16x16x32_bf16 v[90:93], v[162:165], v[192:195], v[90:93]
	v_mfma_f32_16x16x32_bf16 v[86:89], v[170:173], v[192:195], v[86:89]
	v_mfma_f32_16x16x32_bf16 v[82:85], v[162:165], v[224:227], v[82:85]
	v_mfma_f32_16x16x32_bf16 v[78:81], v[170:173], v[224:227], v[78:81]
	v_mfma_f32_16x16x32_bf16 v[74:77], v[162:165], v[232:235], v[74:77]
	v_mfma_f32_16x16x32_bf16 v[70:73], v[170:173], v[232:235], v[70:73]
	v_mfma_f32_16x16x32_bf16 v[98:101], v[166:169], v[188:191], v[98:101]
	v_mfma_f32_16x16x32_bf16 v[94:97], v[174:177], v[188:191], v[94:97]
	v_mfma_f32_16x16x32_bf16 v[90:93], v[166:169], v[206:209], v[90:93]
	v_mfma_f32_16x16x32_bf16 v[86:89], v[174:177], v[206:209], v[86:89]
	v_mfma_f32_16x16x32_bf16 v[82:85], v[166:169], v[228:231], v[82:85]
	v_mfma_f32_16x16x32_bf16 v[78:81], v[174:177], v[228:231], v[78:81]
	v_mfma_f32_16x16x32_bf16 v[74:77], v[166:169], v[236:239], v[74:77]
	v_mfma_f32_16x16x32_bf16 v[70:73], v[174:177], v[236:239], v[70:73]
	s_setprio 0
	s_barrier
	s_add_u32 s100, s6, 0x80
	s_addc_u32 s101, s7, 0
	s_add_i32 s14, s23, s27
	s_mov_b32 m0, s14
	ds_read_b128 v[178:181], v186 offset:49152
	ds_read_b128 v[188:191], v210 offset:49152
	ds_read_b128 v[192:195], v186 offset:51200
	ds_read_b128 v[206:209], v210 offset:51200
	ds_read_b128 v[224:227], v186 offset:53248
	ds_read_b128 v[228:231], v210 offset:53248
	ds_read_b128 v[232:235], v186 offset:55296
	ds_read_b128 v[236:239], v210 offset:55296
	global_load_lds_dwordx4 v152, s[100:101]
	s_add_i32 m0, s14, 0x2000
	s_add_u32 s6, s6, 0x80080
	s_addc_u32 s7, s7, 0
	s_add_i32 s14, s24, s27
	global_load_lds_dwordx4 v156, s[100:101]
	s_mov_b32 m0, s14
	s_nop 0
	global_load_lds_dwordx4 v152, s[6:7]
	s_add_i32 m0, s14, 0x2000
	s_nop 0
	global_load_lds_dwordx4 v156, s[6:7]
	s_waitcnt vmcnt(6)
	s_waitcnt lgkmcnt(0)
	s_barrier
	s_setprio 1
	s_waitcnt lgkmcnt(0)
	v_mfma_f32_16x16x32_bf16 v[66:69], v[134:137], v[178:181], v[66:69]
	v_mfma_f32_16x16x32_bf16 v[62:65], v[142:145], v[178:181], v[62:65]
	v_mfma_f32_16x16x32_bf16 v[58:61], v[134:137], v[192:195], v[58:61]
	v_mfma_f32_16x16x32_bf16 v[54:57], v[142:145], v[192:195], v[54:57]
	v_mfma_f32_16x16x32_bf16 v[50:53], v[134:137], v[224:227], v[50:53]
	v_mfma_f32_16x16x32_bf16 v[46:49], v[142:145], v[224:227], v[46:49]
	v_mfma_f32_16x16x32_bf16 v[42:45], v[134:137], v[232:235], v[42:45]
	v_mfma_f32_16x16x32_bf16 v[38:41], v[142:145], v[232:235], v[38:41]
	v_mfma_f32_16x16x32_bf16 v[66:69], v[138:141], v[188:191], v[66:69]
	v_mfma_f32_16x16x32_bf16 v[62:65], v[146:149], v[188:191], v[62:65]
	v_mfma_f32_16x16x32_bf16 v[58:61], v[138:141], v[206:209], v[58:61]
	v_mfma_f32_16x16x32_bf16 v[54:57], v[146:149], v[206:209], v[54:57]
	v_mfma_f32_16x16x32_bf16 v[50:53], v[138:141], v[228:231], v[50:53]
	v_mfma_f32_16x16x32_bf16 v[46:49], v[146:149], v[228:231], v[46:49]
	v_mfma_f32_16x16x32_bf16 v[42:45], v[138:141], v[236:239], v[42:45]
	v_mfma_f32_16x16x32_bf16 v[38:41], v[146:149], v[236:239], v[38:41]
	s_setprio 0
	s_setprio 1
	v_mfma_f32_16x16x32_bf16 v[34:37], v[162:165], v[178:181], v[34:37]
	v_mfma_f32_16x16x32_bf16 v[30:33], v[170:173], v[178:181], v[30:33]
	v_mfma_f32_16x16x32_bf16 v[26:29], v[162:165], v[192:195], v[26:29]
	v_mfma_f32_16x16x32_bf16 v[22:25], v[170:173], v[192:195], v[22:25]
	v_mfma_f32_16x16x32_bf16 v[18:21], v[162:165], v[224:227], v[18:21]
	v_mfma_f32_16x16x32_bf16 v[14:17], v[170:173], v[224:227], v[14:17]
	v_mfma_f32_16x16x32_bf16 v[8:11], v[162:165], v[232:235], v[10:13]
	v_mfma_f32_16x16x32_bf16 v[4:7], v[170:173], v[232:235], v[4:7]
	v_mfma_f32_16x16x32_bf16 v[34:37], v[166:169], v[188:191], v[34:37]
	v_mfma_f32_16x16x32_bf16 v[30:33], v[174:177], v[188:191], v[30:33]
	v_mfma_f32_16x16x32_bf16 v[26:29], v[166:169], v[206:209], v[26:29]
	v_mfma_f32_16x16x32_bf16 v[22:25], v[174:177], v[206:209], v[22:25]
	v_mfma_f32_16x16x32_bf16 v[18:21], v[166:169], v[228:231], v[18:21]
	v_mfma_f32_16x16x32_bf16 v[14:17], v[174:177], v[228:231], v[14:17]
	v_mfma_f32_16x16x32_bf16 v[10:13], v[166:169], v[236:239], v[8:11]
	v_mfma_f32_16x16x32_bf16 v[6:9], v[174:177], v[236:239], v[4:7]
	s_setprio 0
	s_barrier
	s_add_u32 s4, s4, 0x100
	s_addc_u32 s5, s5, 0
	s_add_u32 s20, s20, 0x100
	s_addc_u32 s21, s21, 0
	s_cmp_ge_i32 s22, s46
	s_mov_b32 s6, s22
	s_cbranch_scc0 .LBB0_500

; #define PG8_STAGE(bufoff, gbase, voff) do { _Pragma("unroll") for (int _i = 0; _i < 2; ++_i) \
;         __builtin_amdgcn_global_load_lds((const unsigned*)((const char*)(gbase) + (voff)[_i]), (LAS unsigned*)(lds + (bufoff) + ldsw + _i * 8192), 16, 0, 0); } while (0)
; #define PG8_WAIT_V(n) asm volatile("s_waitcnt vmcnt(" #n ")" ::: "memory")
; #define PG8_BAR __builtin_amdgcn_s_barrier()
; template <class Epi, bool ALIGN_EPI = true>
; __device__ __forceinline__ void gemm_phase(LAS unsigned char* lds, const Gemm g, const Sched& S, const Epi& E) {
;     ...
;     for (int i = 0; i < 2; ++i) { int R, C; stage_rc(tid * 16 + i * 8192, R, C); const int Rb = (R & ~31) + perm32(R & 31);
;         voffA[i] = (unsigned)(R * g.lda + C) * 2u; voffB[i] = (unsigned)(Rb * g.ldb + C) * 2u; }
;     ...
;     PG8_STAGE(PG8_SB(0, 0), cB, voffB); PG8_STAGE(PG8_SB(0, 1), cB + hstepB, voffB); PG8_STAGE(PG8_SA(0, 0), cA, voffA); PG8_STAGE(PG8_SA(0, 1), cA + hstepA, voffA);
;     if (wr == 1) PG8_BAR;
;     PG8_WAIT_V(2); PG8_BAR;
;     PG8_STAGE(PG8_SB(1, 0), cB + kstep, voffB); PG8_STAGE(PG8_SA(1, 0), cA + kstep, voffA); PG8_STAGE(PG8_SB(1, 1), cB + hstepB + kstep, voffB);
.LBB0_944:
	s_or_b64 exec, exec, s[26:27]
	v_bfe_i32 v5, v12, 27, 1
	v_lshlrev_b32_e32 v4, 4, v12
	v_lshrrev_b32_e32 v5, 22, v5
	v_add_u32_e32 v5, v4, v5
	v_and_b32_e32 v5, 0xfffffc00, v5
	v_sub_u32_e32 v5, v4, v5
	v_lshrrev_b32_e32 v6, 4, v5
	v_ashrrev_i32_e32 v2, 31, v12
	v_bitop3_b32 v5, v6, v5, 32 bitop3:0x6c
	v_lshrrev_b32_e32 v2, 26, v2
	v_ashrrev_i32_e32 v7, 31, v5
	v_add_u32_e32 v2, v12, v2
	v_lshrrev_b32_e32 v7, 26, v7
	v_ashrrev_i32_e32 v2, 6, v2
	v_add_u32_e32 v7, v5, v7
	v_lshlrev_b32_e32 v6, 3, v2
	v_ashrrev_i32_e32 v13, 6, v7
	v_and_b32_e32 v7, 0xc0, v7
	v_and_b32_e32 v6, -16, v6
	v_sub_u32_e32 v5, v5, v7
	v_add_u32_e32 v6, v13, v6
	v_ashrrev_i16_sdwa v5, v213, sext(v5) dst_sel:DWORD dst_unused:UNUSED_PAD src0_sel:DWORD src1_sel:BYTE_0
	v_lshlrev_b32_e32 v8, 5, v2
	v_bfe_i32 v14, v5, 0, 16
	v_lshlrev_b32_e32 v5, 1, v6
	v_lshrrev_b32_e32 v7, 2, v6
	v_and_b32_e32 v9, 3, v13
	s_mov_b32 s10, 0xfffe0
	v_and_b32_e32 v8, 32, v8
	v_and_b32_e32 v5, 24, v5
	v_and_b32_e32 v7, 4, v7
	v_and_or_b32 v9, v6, s10, v9
	v_or3_b32 v5, v9, v7, v5
	v_add_lshl_u32 v7, v8, v14, 1
	v_add_u32_e32 v4, 0x2000, v4
	v_lshl_add_u32 v152, v5, 12, v7
	v_lshrrev_b32_e32 v247, 3, v0
	v_xor_b32_e32 v247, v247, v0
	v_and_b32_e32 v247, 7, v247
	v_lshl_add_u32 v152, v247, 4, v152
	v_and_b32_e32 v247, 64, v0
	v_sub_u32_e32 v152, v152, v247
	v_lshrrev_b32_e32 v247, 4, v0
	v_and_b32_e32 v247, 2, v247
	v_xor_b32_e32 v247, v247, v0
	v_and_b32_e32 v247, 3, v247
	v_lshlrev_b32_e32 v247, 4, v247
	v_sub_u32_e32 v152, v152, v247
	v_and_b32_e32 v247, 64, v0
	v_mul_u32_u24_e32 v247, 0x400, v247
	v_add_u32_e32 v152, v152, v247
	v_and_b32_e32 v247, 32, v0
	v_mul_u32_u24_e32 v247, 0x400, v247
	v_sub_u32_e32 v152, v152, v247
	v_and_b32_e32 v247, 16, v0
	v_mul_u32_u24_e32 v247, 0x600, v247
	v_sub_u32_e32 v152, v152, v247
	v_and_b32_e32 v247, 8, v0
	v_mul_u32_u24_e32 v247, 0x200, v247
	v_sub_u32_e32 v152, v152, v247
	v_and_b32_e32 v247, 4, v0
	v_mul_u32_u24_e32 v247, 0x400, v247
	v_sub_u32_e32 v152, v152, v247
	v_ashrrev_i32_e32 v5, 31, v4
	v_lshrrev_b32_e32 v5, 22, v5
	v_add_u32_e32 v5, v4, v5
	v_ashrrev_i32_e32 v15, 10, v5
	v_mul_i32_i24_e32 v5, 0x400, v15
	v_sub_u32_e32 v4, v4, v5
	v_lshrrev_b32_e32 v5, 4, v4
	v_bitop3_b32 v4, v5, v4, 32 bitop3:0x6c
	v_lshl_add_u32 v150, v6, 12, v7
	v_lshrrev_b32_e32 v247, 3, v0
	v_xor_b32_e32 v247, v247, v0
	v_and_b32_e32 v247, 7, v247
	v_lshl_add_u32 v150, v247, 4, v150
	v_and_b32_e32 v247, 64, v0
	v_sub_u32_e32 v150, v150, v247
	v_lshrrev_b32_e32 v247, 4, v0
	v_and_b32_e32 v247, 2, v247
	v_xor_b32_e32 v247, v247, v0
	v_and_b32_e32 v247, 3, v247
	v_lshlrev_b32_e32 v247, 4, v247
	v_sub_u32_e32 v150, v150, v247
	v_bfe_u32 v247, v0, 2, 4
	v_add_u32_e32 v247, 1, v247
	v_lshrrev_b32_e32 v247, 1, v247
	v_mul_u32_u24_e32 v247, 0x1000, v247
	v_sub_u32_e32 v150, v150, v247
	v_and_b32_e32 v247, 64, v0
	v_mul_u32_u24_e32 v247, 0x200, v247
	v_add_u32_e32 v150, v150, v247
	v_ashrrev_i32_e32 v6, 31, v4
	v_readlane_b32 s36, v246, 42
	v_lshrrev_b32_e32 v6, 26, v6
	v_readlane_b32 s38, v246, 44
	v_lshlrev_b32_e32 v5, 3, v15
	v_add_u32_e32 v6, v4, v6
	v_readlane_b32 s39, v246, 45
	s_add_u32 s26, s38, s42
	v_and_b32_e32 v5, -16, v5
	v_ashrrev_i32_e32 v16, 6, v6
	v_readlane_b32 s37, v246, 43
	s_addc_u32 s27, s39, s43
	s_ashr_i32 s30, s58, 6
	v_add_u32_e32 v5, v16, v5
	v_and_b32_e32 v6, 0xc0, v6
	v_and_b32_e32 v8, 3, v16
	s_ashr_i32 s33, s58, 8
	v_sub_u32_e32 v4, v4, v6
	v_and_or_b32 v8, v5, s10, v8
	s_lshl_b32 s94, s30, 10
	v_readlane_b32 s36, v243, 4
	v_readlane_b32 s10, v242, 27
	v_ashrrev_i16_sdwa v4, v213, sext(v4) dst_sel:DWORD dst_unused:UNUSED_PAD src0_sel:DWORD src1_sel:BYTE_0
	v_readlane_b32 s37, v243, 5
	s_add_u32 s40, s10, s36
	v_readlane_b32 s10, v242, 28
	v_lshlrev_b32_e32 v7, 5, v15
	v_bfe_i32 v17, v4, 0, 16
	v_lshlrev_b32_e32 v4, 1, v5
	v_lshrrev_b32_e32 v6, 2, v5
	s_addc_u32 s41, s10, s37
	s_add_i32 s48, s94, 0
	v_and_b32_e32 v7, 32, v7
	v_and_b32_e32 v4, 24, v4
	v_and_b32_e32 v6, 4, v6
	s_waitcnt lgkmcnt(0)
	s_barrier
	s_add_i32 m0, s48, 0x10000
	v_or3_b32 v4, v8, v6, v4
	v_add_lshl_u32 v6, v7, v17, 1
	global_load_lds_dwordx4 v152, s[40:41]
	s_add_i32 m0, s48, 0x12000
	v_lshl_add_u32 v156, v4, 12, v6
	v_lshrrev_b32_e32 v247, 3, v0
	v_xor_b32_e32 v247, v247, v0
	v_and_b32_e32 v247, 7, v247
	v_lshl_add_u32 v156, v247, 4, v156
	v_and_b32_e32 v247, 64, v0
	v_sub_u32_e32 v156, v156, v247
	v_lshrrev_b32_e32 v247, 4, v0
	v_and_b32_e32 v247, 2, v247
	v_xor_b32_e32 v247, v247, v0
	v_and_b32_e32 v247, 3, v247
	v_lshlrev_b32_e32 v247, 4, v247
	v_sub_u32_e32 v156, v156, v247
	v_and_b32_e32 v247, 64, v0
	v_mul_u32_u24_e32 v247, 0x400, v247
	v_add_u32_e32 v156, v156, v247
	v_and_b32_e32 v247, 32, v0
	v_mul_u32_u24_e32 v247, 0x400, v247
	v_sub_u32_e32 v156, v156, v247
	v_and_b32_e32 v247, 16, v0
	v_mul_u32_u24_e32 v247, 0x600, v247
	v_sub_u32_e32 v156, v156, v247
	v_and_b32_e32 v247, 8, v0
	v_mul_u32_u24_e32 v247, 0x200, v247
	v_sub_u32_e32 v156, v156, v247
	v_and_b32_e32 v247, 4, v0
	v_mul_u32_u24_e32 v247, 0x400, v247
	v_sub_u32_e32 v156, v156, v247
	s_add_u32 s36, s40, 0x80000
	global_load_lds_dwordx4 v156, s[40:41]
	s_addc_u32 s37, s41, 0
	s_add_i32 m0, s48, 0x14000
	v_lshl_add_u32 v154, v5, 12, v6
	v_lshrrev_b32_e32 v247, 3, v0
	v_xor_b32_e32 v247, v247, v0
	v_and_b32_e32 v247, 7, v247
	v_lshl_add_u32 v154, v247, 4, v154
	v_and_b32_e32 v247, 64, v0
	v_sub_u32_e32 v154, v154, v247
	v_lshrrev_b32_e32 v247, 4, v0
	v_and_b32_e32 v247, 2, v247
	v_xor_b32_e32 v247, v247, v0
	v_and_b32_e32 v247, 3, v247
	v_lshlrev_b32_e32 v247, 4, v247
	v_sub_u32_e32 v154, v154, v247
	v_bfe_u32 v247, v0, 2, 4
	v_add_u32_e32 v247, 1, v247
	v_lshrrev_b32_e32 v247, 1, v247
	v_mul_u32_u24_e32 v247, 0x1000, v247
	v_sub_u32_e32 v154, v154, v247
	v_and_b32_e32 v247, 64, v0
	v_mul_u32_u24_e32 v247, 0x200, v247
	v_add_u32_e32 v154, v154, v247
	global_load_lds_dwordx4 v152, s[36:37]
	s_add_i32 m0, s48, 0x16000
	v_mov_b32_e32 v153, v3
	global_load_lds_dwordx4 v156, s[36:37]
	v_readlane_b32 s36, v243, 0
	v_readlane_b32 s37, v243, 1
	s_add_u32 s50, s26, s36
	s_addc_u32 s51, s27, s37
	s_add_i32 s49, s48, 0x2000
	s_mov_b32 m0, s48
	s_add_u32 s36, s50, 0x80000
	global_load_lds_dwordx4 v150, s[50:51]
	s_mov_b32 m0, s49
	s_addc_u32 s37, s51, 0
	s_add_i32 s46, s48, 0x4000
	global_load_lds_dwordx4 v154, s[50:51]
	s_mov_b32 m0, s46
	s_add_i32 s47, s48, 0x6000
	global_load_lds_dwordx4 v150, s[36:37]
	s_mov_b32 m0, s47
	v_mov_b32_e32 v157, v3
	global_load_lds_dwordx4 v154, s[36:37]
	v_mov_b32_e32 v151, v3
	v_mov_b32_e32 v155, v3
	s_cmp_eq_u32 s33, 1
	v_lshl_add_u64 v[10:11], s[40:41], 0, v[152:153]
	v_lshl_add_u64 v[8:9], s[40:41], 0, v[156:157]
	v_lshl_add_u64 v[4:5], s[50:51], 0, v[150:151]
	s_cselect_b64 s[42:43], -1, 0
	s_cmp_lg_u32 s33, 1
	v_lshl_add_u64 v[6:7], s[50:51], 0, v[154:155]
	s_cbranch_scc1 .LBB0_946
	s_barrier
; #define PG8_STAGE(bufoff, gbase, voff) do { _Pragma("unroll") for (int _i = 0; _i < 2; ++_i) \
;         __builtin_amdgcn_global_load_lds((const unsigned*)((const char*)(gbase) + (voff)[_i]), (LAS unsigned*)(lds + (bufoff) + ldsw + _i * 8192), 16, 0, 0); } while (0)
; #define PG8_WAIT_V(n) asm volatile("s_waitcnt vmcnt(" #n ")" ::: "memory")
; #define PG8_BAR __builtin_amdgcn_s_barrier()
; template <class Epi, bool ALIGN_EPI = true>
; __device__ __forceinline__ void gemm_phase(LAS unsigned char* lds, const Gemm g, const Sched& S, const Epi& E) {
;     ...
;     for (int i = 0; i < 2; ++i) { int R, C; stage_rc(tid * 16 + i * 8192, R, C); const int Rb = (R & ~31) + perm32(R & 31);
;         voffA[i] = (unsigned)(R * g.lda + C) * 2u; voffB[i] = (unsigned)(Rb * g.ldb + C) * 2u; }
;     const size_t kstep = (size_t)(BK * 2);
;     const size_t hstepA = (size_t)HALF * g.lda * 2, hstepB = (size_t)HALF * g.ldb * 2;
;     const unsigned ldsw = (unsigned)wid * 1024u;
;     const int aoff = lds_byte(wr * 64 + fr, fq * 8), boff = lds_byte(wc * 32 + fr, fq * 8);
;     ...
;     f32x4 acc[2][2][4][2];
; #pragma unroll
;     for (int a = 0; a < 2; ++a)
; #pragma unroll
;         for (int b = 0; b < 2; ++b)
; #pragma unroll
;             for (int m = 0; m < 4; ++m)
; #pragma unroll
;                 for (int n = 0; n < 2; ++n) acc[a][b][m][n] = (f32x4){0.f, 0.f, 0.f, 0.f};
;     bf16x8 At[4][2], B0[2][2], B1[2][2];
;     const char* cA = (const char*)g.A + cur.aoff; const char* cB = (const char*)g.Bt + cur.boff;
;     PG8_STAGE(PG8_SB(0, 0), cB, voffB); PG8_STAGE(PG8_SB(0, 1), cB + hstepB, voffB); PG8_STAGE(PG8_SA(0, 0), cA, voffA); PG8_STAGE(PG8_SA(0, 1), cA + hstepA, voffA);
;     if (wr == 1) PG8_BAR;
;     PG8_WAIT_V(2); PG8_BAR;
;     PG8_STAGE(PG8_SB(1, 0), cB + kstep, voffB); PG8_STAGE(PG8_SA(1, 0), cA + kstep, voffA); PG8_STAGE(PG8_SB(1, 1), cB + hstepB + kstep, voffB);
;     PG8_WAIT_V(6); PG8_BAR;
.LBB0_946:
	v_readlane_b32 s36, v246, 42
	v_readlane_b32 s38, v246, 44
	v_readlane_b32 s39, v246, 45
	s_add_u32 s52, s38, s44
	s_addc_u32 s53, s39, s45
	s_add_u32 s24, s38, s24
	s_addc_u32 s25, s39, s25
	v_readlane_b32 s37, v246, 43
	s_add_u32 s36, s38, s20
	s_addc_u32 s37, s39, s21
	s_add_u32 s20, s38, s22
	s_addc_u32 s21, s39, s23
	s_add_u32 s18, s38, s18
	s_addc_u32 s19, s39, s19
	s_add_u32 s16, s38, s16
	s_addc_u32 s17, s39, s17
	s_add_u32 s6, s38, s6
	s_addc_u32 s7, s39, s7
	s_add_u32 s54, s38, s4
	s_addc_u32 s44, s39, s5
	s_add_u32 s4, s38, s14
	s_addc_u32 s5, s39, s15
	s_lshl_b64 s[0:1], s[0:1], 2
	s_mov_b64 s[38:39], s[52:53]
	s_add_u32 s52, s4, s0
	s_addc_u32 s53, s5, s1
	s_ashr_i32 s0, s56, 31
	s_lshr_b32 s0, s0, 26
	s_add_i32 s0, s56, s0
	s_ashr_i32 s31, s0, 6
	s_lshl_b32 s0, s30, 5
	s_and_b32 s45, s0, 0x60
	s_add_i32 m0, s48, 0x18000
	v_lshl_add_u64 v[10:11], v[10:11], 0, s[8:9]
	s_lshl_b32 s34, s33, 6
	s_lshl_b32 s4, s33, 13
	s_lshl_b32 s5, s45, 7
	s_waitcnt vmcnt(2)
	s_barrier
	global_load_lds_dwordx4 v[10:11], off
	v_lshl_add_u64 v[8:9], v[8:9], 0, s[8:9]
	s_add_i32 m0, s48, 0x1a000
	s_add_i32 s30, s48, 0x8000
	s_add_i32 s33, s48, 0xa000
	global_load_lds_dwordx4 v[8:9], off
	v_lshl_add_u64 v[4:5], v[4:5], 0, s[8:9]
	s_mov_b32 m0, s30
	s_add_u32 s0, s40, 0x80080
	global_load_lds_dwordx4 v[4:5], off
	v_lshl_add_u64 v[4:5], v[6:7], 0, s[8:9]
	s_mov_b32 m0, s33
	s_addc_u32 s1, s41, 0
	global_load_lds_dwordx4 v[4:5], off
	s_add_i32 m0, s48, 0x1c000
	v_lshl_add_u64 v[4:5], s[0:1], 0, v[152:153]
	global_load_lds_dwordx4 v[4:5], off
	v_lshl_add_u64 v[4:5], s[0:1], 0, v[156:157]
	s_add_i32 m0, s48, 0x1e000
	s_movk_i32 s0, 0x3c0
	global_load_lds_dwordx4 v[4:5], off
	v_and_b32_e32 v4, 48, v12
	v_lshlrev_b32_e32 v5, 6, v12
	v_and_or_b32 v4, v5, s0, v4
	v_lshlrev_b32_e32 v5, 2, v12
	v_and_b32_e32 v5, 32, v5
	v_bitop3_b32 v6, v4, s4, v5 bitop3:0xde
	v_bitop3_b32 v185, s5, v4, v5 bitop3:0xf6
	v_bfe_u32 v185, v0, 4, 2
	v_xor_b32_e32 v185, v185, v0
	v_and_b32_e32 v185, 7, v185
	v_lshlrev_b32_e32 v185, 4, v185
	v_and_b32_e32 v247, 15, v0
	v_lshl_or_b32 v185, v247, 7, v185
	v_and_b32_e32 v247, 0xc0, v0
	v_lshl_or_b32 v185, v247, 6, v185
	v_or_b32_e32 v185, 0x10000, v185
	v_lshlrev_b32_e32 v4, 15, v2
	v_writelane_b32 v242, s24, 29
	v_and_b32_e32 v4, 0xffff0000, v4
	v_lshl_add_u32 v4, v13, 12, v4
	v_writelane_b32 v242, s25, 30
	v_and_b32_e32 v2, 1, v2
	v_writelane_b32 v242, s20, 31
	v_lshl_or_b32 v2, v2, 6, v4
	s_cmp_gt_i32 s56, 63
	v_writelane_b32 v242, s21, 32
	v_lshl_add_u32 v158, v14, 1, v2
	v_lshrrev_b32_e32 v247, 3, v0
	v_xor_b32_e32 v247, v247, v0
	v_and_b32_e32 v247, 7, v247
	v_lshl_add_u32 v158, v247, 4, v158
	v_and_b32_e32 v247, 64, v0
	v_sub_u32_e32 v158, v158, v247
	v_lshrrev_b32_e32 v247, 4, v0
	v_and_b32_e32 v247, 2, v247
	v_xor_b32_e32 v247, v247, v0
	v_and_b32_e32 v247, 3, v247
	v_lshlrev_b32_e32 v247, 4, v247
	v_sub_u32_e32 v158, v158, v247
	v_bfe_u32 v247, v0, 2, 4
	v_add_u32_e32 v247, 1, v247
	v_lshrrev_b32_e32 v247, 1, v247
	v_mul_u32_u24_e32 v247, 0x1000, v247
	v_sub_u32_e32 v158, v158, v247
	v_and_b32_e32 v247, 64, v0
	v_mul_u32_u24_e32 v247, 0x200, v247
	v_add_u32_e32 v158, v158, v247
	v_lshlrev_b32_e32 v2, 15, v15
	v_writelane_b32 v242, s18, 35
	s_cselect_b64 s[84:85], -1, 0
	s_add_i32 s88, s31, -2
	v_and_b32_e32 v2, 0xffff0000, v2
	v_writelane_b32 v242, s19, 36
	s_cmpk_lt_u32 s58, 0x100
	v_lshl_add_u32 v2, v16, 12, v2
	v_and_b32_e32 v4, 1, v15
	v_writelane_b32 v242, s16, 37
	s_waitcnt vmcnt(6)
	s_cselect_b64 s[56:57], -1, 0
	s_and_b32 s0, s58, 0xffffff00
	v_lshl_or_b32 v2, v4, 6, v2
	v_mov_b32_e32 v4, v3
	v_mov_b32_e32 v5, v3
	v_writelane_b32 v242, s17, 38
	v_and_b32_e32 v184, 63, v12
	s_add_i32 s89, s0, 0
	v_lshl_add_u32 v160, v17, 1, v2
	v_lshrrev_b32_e32 v247, 3, v0
	v_xor_b32_e32 v247, v247, v0
	v_and_b32_e32 v247, 7, v247
	v_lshl_add_u32 v160, v247, 4, v160
	v_and_b32_e32 v247, 64, v0
	v_sub_u32_e32 v160, v160, v247
	v_lshrrev_b32_e32 v247, 4, v0
	v_and_b32_e32 v247, 2, v247
	v_xor_b32_e32 v247, v247, v0
	v_and_b32_e32 v247, 3, v247
	v_lshlrev_b32_e32 v247, 4, v247
	v_sub_u32_e32 v160, v160, v247
	v_bfe_u32 v247, v0, 2, 4
	v_add_u32_e32 v247, 1, v247
	v_lshrrev_b32_e32 v247, 1, v247
	v_mul_u32_u24_e32 v247, 0x1000, v247
	v_sub_u32_e32 v160, v160, v247
	v_and_b32_e32 v247, 64, v0
	v_mul_u32_u24_e32 v247, 0x200, v247
	v_add_u32_e32 v160, v160, v247
	v_mov_b32_e32 v2, v3
	v_add_u32_e32 v186, 0, v6
	v_bfe_u32 v186, v0, 4, 2
	v_xor_b32_e32 v186, v186, v0
	v_and_b32_e32 v186, 7, v186
	v_lshlrev_b32_e32 v186, 4, v186
	v_and_b32_e32 v247, 15, v0
	v_lshl_or_b32 v186, v247, 7, v186
	v_and_b32_e32 v247, 0x100, v0
	v_lshl_or_b32 v186, v247, 5, v186
	v_mov_b64_e32 v[8:9], v[4:5]
	v_mov_b64_e32 v[12:13], v[4:5]
	v_mov_b64_e32 v[16:17], v[4:5]
	v_mov_b64_e32 v[20:21], v[4:5]
	v_mov_b64_e32 v[24:25], v[4:5]
	v_mov_b64_e32 v[28:29], v[4:5]
	v_mov_b64_e32 v[32:33], v[4:5]
	v_mov_b64_e32 v[36:37], v[4:5]
	v_mov_b64_e32 v[40:41], v[4:5]
	v_mov_b64_e32 v[44:45], v[4:5]
	v_mov_b64_e32 v[48:49], v[4:5]
	v_mov_b64_e32 v[52:53], v[4:5]
	v_mov_b64_e32 v[56:57], v[4:5]
	v_mov_b64_e32 v[60:61], v[4:5]
	v_mov_b64_e32 v[64:65], v[4:5]
	v_mov_b64_e32 v[68:69], v[4:5]
	v_mov_b64_e32 v[72:73], v[4:5]
	v_mov_b64_e32 v[76:77], v[4:5]
	v_mov_b64_e32 v[80:81], v[4:5]
	v_mov_b64_e32 v[84:85], v[4:5]
	v_mov_b64_e32 v[88:89], v[4:5]
	v_mov_b64_e32 v[92:93], v[4:5]
	v_mov_b64_e32 v[96:97], v[4:5]
	v_mov_b64_e32 v[100:101], v[4:5]
	v_mov_b64_e32 v[104:105], v[4:5]
	v_mov_b64_e32 v[108:109], v[4:5]
	v_mov_b64_e32 v[112:113], v[4:5]
	v_mov_b64_e32 v[116:117], v[4:5]
	v_mov_b64_e32 v[120:121], v[4:5]
	v_mov_b64_e32 v[124:125], v[4:5]
	v_mov_b64_e32 v[128:129], v[4:5]
	v_mov_b64_e32 v[132:133], v[4:5]
	v_writelane_b32 v242, s6, 33
	s_add_i32 s89, s89, 0x20000
	v_mov_b32_e32 v159, v3
	v_mov_b32_e32 v161, v3
	s_mov_b32 s92, 0
	v_mov_b64_e32 v[6:7], v[2:3]
	v_mov_b64_e32 v[10:11], v[2:3]
	v_mov_b64_e32 v[14:15], v[2:3]
	v_mov_b64_e32 v[18:19], v[2:3]
	v_mov_b64_e32 v[22:23], v[2:3]
	v_mov_b64_e32 v[26:27], v[2:3]
	v_mov_b64_e32 v[30:31], v[2:3]
	v_mov_b64_e32 v[34:35], v[2:3]
	v_mov_b64_e32 v[38:39], v[2:3]
	v_mov_b64_e32 v[42:43], v[2:3]
	v_mov_b64_e32 v[46:47], v[2:3]
	v_mov_b64_e32 v[50:51], v[2:3]
	v_mov_b64_e32 v[54:55], v[2:3]
	v_mov_b64_e32 v[58:59], v[2:3]
	v_mov_b64_e32 v[62:63], v[2:3]
	v_mov_b64_e32 v[66:67], v[2:3]
	v_mov_b64_e32 v[70:71], v[2:3]
	v_mov_b64_e32 v[74:75], v[2:3]
	v_mov_b64_e32 v[78:79], v[2:3]
	v_mov_b64_e32 v[82:83], v[2:3]
	v_mov_b64_e32 v[86:87], v[2:3]
	v_mov_b64_e32 v[90:91], v[2:3]
	v_mov_b64_e32 v[94:95], v[2:3]
	v_mov_b64_e32 v[98:99], v[2:3]
	v_mov_b64_e32 v[102:103], v[2:3]
	v_mov_b64_e32 v[106:107], v[2:3]
	v_mov_b64_e32 v[110:111], v[2:3]
	v_mov_b64_e32 v[114:115], v[2:3]
	v_mov_b64_e32 v[118:119], v[2:3]
	v_mov_b64_e32 v[122:123], v[2:3]
	v_mov_b64_e32 v[126:127], v[2:3]
	v_mov_b64_e32 v[130:131], v[2:3]
	v_writelane_b32 v242, s7, 34
	s_barrier
	s_branch .LBB0_949

; #define PG8_STAGE(bufoff, gbase, voff) do { _Pragma("unroll") for (int _i = 0; _i < 2; ++_i) \
;         __builtin_amdgcn_global_load_lds((const unsigned*)((const char*)(gbase) + (voff)[_i]), (LAS unsigned*)(lds + (bufoff) + ldsw + _i * 8192), 16, 0, 0); } while (0)
; #define PG8_LDA(dst, b, h) do { _Pragma("unroll") for (int m = 0; m < 4; ++m) _Pragma("unroll") for (int k = 0; k < 2; ++k) dst[m][k] = *(const LAS bf16x8*)(lds + PG8_SA(b, h) + aoff + m * 2048 + k * 1024); } while (0)
; #define PG8_LDB(dst, b, h) do { _Pragma("unroll") for (int n = 0; n < 2; ++n) _Pragma("unroll") for (int k = 0; k < 2; ++k) dst[n][k] = *(const LAS bf16x8*)(lds + PG8_SB(b, h) + boff + n * 2048 + k * 1024); } while (0)
; #define PG8_WAIT_V(n) asm volatile("s_waitcnt vmcnt(" #n ")" ::: "memory")
; #define PG8_WAIT_L(n) asm volatile("s_waitcnt lgkmcnt(" #n ")" ::: "memory")
; #define PG8_BAR __builtin_amdgcn_s_barrier()
; template <class Epi, bool ALIGN_EPI = true>
; __device__ __forceinline__ void gemm_phase(LAS unsigned char* lds, const Gemm g, const Sched& S, const Epi& E) {
;     ...
;         const bool has_next = S.next(ui + 1, nxt);
;         const char* nA = has_next ? (const char*)g.A + nxt.aoff : cA; const char* nB = has_next ? (const char*)g.Bt + nxt.boff : cB;
;         for (int hh = 0; hh < (Epi::HAS_MID ? 2 : 1); ++hh) {
;         if constexpr (Epi::HAS_MID) { if (hh == 1) { int le = lane; asm volatile("" : "+v"(le)); E.mid(acc, cur, wr, wc, le & 15, le >> 4); } }
;         const int t_lo = Epi::HAS_MID ? hh * (nt >> 1) : 0, t_hi = Epi::HAS_MID ? (hh + 1) * (nt >> 1) : nt;
;         for (int t = t_lo; t < t_hi; t += 2) {
;             const bool last = (t == nt - 2);
;             const char* a1 = cA + (size_t)(t + 1) * kstep;
;             const char* a2 = last ? nA : cA + (size_t)(t + 2) * kstep; const char* b2 = last ? nB : cB + (size_t)(t + 2) * kstep;
;             const char* a3 = a2 + kstep; const char* b3 = b2 + kstep;
;             const int rflag = __builtin_amdgcn_readfirstlane(t | (int)(ui == 0));
;             PG8_LDB(B0, 0, 0); PG8_LDB(B1, 0, 1); PG8_SCHED; PG8_LDA(At, 0, 0); PG8_STAGE(PG8_SA(1, 1), a1 + hstepA, voffA);
;             if constexpr (Epi::NSTORES > 0) PG8_WAIT_RELAX(rflag, 8 + Epi::NSTORES); else PG8_WAIT_V(8);
;             PG8_WAIT_L(0); PG8_BAR; PG8_MMA(0, 0, At, B0); PG8_MMA(0, 1, At, B1); PG8_BAR; PG8_SCHED;
.LBB0_952:
	s_add_u32 s0, s26, s64
	s_addc_u32 s1, s27, s65
	v_readlane_b32 s4, v242, 27
	s_add_u32 s70, s4, s68
	v_readlane_b32 s4, v242, 28
	s_addc_u32 s71, s4, s69
	s_andn2_b64 vcc, exec, s[84:85]
	s_cbranch_vccnz .LBB0_955
	s_and_b64 s[4:5], s[90:91], exec
	s_cselect_b32 s16, s1, s51
	s_cselect_b32 s17, s0, s50
	s_cselect_b32 s18, s71, s41
	s_cselect_b32 s19, s70, s40
	s_cmp_eq_u32 s92, 0
	s_cselect_b64 s[4:5], -1, 0
	v_cndmask_b32_e64 v2, 0, 1, s[4:5]
	s_add_u32 s4, s50, 0x80080
	s_addc_u32 s5, s51, 0
	s_add_u32 s20, s40, 0x100
	s_mov_b32 s6, 0
	s_addc_u32 s21, s41, 0
	v_xor_b32_e32 v210, 64, v186
	v_xor_b32_e32 v211, 64, v185
.LBB0_954:
	s_add_i32 s22, s6, 2
	s_add_u32 s7, s4, 0xfff80080
	s_addc_u32 s14, s5, -1
	s_add_i32 s23, 0, 0x10000
	s_cmp_eq_u32 s88, s6
	v_add_u32_e32 v182, s6, v2
	s_cselect_b32 s15, s16, s14
	s_cselect_b32 s14, s17, s7
	s_waitcnt lgkmcnt(0)
	s_cselect_b32 s7, s18, s21
	s_cselect_b32 s6, s19, s20
	s_add_i32 s58, 0, 0x14000
	ds_read_b128 v[134:137], v185
	ds_read_b128 v[138:141], v211
	ds_read_b128 v[142:145], v185 offset:2048
	ds_read_b128 v[146:149], v211 offset:2048
	ds_read_b128 v[162:165], v185 offset:16384
	ds_read_b128 v[166:169], v211 offset:16384
	ds_read_b128 v[170:173], v185 offset:18432
	ds_read_b128 v[174:177], v211 offset:18432
	s_add_i32 m0, s48, 0xc000
	ds_read_b128 v[178:181], v186
	ds_read_b128 v[188:191], v210
	ds_read_b128 v[192:195], v186 offset:2048
	ds_read_b128 v[206:209], v210 offset:2048
	ds_read_b128 v[224:227], v186 offset:4096
	ds_read_b128 v[228:231], v210 offset:4096
	ds_read_b128 v[232:235], v186 offset:6144
	ds_read_b128 v[236:239], v210 offset:6144
	s_add_u32 s100, s4, 0xfff80000
	s_addc_u32 s101, s5, -1
	s_mov_b32 m0, s30
	s_nop 0
	global_load_lds_dwordx4 v158, s[100:101]
	s_mov_b32 m0, s33
	s_nop 0
	global_load_lds_dwordx4 v160, s[100:101]
	s_add_i32 m0, s48, 0xc000
	s_nop 0
	global_load_lds_dwordx4 v158, s[4:5]
	s_add_i32 m0, s48, 0xe000
	v_readfirstlane_b32 s59, v182
	global_load_lds_dwordx4 v160, s[4:5]
	s_cmp_eq_u32 s59, 0
	s_cbranch_scc1 .Lrw12
	s_waitcnt vmcnt(8)
.Lrw12:
	s_waitcnt vmcnt(24)
	s_waitcnt lgkmcnt(0)
	s_barrier
	s_setprio 1
	s_waitcnt lgkmcnt(0)
	v_mfma_f32_16x16x32_bf16 v[130:133], v[134:137], v[178:181], v[130:133]
	v_mfma_f32_16x16x32_bf16 v[126:129], v[142:145], v[178:181], v[126:129]
	v_mfma_f32_16x16x32_bf16 v[122:125], v[134:137], v[192:195], v[122:125]
	v_mfma_f32_16x16x32_bf16 v[118:121], v[142:145], v[192:195], v[118:121]
	v_mfma_f32_16x16x32_bf16 v[114:117], v[134:137], v[224:227], v[114:117]
	v_mfma_f32_16x16x32_bf16 v[110:113], v[142:145], v[224:227], v[110:113]
	v_mfma_f32_16x16x32_bf16 v[106:109], v[134:137], v[232:235], v[106:109]
	v_mfma_f32_16x16x32_bf16 v[102:105], v[142:145], v[232:235], v[102:105]
	v_mfma_f32_16x16x32_bf16 v[130:133], v[138:141], v[188:191], v[130:133]
	v_mfma_f32_16x16x32_bf16 v[126:129], v[146:149], v[188:191], v[126:129]
	v_mfma_f32_16x16x32_bf16 v[122:125], v[138:141], v[206:209], v[122:125]
	v_mfma_f32_16x16x32_bf16 v[118:121], v[146:149], v[206:209], v[118:121]
	v_mfma_f32_16x16x32_bf16 v[114:117], v[138:141], v[228:231], v[114:117]
	v_mfma_f32_16x16x32_bf16 v[110:113], v[146:149], v[228:231], v[110:113]
	v_mfma_f32_16x16x32_bf16 v[106:109], v[138:141], v[236:239], v[106:109]
	v_mfma_f32_16x16x32_bf16 v[102:105], v[146:149], v[236:239], v[102:105]
	s_setprio 0
	s_setprio 1
	v_mfma_f32_16x16x32_bf16 v[98:101], v[162:165], v[178:181], v[98:101]
	v_mfma_f32_16x16x32_bf16 v[94:97], v[170:173], v[178:181], v[94:97]
	v_mfma_f32_16x16x32_bf16 v[90:93], v[162:165], v[192:195], v[90:93]
	v_mfma_f32_16x16x32_bf16 v[86:89], v[170:173], v[192:195], v[86:89]
	v_mfma_f32_16x16x32_bf16 v[82:85], v[162:165], v[224:227], v[82:85]
	v_mfma_f32_16x16x32_bf16 v[78:81], v[170:173], v[224:227], v[78:81]
	v_mfma_f32_16x16x32_bf16 v[74:77], v[162:165], v[232:235], v[74:77]
	v_mfma_f32_16x16x32_bf16 v[70:73], v[170:173], v[232:235], v[70:73]
	v_mfma_f32_16x16x32_bf16 v[98:101], v[166:169], v[188:191], v[98:101]
	v_mfma_f32_16x16x32_bf16 v[94:97], v[174:177], v[188:191], v[94:97]
	v_mfma_f32_16x16x32_bf16 v[90:93], v[166:169], v[206:209], v[90:93]
	v_mfma_f32_16x16x32_bf16 v[86:89], v[174:177], v[206:209], v[86:89]
	v_mfma_f32_16x16x32_bf16 v[82:85], v[166:169], v[228:231], v[82:85]
	v_mfma_f32_16x16x32_bf16 v[78:81], v[174:177], v[228:231], v[78:81]
	v_mfma_f32_16x16x32_bf16 v[74:77], v[166:169], v[236:239], v[74:77]
	v_mfma_f32_16x16x32_bf16 v[70:73], v[174:177], v[236:239], v[70:73]
	s_setprio 0
	s_barrier
	s_add_i32 s23, s23, s94
	s_mov_b32 m0, s23
	ds_read_b128 v[178:181], v186 offset:16384
	ds_read_b128 v[188:191], v210 offset:16384
	ds_read_b128 v[192:195], v186 offset:18432
	ds_read_b128 v[206:209], v210 offset:18432
	ds_read_b128 v[224:227], v186 offset:20480
	ds_read_b128 v[228:231], v210 offset:20480
	ds_read_b128 v[232:235], v186 offset:22528
	ds_read_b128 v[236:239], v210 offset:22528
	global_load_lds_dwordx4 v152, s[6:7]
	s_add_i32 m0, s23, 0x2000
	s_add_u32 s24, s6, 0x80000
	s_addc_u32 s25, s7, 0
	s_add_i32 s23, s58, s94
	global_load_lds_dwordx4 v156, s[6:7]
	s_mov_b32 m0, s23
	s_nop 0
	global_load_lds_dwordx4 v152, s[24:25]
	s_add_i32 m0, s23, 0x2000
	s_nop 0
	global_load_lds_dwordx4 v156, s[24:25]
	s_cmp_eq_u32 s59, 0
	s_cbranch_scc1 .Lrw13
	s_waitcnt vmcnt(6)
; #define PG8_STAGE(bufoff, gbase, voff) do { _Pragma("unroll") for (int _i = 0; _i < 2; ++_i) \
;         __builtin_amdgcn_global_load_lds((const unsigned*)((const char*)(gbase) + (voff)[_i]), (LAS unsigned*)(lds + (bufoff) + ldsw + _i * 8192), 16, 0, 0); } while (0)
; #define PG8_LDA(dst, b, h) do { _Pragma("unroll") for (int m = 0; m < 4; ++m) _Pragma("unroll") for (int k = 0; k < 2; ++k) dst[m][k] = *(const LAS bf16x8*)(lds + PG8_SA(b, h) + aoff + m * 2048 + k * 1024); } while (0)
; #define PG8_LDB(dst, b, h) do { _Pragma("unroll") for (int n = 0; n < 2; ++n) _Pragma("unroll") for (int k = 0; k < 2; ++k) dst[n][k] = *(const LAS bf16x8*)(lds + PG8_SB(b, h) + boff + n * 2048 + k * 1024); } while (0)
; #define PG8_MMA(ai, bj, At, Bt) do { __builtin_amdgcn_s_setprio(1); _Pragma("unroll") for (int m = 0; m < 4; ++m) _Pragma("unroll") for (int n = 0; n < 2; ++n) _Pragma("unroll") for (int k = 0; k < 2; ++k) \
;         acc[ai][bj][m][n] = __builtin_amdgcn_mfma_f32_16x16x32_bf16(Bt[n][k], At[m][k], acc[ai][bj][m][n], 0, 0, 0); __builtin_amdgcn_s_setprio(0); } while (0)
; #define PG8_WAIT_V(n) asm volatile("s_waitcnt vmcnt(" #n ")" ::: "memory")
; #define PG8_WAIT_L(n) asm volatile("s_waitcnt lgkmcnt(" #n ")" ::: "memory")
; #define PG8_BAR __builtin_amdgcn_s_barrier()
; #define PG8_WAIT_RELAX(flag, n) asm volatile("s_cmp_eq_u32 %0, 0\n\ts_cbranch_scc1 .Lrw%=\n\ts_waitcnt vmcnt(8)\n.Lrw%=:\n\ts_waitcnt vmcnt(%1)" :: "s"(flag), "n"(n) : "scc", "memory")
; #define PG8_SCHED __builtin_amdgcn_sched_barrier(0)
; template <class Epi, bool ALIGN_EPI = true>
; __device__ __forceinline__ void gemm_phase(LAS unsigned char* lds, const Gemm g, const Sched& S, const Epi& E) {
;     ...
;             PG8_WAIT_L(0); PG8_BAR; PG8_MMA(0, 0, At, B0); PG8_MMA(0, 1, At, B1); PG8_BAR; PG8_SCHED;
;             PG8_LDA(At, 0, 1); PG8_STAGE(PG8_SB(0, 0), b2, voffB); PG8_STAGE(PG8_SB(0, 1), b2 + hstepB, voffB); PG8_STAGE(PG8_SA(0, 0), a2, voffA);
;             if constexpr (Epi::NSTORES > 0) PG8_WAIT_RELAX(rflag, 8 + Epi::NSTORES); else PG8_WAIT_V(8);
;             PG8_WAIT_L(0); PG8_BAR; PG8_MMA(1, 0, At, B0); PG8_MMA(1, 1, At, B1); PG8_BAR; PG8_SCHED;
;             PG8_LDB(B0, 1, 0); PG8_LDB(B1, 1, 1); PG8_SCHED; PG8_LDA(At, 1, 0); PG8_STAGE(PG8_SA(0, 1), a2 + hstepA, voffA);
.Lrw13:
	s_waitcnt vmcnt(6)
	s_waitcnt lgkmcnt(0)
	s_barrier
	s_setprio 1
	s_waitcnt lgkmcnt(0)
	v_mfma_f32_16x16x32_bf16 v[66:69], v[134:137], v[178:181], v[66:69]
	v_mfma_f32_16x16x32_bf16 v[62:65], v[142:145], v[178:181], v[62:65]
	v_mfma_f32_16x16x32_bf16 v[58:61], v[134:137], v[192:195], v[58:61]
	v_mfma_f32_16x16x32_bf16 v[54:57], v[142:145], v[192:195], v[54:57]
	v_mfma_f32_16x16x32_bf16 v[50:53], v[134:137], v[224:227], v[50:53]
	v_mfma_f32_16x16x32_bf16 v[46:49], v[142:145], v[224:227], v[46:49]
	v_mfma_f32_16x16x32_bf16 v[42:45], v[134:137], v[232:235], v[42:45]
	v_mfma_f32_16x16x32_bf16 v[38:41], v[142:145], v[232:235], v[38:41]
	v_mfma_f32_16x16x32_bf16 v[66:69], v[138:141], v[188:191], v[66:69]
	v_mfma_f32_16x16x32_bf16 v[62:65], v[146:149], v[188:191], v[62:65]
	v_mfma_f32_16x16x32_bf16 v[58:61], v[138:141], v[206:209], v[58:61]
	v_mfma_f32_16x16x32_bf16 v[54:57], v[146:149], v[206:209], v[54:57]
	v_mfma_f32_16x16x32_bf16 v[50:53], v[138:141], v[228:231], v[50:53]
	v_mfma_f32_16x16x32_bf16 v[46:49], v[146:149], v[228:231], v[46:49]
	v_mfma_f32_16x16x32_bf16 v[42:45], v[138:141], v[236:239], v[42:45]
	v_mfma_f32_16x16x32_bf16 v[38:41], v[146:149], v[236:239], v[38:41]
	s_setprio 0
	s_setprio 1
	v_mfma_f32_16x16x32_bf16 v[34:37], v[162:165], v[178:181], v[34:37]
	v_mfma_f32_16x16x32_bf16 v[30:33], v[170:173], v[178:181], v[30:33]
	v_mfma_f32_16x16x32_bf16 v[26:29], v[162:165], v[192:195], v[26:29]
	v_mfma_f32_16x16x32_bf16 v[22:25], v[170:173], v[192:195], v[22:25]
	v_mfma_f32_16x16x32_bf16 v[18:21], v[162:165], v[224:227], v[18:21]
	v_mfma_f32_16x16x32_bf16 v[14:17], v[170:173], v[224:227], v[14:17]
	v_mfma_f32_16x16x32_bf16 v[10:13], v[162:165], v[232:235], v[10:13]
	v_mfma_f32_16x16x32_bf16 v[4:7], v[170:173], v[232:235], v[6:9]
	v_mfma_f32_16x16x32_bf16 v[34:37], v[166:169], v[188:191], v[34:37]
	v_mfma_f32_16x16x32_bf16 v[30:33], v[174:177], v[188:191], v[30:33]
	v_mfma_f32_16x16x32_bf16 v[26:29], v[166:169], v[206:209], v[26:29]
	v_mfma_f32_16x16x32_bf16 v[22:25], v[174:177], v[206:209], v[22:25]
	v_mfma_f32_16x16x32_bf16 v[18:21], v[166:169], v[228:231], v[18:21]
	v_mfma_f32_16x16x32_bf16 v[14:17], v[174:177], v[228:231], v[14:17]
	v_mfma_f32_16x16x32_bf16 v[10:13], v[166:169], v[236:239], v[10:13]
	v_mfma_f32_16x16x32_bf16 v[4:7], v[174:177], v[236:239], v[4:7]
	s_setprio 0
	s_barrier
	s_add_i32 s23, 0, 0x18000
	s_add_i32 s24, 0, 0x1c000
	ds_read_b128 v[134:137], v185 offset:32768
	ds_read_b128 v[138:141], v211 offset:32768
	ds_read_b128 v[142:145], v185 offset:34816
	ds_read_b128 v[146:149], v211 offset:34816
	ds_read_b128 v[162:165], v185 offset:49152
	ds_read_b128 v[166:169], v211 offset:49152
	ds_read_b128 v[170:173], v185 offset:51200
	ds_read_b128 v[174:177], v211 offset:51200
	s_add_u32 s14, s14, 0x80000
	s_addc_u32 s15, s15, 0
	s_mov_b32 m0, s46
	ds_read_b128 v[178:181], v186 offset:32768
	ds_read_b128 v[188:191], v210 offset:32768
	ds_read_b128 v[192:195], v186 offset:34816
	ds_read_b128 v[206:209], v210 offset:34816
	ds_read_b128 v[224:227], v186 offset:36864
	ds_read_b128 v[228:231], v210 offset:36864
	ds_read_b128 v[232:235], v186 offset:38912
	ds_read_b128 v[236:239], v210 offset:38912
	s_add_u32 s100, s14, 0xfff80000
	s_addc_u32 s101, s15, -1
	s_mov_b32 m0, s48
	s_nop 0
	global_load_lds_dwordx4 v150, s[100:101]
	s_mov_b32 m0, s49
	s_nop 0
	global_load_lds_dwordx4 v154, s[100:101]
	s_mov_b32 m0, s46
	s_nop 0
	global_load_lds_dwordx4 v150, s[14:15]
	s_mov_b32 m0, s47
	s_nop 0
	global_load_lds_dwordx4 v154, s[14:15]
	s_waitcnt vmcnt(8)
	s_waitcnt lgkmcnt(0)
	s_barrier
; #define PG8_STAGE(bufoff, gbase, voff) do { _Pragma("unroll") for (int _i = 0; _i < 2; ++_i) \
;         __builtin_amdgcn_global_load_lds((const unsigned*)((const char*)(gbase) + (voff)[_i]), (LAS unsigned*)(lds + (bufoff) + ldsw + _i * 8192), 16, 0, 0); } while (0)
; #define PG8_LDA(dst, b, h) do { _Pragma("unroll") for (int m = 0; m < 4; ++m) _Pragma("unroll") for (int k = 0; k < 2; ++k) dst[m][k] = *(const LAS bf16x8*)(lds + PG8_SA(b, h) + aoff + m * 2048 + k * 1024); } while (0)
; #define PG8_LDB(dst, b, h) do { _Pragma("unroll") for (int n = 0; n < 2; ++n) _Pragma("unroll") for (int k = 0; k < 2; ++k) dst[n][k] = *(const LAS bf16x8*)(lds + PG8_SB(b, h) + boff + n * 2048 + k * 1024); } while (0)
; #define PG8_MMA(ai, bj, At, Bt) do { __builtin_amdgcn_s_setprio(1); _Pragma("unroll") for (int m = 0; m < 4; ++m) _Pragma("unroll") for (int n = 0; n < 2; ++n) _Pragma("unroll") for (int k = 0; k < 2; ++k) \
;         acc[ai][bj][m][n] = __builtin_amdgcn_mfma_f32_16x16x32_bf16(Bt[n][k], At[m][k], acc[ai][bj][m][n], 0, 0, 0); __builtin_amdgcn_s_setprio(0); } while (0)
; #define PG8_WAIT_V(n) asm volatile("s_waitcnt vmcnt(" #n ")" ::: "memory")
; #define PG8_WAIT_L(n) asm volatile("s_waitcnt lgkmcnt(" #n ")" ::: "memory")
; #define PG8_BAR __builtin_amdgcn_s_barrier()
; #define PG8_SCHED __builtin_amdgcn_sched_barrier(0)
; template <class Epi, bool ALIGN_EPI = true>
; __device__ __forceinline__ void gemm_phase(LAS unsigned char* lds, const Gemm g, const Sched& S, const Epi& E) {
;     ...
;             PG8_LDB(B0, 1, 0); PG8_LDB(B1, 1, 1); PG8_SCHED; PG8_LDA(At, 1, 0); PG8_STAGE(PG8_SA(0, 1), a2 + hstepA, voffA);
;             PG8_WAIT_V(8); PG8_WAIT_L(0); PG8_BAR; PG8_MMA(0, 0, At, B0); PG8_MMA(0, 1, At, B1); PG8_BAR; PG8_SCHED;
;             PG8_LDA(At, 1, 1); PG8_STAGE(PG8_SB(1, 0), b3, voffB); PG8_STAGE(PG8_SB(1, 1), b3 + hstepB, voffB); PG8_STAGE(PG8_SA(1, 0), a3, voffA);
;             PG8_WAIT_V(8); PG8_WAIT_L(0); PG8_BAR; PG8_MMA(1, 0, At, B0); PG8_MMA(1, 1, At, B1); PG8_BAR; PG8_SCHED;
	s_setprio 1
	s_waitcnt lgkmcnt(0)
	v_mfma_f32_16x16x32_bf16 v[130:133], v[134:137], v[178:181], v[130:133]
	v_mfma_f32_16x16x32_bf16 v[126:129], v[142:145], v[178:181], v[126:129]
	v_mfma_f32_16x16x32_bf16 v[122:125], v[134:137], v[192:195], v[122:125]
	v_mfma_f32_16x16x32_bf16 v[118:121], v[142:145], v[192:195], v[118:121]
	v_mfma_f32_16x16x32_bf16 v[114:117], v[134:137], v[224:227], v[114:117]
	v_mfma_f32_16x16x32_bf16 v[110:113], v[142:145], v[224:227], v[110:113]
	v_mfma_f32_16x16x32_bf16 v[106:109], v[134:137], v[232:235], v[106:109]
	v_mfma_f32_16x16x32_bf16 v[102:105], v[142:145], v[232:235], v[102:105]
	v_mfma_f32_16x16x32_bf16 v[130:133], v[138:141], v[188:191], v[130:133]
	v_mfma_f32_16x16x32_bf16 v[126:129], v[146:149], v[188:191], v[126:129]
	v_mfma_f32_16x16x32_bf16 v[122:125], v[138:141], v[206:209], v[122:125]
	v_mfma_f32_16x16x32_bf16 v[118:121], v[146:149], v[206:209], v[118:121]
	v_mfma_f32_16x16x32_bf16 v[114:117], v[138:141], v[228:231], v[114:117]
	v_mfma_f32_16x16x32_bf16 v[110:113], v[146:149], v[228:231], v[110:113]
	v_mfma_f32_16x16x32_bf16 v[106:109], v[138:141], v[236:239], v[106:109]
	v_mfma_f32_16x16x32_bf16 v[102:105], v[146:149], v[236:239], v[102:105]
	s_setprio 0
	s_setprio 1
	v_mfma_f32_16x16x32_bf16 v[98:101], v[162:165], v[178:181], v[98:101]
	v_mfma_f32_16x16x32_bf16 v[94:97], v[170:173], v[178:181], v[94:97]
	v_mfma_f32_16x16x32_bf16 v[90:93], v[162:165], v[192:195], v[90:93]
	v_mfma_f32_16x16x32_bf16 v[86:89], v[170:173], v[192:195], v[86:89]
	v_mfma_f32_16x16x32_bf16 v[82:85], v[162:165], v[224:227], v[82:85]
	v_mfma_f32_16x16x32_bf16 v[78:81], v[170:173], v[224:227], v[78:81]
	v_mfma_f32_16x16x32_bf16 v[74:77], v[162:165], v[232:235], v[74:77]
	v_mfma_f32_16x16x32_bf16 v[70:73], v[170:173], v[232:235], v[70:73]
	v_mfma_f32_16x16x32_bf16 v[98:101], v[166:169], v[188:191], v[98:101]
	v_mfma_f32_16x16x32_bf16 v[94:97], v[174:177], v[188:191], v[94:97]
	v_mfma_f32_16x16x32_bf16 v[90:93], v[166:169], v[206:209], v[90:93]
	v_mfma_f32_16x16x32_bf16 v[86:89], v[174:177], v[206:209], v[86:89]
	v_mfma_f32_16x16x32_bf16 v[82:85], v[166:169], v[228:231], v[82:85]
	v_mfma_f32_16x16x32_bf16 v[78:81], v[174:177], v[228:231], v[78:81]
	v_mfma_f32_16x16x32_bf16 v[74:77], v[166:169], v[236:239], v[74:77]
	v_mfma_f32_16x16x32_bf16 v[70:73], v[174:177], v[236:239], v[70:73]
	s_setprio 0
	s_barrier
	s_add_u32 s100, s6, 0x80
	s_addc_u32 s101, s7, 0
	s_add_i32 s14, s23, s94
	s_mov_b32 m0, s14
	ds_read_b128 v[178:181], v186 offset:49152
	ds_read_b128 v[188:191], v210 offset:49152
	ds_read_b128 v[192:195], v186 offset:51200
	ds_read_b128 v[206:209], v210 offset:51200
	ds_read_b128 v[224:227], v186 offset:53248
	ds_read_b128 v[228:231], v210 offset:53248
	ds_read_b128 v[232:235], v186 offset:55296
	ds_read_b128 v[236:239], v210 offset:55296
	global_load_lds_dwordx4 v152, s[100:101]
	s_add_i32 m0, s14, 0x2000
	s_add_u32 s6, s6, 0x80080
	s_addc_u32 s7, s7, 0
	s_add_i32 s14, s24, s94
	global_load_lds_dwordx4 v156, s[100:101]
	s_mov_b32 m0, s14
	s_nop 0
	global_load_lds_dwordx4 v152, s[6:7]
	s_add_i32 m0, s14, 0x2000
	s_nop 0
	global_load_lds_dwordx4 v156, s[6:7]
	s_waitcnt vmcnt(6)
	s_waitcnt lgkmcnt(0)
	s_barrier
	s_setprio 1
	s_waitcnt lgkmcnt(0)
	v_mfma_f32_16x16x32_bf16 v[66:69], v[134:137], v[178:181], v[66:69]
	v_mfma_f32_16x16x32_bf16 v[62:65], v[142:145], v[178:181], v[62:65]
	v_mfma_f32_16x16x32_bf16 v[58:61], v[134:137], v[192:195], v[58:61]
	v_mfma_f32_16x16x32_bf16 v[54:57], v[142:145], v[192:195], v[54:57]
	v_mfma_f32_16x16x32_bf16 v[50:53], v[134:137], v[224:227], v[50:53]
	v_mfma_f32_16x16x32_bf16 v[46:49], v[142:145], v[224:227], v[46:49]
	v_mfma_f32_16x16x32_bf16 v[42:45], v[134:137], v[232:235], v[42:45]
	v_mfma_f32_16x16x32_bf16 v[38:41], v[142:145], v[232:235], v[38:41]
	v_mfma_f32_16x16x32_bf16 v[66:69], v[138:141], v[188:191], v[66:69]
	v_mfma_f32_16x16x32_bf16 v[62:65], v[146:149], v[188:191], v[62:65]
	v_mfma_f32_16x16x32_bf16 v[58:61], v[138:141], v[206:209], v[58:61]
	v_mfma_f32_16x16x32_bf16 v[54:57], v[146:149], v[206:209], v[54:57]
	v_mfma_f32_16x16x32_bf16 v[50:53], v[138:141], v[228:231], v[50:53]
	v_mfma_f32_16x16x32_bf16 v[46:49], v[146:149], v[228:231], v[46:49]
	v_mfma_f32_16x16x32_bf16 v[42:45], v[138:141], v[236:239], v[42:45]
	v_mfma_f32_16x16x32_bf16 v[38:41], v[146:149], v[236:239], v[38:41]
	s_setprio 0
	s_setprio 1
	v_mfma_f32_16x16x32_bf16 v[34:37], v[162:165], v[178:181], v[34:37]
	v_mfma_f32_16x16x32_bf16 v[30:33], v[170:173], v[178:181], v[30:33]
	v_mfma_f32_16x16x32_bf16 v[26:29], v[162:165], v[192:195], v[26:29]
	v_mfma_f32_16x16x32_bf16 v[22:25], v[170:173], v[192:195], v[22:25]
	v_mfma_f32_16x16x32_bf16 v[18:21], v[162:165], v[224:227], v[18:21]
	v_mfma_f32_16x16x32_bf16 v[14:17], v[170:173], v[224:227], v[14:17]
	v_mfma_f32_16x16x32_bf16 v[8:11], v[162:165], v[232:235], v[10:13]
	v_mfma_f32_16x16x32_bf16 v[4:7], v[170:173], v[232:235], v[4:7]
	v_mfma_f32_16x16x32_bf16 v[34:37], v[166:169], v[188:191], v[34:37]
	v_mfma_f32_16x16x32_bf16 v[30:33], v[174:177], v[188:191], v[30:33]
	v_mfma_f32_16x16x32_bf16 v[26:29], v[166:169], v[206:209], v[26:29]
	v_mfma_f32_16x16x32_bf16 v[22:25], v[174:177], v[206:209], v[22:25]
	v_mfma_f32_16x16x32_bf16 v[18:21], v[166:169], v[228:231], v[18:21]
	v_mfma_f32_16x16x32_bf16 v[14:17], v[174:177], v[228:231], v[14:17]
	v_mfma_f32_16x16x32_bf16 v[10:13], v[166:169], v[236:239], v[8:11]
	v_mfma_f32_16x16x32_bf16 v[6:9], v[174:177], v[236:239], v[4:7]
	s_setprio 0
	s_barrier
	s_add_u32 s4, s4, 0x100
	s_addc_u32 s5, s5, 0
	s_add_u32 s20, s20, 0x100
	s_addc_u32 s21, s21, 0
	s_cmp_ge_i32 s22, s31
	s_mov_b32 s6, s22
	s_cbranch_scc0 .LBB0_954

; #define PG8_STAGE(bufoff, gbase, voff) do { _Pragma("unroll") for (int _i = 0; _i < 2; ++_i) \
;         __builtin_amdgcn_global_load_lds((const unsigned*)((const char*)(gbase) + (voff)[_i]), (LAS unsigned*)(lds + (bufoff) + ldsw + _i * 8192), 16, 0, 0); } while (0)
; #define PG8_WAIT_V(n) asm volatile("s_waitcnt vmcnt(" #n ")" ::: "memory")
; #define PG8_BAR __builtin_amdgcn_s_barrier()
; template <class Epi, bool ALIGN_EPI = true>
; __device__ __forceinline__ void gemm_phase(LAS unsigned char* lds, const Gemm g, const Sched& S, const Epi& E) {
;     ...
;     for (int i = 0; i < 2; ++i) { int R, C; stage_rc(tid * 16 + i * 8192, R, C); const int Rb = (R & ~31) + perm32(R & 31);
;         voffA[i] = (unsigned)(R * g.lda + C) * 2u; voffB[i] = (unsigned)(Rb * g.ldb + C) * 2u; }
;     const size_t kstep = (size_t)(BK * 2);
;     const size_t hstepA = (size_t)HALF * g.lda * 2, hstepB = (size_t)HALF * g.ldb * 2;
;     const unsigned ldsw = (unsigned)wid * 1024u;
;     const int aoff = lds_byte(wr * 64 + fr, fq * 8), boff = lds_byte(wc * 32 + fr, fq * 8);
;     ...
;     const char* cA = (const char*)g.A + cur.aoff; const char* cB = (const char*)g.Bt + cur.boff;
;     PG8_STAGE(PG8_SB(0, 0), cB, voffB); PG8_STAGE(PG8_SB(0, 1), cB + hstepB, voffB); PG8_STAGE(PG8_SA(0, 0), cA, voffA); PG8_STAGE(PG8_SA(0, 1), cA + hstepA, voffA);
;     if (wr == 1) PG8_BAR;
;     PG8_WAIT_V(2); PG8_BAR;
;     PG8_STAGE(PG8_SB(1, 0), cB + kstep, voffB); PG8_STAGE(PG8_SA(1, 0), cA + kstep, voffA); PG8_STAGE(PG8_SB(1, 1), cB + hstepB + kstep, voffB);
;     PG8_WAIT_V(6); PG8_BAR;
.LBB0_1216:
	s_andn2_b64 vcc, exec, s[0:1]
	s_cbranch_vccnz .LBB0_1294
	v_readlane_b32 s18, v244, 0
	s_mov_b64 s[0:1], 0x34000000
	s_mov_b64 s[4:5], 0x37000000
	s_mov_b64 s[14:15], 0x2f000000
	s_mov_b64 s[6:7], 0x31000000
	v_mov_b32_e32 v2, v0
	v_readlane_b32 s19, v244, 1
	s_movk_i32 s17, 0x800
	v_readfirstlane_b32 s16, v2
	s_andn2_b64 vcc, exec, s[18:19]
	s_cbranch_vccnz .LBB0_1244
	s_waitcnt vmcnt(0) lgkmcnt(0)
	v_lshlrev_b32_e32 v4, 4, v2
	v_add_u32_e32 v5, 0x2000, v4
	v_ashrrev_i32_e32 v6, 31, v5
	v_lshrrev_b32_e32 v6, 22, v6
	v_add_u32_e32 v6, v5, v6
	v_ashrrev_i32_e32 v6, 10, v6
	v_mul_i32_i24_e32 v7, 0x400, v6
	v_sub_u32_e32 v5, v5, v7
	v_lshrrev_b32_e32 v7, 4, v5
	v_bitop3_b32 v5, v7, v5, 32 bitop3:0x6c
	v_ashrrev_i32_e32 v7, 31, v5
	v_lshrrev_b32_e32 v7, 26, v7
	s_add_u32 s30, s54, s0
	v_add_u32_e32 v7, v5, v7
	v_lshlrev_b32_e32 v9, 3, v6
	s_addc_u32 s31, s55, s1
	v_readlane_b32 s0, v242, 27
	v_ashrrev_i32_e32 v8, 6, v7
	v_and_b32_e32 v9, -16, v9
	v_and_b32_e32 v7, 0xc0, v7
	s_add_u32 s33, s0, 0x2500000
	v_readlane_b32 s0, v242, 28
	v_add_u32_e32 v9, v8, v9
	v_sub_u32_e32 v5, v5, v7
	s_addc_u32 s34, s0, 0
	v_and_b32_e32 v8, 3, v8
	s_mov_b32 s0, 0xfffe0
	v_lshrrev_b32_e32 v10, 2, v9
	v_lshlrev_b32_e32 v11, 1, v9
	v_lshlrev_b32_e32 v6, 5, v6
	v_ashrrev_i16_sdwa v5, v213, sext(v5) dst_sel:DWORD dst_unused:UNUSED_PAD src0_sel:DWORD src1_sel:BYTE_0
	v_and_or_b32 v8, v9, s0, v8
	v_and_b32_e32 v10, 4, v10
	v_and_b32_e32 v11, 24, v11
	v_and_b32_e32 v6, 32, v6
	v_bfe_i32 v5, v5, 0, 16
	v_or3_b32 v8, v8, v10, v11
	v_add_lshl_u32 v5, v6, v5, 1
	v_lshl_add_u32 v194, v8, 12, v5
	v_lshrrev_b32_e32 v247, 3, v0
	v_xor_b32_e32 v247, v247, v0
	v_and_b32_e32 v247, 7, v247
	v_lshl_add_u32 v194, v247, 4, v194
	v_and_b32_e32 v247, 64, v0
	v_sub_u32_e32 v194, v194, v247
	v_lshrrev_b32_e32 v247, 4, v0
	v_and_b32_e32 v247, 2, v247
	v_xor_b32_e32 v247, v247, v0
	v_and_b32_e32 v247, 3, v247
	v_lshlrev_b32_e32 v247, 4, v247
	v_sub_u32_e32 v194, v194, v247
	v_and_b32_e32 v247, 64, v0
	v_mul_u32_u24_e32 v247, 0x400, v247
	v_add_u32_e32 v194, v194, v247
	v_and_b32_e32 v247, 32, v0
	v_mul_u32_u24_e32 v247, 0x400, v247
	v_sub_u32_e32 v194, v194, v247
	v_and_b32_e32 v247, 16, v0
	v_mul_u32_u24_e32 v247, 0x600, v247
	v_sub_u32_e32 v194, v194, v247
	v_and_b32_e32 v247, 8, v0
	v_mul_u32_u24_e32 v247, 0x200, v247
	v_sub_u32_e32 v194, v194, v247
	v_and_b32_e32 v247, 4, v0
	v_mul_u32_u24_e32 v247, 0x400, v247
	v_sub_u32_e32 v194, v194, v247
	v_lshl_add_u32 v196, v9, 12, v5
	v_lshrrev_b32_e32 v247, 3, v0
	v_xor_b32_e32 v247, v247, v0
	v_and_b32_e32 v247, 7, v247
	v_lshl_add_u32 v196, v247, 4, v196
	v_and_b32_e32 v247, 64, v0
	v_sub_u32_e32 v196, v196, v247
	v_lshrrev_b32_e32 v247, 4, v0
	v_and_b32_e32 v247, 2, v247
	v_xor_b32_e32 v247, v247, v0
	v_and_b32_e32 v247, 3, v247
	v_lshlrev_b32_e32 v247, 4, v247
	v_sub_u32_e32 v196, v196, v247
	v_bfe_u32 v247, v0, 2, 4
	v_add_u32_e32 v247, 1, v247
	v_lshrrev_b32_e32 v247, 1, v247
	v_mul_u32_u24_e32 v247, 0x1000, v247
	v_sub_u32_e32 v196, v196, v247
	v_and_b32_e32 v247, 64, v0
	v_mul_u32_u24_e32 v247, 0x200, v247
	v_add_u32_e32 v196, v196, v247
	v_bfe_i32 v5, v2, 27, 1
	v_lshrrev_b32_e32 v5, 22, v5
	v_add_u32_e32 v5, v4, v5
	v_and_b32_e32 v5, 0xfffffc00, v5
	v_sub_u32_e32 v4, v4, v5
	v_lshrrev_b32_e32 v5, 4, v4
	v_ashrrev_i32_e32 v7, 31, v2
	v_bitop3_b32 v4, v5, v4, 32 bitop3:0x6c
	v_lshrrev_b32_e32 v7, 26, v7
	v_ashrrev_i32_e32 v5, 31, v4
	v_add_u32_e32 v7, v2, v7
	v_lshrrev_b32_e32 v5, 26, v5
	v_ashrrev_i32_e32 v7, 6, v7
	v_add_u32_e32 v5, v4, v5
	v_lshlrev_b32_e32 v8, 3, v7
	v_ashrrev_i32_e32 v6, 6, v5
	v_and_b32_e32 v8, -16, v8
	v_and_b32_e32 v5, 0xc0, v5
	s_ashr_i32 s19, s16, 6
	v_add_u32_e32 v8, v6, v8
	v_and_b32_e32 v6, 3, v6
	v_sub_u32_e32 v4, v4, v5
	s_ashr_i32 s18, s16, 8
	s_lshl_b32 s35, s19, 10
	v_and_or_b32 v6, v8, s0, v6
	v_lshrrev_b32_e32 v9, 2, v8
	v_lshlrev_b32_e32 v10, 1, v8
	v_lshlrev_b32_e32 v7, 5, v7
	v_ashrrev_i16_sdwa v4, v213, sext(v4) dst_sel:DWORD dst_unused:UNUSED_PAD src0_sel:DWORD src1_sel:BYTE_0
	v_readlane_b32 s0, v243, 10
	v_and_b32_e32 v9, 4, v9
	v_and_b32_e32 v10, 24, v10
	v_and_b32_e32 v7, 32, v7
	v_bfe_i32 v4, v4, 0, 16
	v_readlane_b32 s1, v243, 11
	s_add_u32 s54, s33, s0
	v_or3_b32 v6, v6, v9, v10
	v_add_lshl_u32 v4, v7, v4, 1
	s_addc_u32 s55, s34, s1
	s_add_i32 s36, s35, 0
	v_lshl_add_u32 v206, v6, 12, v4
	v_lshrrev_b32_e32 v247, 3, v0
	v_xor_b32_e32 v247, v247, v0
	v_and_b32_e32 v247, 7, v247
	v_lshl_add_u32 v206, v247, 4, v206
	v_and_b32_e32 v247, 64, v0
	v_sub_u32_e32 v206, v206, v247
	v_lshrrev_b32_e32 v247, 4, v0
	v_and_b32_e32 v247, 2, v247
	v_xor_b32_e32 v247, v247, v0
	v_and_b32_e32 v247, 3, v247
	v_lshlrev_b32_e32 v247, 4, v247
	v_sub_u32_e32 v206, v206, v247
	v_and_b32_e32 v247, 64, v0
	v_mul_u32_u24_e32 v247, 0x400, v247
	v_add_u32_e32 v206, v206, v247
	v_and_b32_e32 v247, 32, v0
	v_mul_u32_u24_e32 v247, 0x400, v247
	v_sub_u32_e32 v206, v206, v247
	v_and_b32_e32 v247, 16, v0
	v_mul_u32_u24_e32 v247, 0x600, v247
	v_sub_u32_e32 v206, v206, v247
	v_and_b32_e32 v247, 8, v0
	v_mul_u32_u24_e32 v247, 0x200, v247
	v_sub_u32_e32 v206, v206, v247
	v_and_b32_e32 v247, 4, v0
	v_mul_u32_u24_e32 v247, 0x400, v247
	v_sub_u32_e32 v206, v206, v247
	s_add_i32 m0, s36, 0x10000
	v_lshl_add_u32 v208, v8, 12, v4
	v_lshrrev_b32_e32 v247, 3, v0
	v_xor_b32_e32 v247, v247, v0
	v_and_b32_e32 v247, 7, v247
	v_lshl_add_u32 v208, v247, 4, v208
	v_and_b32_e32 v247, 64, v0
	v_sub_u32_e32 v208, v208, v247
	v_lshrrev_b32_e32 v247, 4, v0
	v_and_b32_e32 v247, 2, v247
	v_xor_b32_e32 v247, v247, v0
	v_and_b32_e32 v247, 3, v247
	v_lshlrev_b32_e32 v247, 4, v247
	v_sub_u32_e32 v208, v208, v247
	v_bfe_u32 v247, v0, 2, 4
	v_add_u32_e32 v247, 1, v247
	v_lshrrev_b32_e32 v247, 1, v247
	v_mul_u32_u24_e32 v247, 0x1000, v247
	v_sub_u32_e32 v208, v208, v247
	v_and_b32_e32 v247, 64, v0
	v_mul_u32_u24_e32 v247, 0x200, v247
	v_add_u32_e32 v208, v208, v247
	global_load_lds_dwordx4 v206, s[54:55]
	s_add_i32 m0, s36, 0x12000
	s_add_u32 s0, s54, 0x80000
	global_load_lds_dwordx4 v194, s[54:55]
	s_addc_u32 s1, s55, 0
	s_add_i32 m0, s36, 0x14000
	v_mov_b32_e32 v207, v3
	global_load_lds_dwordx4 v206, s[0:1]
	s_add_i32 m0, s36, 0x16000
	v_mov_b32_e32 v195, v3
	global_load_lds_dwordx4 v194, s[0:1]
	v_readlane_b32 s0, v243, 8
	v_readlane_b32 s1, v243, 9
	s_add_u32 s56, s30, s0
	s_addc_u32 s57, s31, s1
	s_add_i32 s37, s36, 0x2000
	s_mov_b32 m0, s36
	s_add_u32 s0, s56, 0x80000
	global_load_lds_dwordx4 v208, s[56:57]
	s_mov_b32 m0, s37
	s_addc_u32 s1, s57, 0
	s_add_i32 s76, s36, 0x4000
	global_load_lds_dwordx4 v196, s[56:57]
	s_mov_b32 m0, s76
	s_add_i32 s77, s36, 0x6000
	global_load_lds_dwordx4 v208, s[0:1]
	s_mov_b32 m0, s77
	v_mov_b32_e32 v209, v3
	global_load_lds_dwordx4 v196, s[0:1]
	v_mov_b32_e32 v197, v3
	s_cmp_eq_u32 s18, 1
	v_lshl_add_u64 v[10:11], s[54:55], 0, v[206:207]
	v_lshl_add_u64 v[8:9], s[54:55], 0, v[194:195]
	v_lshl_add_u64 v[4:5], s[56:57], 0, v[208:209]
	s_cselect_b64 s[0:1], -1, 0
	s_cmp_lg_u32 s18, 1
	v_lshl_add_u64 v[6:7], s[56:57], 0, v[196:197]
	s_cbranch_scc1 .LBB0_1220
	s_barrier
; #define PG8_STAGE(bufoff, gbase, voff) do { _Pragma("unroll") for (int _i = 0; _i < 2; ++_i) \
;         __builtin_amdgcn_global_load_lds((const unsigned*)((const char*)(gbase) + (voff)[_i]), (LAS unsigned*)(lds + (bufoff) + ldsw + _i * 8192), 16, 0, 0); } while (0)
; #define PG8_WAIT_V(n) asm volatile("s_waitcnt vmcnt(" #n ")" ::: "memory")
; #define PG8_BAR __builtin_amdgcn_s_barrier()
; template <class Epi, bool ALIGN_EPI = true>
; __device__ __forceinline__ void gemm_phase(LAS unsigned char* lds, const Gemm g, const Sched& S, const Epi& E) {
;     ...
;     for (int i = 0; i < 2; ++i) { int R, C; stage_rc(tid * 16 + i * 8192, R, C); const int Rb = (R & ~31) + perm32(R & 31);
;         voffA[i] = (unsigned)(R * g.lda + C) * 2u; voffB[i] = (unsigned)(Rb * g.ldb + C) * 2u; }
;     const size_t kstep = (size_t)(BK * 2);
;     const size_t hstepA = (size_t)HALF * g.lda * 2, hstepB = (size_t)HALF * g.ldb * 2;
;     const unsigned ldsw = (unsigned)wid * 1024u;
;     const int aoff = lds_byte(wr * 64 + fr, fq * 8), boff = lds_byte(wc * 32 + fr, fq * 8);
;     ...
;     PG8_STAGE(PG8_SB(0, 0), cB, voffB); PG8_STAGE(PG8_SB(0, 1), cB + hstepB, voffB); PG8_STAGE(PG8_SA(0, 0), cA, voffA); PG8_STAGE(PG8_SA(0, 1), cA + hstepA, voffA);
;     if (wr == 1) PG8_BAR;
;     PG8_WAIT_V(2); PG8_BAR;
;     PG8_STAGE(PG8_SB(1, 0), cB + kstep, voffB); PG8_STAGE(PG8_SA(1, 0), cA + kstep, voffA); PG8_STAGE(PG8_SB(1, 1), cB + hstepB + kstep, voffB);
;     PG8_WAIT_V(6); PG8_BAR;
.LBB0_1220:
	v_readlane_b32 s20, v246, 42
	v_readlane_b32 s22, v246, 44
	v_readlane_b32 s23, v246, 45
	s_add_u32 s78, s22, s4
	s_addc_u32 s79, s23, s5
	s_add_u32 s4, s22, s14
	s_addc_u32 s5, s23, s15
	s_add_u32 s6, s22, s6
	s_addc_u32 s7, s23, s7
	s_ashr_i32 s14, s17, 31
	v_and_b32_e32 v223, 63, v2
	s_lshr_b32 s14, s14, 26
	v_and_b32_e32 v12, 48, v2
	v_lshlrev_b32_e32 v13, 6, v2
	s_movk_i32 s10, 0x3c0
	v_lshlrev_b32_e32 v2, 2, v2
	s_and_b32 s19, s19, 3
	s_add_i32 s17, s17, s14
	s_lshl_b32 s14, s18, 13
	v_and_or_b32 v12, v13, s10, v12
	v_and_b32_e32 v2, 32, v2
	s_add_i32 m0, s36, 0x18000
	v_lshl_add_u64 v[10:11], v[10:11], 0, s[8:9]
	s_ashr_i32 s85, s17, 6
	s_lshl_b32 s80, s18, 6
	v_bitop3_b32 v13, v12, s14, v2 bitop3:0xde
	s_lshl_b32 s14, s19, 12
	s_waitcnt vmcnt(2)
	s_barrier
	global_load_lds_dwordx4 v[10:11], off
	v_lshl_add_u64 v[8:9], v[8:9], 0, s[8:9]
	s_add_i32 m0, s36, 0x1a000
	s_add_i32 s81, s36, 0x8000
	s_add_i32 s82, s36, 0xa000
	v_bitop3_b32 v224, v12, s14, v2 bitop3:0xde
	v_bfe_u32 v224, v0, 4, 2
	v_xor_b32_e32 v224, v224, v0
	v_and_b32_e32 v224, 7, v224
	v_lshlrev_b32_e32 v224, 4, v224
	v_and_b32_e32 v247, 15, v0
	v_lshl_or_b32 v224, v247, 7, v224
	v_and_b32_e32 v247, 0xc0, v0
	v_lshl_or_b32 v224, v247, 6, v224
	v_or_b32_e32 v224, 0x10000, v224
	global_load_lds_dwordx4 v[8:9], off
	v_lshl_add_u64 v[4:5], v[4:5], 0, s[8:9]
	s_mov_b32 m0, s81
	s_add_u32 s14, s54, 0x80080
	global_load_lds_dwordx4 v[4:5], off
	v_lshl_add_u64 v[4:5], v[6:7], 0, s[8:9]
	s_mov_b32 m0, s82
	s_addc_u32 s15, s55, 0
	global_load_lds_dwordx4 v[4:5], off
	s_add_i32 m0, s36, 0x1c000
	v_lshl_add_u64 v[4:5], s[14:15], 0, v[206:207]
	global_load_lds_dwordx4 v[4:5], off
	v_lshl_add_u64 v[4:5], s[14:15], 0, v[194:195]
	s_add_i32 m0, s36, 0x1e000
	s_lshl_b32 s83, s19, 6
	global_load_lds_dwordx4 v[4:5], off
	s_ashr_i32 s84, s17, 7
	s_add_i32 s85, s85, -2
	v_readlane_b32 s18, v243, 43
	s_waitcnt vmcnt(6)
	s_cmpk_lt_u32 s16, 0x100
	v_readlane_b32 s19, v243, 44
	s_cselect_b64 s[14:15], -1, 0
	s_cmp_gt_i32 s84, 0
	s_mov_b32 s48, s18
	v_readlane_b32 s18, v243, 39
	s_mov_b32 s86, 0
	s_cselect_b64 s[16:17], -1, 0
	v_add_u32_e32 v225, 0, v13
	v_bfe_u32 v225, v0, 4, 2
	v_xor_b32_e32 v225, v225, v0
	v_and_b32_e32 v225, 7, v225
	v_lshlrev_b32_e32 v225, 4, v225
	v_and_b32_e32 v247, 15, v0
	v_lshl_or_b32 v225, v247, 7, v225
	v_and_b32_e32 v247, 0x100, v0
	v_lshl_or_b32 v225, v247, 5, v225
	s_mov_b32 s49, s18
	v_readlane_b32 s21, v246, 43
	s_barrier
	v_readlane_b32 s19, v243, 40
	s_branch .LBB0_1223

; #define PG8_STAGE(bufoff, gbase, voff) do { _Pragma("unroll") for (int _i = 0; _i < 2; ++_i) \
;         __builtin_amdgcn_global_load_lds((const unsigned*)((const char*)(gbase) + (voff)[_i]), (LAS unsigned*)(lds + (bufoff) + ldsw + _i * 8192), 16, 0, 0); } while (0)
; #define PG8_LDA(dst, b, h) do { _Pragma("unroll") for (int m = 0; m < 4; ++m) _Pragma("unroll") for (int k = 0; k < 2; ++k) dst[m][k] = *(const LAS bf16x8*)(lds + PG8_SA(b, h) + aoff + m * 2048 + k * 1024); } while (0)
; #define PG8_LDB(dst, b, h) do { _Pragma("unroll") for (int n = 0; n < 2; ++n) _Pragma("unroll") for (int k = 0; k < 2; ++k) dst[n][k] = *(const LAS bf16x8*)(lds + PG8_SB(b, h) + boff + n * 2048 + k * 1024); } while (0)
; #define PG8_MMA(ai, bj, At, Bt) do { __builtin_amdgcn_s_setprio(1); _Pragma("unroll") for (int m = 0; m < 4; ++m) _Pragma("unroll") for (int n = 0; n < 2; ++n) _Pragma("unroll") for (int k = 0; k < 2; ++k) \
;         acc[ai][bj][m][n] = __builtin_amdgcn_mfma_f32_16x16x32_bf16(Bt[n][k], At[m][k], acc[ai][bj][m][n], 0, 0, 0); __builtin_amdgcn_s_setprio(0); } while (0)
; template <class Epi, bool ALIGN_EPI = true>
; __device__ __forceinline__ void gemm_phase(LAS unsigned char* lds, const Gemm g, const Sched& S, const Epi& E) {
;     ...
;         for (int t = t_lo; t < t_hi; t += 2) {
;             const bool last = (t == nt - 2);
;             const char* a1 = cA + (size_t)(t + 1) * kstep;
;             const char* a2 = last ? nA : cA + (size_t)(t + 2) * kstep; const char* b2 = last ? nB : cB + (size_t)(t + 2) * kstep;
;             const char* a3 = a2 + kstep; const char* b3 = b2 + kstep;
;             const int rflag = __builtin_amdgcn_readfirstlane(t | (int)(ui == 0));
;             PG8_LDB(B0, 0, 0); PG8_LDB(B1, 0, 1); PG8_SCHED; PG8_LDA(At, 0, 0); PG8_STAGE(PG8_SA(1, 1), a1 + hstepA, voffA);
;             if constexpr (Epi::NSTORES > 0) PG8_WAIT_RELAX(rflag, 8 + Epi::NSTORES); else PG8_WAIT_V(8);
;             PG8_WAIT_L(0); PG8_BAR; PG8_MMA(0, 0, At, B0); PG8_MMA(0, 1, At, B1); PG8_BAR; PG8_SCHED;
;             PG8_LDA(At, 0, 1); PG8_STAGE(PG8_SB(0, 0), b2, voffB); PG8_STAGE(PG8_SB(0, 1), b2 + hstepB, voffB); PG8_STAGE(PG8_SA(0, 0), a2, voffA);
;             if constexpr (Epi::NSTORES > 0) PG8_WAIT_RELAX(rflag, 8 + Epi::NSTORES); else PG8_WAIT_V(8);
;             PG8_WAIT_L(0); PG8_BAR; PG8_MMA(1, 0, At, B0); PG8_MMA(1, 1, At, B1); PG8_BAR; PG8_SCHED;
.LBB0_1235:
	s_andn2_b64 vcc, exec, s[16:17]
	s_cbranch_vccnz .LBB0_1232
	s_add_i32 s90, s26, 1
	s_mul_i32 s90, s90, s84
	s_mul_i32 s24, s26, s84
	v_xor_b32_e32 v232, 64, v225
	v_xor_b32_e32 v233, 64, v224
.LBB0_1237:
	s_add_i32 s94, s24, 1
	s_lshl_b64 s[92:93], s[94:95], 7
	s_add_i32 s94, s24, 2
	s_lshl_b64 s[26:27], s[94:95], 7
	s_add_u32 s25, s56, s26
	s_addc_u32 s91, s57, s27
	s_add_u32 s96, s54, s26
	s_addc_u32 s97, s55, s27
	s_add_i32 vcc_lo, 0, 0x10000
	s_cmp_eq_u32 s85, s24
	s_cselect_b32 s27, s19, s91
	s_cselect_b32 s26, s87, s25
	s_cselect_b32 s25, s88, s97
	s_cselect_b32 s24, s89, s96
	s_add_i32 s91, 0, 0x14000
	ds_read_b128 v[134:137], v224
	ds_read_b128 v[138:141], v233
	ds_read_b128 v[142:145], v224 offset:2048
	ds_read_b128 v[146:149], v233 offset:2048
	ds_read_b128 v[150:153], v224 offset:16384
	ds_read_b128 v[154:157], v233 offset:16384
	ds_read_b128 v[158:161], v224 offset:18432
	ds_read_b128 v[162:165], v233 offset:18432
	s_add_u32 s92, s56, s92
	s_addc_u32 s93, s57, s93
	s_add_u32 s92, s92, 0x80000
	s_addc_u32 s93, s93, 0
	s_add_i32 m0, s36, 0xc000
	ds_read_b128 v[166:169], v225
	ds_read_b128 v[170:173], v232
	ds_read_b128 v[174:177], v225 offset:2048
	ds_read_b128 v[178:181], v232 offset:2048
	ds_read_b128 v[182:185], v225 offset:4096
	ds_read_b128 v[186:189], v232 offset:4096
	ds_read_b128 v[190:193], v225 offset:6144
	ds_read_b128 v[226:229], v232 offset:6144
	s_add_u32 s100, s92, 0xfff80000
	s_addc_u32 s101, s93, -1
	s_mov_b32 m0, s81
	s_nop 0
	global_load_lds_dwordx4 v208, s[100:101]
	s_mov_b32 m0, s82
	s_nop 0
	global_load_lds_dwordx4 v196, s[100:101]
	s_add_i32 m0, s36, 0xc000
	s_nop 0
	global_load_lds_dwordx4 v208, s[92:93]
	s_add_i32 m0, s36, 0xe000
	s_nop 0
	global_load_lds_dwordx4 v196, s[92:93]
	s_waitcnt vmcnt(8)
	s_waitcnt lgkmcnt(0)
	s_barrier
	s_setprio 1
	s_waitcnt lgkmcnt(0)
	v_mfma_f32_16x16x32_bf16 v[130:133], v[134:137], v[166:169], v[130:133]
	v_mfma_f32_16x16x32_bf16 v[126:129], v[142:145], v[166:169], v[126:129]
	v_mfma_f32_16x16x32_bf16 v[114:117], v[134:137], v[174:177], v[114:117]
	v_mfma_f32_16x16x32_bf16 v[110:113], v[142:145], v[174:177], v[110:113]
	v_mfma_f32_16x16x32_bf16 v[98:101], v[134:137], v[182:185], v[98:101]
	v_mfma_f32_16x16x32_bf16 v[94:97], v[142:145], v[182:185], v[94:97]
	v_mfma_f32_16x16x32_bf16 v[82:85], v[134:137], v[190:193], v[82:85]
	v_mfma_f32_16x16x32_bf16 v[78:81], v[142:145], v[190:193], v[78:81]
	v_mfma_f32_16x16x32_bf16 v[130:133], v[138:141], v[170:173], v[130:133]
	v_mfma_f32_16x16x32_bf16 v[126:129], v[146:149], v[170:173], v[126:129]
	v_mfma_f32_16x16x32_bf16 v[114:117], v[138:141], v[178:181], v[114:117]
	v_mfma_f32_16x16x32_bf16 v[110:113], v[146:149], v[178:181], v[110:113]
	v_mfma_f32_16x16x32_bf16 v[98:101], v[138:141], v[186:189], v[98:101]
	v_mfma_f32_16x16x32_bf16 v[94:97], v[146:149], v[186:189], v[94:97]
	v_mfma_f32_16x16x32_bf16 v[82:85], v[138:141], v[226:229], v[82:85]
	v_mfma_f32_16x16x32_bf16 v[78:81], v[146:149], v[226:229], v[78:81]
	s_setprio 0
	s_setprio 1
	v_mfma_f32_16x16x32_bf16 v[122:125], v[150:153], v[166:169], v[122:125]
	v_mfma_f32_16x16x32_bf16 v[118:121], v[158:161], v[166:169], v[118:121]
	v_mfma_f32_16x16x32_bf16 v[106:109], v[150:153], v[174:177], v[106:109]
	v_mfma_f32_16x16x32_bf16 v[102:105], v[158:161], v[174:177], v[102:105]
	v_mfma_f32_16x16x32_bf16 v[90:93], v[150:153], v[182:185], v[90:93]
	v_mfma_f32_16x16x32_bf16 v[86:89], v[158:161], v[182:185], v[86:89]
	v_mfma_f32_16x16x32_bf16 v[74:77], v[150:153], v[190:193], v[74:77]
	v_mfma_f32_16x16x32_bf16 v[70:73], v[158:161], v[190:193], v[70:73]
	v_mfma_f32_16x16x32_bf16 v[122:125], v[154:157], v[170:173], v[122:125]
	v_mfma_f32_16x16x32_bf16 v[118:121], v[162:165], v[170:173], v[118:121]
	v_mfma_f32_16x16x32_bf16 v[106:109], v[154:157], v[178:181], v[106:109]
	v_mfma_f32_16x16x32_bf16 v[102:105], v[162:165], v[178:181], v[102:105]
	v_mfma_f32_16x16x32_bf16 v[90:93], v[154:157], v[186:189], v[90:93]
	v_mfma_f32_16x16x32_bf16 v[86:89], v[162:165], v[186:189], v[86:89]
	v_mfma_f32_16x16x32_bf16 v[74:77], v[154:157], v[226:229], v[74:77]
	v_mfma_f32_16x16x32_bf16 v[70:73], v[162:165], v[226:229], v[70:73]
	s_setprio 0
	s_barrier
	s_add_i32 s92, vcc_lo, s35
	s_mov_b32 m0, s92
	ds_read_b128 v[166:169], v225 offset:16384
	ds_read_b128 v[170:173], v232 offset:16384
	ds_read_b128 v[174:177], v225 offset:18432
	ds_read_b128 v[178:181], v232 offset:18432
	ds_read_b128 v[182:185], v225 offset:20480
	ds_read_b128 v[186:189], v232 offset:20480
	ds_read_b128 v[190:193], v225 offset:22528
	ds_read_b128 v[226:229], v232 offset:22528
	global_load_lds_dwordx4 v206, s[24:25]
	s_add_i32 m0, s92, 0x2000
	s_add_u32 s92, s24, 0x80000
	s_addc_u32 s93, s25, 0
	s_add_i32 s91, s91, s35
	global_load_lds_dwordx4 v194, s[24:25]
	s_mov_b32 m0, s91
	s_nop 0
	global_load_lds_dwordx4 v206, s[92:93]
	s_add_i32 m0, s91, 0x2000
	s_nop 0
	global_load_lds_dwordx4 v194, s[92:93]
	s_waitcnt vmcnt(6)
	s_waitcnt lgkmcnt(0)
	s_barrier
; #define PG8_STAGE(bufoff, gbase, voff) do { _Pragma("unroll") for (int _i = 0; _i < 2; ++_i) \
;         __builtin_amdgcn_global_load_lds((const unsigned*)((const char*)(gbase) + (voff)[_i]), (LAS unsigned*)(lds + (bufoff) + ldsw + _i * 8192), 16, 0, 0); } while (0)
; #define PG8_LDA(dst, b, h) do { _Pragma("unroll") for (int m = 0; m < 4; ++m) _Pragma("unroll") for (int k = 0; k < 2; ++k) dst[m][k] = *(const LAS bf16x8*)(lds + PG8_SA(b, h) + aoff + m * 2048 + k * 1024); } while (0)
; #define PG8_LDB(dst, b, h) do { _Pragma("unroll") for (int n = 0; n < 2; ++n) _Pragma("unroll") for (int k = 0; k < 2; ++k) dst[n][k] = *(const LAS bf16x8*)(lds + PG8_SB(b, h) + boff + n * 2048 + k * 1024); } while (0)
; #define PG8_MMA(ai, bj, At, Bt) do { __builtin_amdgcn_s_setprio(1); _Pragma("unroll") for (int m = 0; m < 4; ++m) _Pragma("unroll") for (int n = 0; n < 2; ++n) _Pragma("unroll") for (int k = 0; k < 2; ++k) \
;         acc[ai][bj][m][n] = __builtin_amdgcn_mfma_f32_16x16x32_bf16(Bt[n][k], At[m][k], acc[ai][bj][m][n], 0, 0, 0); __builtin_amdgcn_s_setprio(0); } while (0)
; #define PG8_WAIT_V(n) asm volatile("s_waitcnt vmcnt(" #n ")" ::: "memory")
; #define PG8_WAIT_L(n) asm volatile("s_waitcnt lgkmcnt(" #n ")" ::: "memory")
; #define PG8_BAR __builtin_amdgcn_s_barrier()
; #define PG8_WAIT_RELAX(flag, n) asm volatile("s_cmp_eq_u32 %0, 0\n\ts_cbranch_scc1 .Lrw%=\n\ts_waitcnt vmcnt(8)\n.Lrw%=:\n\ts_waitcnt vmcnt(%1)" :: "s"(flag), "n"(n) : "scc", "memory")
; #define PG8_SCHED __builtin_amdgcn_sched_barrier(0)
; template <class Epi, bool ALIGN_EPI = true>
; __device__ __forceinline__ void gemm_phase(LAS unsigned char* lds, const Gemm g, const Sched& S, const Epi& E) {
;     ...
;             PG8_WAIT_L(0); PG8_BAR; PG8_MMA(0, 0, At, B0); PG8_MMA(0, 1, At, B1); PG8_BAR; PG8_SCHED;
;             PG8_LDA(At, 0, 1); PG8_STAGE(PG8_SB(0, 0), b2, voffB); PG8_STAGE(PG8_SB(0, 1), b2 + hstepB, voffB); PG8_STAGE(PG8_SA(0, 0), a2, voffA);
;             if constexpr (Epi::NSTORES > 0) PG8_WAIT_RELAX(rflag, 8 + Epi::NSTORES); else PG8_WAIT_V(8);
;             PG8_WAIT_L(0); PG8_BAR; PG8_MMA(1, 0, At, B0); PG8_MMA(1, 1, At, B1); PG8_BAR; PG8_SCHED;
;             PG8_LDB(B0, 1, 0); PG8_LDB(B1, 1, 1); PG8_SCHED; PG8_LDA(At, 1, 0); PG8_STAGE(PG8_SA(0, 1), a2 + hstepA, voffA);
;             PG8_WAIT_V(8); PG8_WAIT_L(0); PG8_BAR; PG8_MMA(0, 0, At, B0); PG8_MMA(0, 1, At, B1); PG8_BAR; PG8_SCHED;
	s_setprio 1
	s_waitcnt lgkmcnt(0)
	v_mfma_f32_16x16x32_bf16 v[66:69], v[134:137], v[166:169], v[66:69]
	v_mfma_f32_16x16x32_bf16 v[62:65], v[142:145], v[166:169], v[62:65]
	v_mfma_f32_16x16x32_bf16 v[50:53], v[134:137], v[174:177], v[50:53]
	v_mfma_f32_16x16x32_bf16 v[46:49], v[142:145], v[174:177], v[46:49]
	v_mfma_f32_16x16x32_bf16 v[34:37], v[134:137], v[182:185], v[34:37]
	v_mfma_f32_16x16x32_bf16 v[30:33], v[142:145], v[182:185], v[30:33]
	v_mfma_f32_16x16x32_bf16 v[18:21], v[134:137], v[190:193], v[18:21]
	v_mfma_f32_16x16x32_bf16 v[14:17], v[142:145], v[190:193], v[14:17]
	v_mfma_f32_16x16x32_bf16 v[66:69], v[138:141], v[170:173], v[66:69]
	v_mfma_f32_16x16x32_bf16 v[62:65], v[146:149], v[170:173], v[62:65]
	v_mfma_f32_16x16x32_bf16 v[50:53], v[138:141], v[178:181], v[50:53]
	v_mfma_f32_16x16x32_bf16 v[46:49], v[146:149], v[178:181], v[46:49]
	v_mfma_f32_16x16x32_bf16 v[34:37], v[138:141], v[186:189], v[34:37]
	v_mfma_f32_16x16x32_bf16 v[30:33], v[146:149], v[186:189], v[30:33]
	v_mfma_f32_16x16x32_bf16 v[18:21], v[138:141], v[226:229], v[18:21]
	v_mfma_f32_16x16x32_bf16 v[14:17], v[146:149], v[226:229], v[14:17]
	s_setprio 0
	s_setprio 1
	v_mfma_f32_16x16x32_bf16 v[58:61], v[150:153], v[166:169], v[58:61]
	v_mfma_f32_16x16x32_bf16 v[54:57], v[158:161], v[166:169], v[54:57]
	v_mfma_f32_16x16x32_bf16 v[42:45], v[150:153], v[174:177], v[42:45]
	v_mfma_f32_16x16x32_bf16 v[38:41], v[158:161], v[174:177], v[38:41]
	v_mfma_f32_16x16x32_bf16 v[26:29], v[150:153], v[182:185], v[26:29]
	v_mfma_f32_16x16x32_bf16 v[22:25], v[158:161], v[182:185], v[22:25]
	v_mfma_f32_16x16x32_bf16 v[10:13], v[150:153], v[190:193], v[10:13]
	v_mfma_f32_16x16x32_bf16 v[4:7], v[158:161], v[190:193], v[6:9]
	v_mfma_f32_16x16x32_bf16 v[58:61], v[154:157], v[170:173], v[58:61]
	v_mfma_f32_16x16x32_bf16 v[54:57], v[162:165], v[170:173], v[54:57]
	v_mfma_f32_16x16x32_bf16 v[42:45], v[154:157], v[178:181], v[42:45]
	v_mfma_f32_16x16x32_bf16 v[38:41], v[162:165], v[178:181], v[38:41]
	v_mfma_f32_16x16x32_bf16 v[26:29], v[154:157], v[186:189], v[26:29]
	v_mfma_f32_16x16x32_bf16 v[22:25], v[162:165], v[186:189], v[22:25]
	v_mfma_f32_16x16x32_bf16 v[10:13], v[154:157], v[226:229], v[10:13]
	v_mfma_f32_16x16x32_bf16 v[4:7], v[162:165], v[226:229], v[4:7]
	s_setprio 0
	s_barrier
	s_add_i32 s91, 0, 0x18000
	s_add_i32 s92, 0, 0x1c000
	ds_read_b128 v[134:137], v224 offset:32768
	ds_read_b128 v[138:141], v233 offset:32768
	ds_read_b128 v[142:145], v224 offset:34816
	ds_read_b128 v[146:149], v233 offset:34816
	ds_read_b128 v[150:153], v224 offset:49152
	ds_read_b128 v[154:157], v233 offset:49152
	ds_read_b128 v[158:161], v224 offset:51200
	ds_read_b128 v[162:165], v233 offset:51200
	s_add_u32 s26, s26, 0x80000
	s_addc_u32 s27, s27, 0
	s_mov_b32 m0, s76
	ds_read_b128 v[166:169], v225 offset:32768
	ds_read_b128 v[170:173], v232 offset:32768
	ds_read_b128 v[174:177], v225 offset:34816
	ds_read_b128 v[178:181], v232 offset:34816
	ds_read_b128 v[182:185], v225 offset:36864
	ds_read_b128 v[186:189], v232 offset:36864
	ds_read_b128 v[190:193], v225 offset:38912
	ds_read_b128 v[226:229], v232 offset:38912
	s_add_u32 s100, s26, 0xfff80000
	s_addc_u32 s101, s27, -1
	s_mov_b32 m0, s36
	s_nop 0
	global_load_lds_dwordx4 v208, s[100:101]
	s_mov_b32 m0, s37
	s_nop 0
	global_load_lds_dwordx4 v196, s[100:101]
	s_mov_b32 m0, s76
	s_nop 0
	global_load_lds_dwordx4 v208, s[26:27]
	s_mov_b32 m0, s77
	s_nop 0
	global_load_lds_dwordx4 v196, s[26:27]
	s_waitcnt vmcnt(8)
	s_waitcnt lgkmcnt(0)
	s_barrier
; #define PG8_STAGE(bufoff, gbase, voff) do { _Pragma("unroll") for (int _i = 0; _i < 2; ++_i) \
;         __builtin_amdgcn_global_load_lds((const unsigned*)((const char*)(gbase) + (voff)[_i]), (LAS unsigned*)(lds + (bufoff) + ldsw + _i * 8192), 16, 0, 0); } while (0)
; #define PG8_LDA(dst, b, h) do { _Pragma("unroll") for (int m = 0; m < 4; ++m) _Pragma("unroll") for (int k = 0; k < 2; ++k) dst[m][k] = *(const LAS bf16x8*)(lds + PG8_SA(b, h) + aoff + m * 2048 + k * 1024); } while (0)
; #define PG8_LDB(dst, b, h) do { _Pragma("unroll") for (int n = 0; n < 2; ++n) _Pragma("unroll") for (int k = 0; k < 2; ++k) dst[n][k] = *(const LAS bf16x8*)(lds + PG8_SB(b, h) + boff + n * 2048 + k * 1024); } while (0)
; #define PG8_MMA(ai, bj, At, Bt) do { __builtin_amdgcn_s_setprio(1); _Pragma("unroll") for (int m = 0; m < 4; ++m) _Pragma("unroll") for (int n = 0; n < 2; ++n) _Pragma("unroll") for (int k = 0; k < 2; ++k) \
;         acc[ai][bj][m][n] = __builtin_amdgcn_mfma_f32_16x16x32_bf16(Bt[n][k], At[m][k], acc[ai][bj][m][n], 0, 0, 0); __builtin_amdgcn_s_setprio(0); } while (0)
; #define PG8_WAIT_V(n) asm volatile("s_waitcnt vmcnt(" #n ")" ::: "memory")
; #define PG8_WAIT_L(n) asm volatile("s_waitcnt lgkmcnt(" #n ")" ::: "memory")
; #define PG8_BAR __builtin_amdgcn_s_barrier()
; #define PG8_SCHED __builtin_amdgcn_sched_barrier(0)
; template <class Epi, bool ALIGN_EPI = true>
; __device__ __forceinline__ void gemm_phase(LAS unsigned char* lds, const Gemm g, const Sched& S, const Epi& E) {
;     ...
;             PG8_LDB(B0, 1, 0); PG8_LDB(B1, 1, 1); PG8_SCHED; PG8_LDA(At, 1, 0); PG8_STAGE(PG8_SA(0, 1), a2 + hstepA, voffA);
;             PG8_WAIT_V(8); PG8_WAIT_L(0); PG8_BAR; PG8_MMA(0, 0, At, B0); PG8_MMA(0, 1, At, B1); PG8_BAR; PG8_SCHED;
;             PG8_LDA(At, 1, 1); PG8_STAGE(PG8_SB(1, 0), b3, voffB); PG8_STAGE(PG8_SB(1, 1), b3 + hstepB, voffB); PG8_STAGE(PG8_SA(1, 0), a3, voffA);
;             PG8_WAIT_V(8); PG8_WAIT_L(0); PG8_BAR; PG8_MMA(1, 0, At, B0); PG8_MMA(1, 1, At, B1); PG8_BAR; PG8_SCHED;
;         }
	s_setprio 1
	s_waitcnt lgkmcnt(0)
	v_mfma_f32_16x16x32_bf16 v[130:133], v[134:137], v[166:169], v[130:133]
	v_mfma_f32_16x16x32_bf16 v[126:129], v[142:145], v[166:169], v[126:129]
	v_mfma_f32_16x16x32_bf16 v[114:117], v[134:137], v[174:177], v[114:117]
	v_mfma_f32_16x16x32_bf16 v[110:113], v[142:145], v[174:177], v[110:113]
	v_mfma_f32_16x16x32_bf16 v[98:101], v[134:137], v[182:185], v[98:101]
	v_mfma_f32_16x16x32_bf16 v[94:97], v[142:145], v[182:185], v[94:97]
	v_mfma_f32_16x16x32_bf16 v[82:85], v[134:137], v[190:193], v[82:85]
	v_mfma_f32_16x16x32_bf16 v[78:81], v[142:145], v[190:193], v[78:81]
	v_mfma_f32_16x16x32_bf16 v[130:133], v[138:141], v[170:173], v[130:133]
	v_mfma_f32_16x16x32_bf16 v[126:129], v[146:149], v[170:173], v[126:129]
	v_mfma_f32_16x16x32_bf16 v[114:117], v[138:141], v[178:181], v[114:117]
	v_mfma_f32_16x16x32_bf16 v[110:113], v[146:149], v[178:181], v[110:113]
	v_mfma_f32_16x16x32_bf16 v[98:101], v[138:141], v[186:189], v[98:101]
	v_mfma_f32_16x16x32_bf16 v[94:97], v[146:149], v[186:189], v[94:97]
	v_mfma_f32_16x16x32_bf16 v[82:85], v[138:141], v[226:229], v[82:85]
	v_mfma_f32_16x16x32_bf16 v[78:81], v[146:149], v[226:229], v[78:81]
	s_setprio 0
	s_setprio 1
	v_mfma_f32_16x16x32_bf16 v[122:125], v[150:153], v[166:169], v[122:125]
	v_mfma_f32_16x16x32_bf16 v[118:121], v[158:161], v[166:169], v[118:121]
	v_mfma_f32_16x16x32_bf16 v[106:109], v[150:153], v[174:177], v[106:109]
	v_mfma_f32_16x16x32_bf16 v[102:105], v[158:161], v[174:177], v[102:105]
	v_mfma_f32_16x16x32_bf16 v[90:93], v[150:153], v[182:185], v[90:93]
	v_mfma_f32_16x16x32_bf16 v[86:89], v[158:161], v[182:185], v[86:89]
	v_mfma_f32_16x16x32_bf16 v[74:77], v[150:153], v[190:193], v[74:77]
	v_mfma_f32_16x16x32_bf16 v[70:73], v[158:161], v[190:193], v[70:73]
	v_mfma_f32_16x16x32_bf16 v[122:125], v[154:157], v[170:173], v[122:125]
	v_mfma_f32_16x16x32_bf16 v[118:121], v[162:165], v[170:173], v[118:121]
	v_mfma_f32_16x16x32_bf16 v[106:109], v[154:157], v[178:181], v[106:109]
	v_mfma_f32_16x16x32_bf16 v[102:105], v[162:165], v[178:181], v[102:105]
	v_mfma_f32_16x16x32_bf16 v[90:93], v[154:157], v[186:189], v[90:93]
	v_mfma_f32_16x16x32_bf16 v[86:89], v[162:165], v[186:189], v[86:89]
	v_mfma_f32_16x16x32_bf16 v[74:77], v[154:157], v[226:229], v[74:77]
	v_mfma_f32_16x16x32_bf16 v[70:73], v[162:165], v[226:229], v[70:73]
	s_setprio 0
	s_barrier
	s_add_u32 s100, s24, 0x80
	s_addc_u32 s101, s25, 0
	s_add_i32 s26, s91, s35
	s_mov_b32 m0, s26
	ds_read_b128 v[166:169], v225 offset:49152
	ds_read_b128 v[170:173], v232 offset:49152
	ds_read_b128 v[174:177], v225 offset:51200
	ds_read_b128 v[178:181], v232 offset:51200
	ds_read_b128 v[182:185], v225 offset:53248
	ds_read_b128 v[186:189], v232 offset:53248
	ds_read_b128 v[190:193], v225 offset:55296
	ds_read_b128 v[226:229], v232 offset:55296
	global_load_lds_dwordx4 v206, s[100:101]
	s_add_i32 m0, s26, 0x2000
	s_add_u32 s24, s24, 0x80080
	s_addc_u32 s25, s25, 0
	s_add_i32 s26, s92, s35
	global_load_lds_dwordx4 v194, s[100:101]
	s_mov_b32 m0, s26
	s_nop 0
	global_load_lds_dwordx4 v206, s[24:25]
	s_add_i32 m0, s26, 0x2000
	s_nop 0
	global_load_lds_dwordx4 v194, s[24:25]
	s_waitcnt vmcnt(6)
	s_waitcnt lgkmcnt(0)
	s_barrier
	s_setprio 1
	s_waitcnt lgkmcnt(0)
	v_mfma_f32_16x16x32_bf16 v[66:69], v[134:137], v[166:169], v[66:69]
	v_mfma_f32_16x16x32_bf16 v[62:65], v[142:145], v[166:169], v[62:65]
	v_mfma_f32_16x16x32_bf16 v[50:53], v[134:137], v[174:177], v[50:53]
	v_mfma_f32_16x16x32_bf16 v[46:49], v[142:145], v[174:177], v[46:49]
	v_mfma_f32_16x16x32_bf16 v[34:37], v[134:137], v[182:185], v[34:37]
	v_mfma_f32_16x16x32_bf16 v[30:33], v[142:145], v[182:185], v[30:33]
	v_mfma_f32_16x16x32_bf16 v[18:21], v[134:137], v[190:193], v[18:21]
	v_mfma_f32_16x16x32_bf16 v[14:17], v[142:145], v[190:193], v[14:17]
	v_mfma_f32_16x16x32_bf16 v[66:69], v[138:141], v[170:173], v[66:69]
	v_mfma_f32_16x16x32_bf16 v[62:65], v[146:149], v[170:173], v[62:65]
	v_mfma_f32_16x16x32_bf16 v[50:53], v[138:141], v[178:181], v[50:53]
	v_mfma_f32_16x16x32_bf16 v[46:49], v[146:149], v[178:181], v[46:49]
	v_mfma_f32_16x16x32_bf16 v[34:37], v[138:141], v[186:189], v[34:37]
	v_mfma_f32_16x16x32_bf16 v[30:33], v[146:149], v[186:189], v[30:33]
	v_mfma_f32_16x16x32_bf16 v[18:21], v[138:141], v[226:229], v[18:21]
	v_mfma_f32_16x16x32_bf16 v[14:17], v[146:149], v[226:229], v[14:17]
	s_setprio 0
	s_setprio 1
	v_mfma_f32_16x16x32_bf16 v[58:61], v[150:153], v[166:169], v[58:61]
	v_mfma_f32_16x16x32_bf16 v[54:57], v[158:161], v[166:169], v[54:57]
	v_mfma_f32_16x16x32_bf16 v[42:45], v[150:153], v[174:177], v[42:45]
	v_mfma_f32_16x16x32_bf16 v[38:41], v[158:161], v[174:177], v[38:41]
	v_mfma_f32_16x16x32_bf16 v[26:29], v[150:153], v[182:185], v[26:29]
	v_mfma_f32_16x16x32_bf16 v[22:25], v[158:161], v[182:185], v[22:25]
	v_mfma_f32_16x16x32_bf16 v[8:11], v[150:153], v[190:193], v[10:13]
	v_mfma_f32_16x16x32_bf16 v[4:7], v[158:161], v[190:193], v[4:7]
	v_mfma_f32_16x16x32_bf16 v[58:61], v[154:157], v[170:173], v[58:61]
	v_mfma_f32_16x16x32_bf16 v[54:57], v[162:165], v[170:173], v[54:57]
	v_mfma_f32_16x16x32_bf16 v[42:45], v[154:157], v[178:181], v[42:45]
	v_mfma_f32_16x16x32_bf16 v[38:41], v[162:165], v[178:181], v[38:41]
	v_mfma_f32_16x16x32_bf16 v[26:29], v[154:157], v[186:189], v[26:29]
	v_mfma_f32_16x16x32_bf16 v[22:25], v[162:165], v[186:189], v[22:25]
	v_mfma_f32_16x16x32_bf16 v[10:13], v[154:157], v[226:229], v[8:11]
	v_mfma_f32_16x16x32_bf16 v[6:9], v[162:165], v[226:229], v[4:7]
	s_setprio 0
	s_barrier
	s_cmp_ge_i32 s94, s90
	s_mov_b32 s24, s94
	s_cbranch_scc0 .LBB0_1237
	s_branch .LBB0_1232

; #define PG8_STAGE(bufoff, gbase, voff) do { _Pragma("unroll") for (int _i = 0; _i < 2; ++_i) \
;         __builtin_amdgcn_global_load_lds((const unsigned*)((const char*)(gbase) + (voff)[_i]), (LAS unsigned*)(lds + (bufoff) + ldsw + _i * 8192), 16, 0, 0); } while (0)
; #define PG8_WAIT_V(n) asm volatile("s_waitcnt vmcnt(" #n ")" ::: "memory")
; #define PG8_BAR __builtin_amdgcn_s_barrier()
; template <class Epi, bool ALIGN_EPI = true>
; __device__ __forceinline__ void gemm_phase(LAS unsigned char* lds, const Gemm g, const Sched& S, const Epi& E) {
;     ...
;     for (int i = 0; i < 2; ++i) { int R, C; stage_rc(tid * 16 + i * 8192, R, C); const int Rb = (R & ~31) + perm32(R & 31);
;         voffA[i] = (unsigned)(R * g.lda + C) * 2u; voffB[i] = (unsigned)(Rb * g.ldb + C) * 2u; }
;     const size_t kstep = (size_t)(BK * 2);
;     const size_t hstepA = (size_t)HALF * g.lda * 2, hstepB = (size_t)HALF * g.ldb * 2;
;     const unsigned ldsw = (unsigned)wid * 1024u;
;     const int aoff = lds_byte(wr * 64 + fr, fq * 8), boff = lds_byte(wc * 32 + fr, fq * 8);
;     ...
;     const char* cA = (const char*)g.A + cur.aoff; const char* cB = (const char*)g.Bt + cur.boff;
;     PG8_STAGE(PG8_SB(0, 0), cB, voffB); PG8_STAGE(PG8_SB(0, 1), cB + hstepB, voffB); PG8_STAGE(PG8_SA(0, 0), cA, voffA); PG8_STAGE(PG8_SA(0, 1), cA + hstepA, voffA);
;     if (wr == 1) PG8_BAR;
;     PG8_WAIT_V(2); PG8_BAR;
.LBB0_1296:
	s_andn2_b64 vcc, exec, s[0:1]
	s_cbranch_vccnz .LBB0_1385
	v_readlane_b32 s14, v244, 0
	s_mov_b64 s[4:5], 0x37000000
	s_mov_b64 s[6:7], 0x26000000
	s_mov_b64 s[0:1], 0x120000
	v_mov_b32_e32 v146, v0
	v_readlane_b32 s15, v244, 1
	s_movk_i32 s18, 0x800
	v_readfirstlane_b32 s30, v146
	s_andn2_b64 vcc, exec, s[14:15]
	s_cbranch_vccnz .LBB0_1335
	s_waitcnt vmcnt(0) lgkmcnt(0)
	v_lshlrev_b32_e32 v4, 4, v146
	v_add_u32_e32 v5, 0x2000, v4
	v_ashrrev_i32_e32 v2, 31, v5
	v_lshrrev_b32_e32 v2, 22, v2
	v_add_u32_e32 v2, v5, v2
	v_ashrrev_i32_e32 v2, 10, v2
	v_mul_i32_i24_e32 v6, 0x400, v2
	v_sub_u32_e32 v5, v5, v6
	v_lshrrev_b32_e32 v6, 4, v5
	v_bitop3_b32 v5, v6, v5, 32 bitop3:0x6c
	v_ashrrev_i32_e32 v6, 31, v5
	v_lshrrev_b32_e32 v6, 26, v6
	v_add_u32_e32 v6, v5, v6
	v_lshlrev_b32_e32 v7, 3, v2
	v_ashrrev_i32_e32 v12, 6, v6
	v_and_b32_e32 v7, -16, v7
	v_add_u32_e32 v7, v12, v7
	v_and_b32_e32 v8, 3, v12
	s_mov_b32 s10, 0xfffe0
	v_lshrrev_b32_e32 v9, 2, v7
	v_lshlrev_b32_e32 v10, 1, v7
	v_and_b32_e32 v6, 0xc0, v6
	v_and_or_b32 v8, v7, s10, v8
	v_and_b32_e32 v9, 4, v9
	v_and_b32_e32 v10, 24, v10
	v_sub_u32_e32 v5, v5, v6
	v_or3_b32 v8, v8, v9, v10
	v_lshlrev_b32_e32 v9, 5, v2
	v_ashrrev_i16_sdwa v5, v213, sext(v5) dst_sel:DWORD dst_unused:UNUSED_PAD src0_sel:DWORD src1_sel:BYTE_0
	v_and_b32_e32 v9, 32, v9
	v_bfe_i32 v13, v5, 0, 16
	v_add_lshl_u32 v5, v9, v13, 1
	v_lshl_add_u32 v134, v8, 12, v5
	v_lshrrev_b32_e32 v247, 3, v0
	v_xor_b32_e32 v247, v247, v0
	v_and_b32_e32 v247, 7, v247
	v_lshl_add_u32 v134, v247, 4, v134
	v_and_b32_e32 v247, 64, v0
	v_sub_u32_e32 v134, v134, v247
	v_lshrrev_b32_e32 v247, 4, v0
	v_and_b32_e32 v247, 2, v247
	v_xor_b32_e32 v247, v247, v0
	v_and_b32_e32 v247, 3, v247
	v_lshlrev_b32_e32 v247, 4, v247
	v_sub_u32_e32 v134, v134, v247
	v_and_b32_e32 v247, 64, v0
	v_mul_u32_u24_e32 v247, 0x400, v247
	v_add_u32_e32 v134, v134, v247
	v_and_b32_e32 v247, 32, v0
	v_mul_u32_u24_e32 v247, 0x400, v247
	v_sub_u32_e32 v134, v134, v247
	v_and_b32_e32 v247, 16, v0
	v_mul_u32_u24_e32 v247, 0x600, v247
	v_sub_u32_e32 v134, v134, v247
	v_and_b32_e32 v247, 8, v0
	v_mul_u32_u24_e32 v247, 0x200, v247
	v_sub_u32_e32 v134, v134, v247
	v_and_b32_e32 v247, 4, v0
	v_mul_u32_u24_e32 v247, 0x400, v247
	v_sub_u32_e32 v134, v134, v247
	v_lshl_add_u32 v136, v7, 12, v5
	v_lshrrev_b32_e32 v247, 3, v0
	v_xor_b32_e32 v247, v247, v0
	v_and_b32_e32 v247, 7, v247
	v_lshl_add_u32 v136, v247, 4, v136
	v_and_b32_e32 v247, 64, v0
	v_sub_u32_e32 v136, v136, v247
	v_lshrrev_b32_e32 v247, 4, v0
	v_and_b32_e32 v247, 2, v247
	v_xor_b32_e32 v247, v247, v0
	v_and_b32_e32 v247, 3, v247
	v_lshlrev_b32_e32 v247, 4, v247
	v_sub_u32_e32 v136, v136, v247
	v_bfe_u32 v247, v0, 2, 4
	v_add_u32_e32 v247, 1, v247
	v_lshrrev_b32_e32 v247, 1, v247
	v_mul_u32_u24_e32 v247, 0x1000, v247
	v_sub_u32_e32 v136, v136, v247
	v_and_b32_e32 v247, 64, v0
	v_mul_u32_u24_e32 v247, 0x200, v247
	v_add_u32_e32 v136, v136, v247
	v_bfe_i32 v5, v146, 27, 1
	v_lshrrev_b32_e32 v5, 22, v5
	v_add_u32_e32 v5, v4, v5
	v_and_b32_e32 v5, 0xfffffc00, v5
	v_sub_u32_e32 v4, v4, v5
	v_lshrrev_b32_e32 v5, 4, v4
	v_ashrrev_i32_e32 v6, 31, v146
	v_bitop3_b32 v4, v5, v4, 32 bitop3:0x6c
	v_lshrrev_b32_e32 v6, 26, v6
	v_ashrrev_i32_e32 v5, 31, v4
	v_add_u32_e32 v6, v146, v6
	v_lshrrev_b32_e32 v5, 26, v5
	v_ashrrev_i32_e32 v15, 6, v6
	v_add_u32_e32 v5, v4, v5
	v_lshlrev_b32_e32 v6, 3, v15
	s_add_u32 s33, s54, s4
	v_ashrrev_i32_e32 v14, 6, v5
	v_and_b32_e32 v6, -16, v6
	s_addc_u32 s34, s55, s5
	v_readlane_b32 s4, v242, 27
	v_add_u32_e32 v6, v14, v6
	s_add_u32 s35, s4, 0x2d00000
	v_readlane_b32 s4, v242, 28
	v_and_b32_e32 v7, 3, v14
	v_lshrrev_b32_e32 v8, 2, v6
	v_lshlrev_b32_e32 v9, 1, v6
	v_and_b32_e32 v5, 0xc0, v5
	s_addc_u32 s36, s4, 0
	s_ashr_i32 s5, s30, 6
	v_and_or_b32 v7, v6, s10, v7
	v_and_b32_e32 v8, 4, v8
	v_and_b32_e32 v9, 24, v9
	v_sub_u32_e32 v4, v4, v5
	s_ashr_i32 s4, s30, 8
	s_lshl_b32 s37, s5, 10
	v_or3_b32 v7, v7, v8, v9
	v_lshlrev_b32_e32 v8, 5, v15
	v_ashrrev_i16_sdwa v4, v213, sext(v4) dst_sel:DWORD dst_unused:UNUSED_PAD src0_sel:DWORD src1_sel:BYTE_0
	v_readlane_b32 s14, v243, 10
	v_and_b32_e32 v8, 32, v8
	v_bfe_i32 v16, v4, 0, 16
	v_readlane_b32 s15, v243, 11
	s_add_u32 s14, s35, s14
	v_add_lshl_u32 v4, v8, v16, 1
	s_addc_u32 s15, s36, s15
	s_add_i32 s52, s37, 0
	v_lshl_add_u32 v138, v7, 12, v4
	v_lshrrev_b32_e32 v247, 3, v0
	v_xor_b32_e32 v247, v247, v0
	v_and_b32_e32 v247, 7, v247
	v_lshl_add_u32 v138, v247, 4, v138
	v_and_b32_e32 v247, 64, v0
	v_sub_u32_e32 v138, v138, v247
	v_lshrrev_b32_e32 v247, 4, v0
	v_and_b32_e32 v247, 2, v247
	v_xor_b32_e32 v247, v247, v0
	v_and_b32_e32 v247, 3, v247
	v_lshlrev_b32_e32 v247, 4, v247
	v_sub_u32_e32 v138, v138, v247
	v_and_b32_e32 v247, 64, v0
	v_mul_u32_u24_e32 v247, 0x400, v247
	v_add_u32_e32 v138, v138, v247
	v_and_b32_e32 v247, 32, v0
	v_mul_u32_u24_e32 v247, 0x400, v247
	v_sub_u32_e32 v138, v138, v247
	v_and_b32_e32 v247, 16, v0
	v_mul_u32_u24_e32 v247, 0x600, v247
	v_sub_u32_e32 v138, v138, v247
	v_and_b32_e32 v247, 8, v0
	v_mul_u32_u24_e32 v247, 0x200, v247
	v_sub_u32_e32 v138, v138, v247
	v_and_b32_e32 v247, 4, v0
	v_mul_u32_u24_e32 v247, 0x400, v247
	v_sub_u32_e32 v138, v138, v247
	s_add_i32 m0, s52, 0x10000
	v_lshl_add_u32 v140, v6, 12, v4
	v_lshrrev_b32_e32 v247, 3, v0
	v_xor_b32_e32 v247, v247, v0
	v_and_b32_e32 v247, 7, v247
	v_lshl_add_u32 v140, v247, 4, v140
	v_and_b32_e32 v247, 64, v0
	v_sub_u32_e32 v140, v140, v247
	v_lshrrev_b32_e32 v247, 4, v0
	v_and_b32_e32 v247, 2, v247
	v_xor_b32_e32 v247, v247, v0
	v_and_b32_e32 v247, 3, v247
	v_lshlrev_b32_e32 v247, 4, v247
	v_sub_u32_e32 v140, v140, v247
	v_bfe_u32 v247, v0, 2, 4
	v_add_u32_e32 v247, 1, v247
	v_lshrrev_b32_e32 v247, 1, v247
	v_mul_u32_u24_e32 v247, 0x1000, v247
	v_sub_u32_e32 v140, v140, v247
	v_and_b32_e32 v247, 64, v0
	v_mul_u32_u24_e32 v247, 0x200, v247
	v_add_u32_e32 v140, v140, v247
	global_load_lds_dwordx4 v138, s[14:15]
	s_add_i32 m0, s52, 0x12000
	s_add_u32 s16, s14, 0x80000
	global_load_lds_dwordx4 v134, s[14:15]
	s_addc_u32 s17, s15, 0
	s_add_i32 m0, s52, 0x14000
	v_mov_b32_e32 v139, v3
	global_load_lds_dwordx4 v138, s[16:17]
	s_add_i32 m0, s52, 0x16000
	v_mov_b32_e32 v135, v3
	global_load_lds_dwordx4 v134, s[16:17]
	v_readlane_b32 s16, v243, 8
	v_readlane_b32 s17, v243, 9
	s_add_u32 s16, s33, s16
	s_addc_u32 s17, s34, s17
	s_add_i32 s53, s52, 0x2000
	s_mov_b32 m0, s52
	s_add_u32 s20, s16, 0x80000
	global_load_lds_dwordx4 v140, s[16:17]
	s_mov_b32 m0, s53
	s_addc_u32 s21, s17, 0
	s_add_i32 s54, s52, 0x4000
	global_load_lds_dwordx4 v136, s[16:17]
	s_mov_b32 m0, s54
	s_add_i32 s55, s52, 0x6000
	global_load_lds_dwordx4 v140, s[20:21]
	s_mov_b32 m0, s55
	v_mov_b32_e32 v141, v3
	global_load_lds_dwordx4 v136, s[20:21]
	v_mov_b32_e32 v137, v3
	v_lshl_add_u64 v[10:11], s[14:15], 0, v[138:139]
	v_lshl_add_u64 v[8:9], s[14:15], 0, v[134:135]
	v_lshl_add_u64 v[6:7], s[16:17], 0, v[140:141]
	s_cmp_lg_u32 s4, 1
	v_lshl_add_u64 v[4:5], s[16:17], 0, v[136:137]
	s_cbranch_scc1 .LBB0_1300
	s_barrier
; #define PG8_STAGE(bufoff, gbase, voff) do { _Pragma("unroll") for (int _i = 0; _i < 2; ++_i) \
;         __builtin_amdgcn_global_load_lds((const unsigned*)((const char*)(gbase) + (voff)[_i]), (LAS unsigned*)(lds + (bufoff) + ldsw + _i * 8192), 16, 0, 0); } while (0)
; #define PG8_WAIT_V(n) asm volatile("s_waitcnt vmcnt(" #n ")" ::: "memory")
; #define PG8_BAR __builtin_amdgcn_s_barrier()
; template <class Epi, bool ALIGN_EPI = true>
; __device__ __forceinline__ void gemm_phase(LAS unsigned char* lds, const Gemm g, const Sched& S, const Epi& E) {
;     ...
;     f32x4 acc[2][2][4][2];
; #pragma unroll
;     for (int a = 0; a < 2; ++a)
; #pragma unroll
;         for (int b = 0; b < 2; ++b)
; #pragma unroll
;             for (int m = 0; m < 4; ++m)
; #pragma unroll
;                 for (int n = 0; n < 2; ++n) acc[a][b][m][n] = (f32x4){0.f, 0.f, 0.f, 0.f};
;     bf16x8 At[4][2], B0[2][2], B1[2][2];
;     const char* cA = (const char*)g.A + cur.aoff; const char* cB = (const char*)g.Bt + cur.boff;
;     PG8_STAGE(PG8_SB(0, 0), cB, voffB); PG8_STAGE(PG8_SB(0, 1), cB + hstepB, voffB); PG8_STAGE(PG8_SA(0, 0), cA, voffA); PG8_STAGE(PG8_SA(0, 1), cA + hstepA, voffA);
;     if (wr == 1) PG8_BAR;
;     PG8_WAIT_V(2); PG8_BAR;
;     PG8_STAGE(PG8_SB(1, 0), cB + kstep, voffB); PG8_STAGE(PG8_SA(1, 0), cA + kstep, voffA); PG8_STAGE(PG8_SB(1, 1), cB + hstepB + kstep, voffB);
;     PG8_WAIT_V(6); PG8_BAR;
.LBB0_1300:
	s_ashr_i32 s19, s18, 31
	s_lshr_b32 s19, s19, 26
	s_and_b32 s5, s5, 3
	s_add_i32 s19, s18, s19
	s_add_i32 m0, s52, 0x18000
	v_lshl_add_u64 v[10:11], v[10:11], 0, s[8:9]
	s_ashr_i32 s56, s19, 6
	s_lshl_b32 s31, s4, 6
	s_lshl_b32 s4, s4, 13
	s_lshl_b32 s19, s5, 12
	s_waitcnt vmcnt(2)
	s_barrier
	global_load_lds_dwordx4 v[10:11], off
	v_lshl_add_u64 v[8:9], v[8:9], 0, s[8:9]
	s_add_i32 m0, s52, 0x1a000
	s_add_i32 s57, s52, 0x8000
	s_add_i32 s58, s52, 0xa000
	global_load_lds_dwordx4 v[8:9], off
	v_lshl_add_u64 v[6:7], v[6:7], 0, s[8:9]
	s_mov_b32 m0, s57
	s_add_u32 s20, s14, 0x80080
	global_load_lds_dwordx4 v[6:7], off
	v_lshl_add_u64 v[4:5], v[4:5], 0, s[8:9]
	s_mov_b32 m0, s58
	s_addc_u32 s21, s15, 0
	global_load_lds_dwordx4 v[4:5], off
	s_add_i32 m0, s52, 0x1c000
	v_lshl_add_u64 v[4:5], s[20:21], 0, v[138:139]
	global_load_lds_dwordx4 v[4:5], off
	v_lshl_add_u64 v[4:5], s[20:21], 0, v[134:135]
	s_add_i32 m0, s52, 0x1e000
	s_movk_i32 s10, 0x3c0
	global_load_lds_dwordx4 v[4:5], off
	v_and_b32_e32 v4, 48, v146
	v_lshlrev_b32_e32 v5, 6, v146
	v_and_or_b32 v4, v5, s10, v4
	v_lshlrev_b32_e32 v5, 2, v146
	v_and_b32_e32 v5, 32, v5
	v_bitop3_b32 v6, v4, s4, v5 bitop3:0xde
	v_bitop3_b32 v147, v4, s19, v5 bitop3:0xde
	v_bfe_u32 v147, v0, 4, 2
	v_xor_b32_e32 v147, v147, v0
	v_and_b32_e32 v147, 7, v147
	v_lshlrev_b32_e32 v147, 4, v147
	v_and_b32_e32 v247, 15, v0
	v_lshl_or_b32 v147, v247, 7, v147
	v_and_b32_e32 v247, 0xc0, v0
	v_lshl_or_b32 v147, v247, 6, v147
	v_or_b32_e32 v147, 0x10000, v147
	v_lshlrev_b32_e32 v4, 15, v15
	v_and_b32_e32 v4, 0xffff0000, v4
	v_lshl_add_u32 v4, v14, 12, v4
	v_and_b32_e32 v5, 1, v15
	v_lshl_or_b32 v4, v5, 6, v4
	v_lshl_add_u32 v142, v16, 1, v4
	v_lshrrev_b32_e32 v247, 3, v0
	v_xor_b32_e32 v247, v247, v0
	v_and_b32_e32 v247, 7, v247
	v_lshl_add_u32 v142, v247, 4, v142
	v_and_b32_e32 v247, 64, v0
	v_sub_u32_e32 v142, v142, v247
	v_lshrrev_b32_e32 v247, 4, v0
	v_and_b32_e32 v247, 2, v247
	v_xor_b32_e32 v247, v247, v0
	v_and_b32_e32 v247, 3, v247
	v_lshlrev_b32_e32 v247, 4, v247
	v_sub_u32_e32 v142, v142, v247
	v_bfe_u32 v247, v0, 2, 4
	v_add_u32_e32 v247, 1, v247
	v_lshrrev_b32_e32 v247, 1, v247
	v_mul_u32_u24_e32 v247, 0x1000, v247
	v_sub_u32_e32 v142, v142, v247
	v_and_b32_e32 v247, 64, v0
	v_mul_u32_u24_e32 v247, 0x200, v247
	v_add_u32_e32 v142, v142, v247
	v_lshlrev_b32_e32 v4, 15, v2
	v_and_b32_e32 v4, 0xffff0000, v4
	v_lshl_add_u32 v4, v12, 12, v4
	v_and_b32_e32 v2, 1, v2
	v_readlane_b32 s20, v243, 43
	s_waitcnt vmcnt(6)
	v_lshl_or_b32 v2, v2, 6, v4
	v_mov_b32_e32 v4, v3
	v_mov_b32_e32 v5, v3
	v_readlane_b32 s21, v243, 44
	s_cmp_gt_i32 s18, 63
	v_lshl_add_u32 v144, v13, 1, v2
	v_lshrrev_b32_e32 v247, 3, v0
	v_xor_b32_e32 v247, v247, v0
	v_and_b32_e32 v247, 7, v247
	v_lshl_add_u32 v144, v247, 4, v144
	v_and_b32_e32 v247, 64, v0
	v_sub_u32_e32 v144, v144, v247
	v_lshrrev_b32_e32 v247, 4, v0
	v_and_b32_e32 v247, 2, v247
	v_xor_b32_e32 v247, v247, v0
	v_and_b32_e32 v247, 3, v247
	v_lshlrev_b32_e32 v247, 4, v247
	v_sub_u32_e32 v144, v144, v247
	v_bfe_u32 v247, v0, 2, 4
	v_add_u32_e32 v247, 1, v247
	v_lshrrev_b32_e32 v247, 1, v247
	v_mul_u32_u24_e32 v247, 0x1000, v247
	v_sub_u32_e32 v144, v144, v247
	v_and_b32_e32 v247, 64, v0
	v_mul_u32_u24_e32 v247, 0x200, v247
	v_add_u32_e32 v144, v144, v247
	v_mov_b32_e32 v2, v3
	v_add_u32_e32 v148, 0, v6
	v_bfe_u32 v148, v0, 4, 2
	v_xor_b32_e32 v148, v148, v0
	v_and_b32_e32 v148, 7, v148
	v_lshlrev_b32_e32 v148, 4, v148
	v_and_b32_e32 v247, 15, v0
	v_lshl_or_b32 v148, v247, 7, v148
	v_and_b32_e32 v247, 0x100, v0
	v_lshl_or_b32 v148, v247, 5, v148
	v_mov_b64_e32 v[8:9], v[4:5]
	v_mov_b64_e32 v[12:13], v[4:5]
	v_mov_b64_e32 v[24:25], v[4:5]
	v_mov_b64_e32 v[28:29], v[4:5]
	v_mov_b64_e32 v[40:41], v[4:5]
	v_mov_b64_e32 v[44:45], v[4:5]
	v_mov_b64_e32 v[56:57], v[4:5]
	v_mov_b64_e32 v[60:61], v[4:5]
	v_mov_b64_e32 v[16:17], v[4:5]
	v_mov_b64_e32 v[20:21], v[4:5]
	v_mov_b64_e32 v[32:33], v[4:5]
	v_mov_b64_e32 v[36:37], v[4:5]
	v_mov_b64_e32 v[48:49], v[4:5]
	v_mov_b64_e32 v[52:53], v[4:5]
	v_mov_b64_e32 v[64:65], v[4:5]
	v_mov_b64_e32 v[68:69], v[4:5]
	v_mov_b64_e32 v[72:73], v[4:5]
	v_mov_b64_e32 v[76:77], v[4:5]
	v_mov_b64_e32 v[88:89], v[4:5]
	v_mov_b64_e32 v[92:93], v[4:5]
	v_mov_b64_e32 v[104:105], v[4:5]
	v_mov_b64_e32 v[108:109], v[4:5]
	v_mov_b64_e32 v[120:121], v[4:5]
	v_mov_b64_e32 v[124:125], v[4:5]
	v_mov_b64_e32 v[80:81], v[4:5]
	v_mov_b64_e32 v[84:85], v[4:5]
	v_mov_b64_e32 v[96:97], v[4:5]
	v_mov_b64_e32 v[100:101], v[4:5]
	v_mov_b64_e32 v[112:113], v[4:5]
	v_mov_b64_e32 v[116:117], v[4:5]
	v_mov_b64_e32 v[128:129], v[4:5]
	v_mov_b64_e32 v[132:133], v[4:5]
	s_mov_b32 s4, s20
	v_readlane_b32 s20, v243, 39
	s_cselect_b64 s[18:19], -1, 0
	s_add_i32 s59, s56, -2
	v_mov_b32_e32 v143, v3
	v_mov_b32_e32 v145, v3
	s_mov_b32 s60, 0
	v_mov_b64_e32 v[6:7], v[2:3]
	v_mov_b64_e32 v[10:11], v[2:3]
	v_mov_b64_e32 v[22:23], v[2:3]
	v_mov_b64_e32 v[26:27], v[2:3]
	v_mov_b64_e32 v[38:39], v[2:3]
	v_mov_b64_e32 v[42:43], v[2:3]
	v_mov_b64_e32 v[54:55], v[2:3]
	v_mov_b64_e32 v[58:59], v[2:3]
	v_mov_b64_e32 v[14:15], v[2:3]
	v_mov_b64_e32 v[18:19], v[2:3]
	v_mov_b64_e32 v[30:31], v[2:3]
	v_mov_b64_e32 v[34:35], v[2:3]
	v_mov_b64_e32 v[46:47], v[2:3]
	v_mov_b64_e32 v[50:51], v[2:3]
	v_mov_b64_e32 v[62:63], v[2:3]
	v_mov_b64_e32 v[66:67], v[2:3]
	v_mov_b64_e32 v[70:71], v[2:3]
	v_mov_b64_e32 v[74:75], v[2:3]
	v_mov_b64_e32 v[86:87], v[2:3]
	v_mov_b64_e32 v[90:91], v[2:3]
	v_mov_b64_e32 v[102:103], v[2:3]
	v_mov_b64_e32 v[106:107], v[2:3]
	v_mov_b64_e32 v[118:119], v[2:3]
	v_mov_b64_e32 v[122:123], v[2:3]
	v_mov_b64_e32 v[78:79], v[2:3]
	v_mov_b64_e32 v[82:83], v[2:3]
	v_mov_b64_e32 v[94:95], v[2:3]
	v_mov_b64_e32 v[98:99], v[2:3]
	v_mov_b64_e32 v[110:111], v[2:3]
	v_mov_b64_e32 v[114:115], v[2:3]
	v_mov_b64_e32 v[126:127], v[2:3]
	v_mov_b64_e32 v[130:131], v[2:3]
	s_mov_b32 s61, s20
	s_barrier
	v_readlane_b32 s21, v243, 40
	s_branch .LBB0_1302

; #define PG8_STAGE(bufoff, gbase, voff) do { _Pragma("unroll") for (int _i = 0; _i < 2; ++_i) \
;         __builtin_amdgcn_global_load_lds((const unsigned*)((const char*)(gbase) + (voff)[_i]), (LAS unsigned*)(lds + (bufoff) + ldsw + _i * 8192), 16, 0, 0); } while (0)
; #define PG8_LDA(dst, b, h) do { _Pragma("unroll") for (int m = 0; m < 4; ++m) _Pragma("unroll") for (int k = 0; k < 2; ++k) dst[m][k] = *(const LAS bf16x8*)(lds + PG8_SA(b, h) + aoff + m * 2048 + k * 1024); } while (0)
; #define PG8_LDB(dst, b, h) do { _Pragma("unroll") for (int n = 0; n < 2; ++n) _Pragma("unroll") for (int k = 0; k < 2; ++k) dst[n][k] = *(const LAS bf16x8*)(lds + PG8_SB(b, h) + boff + n * 2048 + k * 1024); } while (0)
; #define PG8_MMA(ai, bj, At, Bt) do { __builtin_amdgcn_s_setprio(1); _Pragma("unroll") for (int m = 0; m < 4; ++m) _Pragma("unroll") for (int n = 0; n < 2; ++n) _Pragma("unroll") for (int k = 0; k < 2; ++k) \
;         acc[ai][bj][m][n] = __builtin_amdgcn_mfma_f32_16x16x32_bf16(Bt[n][k], At[m][k], acc[ai][bj][m][n], 0, 0, 0); __builtin_amdgcn_s_setprio(0); } while (0)
; template <class Epi, bool ALIGN_EPI = true>
; __device__ __forceinline__ void gemm_phase(LAS unsigned char* lds, const Gemm g, const Sched& S, const Epi& E) {
;     ...
;         for (int t = t_lo; t < t_hi; t += 2) {
;             const bool last = (t == nt - 2);
;             const char* a1 = cA + (size_t)(t + 1) * kstep;
;             const char* a2 = last ? nA : cA + (size_t)(t + 2) * kstep; const char* b2 = last ? nB : cB + (size_t)(t + 2) * kstep;
;             const char* a3 = a2 + kstep; const char* b3 = b2 + kstep;
;             const int rflag = __builtin_amdgcn_readfirstlane(t | (int)(ui == 0));
;             PG8_LDB(B0, 0, 0); PG8_LDB(B1, 0, 1); PG8_SCHED; PG8_LDA(At, 0, 0); PG8_STAGE(PG8_SA(1, 1), a1 + hstepA, voffA);
;             if constexpr (Epi::NSTORES > 0) PG8_WAIT_RELAX(rflag, 8 + Epi::NSTORES); else PG8_WAIT_V(8);
;             PG8_WAIT_L(0); PG8_BAR; PG8_MMA(0, 0, At, B0); PG8_MMA(0, 1, At, B1); PG8_BAR; PG8_SCHED;
;             PG8_LDA(At, 0, 1); PG8_STAGE(PG8_SB(0, 0), b2, voffB); PG8_STAGE(PG8_SB(0, 1), b2 + hstepB, voffB); PG8_STAGE(PG8_SA(0, 0), a2, voffA);
;             if constexpr (Epi::NSTORES > 0) PG8_WAIT_RELAX(rflag, 8 + Epi::NSTORES); else PG8_WAIT_V(8);
;             PG8_WAIT_L(0); PG8_BAR; PG8_MMA(1, 0, At, B0); PG8_MMA(1, 1, At, B1); PG8_BAR; PG8_SCHED;
.LBB0_1309:
	s_add_u32 s26, s33, s24
	s_addc_u32 s27, s34, s25
	s_add_u32 s42, s35, s40
	s_addc_u32 s43, s36, s41
	s_andn2_b64 vcc, exec, s[18:19]
	s_cbranch_vccnz .LBB0_1312
	s_and_b64 s[46:47], s[44:45], exec
	s_cselect_b32 s21, s27, s17
	s_cselect_b32 s23, s26, s16
	s_cselect_b32 s63, s43, s15
	s_cselect_b32 s64, s42, s14
	s_add_u32 s46, s16, 0x80080
	s_addc_u32 s47, s17, 0
	s_add_u32 s65, s14, 0x100
	s_addc_u32 s66, s15, 0
	s_mov_b32 s48, 0
	v_xor_b32_e32 v238, 64, v148
	v_xor_b32_e32 v239, 64, v147
.LBB0_1311:
	s_add_i32 s67, s48, 2
	s_add_u32 s49, s46, 0xfff80080
	s_addc_u32 s50, s47, -1
	s_add_i32 s68, 0, 0x10000
	s_cmp_eq_u32 s59, s48
	s_cselect_b32 s51, s21, s50
	s_cselect_b32 s50, s23, s49
	s_cselect_b32 s49, s63, s66
	s_cselect_b32 s48, s64, s65
	s_add_i32 s70, 0, 0x14000
	ds_read_b128 v[150:153], v147
	ds_read_b128 v[154:157], v239
	ds_read_b128 v[158:161], v147 offset:2048
	ds_read_b128 v[162:165], v239 offset:2048
	ds_read_b128 v[166:169], v147 offset:16384
	ds_read_b128 v[170:173], v239 offset:16384
	ds_read_b128 v[174:177], v147 offset:18432
	ds_read_b128 v[178:181], v239 offset:18432
	s_add_i32 m0, s52, 0xc000
	ds_read_b128 v[182:185], v148
	ds_read_b128 v[186:189], v238
	ds_read_b128 v[190:193], v148 offset:2048
	ds_read_b128 v[194:197], v238 offset:2048
	ds_read_b128 v[206:209], v148 offset:4096
	ds_read_b128 v[224:227], v238 offset:4096
	ds_read_b128 v[228:231], v148 offset:6144
	ds_read_b128 v[232:235], v238 offset:6144
	s_add_u32 s100, s46, 0xfff80000
	s_addc_u32 s101, s47, -1
	s_mov_b32 m0, s57
	s_nop 0
	global_load_lds_dwordx4 v142, s[100:101]
	s_mov_b32 m0, s58
	s_nop 0
	global_load_lds_dwordx4 v144, s[100:101]
	s_add_i32 m0, s52, 0xc000
	s_nop 0
	global_load_lds_dwordx4 v142, s[46:47]
	s_add_i32 m0, s52, 0xe000
	s_nop 0
	global_load_lds_dwordx4 v144, s[46:47]
	s_waitcnt vmcnt(8)
	s_waitcnt lgkmcnt(0)
	s_barrier
	s_setprio 1
	s_waitcnt lgkmcnt(0)
	v_mfma_f32_16x16x32_bf16 v[130:133], v[150:153], v[182:185], v[130:133]
	v_mfma_f32_16x16x32_bf16 v[126:129], v[158:161], v[182:185], v[126:129]
	v_mfma_f32_16x16x32_bf16 v[114:117], v[150:153], v[190:193], v[114:117]
	v_mfma_f32_16x16x32_bf16 v[110:113], v[158:161], v[190:193], v[110:113]
	v_mfma_f32_16x16x32_bf16 v[98:101], v[150:153], v[206:209], v[98:101]
	v_mfma_f32_16x16x32_bf16 v[94:97], v[158:161], v[206:209], v[94:97]
	v_mfma_f32_16x16x32_bf16 v[82:85], v[150:153], v[228:231], v[82:85]
	v_mfma_f32_16x16x32_bf16 v[78:81], v[158:161], v[228:231], v[78:81]
	v_mfma_f32_16x16x32_bf16 v[130:133], v[154:157], v[186:189], v[130:133]
	v_mfma_f32_16x16x32_bf16 v[126:129], v[162:165], v[186:189], v[126:129]
	v_mfma_f32_16x16x32_bf16 v[114:117], v[154:157], v[194:197], v[114:117]
	v_mfma_f32_16x16x32_bf16 v[110:113], v[162:165], v[194:197], v[110:113]
	v_mfma_f32_16x16x32_bf16 v[98:101], v[154:157], v[224:227], v[98:101]
	v_mfma_f32_16x16x32_bf16 v[94:97], v[162:165], v[224:227], v[94:97]
	v_mfma_f32_16x16x32_bf16 v[82:85], v[154:157], v[232:235], v[82:85]
	v_mfma_f32_16x16x32_bf16 v[78:81], v[162:165], v[232:235], v[78:81]
	s_setprio 0
	s_setprio 1
	v_mfma_f32_16x16x32_bf16 v[122:125], v[166:169], v[182:185], v[122:125]
	v_mfma_f32_16x16x32_bf16 v[118:121], v[174:177], v[182:185], v[118:121]
	v_mfma_f32_16x16x32_bf16 v[106:109], v[166:169], v[190:193], v[106:109]
	v_mfma_f32_16x16x32_bf16 v[102:105], v[174:177], v[190:193], v[102:105]
	v_mfma_f32_16x16x32_bf16 v[90:93], v[166:169], v[206:209], v[90:93]
	v_mfma_f32_16x16x32_bf16 v[86:89], v[174:177], v[206:209], v[86:89]
	v_mfma_f32_16x16x32_bf16 v[74:77], v[166:169], v[228:231], v[74:77]
	v_mfma_f32_16x16x32_bf16 v[70:73], v[174:177], v[228:231], v[70:73]
	v_mfma_f32_16x16x32_bf16 v[122:125], v[170:173], v[186:189], v[122:125]
	v_mfma_f32_16x16x32_bf16 v[118:121], v[178:181], v[186:189], v[118:121]
	v_mfma_f32_16x16x32_bf16 v[106:109], v[170:173], v[194:197], v[106:109]
	v_mfma_f32_16x16x32_bf16 v[102:105], v[178:181], v[194:197], v[102:105]
	v_mfma_f32_16x16x32_bf16 v[90:93], v[170:173], v[224:227], v[90:93]
	v_mfma_f32_16x16x32_bf16 v[86:89], v[178:181], v[224:227], v[86:89]
	v_mfma_f32_16x16x32_bf16 v[74:77], v[170:173], v[232:235], v[74:77]
	v_mfma_f32_16x16x32_bf16 v[70:73], v[178:181], v[232:235], v[70:73]
	s_setprio 0
	s_barrier
	s_add_i32 s68, s68, s37
	s_mov_b32 m0, s68
	ds_read_b128 v[182:185], v148 offset:16384
	ds_read_b128 v[186:189], v238 offset:16384
	ds_read_b128 v[190:193], v148 offset:18432
	ds_read_b128 v[194:197], v238 offset:18432
	ds_read_b128 v[206:209], v148 offset:20480
	ds_read_b128 v[224:227], v238 offset:20480
	ds_read_b128 v[228:231], v148 offset:22528
	ds_read_b128 v[232:235], v238 offset:22528
	global_load_lds_dwordx4 v138, s[48:49]
	s_add_i32 m0, s68, 0x2000
	s_add_u32 s68, s48, 0x80000
	s_addc_u32 s69, s49, 0
	s_add_i32 s70, s70, s37
	global_load_lds_dwordx4 v134, s[48:49]
	s_mov_b32 m0, s70
	s_nop 0
	global_load_lds_dwordx4 v138, s[68:69]
	s_add_i32 m0, s70, 0x2000
	s_nop 0
	global_load_lds_dwordx4 v134, s[68:69]
	s_waitcnt vmcnt(6)
	s_waitcnt lgkmcnt(0)
	s_barrier
; #define PG8_STAGE(bufoff, gbase, voff) do { _Pragma("unroll") for (int _i = 0; _i < 2; ++_i) \
;         __builtin_amdgcn_global_load_lds((const unsigned*)((const char*)(gbase) + (voff)[_i]), (LAS unsigned*)(lds + (bufoff) + ldsw + _i * 8192), 16, 0, 0); } while (0)
; #define PG8_LDA(dst, b, h) do { _Pragma("unroll") for (int m = 0; m < 4; ++m) _Pragma("unroll") for (int k = 0; k < 2; ++k) dst[m][k] = *(const LAS bf16x8*)(lds + PG8_SA(b, h) + aoff + m * 2048 + k * 1024); } while (0)
; #define PG8_LDB(dst, b, h) do { _Pragma("unroll") for (int n = 0; n < 2; ++n) _Pragma("unroll") for (int k = 0; k < 2; ++k) dst[n][k] = *(const LAS bf16x8*)(lds + PG8_SB(b, h) + boff + n * 2048 + k * 1024); } while (0)
; #define PG8_MMA(ai, bj, At, Bt) do { __builtin_amdgcn_s_setprio(1); _Pragma("unroll") for (int m = 0; m < 4; ++m) _Pragma("unroll") for (int n = 0; n < 2; ++n) _Pragma("unroll") for (int k = 0; k < 2; ++k) \
;         acc[ai][bj][m][n] = __builtin_amdgcn_mfma_f32_16x16x32_bf16(Bt[n][k], At[m][k], acc[ai][bj][m][n], 0, 0, 0); __builtin_amdgcn_s_setprio(0); } while (0)
; #define PG8_WAIT_V(n) asm volatile("s_waitcnt vmcnt(" #n ")" ::: "memory")
; #define PG8_WAIT_L(n) asm volatile("s_waitcnt lgkmcnt(" #n ")" ::: "memory")
; #define PG8_BAR __builtin_amdgcn_s_barrier()
; #define PG8_WAIT_RELAX(flag, n) asm volatile("s_cmp_eq_u32 %0, 0\n\ts_cbranch_scc1 .Lrw%=\n\ts_waitcnt vmcnt(8)\n.Lrw%=:\n\ts_waitcnt vmcnt(%1)" :: "s"(flag), "n"(n) : "scc", "memory")
; #define PG8_SCHED __builtin_amdgcn_sched_barrier(0)
; template <class Epi, bool ALIGN_EPI = true>
; __device__ __forceinline__ void gemm_phase(LAS unsigned char* lds, const Gemm g, const Sched& S, const Epi& E) {
;     ...
;             PG8_WAIT_L(0); PG8_BAR; PG8_MMA(0, 0, At, B0); PG8_MMA(0, 1, At, B1); PG8_BAR; PG8_SCHED;
;             PG8_LDA(At, 0, 1); PG8_STAGE(PG8_SB(0, 0), b2, voffB); PG8_STAGE(PG8_SB(0, 1), b2 + hstepB, voffB); PG8_STAGE(PG8_SA(0, 0), a2, voffA);
;             if constexpr (Epi::NSTORES > 0) PG8_WAIT_RELAX(rflag, 8 + Epi::NSTORES); else PG8_WAIT_V(8);
;             PG8_WAIT_L(0); PG8_BAR; PG8_MMA(1, 0, At, B0); PG8_MMA(1, 1, At, B1); PG8_BAR; PG8_SCHED;
;             PG8_LDB(B0, 1, 0); PG8_LDB(B1, 1, 1); PG8_SCHED; PG8_LDA(At, 1, 0); PG8_STAGE(PG8_SA(0, 1), a2 + hstepA, voffA);
;             PG8_WAIT_V(8); PG8_WAIT_L(0); PG8_BAR; PG8_MMA(0, 0, At, B0); PG8_MMA(0, 1, At, B1); PG8_BAR; PG8_SCHED;
	s_setprio 1
	s_waitcnt lgkmcnt(0)
	v_mfma_f32_16x16x32_bf16 v[66:69], v[150:153], v[182:185], v[66:69]
	v_mfma_f32_16x16x32_bf16 v[62:65], v[158:161], v[182:185], v[62:65]
	v_mfma_f32_16x16x32_bf16 v[50:53], v[150:153], v[190:193], v[50:53]
	v_mfma_f32_16x16x32_bf16 v[46:49], v[158:161], v[190:193], v[46:49]
	v_mfma_f32_16x16x32_bf16 v[34:37], v[150:153], v[206:209], v[34:37]
	v_mfma_f32_16x16x32_bf16 v[30:33], v[158:161], v[206:209], v[30:33]
	v_mfma_f32_16x16x32_bf16 v[18:21], v[150:153], v[228:231], v[18:21]
	v_mfma_f32_16x16x32_bf16 v[14:17], v[158:161], v[228:231], v[14:17]
	v_mfma_f32_16x16x32_bf16 v[66:69], v[154:157], v[186:189], v[66:69]
	v_mfma_f32_16x16x32_bf16 v[62:65], v[162:165], v[186:189], v[62:65]
	v_mfma_f32_16x16x32_bf16 v[50:53], v[154:157], v[194:197], v[50:53]
	v_mfma_f32_16x16x32_bf16 v[46:49], v[162:165], v[194:197], v[46:49]
	v_mfma_f32_16x16x32_bf16 v[34:37], v[154:157], v[224:227], v[34:37]
	v_mfma_f32_16x16x32_bf16 v[30:33], v[162:165], v[224:227], v[30:33]
	v_mfma_f32_16x16x32_bf16 v[18:21], v[154:157], v[232:235], v[18:21]
	v_mfma_f32_16x16x32_bf16 v[14:17], v[162:165], v[232:235], v[14:17]
	s_setprio 0
	s_setprio 1
	v_mfma_f32_16x16x32_bf16 v[58:61], v[166:169], v[182:185], v[58:61]
	v_mfma_f32_16x16x32_bf16 v[54:57], v[174:177], v[182:185], v[54:57]
	v_mfma_f32_16x16x32_bf16 v[42:45], v[166:169], v[190:193], v[42:45]
	v_mfma_f32_16x16x32_bf16 v[38:41], v[174:177], v[190:193], v[38:41]
	v_mfma_f32_16x16x32_bf16 v[26:29], v[166:169], v[206:209], v[26:29]
	v_mfma_f32_16x16x32_bf16 v[22:25], v[174:177], v[206:209], v[22:25]
	v_mfma_f32_16x16x32_bf16 v[10:13], v[166:169], v[228:231], v[10:13]
	v_mfma_f32_16x16x32_bf16 v[4:7], v[174:177], v[228:231], v[6:9]
	v_mfma_f32_16x16x32_bf16 v[58:61], v[170:173], v[186:189], v[58:61]
	v_mfma_f32_16x16x32_bf16 v[54:57], v[178:181], v[186:189], v[54:57]
	v_mfma_f32_16x16x32_bf16 v[42:45], v[170:173], v[194:197], v[42:45]
	v_mfma_f32_16x16x32_bf16 v[38:41], v[178:181], v[194:197], v[38:41]
	v_mfma_f32_16x16x32_bf16 v[26:29], v[170:173], v[224:227], v[26:29]
	v_mfma_f32_16x16x32_bf16 v[22:25], v[178:181], v[224:227], v[22:25]
	v_mfma_f32_16x16x32_bf16 v[10:13], v[170:173], v[232:235], v[10:13]
	v_mfma_f32_16x16x32_bf16 v[4:7], v[178:181], v[232:235], v[4:7]
	s_setprio 0
	s_barrier
	s_add_i32 s68, 0, 0x18000
	s_add_i32 s69, 0, 0x1c000
	ds_read_b128 v[150:153], v147 offset:32768
	ds_read_b128 v[154:157], v239 offset:32768
	ds_read_b128 v[158:161], v147 offset:34816
	ds_read_b128 v[162:165], v239 offset:34816
	ds_read_b128 v[166:169], v147 offset:49152
	ds_read_b128 v[170:173], v239 offset:49152
	ds_read_b128 v[174:177], v147 offset:51200
	ds_read_b128 v[178:181], v239 offset:51200
	s_add_u32 s50, s50, 0x80000
	s_addc_u32 s51, s51, 0
	s_mov_b32 m0, s54
	ds_read_b128 v[182:185], v148 offset:32768
	ds_read_b128 v[186:189], v238 offset:32768
	ds_read_b128 v[190:193], v148 offset:34816
	ds_read_b128 v[194:197], v238 offset:34816
	ds_read_b128 v[206:209], v148 offset:36864
	ds_read_b128 v[224:227], v238 offset:36864
	ds_read_b128 v[228:231], v148 offset:38912
	ds_read_b128 v[232:235], v238 offset:38912
	s_add_u32 s100, s50, 0xfff80000
	s_addc_u32 s101, s51, -1
	s_mov_b32 m0, s52
	s_nop 0
	global_load_lds_dwordx4 v140, s[100:101]
	s_mov_b32 m0, s53
	s_nop 0
	global_load_lds_dwordx4 v136, s[100:101]
	s_mov_b32 m0, s54
	s_nop 0
	global_load_lds_dwordx4 v140, s[50:51]
	s_mov_b32 m0, s55
	s_nop 0
	global_load_lds_dwordx4 v136, s[50:51]
	s_waitcnt vmcnt(8)
	s_waitcnt lgkmcnt(0)
	s_barrier
; #define PG8_STAGE(bufoff, gbase, voff) do { _Pragma("unroll") for (int _i = 0; _i < 2; ++_i) \
;         __builtin_amdgcn_global_load_lds((const unsigned*)((const char*)(gbase) + (voff)[_i]), (LAS unsigned*)(lds + (bufoff) + ldsw + _i * 8192), 16, 0, 0); } while (0)
; #define PG8_LDA(dst, b, h) do { _Pragma("unroll") for (int m = 0; m < 4; ++m) _Pragma("unroll") for (int k = 0; k < 2; ++k) dst[m][k] = *(const LAS bf16x8*)(lds + PG8_SA(b, h) + aoff + m * 2048 + k * 1024); } while (0)
; #define PG8_LDB(dst, b, h) do { _Pragma("unroll") for (int n = 0; n < 2; ++n) _Pragma("unroll") for (int k = 0; k < 2; ++k) dst[n][k] = *(const LAS bf16x8*)(lds + PG8_SB(b, h) + boff + n * 2048 + k * 1024); } while (0)
; #define PG8_MMA(ai, bj, At, Bt) do { __builtin_amdgcn_s_setprio(1); _Pragma("unroll") for (int m = 0; m < 4; ++m) _Pragma("unroll") for (int n = 0; n < 2; ++n) _Pragma("unroll") for (int k = 0; k < 2; ++k) \
;         acc[ai][bj][m][n] = __builtin_amdgcn_mfma_f32_16x16x32_bf16(Bt[n][k], At[m][k], acc[ai][bj][m][n], 0, 0, 0); __builtin_amdgcn_s_setprio(0); } while (0)
; #define PG8_WAIT_V(n) asm volatile("s_waitcnt vmcnt(" #n ")" ::: "memory")
; #define PG8_WAIT_L(n) asm volatile("s_waitcnt lgkmcnt(" #n ")" ::: "memory")
; #define PG8_BAR __builtin_amdgcn_s_barrier()
; #define PG8_SCHED __builtin_amdgcn_sched_barrier(0)
; template <class Epi, bool ALIGN_EPI = true>
; __device__ __forceinline__ void gemm_phase(LAS unsigned char* lds, const Gemm g, const Sched& S, const Epi& E) {
;     ...
;             PG8_LDB(B0, 1, 0); PG8_LDB(B1, 1, 1); PG8_SCHED; PG8_LDA(At, 1, 0); PG8_STAGE(PG8_SA(0, 1), a2 + hstepA, voffA);
;             PG8_WAIT_V(8); PG8_WAIT_L(0); PG8_BAR; PG8_MMA(0, 0, At, B0); PG8_MMA(0, 1, At, B1); PG8_BAR; PG8_SCHED;
;             PG8_LDA(At, 1, 1); PG8_STAGE(PG8_SB(1, 0), b3, voffB); PG8_STAGE(PG8_SB(1, 1), b3 + hstepB, voffB); PG8_STAGE(PG8_SA(1, 0), a3, voffA);
;             PG8_WAIT_V(8); PG8_WAIT_L(0); PG8_BAR; PG8_MMA(1, 0, At, B0); PG8_MMA(1, 1, At, B1); PG8_BAR; PG8_SCHED;
;         }
	s_setprio 1
	s_waitcnt lgkmcnt(0)
	v_mfma_f32_16x16x32_bf16 v[130:133], v[150:153], v[182:185], v[130:133]
	v_mfma_f32_16x16x32_bf16 v[126:129], v[158:161], v[182:185], v[126:129]
	v_mfma_f32_16x16x32_bf16 v[114:117], v[150:153], v[190:193], v[114:117]
	v_mfma_f32_16x16x32_bf16 v[110:113], v[158:161], v[190:193], v[110:113]
	v_mfma_f32_16x16x32_bf16 v[98:101], v[150:153], v[206:209], v[98:101]
	v_mfma_f32_16x16x32_bf16 v[94:97], v[158:161], v[206:209], v[94:97]
	v_mfma_f32_16x16x32_bf16 v[82:85], v[150:153], v[228:231], v[82:85]
	v_mfma_f32_16x16x32_bf16 v[78:81], v[158:161], v[228:231], v[78:81]
	v_mfma_f32_16x16x32_bf16 v[130:133], v[154:157], v[186:189], v[130:133]
	v_mfma_f32_16x16x32_bf16 v[126:129], v[162:165], v[186:189], v[126:129]
	v_mfma_f32_16x16x32_bf16 v[114:117], v[154:157], v[194:197], v[114:117]
	v_mfma_f32_16x16x32_bf16 v[110:113], v[162:165], v[194:197], v[110:113]
	v_mfma_f32_16x16x32_bf16 v[98:101], v[154:157], v[224:227], v[98:101]
	v_mfma_f32_16x16x32_bf16 v[94:97], v[162:165], v[224:227], v[94:97]
	v_mfma_f32_16x16x32_bf16 v[82:85], v[154:157], v[232:235], v[82:85]
	v_mfma_f32_16x16x32_bf16 v[78:81], v[162:165], v[232:235], v[78:81]
	s_setprio 0
	s_setprio 1
	v_mfma_f32_16x16x32_bf16 v[122:125], v[166:169], v[182:185], v[122:125]
	v_mfma_f32_16x16x32_bf16 v[118:121], v[174:177], v[182:185], v[118:121]
	v_mfma_f32_16x16x32_bf16 v[106:109], v[166:169], v[190:193], v[106:109]
	v_mfma_f32_16x16x32_bf16 v[102:105], v[174:177], v[190:193], v[102:105]
	v_mfma_f32_16x16x32_bf16 v[90:93], v[166:169], v[206:209], v[90:93]
	v_mfma_f32_16x16x32_bf16 v[86:89], v[174:177], v[206:209], v[86:89]
	v_mfma_f32_16x16x32_bf16 v[74:77], v[166:169], v[228:231], v[74:77]
	v_mfma_f32_16x16x32_bf16 v[70:73], v[174:177], v[228:231], v[70:73]
	v_mfma_f32_16x16x32_bf16 v[122:125], v[170:173], v[186:189], v[122:125]
	v_mfma_f32_16x16x32_bf16 v[118:121], v[178:181], v[186:189], v[118:121]
	v_mfma_f32_16x16x32_bf16 v[106:109], v[170:173], v[194:197], v[106:109]
	v_mfma_f32_16x16x32_bf16 v[102:105], v[178:181], v[194:197], v[102:105]
	v_mfma_f32_16x16x32_bf16 v[90:93], v[170:173], v[224:227], v[90:93]
	v_mfma_f32_16x16x32_bf16 v[86:89], v[178:181], v[224:227], v[86:89]
	v_mfma_f32_16x16x32_bf16 v[74:77], v[170:173], v[232:235], v[74:77]
	v_mfma_f32_16x16x32_bf16 v[70:73], v[178:181], v[232:235], v[70:73]
	s_setprio 0
	s_barrier
	s_add_u32 s100, s48, 0x80
	s_addc_u32 s101, s49, 0
	s_add_i32 s50, s68, s37
	s_mov_b32 m0, s50
	ds_read_b128 v[182:185], v148 offset:49152
	ds_read_b128 v[186:189], v238 offset:49152
	ds_read_b128 v[190:193], v148 offset:51200
	ds_read_b128 v[194:197], v238 offset:51200
	ds_read_b128 v[206:209], v148 offset:53248
	ds_read_b128 v[224:227], v238 offset:53248
	ds_read_b128 v[228:231], v148 offset:55296
	ds_read_b128 v[232:235], v238 offset:55296
	global_load_lds_dwordx4 v138, s[100:101]
	s_add_i32 m0, s50, 0x2000
	s_add_u32 s48, s48, 0x80080
	s_addc_u32 s49, s49, 0
	s_add_i32 s50, s69, s37
	global_load_lds_dwordx4 v134, s[100:101]
	s_mov_b32 m0, s50
	s_nop 0
	global_load_lds_dwordx4 v138, s[48:49]
	s_add_i32 m0, s50, 0x2000
	s_nop 0
	global_load_lds_dwordx4 v134, s[48:49]
	s_waitcnt vmcnt(6)
	s_waitcnt lgkmcnt(0)
	s_barrier
	s_setprio 1
	s_waitcnt lgkmcnt(0)
	v_mfma_f32_16x16x32_bf16 v[66:69], v[150:153], v[182:185], v[66:69]
	v_mfma_f32_16x16x32_bf16 v[62:65], v[158:161], v[182:185], v[62:65]
	v_mfma_f32_16x16x32_bf16 v[50:53], v[150:153], v[190:193], v[50:53]
	v_mfma_f32_16x16x32_bf16 v[46:49], v[158:161], v[190:193], v[46:49]
	v_mfma_f32_16x16x32_bf16 v[34:37], v[150:153], v[206:209], v[34:37]
	v_mfma_f32_16x16x32_bf16 v[30:33], v[158:161], v[206:209], v[30:33]
	v_mfma_f32_16x16x32_bf16 v[18:21], v[150:153], v[228:231], v[18:21]
	v_mfma_f32_16x16x32_bf16 v[14:17], v[158:161], v[228:231], v[14:17]
	v_mfma_f32_16x16x32_bf16 v[66:69], v[154:157], v[186:189], v[66:69]
	v_mfma_f32_16x16x32_bf16 v[62:65], v[162:165], v[186:189], v[62:65]
	v_mfma_f32_16x16x32_bf16 v[50:53], v[154:157], v[194:197], v[50:53]
	v_mfma_f32_16x16x32_bf16 v[46:49], v[162:165], v[194:197], v[46:49]
	v_mfma_f32_16x16x32_bf16 v[34:37], v[154:157], v[224:227], v[34:37]
	v_mfma_f32_16x16x32_bf16 v[30:33], v[162:165], v[224:227], v[30:33]
	v_mfma_f32_16x16x32_bf16 v[18:21], v[154:157], v[232:235], v[18:21]
	v_mfma_f32_16x16x32_bf16 v[14:17], v[162:165], v[232:235], v[14:17]
	s_setprio 0
	s_setprio 1
	v_mfma_f32_16x16x32_bf16 v[58:61], v[166:169], v[182:185], v[58:61]
	v_mfma_f32_16x16x32_bf16 v[54:57], v[174:177], v[182:185], v[54:57]
	v_mfma_f32_16x16x32_bf16 v[42:45], v[166:169], v[190:193], v[42:45]
	v_mfma_f32_16x16x32_bf16 v[38:41], v[174:177], v[190:193], v[38:41]
	v_mfma_f32_16x16x32_bf16 v[26:29], v[166:169], v[206:209], v[26:29]
	v_mfma_f32_16x16x32_bf16 v[22:25], v[174:177], v[206:209], v[22:25]
	v_mfma_f32_16x16x32_bf16 v[8:11], v[166:169], v[228:231], v[10:13]
	v_mfma_f32_16x16x32_bf16 v[4:7], v[174:177], v[228:231], v[4:7]
	v_mfma_f32_16x16x32_bf16 v[58:61], v[170:173], v[186:189], v[58:61]
	v_mfma_f32_16x16x32_bf16 v[54:57], v[178:181], v[186:189], v[54:57]
	v_mfma_f32_16x16x32_bf16 v[42:45], v[170:173], v[194:197], v[42:45]
	v_mfma_f32_16x16x32_bf16 v[38:41], v[178:181], v[194:197], v[38:41]
	v_mfma_f32_16x16x32_bf16 v[26:29], v[170:173], v[224:227], v[26:29]
	v_mfma_f32_16x16x32_bf16 v[22:25], v[178:181], v[224:227], v[22:25]
	v_mfma_f32_16x16x32_bf16 v[10:13], v[170:173], v[232:235], v[8:11]
	v_mfma_f32_16x16x32_bf16 v[6:9], v[178:181], v[232:235], v[4:7]
	s_setprio 0
	s_barrier
	s_add_u32 s46, s46, 0x100
	s_addc_u32 s47, s47, 0
	s_add_u32 s65, s65, 0x100
	s_addc_u32 s66, s66, 0
	s_cmp_ge_i32 s67, s56
	s_mov_b32 s48, s67
	s_cbranch_scc0 .LBB0_1311

; #define LAS __attribute__((address_space(3)))
; template <class Epi, bool ALIGN_EPI = true>
; __device__ __forceinline__ void gemm_phase(LAS unsigned char* lds, const Gemm g, const Sched& S, const Epi& E) {
;     int tid = threadIdx.x; asm volatile("" : "+v"(tid));
;     const int wid = __builtin_amdgcn_readfirstlane(tid >> 6), lane = tid & 63, wr = wid >> 2, wc = wid & 3, fr = lane & 15, fq = lane >> 4;
;     int K = g.K; asm volatile("" : "+s"(K));
;     const int nt = K / BK;
;     unsigned voffA[2], voffB[2];
; #pragma unroll
;     for (int i = 0; i < 2; ++i) { int R, C; stage_rc(tid * 16 + i * 8192, R, C); const int Rb = (R & ~31) + perm32(R & 31);
;         voffA[i] = (unsigned)(R * g.lda + C) * 2u; voffB[i] = (unsigned)(Rb * g.ldb + C) * 2u; }
;     const size_t kstep = (size_t)(BK * 2);
;     const size_t hstepA = (size_t)HALF * g.lda * 2, hstepB = (size_t)HALF * g.ldb * 2;
;     const unsigned ldsw = (unsigned)wid * 1024u;
;     const int aoff = lds_byte(wr * 64 + fr, fq * 8), boff = lds_byte(wc * 32 + fr, fq * 8);
.LBB0_1387:
	s_andn2_b64 vcc, exec, s[0:1]
	s_cbranch_vccnz .LBB0_1912
	v_readlane_b32 s18, v244, 31
	s_mov_b64 s[6:7], 0x26000000
	s_mov_b64 s[14:15], 0x41800000
	s_mov_b64 s[0:1], 0x39000000
	s_mov_b64 s[4:5], 0x120000
	v_mov_b32_e32 v146, v0
	v_readlane_b32 s19, v244, 32
	s_movk_i32 s16, 0x800
	v_readfirstlane_b32 s34, v146
	s_andn2_b64 vcc, exec, s[18:19]
	s_cbranch_vccnz .LBB0_1440
	s_waitcnt vmcnt(0) lgkmcnt(0)
	v_lshlrev_b32_e32 v4, 4, v146
	v_add_u32_e32 v5, 0x2000, v4
	v_ashrrev_i32_e32 v2, 31, v5
	v_lshrrev_b32_e32 v2, 22, v2
	v_add_u32_e32 v2, v5, v2
	v_ashrrev_i32_e32 v2, 10, v2
	v_mul_i32_i24_e32 v6, 0x400, v2
	v_sub_u32_e32 v5, v5, v6
	v_lshrrev_b32_e32 v6, 4, v5
	v_bitop3_b32 v5, v6, v5, 32 bitop3:0x6c
	v_ashrrev_i32_e32 v6, 31, v5
	s_add_u32 s35, s54, s6
	v_lshrrev_b32_e32 v6, 26, v6
	s_addc_u32 s36, s55, s7
	v_readlane_b32 s6, v242, 25
	v_add_u32_e32 v6, v5, v6
	v_lshlrev_b32_e32 v7, 3, v2
	s_add_u32 s14, s54, s14
	v_readlane_b32 s7, v242, 26
	v_ashrrev_i32_e32 v12, 6, v6
	v_and_b32_e32 v7, -16, v7
	s_addc_u32 s15, s55, s15
	s_lshl_b64 s[6:7], s[6:7], 24
	v_add_u32_e32 v7, v12, v7
	s_add_u32 s37, s14, s6
	v_and_b32_e32 v8, 3, v12
	s_mov_b32 s6, 0xfffe0
	v_lshrrev_b32_e32 v9, 2, v7
	v_lshlrev_b32_e32 v10, 1, v7
	v_and_b32_e32 v6, 0xc0, v6
	v_and_or_b32 v8, v7, s6, v8
	v_and_b32_e32 v9, 4, v9
	v_and_b32_e32 v10, 24, v10
	v_sub_u32_e32 v5, v5, v6
	v_or3_b32 v8, v8, v9, v10
	v_lshlrev_b32_e32 v9, 5, v2
	v_ashrrev_i16_sdwa v5, v213, sext(v5) dst_sel:DWORD dst_unused:UNUSED_PAD src0_sel:DWORD src1_sel:BYTE_0
	v_and_b32_e32 v9, 32, v9
	v_bfe_i32 v13, v5, 0, 16
	v_add_lshl_u32 v5, v9, v13, 1
	v_lshl_add_u32 v134, v8, 12, v5
	v_lshrrev_b32_e32 v247, 3, v0
	v_xor_b32_e32 v247, v247, v0
	v_and_b32_e32 v247, 7, v247
	v_lshl_add_u32 v134, v247, 4, v134
	v_and_b32_e32 v247, 64, v0
	v_sub_u32_e32 v134, v134, v247
	v_lshrrev_b32_e32 v247, 4, v0
	v_and_b32_e32 v247, 2, v247
	v_xor_b32_e32 v247, v247, v0
	v_and_b32_e32 v247, 3, v247
	v_lshlrev_b32_e32 v247, 4, v247
	v_sub_u32_e32 v134, v134, v247
	v_and_b32_e32 v247, 64, v0
	v_mul_u32_u24_e32 v247, 0x400, v247
	v_add_u32_e32 v134, v134, v247
	v_and_b32_e32 v247, 32, v0
	v_mul_u32_u24_e32 v247, 0x400, v247
	v_sub_u32_e32 v134, v134, v247
	v_and_b32_e32 v247, 16, v0
	v_mul_u32_u24_e32 v247, 0x600, v247
	v_sub_u32_e32 v134, v134, v247
	v_and_b32_e32 v247, 8, v0
	v_mul_u32_u24_e32 v247, 0x200, v247
	v_sub_u32_e32 v134, v134, v247
	v_and_b32_e32 v247, 4, v0
	v_mul_u32_u24_e32 v247, 0x400, v247
	v_sub_u32_e32 v134, v134, v247
	v_lshl_add_u32 v136, v7, 12, v5
	v_lshrrev_b32_e32 v247, 3, v0
	v_xor_b32_e32 v247, v247, v0
	v_and_b32_e32 v247, 7, v247
	v_lshl_add_u32 v136, v247, 4, v136
	v_and_b32_e32 v247, 64, v0
	v_sub_u32_e32 v136, v136, v247
	v_lshrrev_b32_e32 v247, 4, v0
	v_and_b32_e32 v247, 2, v247
	v_xor_b32_e32 v247, v247, v0
	v_and_b32_e32 v247, 3, v247
	v_lshlrev_b32_e32 v247, 4, v247
	v_sub_u32_e32 v136, v136, v247
	v_bfe_u32 v247, v0, 2, 4
	v_add_u32_e32 v247, 1, v247
	v_lshrrev_b32_e32 v247, 1, v247
	v_mul_u32_u24_e32 v247, 0x1000, v247
	v_sub_u32_e32 v136, v136, v247
	v_and_b32_e32 v247, 64, v0
	v_mul_u32_u24_e32 v247, 0x200, v247
	v_add_u32_e32 v136, v136, v247
	v_bfe_i32 v5, v146, 27, 1
	v_lshrrev_b32_e32 v5, 22, v5
	v_add_u32_e32 v5, v4, v5
	v_and_b32_e32 v5, 0xfffffc00, v5
	v_sub_u32_e32 v4, v4, v5
	v_lshrrev_b32_e32 v5, 4, v4
	v_ashrrev_i32_e32 v6, 31, v146
	v_bitop3_b32 v4, v5, v4, 32 bitop3:0x6c
	v_lshrrev_b32_e32 v6, 26, v6
	v_ashrrev_i32_e32 v5, 31, v4
	v_add_u32_e32 v6, v146, v6
	v_lshrrev_b32_e32 v5, 26, v5
	v_ashrrev_i32_e32 v15, 6, v6
	v_add_u32_e32 v5, v4, v5
	v_lshlrev_b32_e32 v6, 3, v15
	v_ashrrev_i32_e32 v14, 6, v5
	v_and_b32_e32 v6, -16, v6
	s_addc_u32 s50, s15, s7
	s_ashr_i32 s18, s34, 6
	v_add_u32_e32 v6, v14, v6
	v_and_b32_e32 v7, 3, v14
	s_ashr_i32 s17, s34, 8
	s_lshl_b32 s51, s18, 10
	v_and_or_b32 v7, v6, s6, v7
	v_lshrrev_b32_e32 v8, 2, v6
	v_lshlrev_b32_e32 v9, 1, v6
	v_and_b32_e32 v5, 0xc0, v5
	v_readlane_b32 s6, v243, 6
	v_and_b32_e32 v8, 4, v8
	v_and_b32_e32 v9, 24, v9
	v_sub_u32_e32 v4, v4, v5
	v_readlane_b32 s7, v243, 7
	s_add_u32 s6, s37, s6
	v_or3_b32 v7, v7, v8, v9
	v_lshlrev_b32_e32 v8, 5, v15
	v_ashrrev_i16_sdwa v4, v213, sext(v4) dst_sel:DWORD dst_unused:UNUSED_PAD src0_sel:DWORD src1_sel:BYTE_0
	s_addc_u32 s7, s50, s7
	v_readlane_b32 s14, v243, 18
	v_and_b32_e32 v8, 32, v8
	v_bfe_i32 v16, v4, 0, 16
	v_readlane_b32 s15, v243, 19
	s_add_u32 s6, s6, s14
	v_add_lshl_u32 v4, v8, v16, 1
	s_addc_u32 s7, s7, s15
	s_add_i32 s52, s51, 0
	v_lshl_add_u32 v138, v7, 12, v4
	v_lshrrev_b32_e32 v247, 3, v0
	v_xor_b32_e32 v247, v247, v0
	v_and_b32_e32 v247, 7, v247
	v_lshl_add_u32 v138, v247, 4, v138
	v_and_b32_e32 v247, 64, v0
	v_sub_u32_e32 v138, v138, v247
	v_lshrrev_b32_e32 v247, 4, v0
	v_and_b32_e32 v247, 2, v247
	v_xor_b32_e32 v247, v247, v0
	v_and_b32_e32 v247, 3, v247
	v_lshlrev_b32_e32 v247, 4, v247
	v_sub_u32_e32 v138, v138, v247
	v_and_b32_e32 v247, 64, v0
	v_mul_u32_u24_e32 v247, 0x400, v247
	v_add_u32_e32 v138, v138, v247
	v_and_b32_e32 v247, 32, v0
	v_mul_u32_u24_e32 v247, 0x400, v247
	v_sub_u32_e32 v138, v138, v247
	v_and_b32_e32 v247, 16, v0
	v_mul_u32_u24_e32 v247, 0x600, v247
	v_sub_u32_e32 v138, v138, v247
	v_and_b32_e32 v247, 8, v0
	v_mul_u32_u24_e32 v247, 0x200, v247
	v_sub_u32_e32 v138, v138, v247
	v_and_b32_e32 v247, 4, v0
	v_mul_u32_u24_e32 v247, 0x400, v247
	v_sub_u32_e32 v138, v138, v247
	s_add_i32 m0, s52, 0x10000
	v_lshl_add_u32 v140, v6, 12, v4
	v_lshrrev_b32_e32 v247, 3, v0
	v_xor_b32_e32 v247, v247, v0
	v_and_b32_e32 v247, 7, v247
	v_lshl_add_u32 v140, v247, 4, v140
	v_and_b32_e32 v247, 64, v0
	v_sub_u32_e32 v140, v140, v247
; #define PG8_STAGE(bufoff, gbase, voff) do { _Pragma("unroll") for (int _i = 0; _i < 2; ++_i) \
;         __builtin_amdgcn_global_load_lds((const unsigned*)((const char*)(gbase) + (voff)[_i]), (LAS unsigned*)(lds + (bufoff) + ldsw + _i * 8192), 16, 0, 0); } while (0)
; #define PG8_WAIT_V(n) asm volatile("s_waitcnt vmcnt(" #n ")" ::: "memory")
; #define PG8_BAR __builtin_amdgcn_s_barrier()
; template <class Epi, bool ALIGN_EPI = true>
; __device__ __forceinline__ void gemm_phase(LAS unsigned char* lds, const Gemm g, const Sched& S, const Epi& E) {
;     ...
;     const char* cA = (const char*)g.A + cur.aoff; const char* cB = (const char*)g.Bt + cur.boff;
;     PG8_STAGE(PG8_SB(0, 0), cB, voffB); PG8_STAGE(PG8_SB(0, 1), cB + hstepB, voffB); PG8_STAGE(PG8_SA(0, 0), cA, voffA); PG8_STAGE(PG8_SA(0, 1), cA + hstepA, voffA);
;     if (wr == 1) PG8_BAR;
;     PG8_WAIT_V(2); PG8_BAR;
;     PG8_STAGE(PG8_SB(1, 0), cB + kstep, voffB); PG8_STAGE(PG8_SA(1, 0), cA + kstep, voffA); PG8_STAGE(PG8_SB(1, 1), cB + hstepB + kstep, voffB);
	v_lshrrev_b32_e32 v247, 4, v0
	v_and_b32_e32 v247, 2, v247
	v_xor_b32_e32 v247, v247, v0
	v_and_b32_e32 v247, 3, v247
	v_lshlrev_b32_e32 v247, 4, v247
	v_sub_u32_e32 v140, v140, v247
	v_bfe_u32 v247, v0, 2, 4
	v_add_u32_e32 v247, 1, v247
	v_lshrrev_b32_e32 v247, 1, v247
	v_mul_u32_u24_e32 v247, 0x1000, v247
	v_sub_u32_e32 v140, v140, v247
	v_and_b32_e32 v247, 64, v0
	v_mul_u32_u24_e32 v247, 0x200, v247
	v_add_u32_e32 v140, v140, v247
	global_load_lds_dwordx4 v138, s[6:7]
	s_add_i32 m0, s52, 0x12000
	s_add_u32 s14, s6, 0x80000
	global_load_lds_dwordx4 v134, s[6:7]
	s_addc_u32 s15, s7, 0
	s_add_i32 m0, s52, 0x14000
	v_mov_b32_e32 v139, v3
	global_load_lds_dwordx4 v138, s[14:15]
	s_add_i32 m0, s52, 0x16000
	v_mov_b32_e32 v135, v3
	global_load_lds_dwordx4 v134, s[14:15]
	v_readlane_b32 s14, v243, 14
	v_readlane_b32 s15, v243, 15
	s_add_u32 s14, s35, s14
	s_addc_u32 s15, s36, s15
	s_add_i32 s53, s52, 0x2000
	s_mov_b32 m0, s52
	s_add_u32 s20, s14, 0x80000
	global_load_lds_dwordx4 v140, s[14:15]
	s_mov_b32 m0, s53
	s_addc_u32 s21, s15, 0
	s_add_i32 s54, s52, 0x4000
	global_load_lds_dwordx4 v136, s[14:15]
	s_mov_b32 m0, s54
	s_add_i32 s55, s52, 0x6000
	global_load_lds_dwordx4 v140, s[20:21]
	s_mov_b32 m0, s55
	v_mov_b32_e32 v141, v3
	global_load_lds_dwordx4 v136, s[20:21]
	v_mov_b32_e32 v137, v3
	v_lshl_add_u64 v[10:11], s[6:7], 0, v[138:139]
	v_lshl_add_u64 v[8:9], s[6:7], 0, v[134:135]
	v_lshl_add_u64 v[6:7], s[14:15], 0, v[140:141]
	s_cmp_lg_u32 s17, 1
	v_lshl_add_u64 v[4:5], s[14:15], 0, v[136:137]
	s_cbranch_scc1 .LBB0_1391
	s_barrier
; #define PG8_STAGE(bufoff, gbase, voff) do { _Pragma("unroll") for (int _i = 0; _i < 2; ++_i) \
;         __builtin_amdgcn_global_load_lds((const unsigned*)((const char*)(gbase) + (voff)[_i]), (LAS unsigned*)(lds + (bufoff) + ldsw + _i * 8192), 16, 0, 0); } while (0)
; #define PG8_WAIT_V(n) asm volatile("s_waitcnt vmcnt(" #n ")" ::: "memory")
; #define PG8_BAR __builtin_amdgcn_s_barrier()
; template <class Epi, bool ALIGN_EPI = true>
; __device__ __forceinline__ void gemm_phase(LAS unsigned char* lds, const Gemm g, const Sched& S, const Epi& E) {
;     ...
;     f32x4 acc[2][2][4][2];
; #pragma unroll
;     for (int a = 0; a < 2; ++a)
; #pragma unroll
;         for (int b = 0; b < 2; ++b)
; #pragma unroll
;             for (int m = 0; m < 4; ++m)
; #pragma unroll
;                 for (int n = 0; n < 2; ++n) acc[a][b][m][n] = (f32x4){0.f, 0.f, 0.f, 0.f};
;     bf16x8 At[4][2], B0[2][2], B1[2][2];
;     const char* cA = (const char*)g.A + cur.aoff; const char* cB = (const char*)g.Bt + cur.boff;
;     PG8_STAGE(PG8_SB(0, 0), cB, voffB); PG8_STAGE(PG8_SB(0, 1), cB + hstepB, voffB); PG8_STAGE(PG8_SA(0, 0), cA, voffA); PG8_STAGE(PG8_SA(0, 1), cA + hstepA, voffA);
;     if (wr == 1) PG8_BAR;
;     PG8_WAIT_V(2); PG8_BAR;
;     PG8_STAGE(PG8_SB(1, 0), cB + kstep, voffB); PG8_STAGE(PG8_SA(1, 0), cA + kstep, voffA); PG8_STAGE(PG8_SB(1, 1), cB + hstepB + kstep, voffB);
;     PG8_WAIT_V(6); PG8_BAR;
.LBB0_1391:
	s_and_b32 s30, s18, 3
	s_ashr_i32 s18, s16, 31
	s_lshr_b32 s18, s18, 26
	s_add_i32 s18, s16, s18
	s_add_i32 m0, s52, 0x18000
	v_lshl_add_u64 v[10:11], v[10:11], 0, s[8:9]
	s_ashr_i32 s56, s18, 6
	s_lshl_b32 s33, s17, 6
	s_lshl_b32 s17, s17, 13
	s_lshl_b32 s20, s30, 12
	s_waitcnt vmcnt(2)
	s_barrier
	global_load_lds_dwordx4 v[10:11], off
	v_lshl_add_u64 v[8:9], v[8:9], 0, s[8:9]
	s_add_i32 m0, s52, 0x1a000
	s_add_i32 s57, s52, 0x8000
	s_add_i32 s58, s52, 0xa000
	global_load_lds_dwordx4 v[8:9], off
	v_lshl_add_u64 v[6:7], v[6:7], 0, s[8:9]
	s_mov_b32 m0, s57
	s_add_u32 s18, s6, 0x80080
	global_load_lds_dwordx4 v[6:7], off
	v_lshl_add_u64 v[4:5], v[4:5], 0, s[8:9]
	s_mov_b32 m0, s58
	s_addc_u32 s19, s7, 0
	global_load_lds_dwordx4 v[4:5], off
	s_add_i32 m0, s52, 0x1c000
	v_lshl_add_u64 v[4:5], s[18:19], 0, v[138:139]
	global_load_lds_dwordx4 v[4:5], off
	v_lshl_add_u64 v[4:5], s[18:19], 0, v[134:135]
	s_add_i32 m0, s52, 0x1e000
	s_movk_i32 s10, 0x3c0
	global_load_lds_dwordx4 v[4:5], off
	v_and_b32_e32 v4, 48, v146
	v_lshlrev_b32_e32 v5, 6, v146
	v_and_or_b32 v4, v5, s10, v4
	v_lshlrev_b32_e32 v5, 2, v146
	v_and_b32_e32 v5, 32, v5
	v_bitop3_b32 v6, v4, s17, v5 bitop3:0xde
	v_bitop3_b32 v147, v4, s20, v5 bitop3:0xde
	v_bfe_u32 v147, v0, 4, 2
	v_xor_b32_e32 v147, v147, v0
	v_and_b32_e32 v147, 7, v147
	v_lshlrev_b32_e32 v147, 4, v147
	v_and_b32_e32 v247, 15, v0
	v_lshl_or_b32 v147, v247, 7, v147
	v_and_b32_e32 v247, 0xc0, v0
	v_lshl_or_b32 v147, v247, 6, v147
	v_or_b32_e32 v147, 0x10000, v147
	v_lshlrev_b32_e32 v4, 15, v15
	v_and_b32_e32 v4, 0xffff0000, v4
	v_lshl_add_u32 v4, v14, 12, v4
	v_and_b32_e32 v5, 1, v15
	v_lshl_or_b32 v4, v5, 6, v4
	v_lshl_add_u32 v142, v16, 1, v4
	v_lshrrev_b32_e32 v247, 3, v0
	v_xor_b32_e32 v247, v247, v0
	v_and_b32_e32 v247, 7, v247
	v_lshl_add_u32 v142, v247, 4, v142
	v_and_b32_e32 v247, 64, v0
	v_sub_u32_e32 v142, v142, v247
	v_lshrrev_b32_e32 v247, 4, v0
	v_and_b32_e32 v247, 2, v247
	v_xor_b32_e32 v247, v247, v0
	v_and_b32_e32 v247, 3, v247
	v_lshlrev_b32_e32 v247, 4, v247
	v_sub_u32_e32 v142, v142, v247
	v_bfe_u32 v247, v0, 2, 4
	v_add_u32_e32 v247, 1, v247
	v_lshrrev_b32_e32 v247, 1, v247
	v_mul_u32_u24_e32 v247, 0x1000, v247
	v_sub_u32_e32 v142, v142, v247
	v_and_b32_e32 v247, 64, v0
	v_mul_u32_u24_e32 v247, 0x200, v247
	v_add_u32_e32 v142, v142, v247
	v_lshlrev_b32_e32 v4, 15, v2
	v_and_b32_e32 v4, 0xffff0000, v4
	v_lshl_add_u32 v4, v12, 12, v4
	v_and_b32_e32 v2, 1, v2
	v_readlane_b32 s18, v243, 16
	s_waitcnt vmcnt(6)
	v_lshl_or_b32 v2, v2, 6, v4
	v_mov_b32_e32 v4, v3
	v_mov_b32_e32 v5, v3
	v_readlane_b32 s19, v243, 17
	s_cmp_gt_i32 s16, 63
	v_lshl_add_u32 v144, v13, 1, v2
	v_lshrrev_b32_e32 v247, 3, v0
	v_xor_b32_e32 v247, v247, v0
	v_and_b32_e32 v247, 7, v247
	v_lshl_add_u32 v144, v247, 4, v144
	v_and_b32_e32 v247, 64, v0
	v_sub_u32_e32 v144, v144, v247
	v_lshrrev_b32_e32 v247, 4, v0
	v_and_b32_e32 v247, 2, v247
	v_xor_b32_e32 v247, v247, v0
	v_and_b32_e32 v247, 3, v247
	v_lshlrev_b32_e32 v247, 4, v247
	v_sub_u32_e32 v144, v144, v247
	v_bfe_u32 v247, v0, 2, 4
	v_add_u32_e32 v247, 1, v247
	v_lshrrev_b32_e32 v247, 1, v247
	v_mul_u32_u24_e32 v247, 0x1000, v247
	v_sub_u32_e32 v144, v144, v247
	v_and_b32_e32 v247, 64, v0
	v_mul_u32_u24_e32 v247, 0x200, v247
	v_add_u32_e32 v144, v144, v247
	v_mov_b32_e32 v2, v3
	v_add_u32_e32 v148, 0, v6
	v_bfe_u32 v148, v0, 4, 2
	v_xor_b32_e32 v148, v148, v0
	v_and_b32_e32 v148, 7, v148
	v_lshlrev_b32_e32 v148, 4, v148
	v_and_b32_e32 v247, 15, v0
	v_lshl_or_b32 v148, v247, 7, v148
	v_and_b32_e32 v247, 0x100, v0
	v_lshl_or_b32 v148, v247, 5, v148
	v_mov_b64_e32 v[8:9], v[4:5]
	v_mov_b64_e32 v[12:13], v[4:5]
	v_mov_b64_e32 v[24:25], v[4:5]
	v_mov_b64_e32 v[28:29], v[4:5]
	v_mov_b64_e32 v[40:41], v[4:5]
	v_mov_b64_e32 v[44:45], v[4:5]
	v_mov_b64_e32 v[56:57], v[4:5]
	v_mov_b64_e32 v[60:61], v[4:5]
	v_mov_b64_e32 v[16:17], v[4:5]
	v_mov_b64_e32 v[20:21], v[4:5]
	v_mov_b64_e32 v[32:33], v[4:5]
	v_mov_b64_e32 v[36:37], v[4:5]
	v_mov_b64_e32 v[48:49], v[4:5]
	v_mov_b64_e32 v[52:53], v[4:5]
	v_mov_b64_e32 v[64:65], v[4:5]
	v_mov_b64_e32 v[68:69], v[4:5]
	v_mov_b64_e32 v[72:73], v[4:5]
	v_mov_b64_e32 v[76:77], v[4:5]
	v_mov_b64_e32 v[88:89], v[4:5]
	v_mov_b64_e32 v[92:93], v[4:5]
	v_mov_b64_e32 v[104:105], v[4:5]
	v_mov_b64_e32 v[108:109], v[4:5]
	v_mov_b64_e32 v[120:121], v[4:5]
	v_mov_b64_e32 v[124:125], v[4:5]
	v_mov_b64_e32 v[80:81], v[4:5]
	v_mov_b64_e32 v[84:85], v[4:5]
	v_mov_b64_e32 v[96:97], v[4:5]
	v_mov_b64_e32 v[100:101], v[4:5]
	v_mov_b64_e32 v[112:113], v[4:5]
	v_mov_b64_e32 v[116:117], v[4:5]
	v_mov_b64_e32 v[128:129], v[4:5]
	v_mov_b64_e32 v[132:133], v[4:5]
	s_mov_b32 s31, s18
	v_readlane_b32 s18, v243, 12
	s_cselect_b64 s[16:17], -1, 0
	s_add_i32 s59, s56, -2
	v_mov_b32_e32 v143, v3
	v_mov_b32_e32 v145, v3
	s_mov_b32 s60, 0
	v_mov_b64_e32 v[6:7], v[2:3]
	v_mov_b64_e32 v[10:11], v[2:3]
	v_mov_b64_e32 v[22:23], v[2:3]
	v_mov_b64_e32 v[26:27], v[2:3]
	v_mov_b64_e32 v[38:39], v[2:3]
	v_mov_b64_e32 v[42:43], v[2:3]
	v_mov_b64_e32 v[54:55], v[2:3]
	v_mov_b64_e32 v[58:59], v[2:3]
	v_mov_b64_e32 v[14:15], v[2:3]
	v_mov_b64_e32 v[18:19], v[2:3]
	v_mov_b64_e32 v[30:31], v[2:3]
	v_mov_b64_e32 v[34:35], v[2:3]
	v_mov_b64_e32 v[46:47], v[2:3]
	v_mov_b64_e32 v[50:51], v[2:3]
	v_mov_b64_e32 v[62:63], v[2:3]
	v_mov_b64_e32 v[66:67], v[2:3]
	v_mov_b64_e32 v[70:71], v[2:3]
	v_mov_b64_e32 v[74:75], v[2:3]
	v_mov_b64_e32 v[86:87], v[2:3]
	v_mov_b64_e32 v[90:91], v[2:3]
	v_mov_b64_e32 v[102:103], v[2:3]
	v_mov_b64_e32 v[106:107], v[2:3]
	v_mov_b64_e32 v[118:119], v[2:3]
	v_mov_b64_e32 v[122:123], v[2:3]
	v_mov_b64_e32 v[78:79], v[2:3]
	v_mov_b64_e32 v[82:83], v[2:3]
	v_mov_b64_e32 v[94:95], v[2:3]
	v_mov_b64_e32 v[98:99], v[2:3]
	v_mov_b64_e32 v[110:111], v[2:3]
	v_mov_b64_e32 v[114:115], v[2:3]
	v_mov_b64_e32 v[126:127], v[2:3]
	v_mov_b64_e32 v[130:131], v[2:3]
	s_mov_b32 s61, s18
	s_barrier
	v_readlane_b32 s19, v243, 13
	s_branch .LBB0_1393

; #define PG8_STAGE(bufoff, gbase, voff) do { _Pragma("unroll") for (int _i = 0; _i < 2; ++_i) \
;         __builtin_amdgcn_global_load_lds((const unsigned*)((const char*)(gbase) + (voff)[_i]), (LAS unsigned*)(lds + (bufoff) + ldsw + _i * 8192), 16, 0, 0); } while (0)
; #define PG8_LDA(dst, b, h) do { _Pragma("unroll") for (int m = 0; m < 4; ++m) _Pragma("unroll") for (int k = 0; k < 2; ++k) dst[m][k] = *(const LAS bf16x8*)(lds + PG8_SA(b, h) + aoff + m * 2048 + k * 1024); } while (0)
; #define PG8_LDB(dst, b, h) do { _Pragma("unroll") for (int n = 0; n < 2; ++n) _Pragma("unroll") for (int k = 0; k < 2; ++k) dst[n][k] = *(const LAS bf16x8*)(lds + PG8_SB(b, h) + boff + n * 2048 + k * 1024); } while (0)
; #define PG8_MMA(ai, bj, At, Bt) do { __builtin_amdgcn_s_setprio(1); _Pragma("unroll") for (int m = 0; m < 4; ++m) _Pragma("unroll") for (int n = 0; n < 2; ++n) _Pragma("unroll") for (int k = 0; k < 2; ++k) \
;         acc[ai][bj][m][n] = __builtin_amdgcn_mfma_f32_16x16x32_bf16(Bt[n][k], At[m][k], acc[ai][bj][m][n], 0, 0, 0); __builtin_amdgcn_s_setprio(0); } while (0)
; template <class Epi, bool ALIGN_EPI = true>
; __device__ __forceinline__ void gemm_phase(LAS unsigned char* lds, const Gemm g, const Sched& S, const Epi& E) {
;     ...
;         for (int t = t_lo; t < t_hi; t += 2) {
;             const bool last = (t == nt - 2);
;             const char* a1 = cA + (size_t)(t + 1) * kstep;
;             const char* a2 = last ? nA : cA + (size_t)(t + 2) * kstep; const char* b2 = last ? nB : cB + (size_t)(t + 2) * kstep;
;             const char* a3 = a2 + kstep; const char* b3 = b2 + kstep;
;             const int rflag = __builtin_amdgcn_readfirstlane(t | (int)(ui == 0));
;             PG8_LDB(B0, 0, 0); PG8_LDB(B1, 0, 1); PG8_SCHED; PG8_LDA(At, 0, 0); PG8_STAGE(PG8_SA(1, 1), a1 + hstepA, voffA);
;             if constexpr (Epi::NSTORES > 0) PG8_WAIT_RELAX(rflag, 8 + Epi::NSTORES); else PG8_WAIT_V(8);
;             PG8_WAIT_L(0); PG8_BAR; PG8_MMA(0, 0, At, B0); PG8_MMA(0, 1, At, B1); PG8_BAR; PG8_SCHED;
;             PG8_LDA(At, 0, 1); PG8_STAGE(PG8_SB(0, 0), b2, voffB); PG8_STAGE(PG8_SB(0, 1), b2 + hstepB, voffB); PG8_STAGE(PG8_SA(0, 0), a2, voffA);
;             if constexpr (Epi::NSTORES > 0) PG8_WAIT_RELAX(rflag, 8 + Epi::NSTORES); else PG8_WAIT_V(8);
;             PG8_WAIT_L(0); PG8_BAR; PG8_MMA(1, 0, At, B0); PG8_MMA(1, 1, At, B1); PG8_BAR; PG8_SCHED;
.LBB0_1400:
	s_add_u32 s26, s35, s22
	s_addc_u32 s27, s36, s23
	s_add_u32 s40, s37, s24
	s_addc_u32 s41, s50, s25
	s_andn2_b64 vcc, exec, s[16:17]
	s_cbranch_vccnz .LBB0_1403
	s_and_b64 s[44:45], s[42:43], exec
	s_cselect_b32 s19, s27, s15
	s_cselect_b32 s21, s26, s14
	s_cselect_b32 s63, s41, s7
	s_cselect_b32 s64, s40, s6
	s_add_u32 s44, s14, 0x80080
	s_addc_u32 s45, s15, 0
	s_add_u32 s65, s6, 0x100
	s_addc_u32 s66, s7, 0
	s_mov_b32 s46, 0
	v_xor_b32_e32 v238, 64, v148
	v_xor_b32_e32 v239, 64, v147
.LBB0_1402:
	s_add_i32 s67, s46, 2
	s_add_u32 s47, s44, 0xfff80080
	s_addc_u32 s48, s45, -1
	s_add_i32 s68, 0, 0x10000
	s_cmp_eq_u32 s59, s46
	s_cselect_b32 s49, s19, s48
	s_cselect_b32 s48, s21, s47
	s_cselect_b32 s47, s63, s66
	s_cselect_b32 s46, s64, s65
	s_add_i32 s70, 0, 0x14000
	ds_read_b128 v[150:153], v147
	ds_read_b128 v[154:157], v239
	ds_read_b128 v[158:161], v147 offset:2048
	ds_read_b128 v[162:165], v239 offset:2048
	ds_read_b128 v[166:169], v147 offset:16384
	ds_read_b128 v[170:173], v239 offset:16384
	ds_read_b128 v[174:177], v147 offset:18432
	ds_read_b128 v[178:181], v239 offset:18432
	s_add_i32 m0, s52, 0xc000
	ds_read_b128 v[182:185], v148
	ds_read_b128 v[186:189], v238
	ds_read_b128 v[190:193], v148 offset:2048
	ds_read_b128 v[194:197], v238 offset:2048
	ds_read_b128 v[206:209], v148 offset:4096
	ds_read_b128 v[224:227], v238 offset:4096
	ds_read_b128 v[228:231], v148 offset:6144
	ds_read_b128 v[232:235], v238 offset:6144
	s_add_u32 s100, s44, 0xfff80000
	s_addc_u32 s101, s45, -1
	s_mov_b32 m0, s57
	s_nop 0
	global_load_lds_dwordx4 v142, s[100:101]
	s_mov_b32 m0, s58
	s_nop 0
	global_load_lds_dwordx4 v144, s[100:101]
	s_add_i32 m0, s52, 0xc000
	s_nop 0
	global_load_lds_dwordx4 v142, s[44:45]
	s_add_i32 m0, s52, 0xe000
	s_nop 0
	global_load_lds_dwordx4 v144, s[44:45]
	s_waitcnt vmcnt(8)
	s_waitcnt lgkmcnt(0)
	s_barrier
	s_setprio 1
	s_waitcnt lgkmcnt(0)
	v_mfma_f32_16x16x32_bf16 v[130:133], v[150:153], v[182:185], v[130:133]
	v_mfma_f32_16x16x32_bf16 v[126:129], v[158:161], v[182:185], v[126:129]
	v_mfma_f32_16x16x32_bf16 v[114:117], v[150:153], v[190:193], v[114:117]
	v_mfma_f32_16x16x32_bf16 v[110:113], v[158:161], v[190:193], v[110:113]
	v_mfma_f32_16x16x32_bf16 v[98:101], v[150:153], v[206:209], v[98:101]
	v_mfma_f32_16x16x32_bf16 v[94:97], v[158:161], v[206:209], v[94:97]
	v_mfma_f32_16x16x32_bf16 v[82:85], v[150:153], v[228:231], v[82:85]
	v_mfma_f32_16x16x32_bf16 v[78:81], v[158:161], v[228:231], v[78:81]
	v_mfma_f32_16x16x32_bf16 v[130:133], v[154:157], v[186:189], v[130:133]
	v_mfma_f32_16x16x32_bf16 v[126:129], v[162:165], v[186:189], v[126:129]
	v_mfma_f32_16x16x32_bf16 v[114:117], v[154:157], v[194:197], v[114:117]
	v_mfma_f32_16x16x32_bf16 v[110:113], v[162:165], v[194:197], v[110:113]
	v_mfma_f32_16x16x32_bf16 v[98:101], v[154:157], v[224:227], v[98:101]
	v_mfma_f32_16x16x32_bf16 v[94:97], v[162:165], v[224:227], v[94:97]
	v_mfma_f32_16x16x32_bf16 v[82:85], v[154:157], v[232:235], v[82:85]
	v_mfma_f32_16x16x32_bf16 v[78:81], v[162:165], v[232:235], v[78:81]
	s_setprio 0
	s_setprio 1
	v_mfma_f32_16x16x32_bf16 v[122:125], v[166:169], v[182:185], v[122:125]
	v_mfma_f32_16x16x32_bf16 v[118:121], v[174:177], v[182:185], v[118:121]
	v_mfma_f32_16x16x32_bf16 v[106:109], v[166:169], v[190:193], v[106:109]
	v_mfma_f32_16x16x32_bf16 v[102:105], v[174:177], v[190:193], v[102:105]
	v_mfma_f32_16x16x32_bf16 v[90:93], v[166:169], v[206:209], v[90:93]
	v_mfma_f32_16x16x32_bf16 v[86:89], v[174:177], v[206:209], v[86:89]
	v_mfma_f32_16x16x32_bf16 v[74:77], v[166:169], v[228:231], v[74:77]
	v_mfma_f32_16x16x32_bf16 v[70:73], v[174:177], v[228:231], v[70:73]
	v_mfma_f32_16x16x32_bf16 v[122:125], v[170:173], v[186:189], v[122:125]
	v_mfma_f32_16x16x32_bf16 v[118:121], v[178:181], v[186:189], v[118:121]
	v_mfma_f32_16x16x32_bf16 v[106:109], v[170:173], v[194:197], v[106:109]
	v_mfma_f32_16x16x32_bf16 v[102:105], v[178:181], v[194:197], v[102:105]
	v_mfma_f32_16x16x32_bf16 v[90:93], v[170:173], v[224:227], v[90:93]
	v_mfma_f32_16x16x32_bf16 v[86:89], v[178:181], v[224:227], v[86:89]
	v_mfma_f32_16x16x32_bf16 v[74:77], v[170:173], v[232:235], v[74:77]
	v_mfma_f32_16x16x32_bf16 v[70:73], v[178:181], v[232:235], v[70:73]
	s_setprio 0
	s_barrier
	s_add_i32 s68, s68, s51
	s_mov_b32 m0, s68
	ds_read_b128 v[182:185], v148 offset:16384
	ds_read_b128 v[186:189], v238 offset:16384
	ds_read_b128 v[190:193], v148 offset:18432
	ds_read_b128 v[194:197], v238 offset:18432
	ds_read_b128 v[206:209], v148 offset:20480
	ds_read_b128 v[224:227], v238 offset:20480
	ds_read_b128 v[228:231], v148 offset:22528
	ds_read_b128 v[232:235], v238 offset:22528
	global_load_lds_dwordx4 v138, s[46:47]
	s_add_i32 m0, s68, 0x2000
	s_add_u32 s68, s46, 0x80000
	s_addc_u32 s69, s47, 0
	s_add_i32 s70, s70, s51
	global_load_lds_dwordx4 v134, s[46:47]
	s_mov_b32 m0, s70
	s_nop 0
	global_load_lds_dwordx4 v138, s[68:69]
	s_add_i32 m0, s70, 0x2000
	s_nop 0
	global_load_lds_dwordx4 v134, s[68:69]
	s_waitcnt vmcnt(6)
	s_waitcnt lgkmcnt(0)
	s_barrier
; #define PG8_STAGE(bufoff, gbase, voff) do { _Pragma("unroll") for (int _i = 0; _i < 2; ++_i) \
;         __builtin_amdgcn_global_load_lds((const unsigned*)((const char*)(gbase) + (voff)[_i]), (LAS unsigned*)(lds + (bufoff) + ldsw + _i * 8192), 16, 0, 0); } while (0)
; #define PG8_LDA(dst, b, h) do { _Pragma("unroll") for (int m = 0; m < 4; ++m) _Pragma("unroll") for (int k = 0; k < 2; ++k) dst[m][k] = *(const LAS bf16x8*)(lds + PG8_SA(b, h) + aoff + m * 2048 + k * 1024); } while (0)
; #define PG8_LDB(dst, b, h) do { _Pragma("unroll") for (int n = 0; n < 2; ++n) _Pragma("unroll") for (int k = 0; k < 2; ++k) dst[n][k] = *(const LAS bf16x8*)(lds + PG8_SB(b, h) + boff + n * 2048 + k * 1024); } while (0)
; #define PG8_MMA(ai, bj, At, Bt) do { __builtin_amdgcn_s_setprio(1); _Pragma("unroll") for (int m = 0; m < 4; ++m) _Pragma("unroll") for (int n = 0; n < 2; ++n) _Pragma("unroll") for (int k = 0; k < 2; ++k) \
;         acc[ai][bj][m][n] = __builtin_amdgcn_mfma_f32_16x16x32_bf16(Bt[n][k], At[m][k], acc[ai][bj][m][n], 0, 0, 0); __builtin_amdgcn_s_setprio(0); } while (0)
; #define PG8_WAIT_V(n) asm volatile("s_waitcnt vmcnt(" #n ")" ::: "memory")
; #define PG8_WAIT_L(n) asm volatile("s_waitcnt lgkmcnt(" #n ")" ::: "memory")
; #define PG8_BAR __builtin_amdgcn_s_barrier()
; #define PG8_WAIT_RELAX(flag, n) asm volatile("s_cmp_eq_u32 %0, 0\n\ts_cbranch_scc1 .Lrw%=\n\ts_waitcnt vmcnt(8)\n.Lrw%=:\n\ts_waitcnt vmcnt(%1)" :: "s"(flag), "n"(n) : "scc", "memory")
; #define PG8_SCHED __builtin_amdgcn_sched_barrier(0)
; template <class Epi, bool ALIGN_EPI = true>
; __device__ __forceinline__ void gemm_phase(LAS unsigned char* lds, const Gemm g, const Sched& S, const Epi& E) {
;     ...
;             PG8_WAIT_L(0); PG8_BAR; PG8_MMA(0, 0, At, B0); PG8_MMA(0, 1, At, B1); PG8_BAR; PG8_SCHED;
;             PG8_LDA(At, 0, 1); PG8_STAGE(PG8_SB(0, 0), b2, voffB); PG8_STAGE(PG8_SB(0, 1), b2 + hstepB, voffB); PG8_STAGE(PG8_SA(0, 0), a2, voffA);
;             if constexpr (Epi::NSTORES > 0) PG8_WAIT_RELAX(rflag, 8 + Epi::NSTORES); else PG8_WAIT_V(8);
;             PG8_WAIT_L(0); PG8_BAR; PG8_MMA(1, 0, At, B0); PG8_MMA(1, 1, At, B1); PG8_BAR; PG8_SCHED;
;             PG8_LDB(B0, 1, 0); PG8_LDB(B1, 1, 1); PG8_SCHED; PG8_LDA(At, 1, 0); PG8_STAGE(PG8_SA(0, 1), a2 + hstepA, voffA);
;             PG8_WAIT_V(8); PG8_WAIT_L(0); PG8_BAR; PG8_MMA(0, 0, At, B0); PG8_MMA(0, 1, At, B1); PG8_BAR; PG8_SCHED;
	s_setprio 1
	s_waitcnt lgkmcnt(0)
	v_mfma_f32_16x16x32_bf16 v[66:69], v[150:153], v[182:185], v[66:69]
	v_mfma_f32_16x16x32_bf16 v[62:65], v[158:161], v[182:185], v[62:65]
	v_mfma_f32_16x16x32_bf16 v[50:53], v[150:153], v[190:193], v[50:53]
	v_mfma_f32_16x16x32_bf16 v[46:49], v[158:161], v[190:193], v[46:49]
	v_mfma_f32_16x16x32_bf16 v[34:37], v[150:153], v[206:209], v[34:37]
	v_mfma_f32_16x16x32_bf16 v[30:33], v[158:161], v[206:209], v[30:33]
	v_mfma_f32_16x16x32_bf16 v[18:21], v[150:153], v[228:231], v[18:21]
	v_mfma_f32_16x16x32_bf16 v[14:17], v[158:161], v[228:231], v[14:17]
	v_mfma_f32_16x16x32_bf16 v[66:69], v[154:157], v[186:189], v[66:69]
	v_mfma_f32_16x16x32_bf16 v[62:65], v[162:165], v[186:189], v[62:65]
	v_mfma_f32_16x16x32_bf16 v[50:53], v[154:157], v[194:197], v[50:53]
	v_mfma_f32_16x16x32_bf16 v[46:49], v[162:165], v[194:197], v[46:49]
	v_mfma_f32_16x16x32_bf16 v[34:37], v[154:157], v[224:227], v[34:37]
	v_mfma_f32_16x16x32_bf16 v[30:33], v[162:165], v[224:227], v[30:33]
	v_mfma_f32_16x16x32_bf16 v[18:21], v[154:157], v[232:235], v[18:21]
	v_mfma_f32_16x16x32_bf16 v[14:17], v[162:165], v[232:235], v[14:17]
	s_setprio 0
	s_setprio 1
	v_mfma_f32_16x16x32_bf16 v[58:61], v[166:169], v[182:185], v[58:61]
	v_mfma_f32_16x16x32_bf16 v[54:57], v[174:177], v[182:185], v[54:57]
	v_mfma_f32_16x16x32_bf16 v[42:45], v[166:169], v[190:193], v[42:45]
	v_mfma_f32_16x16x32_bf16 v[38:41], v[174:177], v[190:193], v[38:41]
	v_mfma_f32_16x16x32_bf16 v[26:29], v[166:169], v[206:209], v[26:29]
	v_mfma_f32_16x16x32_bf16 v[22:25], v[174:177], v[206:209], v[22:25]
	v_mfma_f32_16x16x32_bf16 v[10:13], v[166:169], v[228:231], v[10:13]
	v_mfma_f32_16x16x32_bf16 v[4:7], v[174:177], v[228:231], v[6:9]
	v_mfma_f32_16x16x32_bf16 v[58:61], v[170:173], v[186:189], v[58:61]
	v_mfma_f32_16x16x32_bf16 v[54:57], v[178:181], v[186:189], v[54:57]
	v_mfma_f32_16x16x32_bf16 v[42:45], v[170:173], v[194:197], v[42:45]
	v_mfma_f32_16x16x32_bf16 v[38:41], v[178:181], v[194:197], v[38:41]
	v_mfma_f32_16x16x32_bf16 v[26:29], v[170:173], v[224:227], v[26:29]
	v_mfma_f32_16x16x32_bf16 v[22:25], v[178:181], v[224:227], v[22:25]
	v_mfma_f32_16x16x32_bf16 v[10:13], v[170:173], v[232:235], v[10:13]
	v_mfma_f32_16x16x32_bf16 v[4:7], v[178:181], v[232:235], v[4:7]
	s_setprio 0
	s_barrier
	s_add_i32 s68, 0, 0x18000
	s_add_i32 s69, 0, 0x1c000
	ds_read_b128 v[150:153], v147 offset:32768
	ds_read_b128 v[154:157], v239 offset:32768
	ds_read_b128 v[158:161], v147 offset:34816
	ds_read_b128 v[162:165], v239 offset:34816
	ds_read_b128 v[166:169], v147 offset:49152
	ds_read_b128 v[170:173], v239 offset:49152
	ds_read_b128 v[174:177], v147 offset:51200
	ds_read_b128 v[178:181], v239 offset:51200
	s_add_u32 s48, s48, 0x80000
	s_addc_u32 s49, s49, 0
	s_mov_b32 m0, s54
	ds_read_b128 v[182:185], v148 offset:32768
	ds_read_b128 v[186:189], v238 offset:32768
	ds_read_b128 v[190:193], v148 offset:34816
	ds_read_b128 v[194:197], v238 offset:34816
	ds_read_b128 v[206:209], v148 offset:36864
	ds_read_b128 v[224:227], v238 offset:36864
	ds_read_b128 v[228:231], v148 offset:38912
	ds_read_b128 v[232:235], v238 offset:38912
	s_add_u32 s100, s48, 0xfff80000
	s_addc_u32 s101, s49, -1
	s_mov_b32 m0, s52
	s_nop 0
	global_load_lds_dwordx4 v140, s[100:101]
	s_mov_b32 m0, s53
	s_nop 0
	global_load_lds_dwordx4 v136, s[100:101]
	s_mov_b32 m0, s54
	s_nop 0
	global_load_lds_dwordx4 v140, s[48:49]
	s_mov_b32 m0, s55
	s_nop 0
	global_load_lds_dwordx4 v136, s[48:49]
	s_waitcnt vmcnt(8)
	s_waitcnt lgkmcnt(0)
	s_barrier
; #define PG8_STAGE(bufoff, gbase, voff) do { _Pragma("unroll") for (int _i = 0; _i < 2; ++_i) \
;         __builtin_amdgcn_global_load_lds((const unsigned*)((const char*)(gbase) + (voff)[_i]), (LAS unsigned*)(lds + (bufoff) + ldsw + _i * 8192), 16, 0, 0); } while (0)
; #define PG8_LDA(dst, b, h) do { _Pragma("unroll") for (int m = 0; m < 4; ++m) _Pragma("unroll") for (int k = 0; k < 2; ++k) dst[m][k] = *(const LAS bf16x8*)(lds + PG8_SA(b, h) + aoff + m * 2048 + k * 1024); } while (0)
; #define PG8_LDB(dst, b, h) do { _Pragma("unroll") for (int n = 0; n < 2; ++n) _Pragma("unroll") for (int k = 0; k < 2; ++k) dst[n][k] = *(const LAS bf16x8*)(lds + PG8_SB(b, h) + boff + n * 2048 + k * 1024); } while (0)
; #define PG8_MMA(ai, bj, At, Bt) do { __builtin_amdgcn_s_setprio(1); _Pragma("unroll") for (int m = 0; m < 4; ++m) _Pragma("unroll") for (int n = 0; n < 2; ++n) _Pragma("unroll") for (int k = 0; k < 2; ++k) \
;         acc[ai][bj][m][n] = __builtin_amdgcn_mfma_f32_16x16x32_bf16(Bt[n][k], At[m][k], acc[ai][bj][m][n], 0, 0, 0); __builtin_amdgcn_s_setprio(0); } while (0)
; #define PG8_WAIT_V(n) asm volatile("s_waitcnt vmcnt(" #n ")" ::: "memory")
; #define PG8_WAIT_L(n) asm volatile("s_waitcnt lgkmcnt(" #n ")" ::: "memory")
; #define PG8_BAR __builtin_amdgcn_s_barrier()
; #define PG8_SCHED __builtin_amdgcn_sched_barrier(0)
; template <class Epi, bool ALIGN_EPI = true>
; __device__ __forceinline__ void gemm_phase(LAS unsigned char* lds, const Gemm g, const Sched& S, const Epi& E) {
;     ...
;             PG8_LDB(B0, 1, 0); PG8_LDB(B1, 1, 1); PG8_SCHED; PG8_LDA(At, 1, 0); PG8_STAGE(PG8_SA(0, 1), a2 + hstepA, voffA);
;             PG8_WAIT_V(8); PG8_WAIT_L(0); PG8_BAR; PG8_MMA(0, 0, At, B0); PG8_MMA(0, 1, At, B1); PG8_BAR; PG8_SCHED;
;             PG8_LDA(At, 1, 1); PG8_STAGE(PG8_SB(1, 0), b3, voffB); PG8_STAGE(PG8_SB(1, 1), b3 + hstepB, voffB); PG8_STAGE(PG8_SA(1, 0), a3, voffA);
;             PG8_WAIT_V(8); PG8_WAIT_L(0); PG8_BAR; PG8_MMA(1, 0, At, B0); PG8_MMA(1, 1, At, B1); PG8_BAR; PG8_SCHED;
;         }
	s_setprio 1
	s_waitcnt lgkmcnt(0)
	v_mfma_f32_16x16x32_bf16 v[130:133], v[150:153], v[182:185], v[130:133]
	v_mfma_f32_16x16x32_bf16 v[126:129], v[158:161], v[182:185], v[126:129]
	v_mfma_f32_16x16x32_bf16 v[114:117], v[150:153], v[190:193], v[114:117]
	v_mfma_f32_16x16x32_bf16 v[110:113], v[158:161], v[190:193], v[110:113]
	v_mfma_f32_16x16x32_bf16 v[98:101], v[150:153], v[206:209], v[98:101]
	v_mfma_f32_16x16x32_bf16 v[94:97], v[158:161], v[206:209], v[94:97]
	v_mfma_f32_16x16x32_bf16 v[82:85], v[150:153], v[228:231], v[82:85]
	v_mfma_f32_16x16x32_bf16 v[78:81], v[158:161], v[228:231], v[78:81]
	v_mfma_f32_16x16x32_bf16 v[130:133], v[154:157], v[186:189], v[130:133]
	v_mfma_f32_16x16x32_bf16 v[126:129], v[162:165], v[186:189], v[126:129]
	v_mfma_f32_16x16x32_bf16 v[114:117], v[154:157], v[194:197], v[114:117]
	v_mfma_f32_16x16x32_bf16 v[110:113], v[162:165], v[194:197], v[110:113]
	v_mfma_f32_16x16x32_bf16 v[98:101], v[154:157], v[224:227], v[98:101]
	v_mfma_f32_16x16x32_bf16 v[94:97], v[162:165], v[224:227], v[94:97]
	v_mfma_f32_16x16x32_bf16 v[82:85], v[154:157], v[232:235], v[82:85]
	v_mfma_f32_16x16x32_bf16 v[78:81], v[162:165], v[232:235], v[78:81]
	s_setprio 0
	s_setprio 1
	v_mfma_f32_16x16x32_bf16 v[122:125], v[166:169], v[182:185], v[122:125]
	v_mfma_f32_16x16x32_bf16 v[118:121], v[174:177], v[182:185], v[118:121]
	v_mfma_f32_16x16x32_bf16 v[106:109], v[166:169], v[190:193], v[106:109]
	v_mfma_f32_16x16x32_bf16 v[102:105], v[174:177], v[190:193], v[102:105]
	v_mfma_f32_16x16x32_bf16 v[90:93], v[166:169], v[206:209], v[90:93]
	v_mfma_f32_16x16x32_bf16 v[86:89], v[174:177], v[206:209], v[86:89]
	v_mfma_f32_16x16x32_bf16 v[74:77], v[166:169], v[228:231], v[74:77]
	v_mfma_f32_16x16x32_bf16 v[70:73], v[174:177], v[228:231], v[70:73]
	v_mfma_f32_16x16x32_bf16 v[122:125], v[170:173], v[186:189], v[122:125]
	v_mfma_f32_16x16x32_bf16 v[118:121], v[178:181], v[186:189], v[118:121]
	v_mfma_f32_16x16x32_bf16 v[106:109], v[170:173], v[194:197], v[106:109]
	v_mfma_f32_16x16x32_bf16 v[102:105], v[178:181], v[194:197], v[102:105]
	v_mfma_f32_16x16x32_bf16 v[90:93], v[170:173], v[224:227], v[90:93]
	v_mfma_f32_16x16x32_bf16 v[86:89], v[178:181], v[224:227], v[86:89]
	v_mfma_f32_16x16x32_bf16 v[74:77], v[170:173], v[232:235], v[74:77]
	v_mfma_f32_16x16x32_bf16 v[70:73], v[178:181], v[232:235], v[70:73]
	s_setprio 0
	s_barrier
	s_add_u32 s100, s46, 0x80
	s_addc_u32 s101, s47, 0
	s_add_i32 s48, s68, s51
	s_mov_b32 m0, s48
	ds_read_b128 v[182:185], v148 offset:49152
	ds_read_b128 v[186:189], v238 offset:49152
	ds_read_b128 v[190:193], v148 offset:51200
	ds_read_b128 v[194:197], v238 offset:51200
	ds_read_b128 v[206:209], v148 offset:53248
	ds_read_b128 v[224:227], v238 offset:53248
	ds_read_b128 v[228:231], v148 offset:55296
	ds_read_b128 v[232:235], v238 offset:55296
	global_load_lds_dwordx4 v138, s[100:101]
	s_add_i32 m0, s48, 0x2000
	s_add_u32 s46, s46, 0x80080
	s_addc_u32 s47, s47, 0
	s_add_i32 s48, s69, s51
	global_load_lds_dwordx4 v134, s[100:101]
	s_mov_b32 m0, s48
	s_nop 0
	global_load_lds_dwordx4 v138, s[46:47]
	s_add_i32 m0, s48, 0x2000
	s_nop 0
	global_load_lds_dwordx4 v134, s[46:47]
	s_waitcnt vmcnt(6)
	s_waitcnt lgkmcnt(0)
	s_barrier
	s_setprio 1
	s_waitcnt lgkmcnt(0)
	v_mfma_f32_16x16x32_bf16 v[66:69], v[150:153], v[182:185], v[66:69]
	v_mfma_f32_16x16x32_bf16 v[62:65], v[158:161], v[182:185], v[62:65]
	v_mfma_f32_16x16x32_bf16 v[50:53], v[150:153], v[190:193], v[50:53]
	v_mfma_f32_16x16x32_bf16 v[46:49], v[158:161], v[190:193], v[46:49]
	v_mfma_f32_16x16x32_bf16 v[34:37], v[150:153], v[206:209], v[34:37]
	v_mfma_f32_16x16x32_bf16 v[30:33], v[158:161], v[206:209], v[30:33]
	v_mfma_f32_16x16x32_bf16 v[18:21], v[150:153], v[228:231], v[18:21]
	v_mfma_f32_16x16x32_bf16 v[14:17], v[158:161], v[228:231], v[14:17]
	v_mfma_f32_16x16x32_bf16 v[66:69], v[154:157], v[186:189], v[66:69]
	v_mfma_f32_16x16x32_bf16 v[62:65], v[162:165], v[186:189], v[62:65]
	v_mfma_f32_16x16x32_bf16 v[50:53], v[154:157], v[194:197], v[50:53]
	v_mfma_f32_16x16x32_bf16 v[46:49], v[162:165], v[194:197], v[46:49]
	v_mfma_f32_16x16x32_bf16 v[34:37], v[154:157], v[224:227], v[34:37]
	v_mfma_f32_16x16x32_bf16 v[30:33], v[162:165], v[224:227], v[30:33]
	v_mfma_f32_16x16x32_bf16 v[18:21], v[154:157], v[232:235], v[18:21]
	v_mfma_f32_16x16x32_bf16 v[14:17], v[162:165], v[232:235], v[14:17]
	s_setprio 0
	s_setprio 1
	v_mfma_f32_16x16x32_bf16 v[58:61], v[166:169], v[182:185], v[58:61]
	v_mfma_f32_16x16x32_bf16 v[54:57], v[174:177], v[182:185], v[54:57]
	v_mfma_f32_16x16x32_bf16 v[42:45], v[166:169], v[190:193], v[42:45]
	v_mfma_f32_16x16x32_bf16 v[38:41], v[174:177], v[190:193], v[38:41]
	v_mfma_f32_16x16x32_bf16 v[26:29], v[166:169], v[206:209], v[26:29]
	v_mfma_f32_16x16x32_bf16 v[22:25], v[174:177], v[206:209], v[22:25]
	v_mfma_f32_16x16x32_bf16 v[8:11], v[166:169], v[228:231], v[10:13]
	v_mfma_f32_16x16x32_bf16 v[4:7], v[174:177], v[228:231], v[4:7]
	v_mfma_f32_16x16x32_bf16 v[58:61], v[170:173], v[186:189], v[58:61]
	v_mfma_f32_16x16x32_bf16 v[54:57], v[178:181], v[186:189], v[54:57]
	v_mfma_f32_16x16x32_bf16 v[42:45], v[170:173], v[194:197], v[42:45]
	v_mfma_f32_16x16x32_bf16 v[38:41], v[178:181], v[194:197], v[38:41]
	v_mfma_f32_16x16x32_bf16 v[26:29], v[170:173], v[224:227], v[26:29]
	v_mfma_f32_16x16x32_bf16 v[22:25], v[178:181], v[224:227], v[22:25]
	v_mfma_f32_16x16x32_bf16 v[10:13], v[170:173], v[232:235], v[8:11]
	v_mfma_f32_16x16x32_bf16 v[6:9], v[178:181], v[232:235], v[4:7]
	s_setprio 0
	s_barrier
	s_add_u32 s44, s44, 0x100
	s_addc_u32 s45, s45, 0
	s_add_u32 s65, s65, 0x100
	s_addc_u32 s66, s66, 0
	s_cmp_ge_i32 s67, s56
	s_mov_b32 s46, s67
	s_cbranch_scc0 .LBB0_1402

; #define LAS __attribute__((address_space(3)))
; template <class Epi, bool ALIGN_EPI = true>
; __device__ __forceinline__ void gemm_phase(LAS unsigned char* lds, const Gemm g, const Sched& S, const Epi& E) {
;     int tid = threadIdx.x; asm volatile("" : "+v"(tid));
;     const int wid = __builtin_amdgcn_readfirstlane(tid >> 6), lane = tid & 63, wr = wid >> 2, wc = wid & 3, fr = lane & 15, fq = lane >> 4;
;     int K = g.K; asm volatile("" : "+s"(K));
;     const int nt = K / BK;
;     unsigned voffA[2], voffB[2];
; #pragma unroll
;     for (int i = 0; i < 2; ++i) { int R, C; stage_rc(tid * 16 + i * 8192, R, C); const int Rb = (R & ~31) + perm32(R & 31);
;         voffA[i] = (unsigned)(R * g.lda + C) * 2u; voffB[i] = (unsigned)(Rb * g.ldb + C) * 2u; }
;     const size_t kstep = (size_t)(BK * 2);
;     const size_t hstepA = (size_t)HALF * g.lda * 2, hstepB = (size_t)HALF * g.ldb * 2;
;     const unsigned ldsw = (unsigned)wid * 1024u;
;     const int aoff = lds_byte(wr * 64 + fr, fq * 8), boff = lds_byte(wc * 32 + fr, fq * 8);
.LBB0_1914:
	s_andn2_b64 vcc, exec, s[0:1]
	s_cbranch_vccnz .LBB0_2003
	v_readlane_b32 s16, v244, 0
	s_mov_b64 s[4:5], 0x39000000
	s_mov_b64 s[14:15], 0x45800000
	s_mov_b64 s[6:7], 0x26000000
	s_mov_b64 s[0:1], 0x120000
	v_mov_b32_e32 v146, v0
	v_readlane_b32 s17, v244, 1
	s_movk_i32 s18, 0x400
	v_readfirstlane_b32 s30, v146
	s_andn2_b64 vcc, exec, s[16:17]
	s_cbranch_vccnz .LBB0_1953
	s_waitcnt vmcnt(0) lgkmcnt(0)
	v_lshlrev_b32_e32 v4, 4, v146
	v_add_u32_e32 v5, 0x2000, v4
	v_ashrrev_i32_e32 v2, 31, v5
	v_lshrrev_b32_e32 v2, 22, v2
	v_add_u32_e32 v2, v5, v2
	v_ashrrev_i32_e32 v2, 10, v2
	v_mul_i32_i24_e32 v6, 0x400, v2
	v_sub_u32_e32 v5, v5, v6
	v_lshrrev_b32_e32 v6, 4, v5
	v_bitop3_b32 v5, v6, v5, 32 bitop3:0x6c
	v_ashrrev_i32_e32 v6, 31, v5
	v_lshrrev_b32_e32 v6, 26, v6
	v_add_u32_e32 v6, v5, v6
	v_lshlrev_b32_e32 v7, 3, v2
	v_ashrrev_i32_e32 v12, 6, v6
	v_and_b32_e32 v7, -16, v7
	v_add_u32_e32 v7, v12, v7
	v_and_b32_e32 v8, 3, v12
	s_mov_b32 s10, 0x1fffe0
	v_lshrrev_b32_e32 v9, 2, v7
	v_lshlrev_b32_e32 v10, 1, v7
	v_and_b32_e32 v6, 0xc0, v6
	v_and_or_b32 v8, v7, s10, v8
	v_and_b32_e32 v9, 4, v9
	v_and_b32_e32 v10, 24, v10
	v_sub_u32_e32 v5, v5, v6
	v_or3_b32 v8, v8, v9, v10
	v_lshlrev_b32_e32 v9, 5, v2
	v_ashrrev_i16_sdwa v5, v213, sext(v5) dst_sel:DWORD dst_unused:UNUSED_PAD src0_sel:DWORD src1_sel:BYTE_0
	v_and_b32_e32 v9, 32, v9
	v_bfe_i32 v13, v5, 0, 16
	v_add_lshl_u32 v5, v9, v13, 1
	v_lshl_add_u32 v134, v8, 11, v5
	v_lshrrev_b32_e32 v247, 3, v0
	v_xor_b32_e32 v247, v247, v0
	v_and_b32_e32 v247, 7, v247
	v_lshl_add_u32 v134, v247, 4, v134
	v_and_b32_e32 v247, 64, v0
	v_sub_u32_e32 v134, v134, v247
	v_lshrrev_b32_e32 v247, 4, v0
	v_and_b32_e32 v247, 2, v247
	v_xor_b32_e32 v247, v247, v0
	v_and_b32_e32 v247, 3, v247
	v_lshlrev_b32_e32 v247, 4, v247
	v_sub_u32_e32 v134, v134, v247
	v_and_b32_e32 v247, 64, v0
	v_mul_u32_u24_e32 v247, 0x200, v247
	v_add_u32_e32 v134, v134, v247
	v_and_b32_e32 v247, 32, v0
	v_mul_u32_u24_e32 v247, 0x200, v247
	v_sub_u32_e32 v134, v134, v247
	v_and_b32_e32 v247, 16, v0
	v_mul_u32_u24_e32 v247, 0x300, v247
	v_sub_u32_e32 v134, v134, v247
	v_and_b32_e32 v247, 8, v0
	v_mul_u32_u24_e32 v247, 0x100, v247
	v_sub_u32_e32 v134, v134, v247
	v_and_b32_e32 v247, 4, v0
	v_mul_u32_u24_e32 v247, 0x200, v247
	v_sub_u32_e32 v134, v134, v247
	v_lshl_add_u32 v136, v7, 11, v5
	v_lshrrev_b32_e32 v247, 3, v0
	v_xor_b32_e32 v247, v247, v0
	v_and_b32_e32 v247, 7, v247
	v_lshl_add_u32 v136, v247, 4, v136
	v_and_b32_e32 v247, 64, v0
	v_sub_u32_e32 v136, v136, v247
	v_lshrrev_b32_e32 v247, 4, v0
	v_and_b32_e32 v247, 2, v247
	v_xor_b32_e32 v247, v247, v0
	v_and_b32_e32 v247, 3, v247
	v_lshlrev_b32_e32 v247, 4, v247
	v_sub_u32_e32 v136, v136, v247
	v_bfe_u32 v247, v0, 2, 4
	v_add_u32_e32 v247, 1, v247
	v_lshrrev_b32_e32 v247, 1, v247
	v_mul_u32_u24_e32 v247, 0x800, v247
	v_sub_u32_e32 v136, v136, v247
	v_and_b32_e32 v247, 64, v0
	v_mul_u32_u24_e32 v247, 0x100, v247
	v_add_u32_e32 v136, v136, v247
	v_bfe_i32 v5, v146, 27, 1
	v_lshrrev_b32_e32 v5, 22, v5
	v_add_u32_e32 v5, v4, v5
	v_and_b32_e32 v5, 0xfffffc00, v5
	v_sub_u32_e32 v4, v4, v5
	v_lshrrev_b32_e32 v5, 4, v4
	v_ashrrev_i32_e32 v6, 31, v146
	s_add_u32 s33, s54, s4
	v_bitop3_b32 v4, v5, v4, 32 bitop3:0x6c
	v_lshrrev_b32_e32 v6, 26, v6
	s_addc_u32 s34, s55, s5
	v_readlane_b32 s4, v242, 25
	v_ashrrev_i32_e32 v5, 31, v4
	v_add_u32_e32 v6, v146, v6
	s_add_u32 s14, s54, s14
	v_readlane_b32 s5, v242, 26
	v_lshrrev_b32_e32 v5, 26, v5
	v_ashrrev_i32_e32 v15, 6, v6
	s_addc_u32 s15, s55, s15
	s_lshl_b64 s[4:5], s[4:5], 24
	v_add_u32_e32 v5, v4, v5
	v_lshlrev_b32_e32 v6, 3, v15
	s_add_u32 s35, s14, s4
	v_ashrrev_i32_e32 v14, 6, v5
	v_and_b32_e32 v6, -16, v6
	s_addc_u32 s36, s15, s5
	s_ashr_i32 s5, s30, 6
	v_add_u32_e32 v6, v14, v6
	s_ashr_i32 s4, s30, 8
	s_lshl_b32 s37, s5, 10
	v_and_b32_e32 v7, 3, v14
	v_lshrrev_b32_e32 v8, 2, v6
	v_lshlrev_b32_e32 v9, 1, v6
	v_and_b32_e32 v5, 0xc0, v5
	v_readlane_b32 s14, v243, 27
	v_and_or_b32 v7, v6, s10, v7
	v_and_b32_e32 v8, 4, v8
	v_and_b32_e32 v9, 24, v9
	v_sub_u32_e32 v4, v4, v5
	v_readlane_b32 s15, v243, 28
	s_add_u32 s14, s35, s14
	v_or3_b32 v7, v7, v8, v9
	v_lshlrev_b32_e32 v8, 5, v15
	v_ashrrev_i16_sdwa v4, v213, sext(v4) dst_sel:DWORD dst_unused:UNUSED_PAD src0_sel:DWORD src1_sel:BYTE_0
	s_addc_u32 s15, s36, s15
	v_readlane_b32 s16, v243, 45
	v_and_b32_e32 v8, 32, v8
	v_bfe_i32 v16, v4, 0, 16
	v_readlane_b32 s17, v243, 46
	s_add_u32 s14, s14, s16
	v_add_lshl_u32 v4, v8, v16, 1
	s_addc_u32 s15, s15, s17
	s_add_i32 s52, s37, 0
	v_lshl_add_u32 v138, v7, 11, v4
	v_lshrrev_b32_e32 v247, 3, v0
	v_xor_b32_e32 v247, v247, v0
	v_and_b32_e32 v247, 7, v247
	v_lshl_add_u32 v138, v247, 4, v138
	v_and_b32_e32 v247, 64, v0
	v_sub_u32_e32 v138, v138, v247
	v_lshrrev_b32_e32 v247, 4, v0
	v_and_b32_e32 v247, 2, v247
	v_xor_b32_e32 v247, v247, v0
	v_and_b32_e32 v247, 3, v247
	v_lshlrev_b32_e32 v247, 4, v247
	v_sub_u32_e32 v138, v138, v247
	v_and_b32_e32 v247, 64, v0
	v_mul_u32_u24_e32 v247, 0x200, v247
	v_add_u32_e32 v138, v138, v247
	v_and_b32_e32 v247, 32, v0
	v_mul_u32_u24_e32 v247, 0x200, v247
	v_sub_u32_e32 v138, v138, v247
	v_and_b32_e32 v247, 16, v0
	v_mul_u32_u24_e32 v247, 0x300, v247
	v_sub_u32_e32 v138, v138, v247
	v_and_b32_e32 v247, 8, v0
	v_mul_u32_u24_e32 v247, 0x100, v247
	v_sub_u32_e32 v138, v138, v247
	v_and_b32_e32 v247, 4, v0
	v_mul_u32_u24_e32 v247, 0x200, v247
	v_sub_u32_e32 v138, v138, v247
	s_add_i32 m0, s52, 0x10000
	v_lshl_add_u32 v140, v6, 11, v4
	v_lshrrev_b32_e32 v247, 3, v0
	v_xor_b32_e32 v247, v247, v0
	v_and_b32_e32 v247, 7, v247
	v_lshl_add_u32 v140, v247, 4, v140
	v_and_b32_e32 v247, 64, v0
	v_sub_u32_e32 v140, v140, v247
; #define PG8_STAGE(bufoff, gbase, voff) do { _Pragma("unroll") for (int _i = 0; _i < 2; ++_i) \
;         __builtin_amdgcn_global_load_lds((const unsigned*)((const char*)(gbase) + (voff)[_i]), (LAS unsigned*)(lds + (bufoff) + ldsw + _i * 8192), 16, 0, 0); } while (0)
; #define PG8_WAIT_V(n) asm volatile("s_waitcnt vmcnt(" #n ")" ::: "memory")
; #define PG8_BAR __builtin_amdgcn_s_barrier()
; template <class Epi, bool ALIGN_EPI = true>
; __device__ __forceinline__ void gemm_phase(LAS unsigned char* lds, const Gemm g, const Sched& S, const Epi& E) {
;     ...
;     const char* cA = (const char*)g.A + cur.aoff; const char* cB = (const char*)g.Bt + cur.boff;
;     PG8_STAGE(PG8_SB(0, 0), cB, voffB); PG8_STAGE(PG8_SB(0, 1), cB + hstepB, voffB); PG8_STAGE(PG8_SA(0, 0), cA, voffA); PG8_STAGE(PG8_SA(0, 1), cA + hstepA, voffA);
;     if (wr == 1) PG8_BAR;
;     PG8_WAIT_V(2); PG8_BAR;
;     PG8_STAGE(PG8_SB(1, 0), cB + kstep, voffB); PG8_STAGE(PG8_SA(1, 0), cA + kstep, voffA); PG8_STAGE(PG8_SB(1, 1), cB + hstepB + kstep, voffB);
	v_lshrrev_b32_e32 v247, 4, v0
	v_and_b32_e32 v247, 2, v247
	v_xor_b32_e32 v247, v247, v0
	v_and_b32_e32 v247, 3, v247
	v_lshlrev_b32_e32 v247, 4, v247
	v_sub_u32_e32 v140, v140, v247
	v_bfe_u32 v247, v0, 2, 4
	v_add_u32_e32 v247, 1, v247
	v_lshrrev_b32_e32 v247, 1, v247
	v_mul_u32_u24_e32 v247, 0x800, v247
	v_sub_u32_e32 v140, v140, v247
	v_and_b32_e32 v247, 64, v0
	v_mul_u32_u24_e32 v247, 0x100, v247
	v_add_u32_e32 v140, v140, v247
	global_load_lds_dwordx4 v138, s[14:15]
	s_add_i32 m0, s52, 0x12000
	s_add_u32 s16, s14, 0x40000
	global_load_lds_dwordx4 v134, s[14:15]
	s_addc_u32 s17, s15, 0
	s_add_i32 m0, s52, 0x14000
	v_mov_b32_e32 v139, v3
	global_load_lds_dwordx4 v138, s[16:17]
	s_add_i32 m0, s52, 0x16000
	v_mov_b32_e32 v135, v3
	global_load_lds_dwordx4 v134, s[16:17]
	v_readlane_b32 s16, v243, 41
	v_readlane_b32 s17, v243, 42
	s_add_u32 s16, s33, s16
	s_addc_u32 s17, s34, s17
	s_add_i32 s53, s52, 0x2000
	s_mov_b32 m0, s52
	s_add_u32 s20, s16, 0x40000
	global_load_lds_dwordx4 v140, s[16:17]
	s_mov_b32 m0, s53
	s_addc_u32 s21, s17, 0
	s_add_i32 s54, s52, 0x4000
	global_load_lds_dwordx4 v136, s[16:17]
	s_mov_b32 m0, s54
	s_add_i32 s55, s52, 0x6000
	global_load_lds_dwordx4 v140, s[20:21]
	s_mov_b32 m0, s55
	v_mov_b32_e32 v141, v3
	global_load_lds_dwordx4 v136, s[20:21]
	v_mov_b32_e32 v137, v3
	v_lshl_add_u64 v[10:11], s[14:15], 0, v[138:139]
	v_lshl_add_u64 v[8:9], s[14:15], 0, v[134:135]
	v_lshl_add_u64 v[6:7], s[16:17], 0, v[140:141]
	s_cmp_lg_u32 s4, 1
	v_lshl_add_u64 v[4:5], s[16:17], 0, v[136:137]
	s_cbranch_scc1 .LBB0_1918
	s_barrier
; #define PG8_STAGE(bufoff, gbase, voff) do { _Pragma("unroll") for (int _i = 0; _i < 2; ++_i) \
;         __builtin_amdgcn_global_load_lds((const unsigned*)((const char*)(gbase) + (voff)[_i]), (LAS unsigned*)(lds + (bufoff) + ldsw + _i * 8192), 16, 0, 0); } while (0)
; #define PG8_WAIT_V(n) asm volatile("s_waitcnt vmcnt(" #n ")" ::: "memory")
; #define PG8_BAR __builtin_amdgcn_s_barrier()
; template <class Epi, bool ALIGN_EPI = true>
; __device__ __forceinline__ void gemm_phase(LAS unsigned char* lds, const Gemm g, const Sched& S, const Epi& E) {
;     ...
;     f32x4 acc[2][2][4][2];
; #pragma unroll
;     for (int a = 0; a < 2; ++a)
; #pragma unroll
;         for (int b = 0; b < 2; ++b)
; #pragma unroll
;             for (int m = 0; m < 4; ++m)
; #pragma unroll
;                 for (int n = 0; n < 2; ++n) acc[a][b][m][n] = (f32x4){0.f, 0.f, 0.f, 0.f};
;     bf16x8 At[4][2], B0[2][2], B1[2][2];
;     const char* cA = (const char*)g.A + cur.aoff; const char* cB = (const char*)g.Bt + cur.boff;
;     PG8_STAGE(PG8_SB(0, 0), cB, voffB); PG8_STAGE(PG8_SB(0, 1), cB + hstepB, voffB); PG8_STAGE(PG8_SA(0, 0), cA, voffA); PG8_STAGE(PG8_SA(0, 1), cA + hstepA, voffA);
;     if (wr == 1) PG8_BAR;
;     PG8_WAIT_V(2); PG8_BAR;
;     PG8_STAGE(PG8_SB(1, 0), cB + kstep, voffB); PG8_STAGE(PG8_SA(1, 0), cA + kstep, voffA); PG8_STAGE(PG8_SB(1, 1), cB + hstepB + kstep, voffB);
;     PG8_WAIT_V(6); PG8_BAR;
.LBB0_1918:
	s_ashr_i32 s19, s18, 31
	s_lshr_b32 s19, s19, 26
	s_and_b32 s5, s5, 3
	s_add_i32 s19, s18, s19
	s_add_i32 m0, s52, 0x18000
	v_lshl_add_u64 v[10:11], v[10:11], 0, s[8:9]
	s_ashr_i32 s56, s19, 6
	s_lshl_b32 s31, s4, 6
	s_lshl_b32 s4, s4, 13
	s_lshl_b32 s19, s5, 12
	s_waitcnt vmcnt(2)
	s_barrier
	global_load_lds_dwordx4 v[10:11], off
	v_lshl_add_u64 v[8:9], v[8:9], 0, s[8:9]
	s_add_i32 m0, s52, 0x1a000
	s_add_i32 s57, s52, 0x8000
	s_add_i32 s58, s52, 0xa000
	global_load_lds_dwordx4 v[8:9], off
	v_lshl_add_u64 v[6:7], v[6:7], 0, s[8:9]
	s_mov_b32 m0, s57
	s_add_u32 s20, s14, 0x40080
	global_load_lds_dwordx4 v[6:7], off
	v_lshl_add_u64 v[4:5], v[4:5], 0, s[8:9]
	s_mov_b32 m0, s58
	s_addc_u32 s21, s15, 0
	global_load_lds_dwordx4 v[4:5], off
	s_add_i32 m0, s52, 0x1c000
	v_lshl_add_u64 v[4:5], s[20:21], 0, v[138:139]
	global_load_lds_dwordx4 v[4:5], off
	v_lshl_add_u64 v[4:5], s[20:21], 0, v[134:135]
	s_add_i32 m0, s52, 0x1e000
	s_movk_i32 s10, 0x3c0
	global_load_lds_dwordx4 v[4:5], off
	v_and_b32_e32 v4, 48, v146
	v_lshlrev_b32_e32 v5, 6, v146
	v_and_or_b32 v4, v5, s10, v4
	v_lshlrev_b32_e32 v5, 2, v146
	v_and_b32_e32 v5, 32, v5
	v_bitop3_b32 v6, v4, s4, v5 bitop3:0xde
	v_bitop3_b32 v147, v4, s19, v5 bitop3:0xde
	v_bfe_u32 v147, v0, 4, 2
	v_xor_b32_e32 v147, v147, v0
	v_and_b32_e32 v147, 7, v147
	v_lshlrev_b32_e32 v147, 4, v147
	v_and_b32_e32 v247, 15, v0
	v_lshl_or_b32 v147, v247, 7, v147
	v_and_b32_e32 v247, 0xc0, v0
	v_lshl_or_b32 v147, v247, 6, v147
	v_or_b32_e32 v147, 0x10000, v147
	v_lshlrev_b32_e32 v4, 14, v15
	v_and_b32_e32 v4, 0xffff8000, v4
	v_lshl_add_u32 v4, v14, 11, v4
	v_and_b32_e32 v5, 1, v15
	v_lshl_or_b32 v4, v5, 6, v4
	v_lshl_add_u32 v142, v16, 1, v4
	v_lshrrev_b32_e32 v247, 3, v0
	v_xor_b32_e32 v247, v247, v0
	v_and_b32_e32 v247, 7, v247
	v_lshl_add_u32 v142, v247, 4, v142
	v_and_b32_e32 v247, 64, v0
	v_sub_u32_e32 v142, v142, v247
	v_lshrrev_b32_e32 v247, 4, v0
	v_and_b32_e32 v247, 2, v247
	v_xor_b32_e32 v247, v247, v0
	v_and_b32_e32 v247, 3, v247
	v_lshlrev_b32_e32 v247, 4, v247
	v_sub_u32_e32 v142, v142, v247
	v_bfe_u32 v247, v0, 2, 4
	v_add_u32_e32 v247, 1, v247
	v_lshrrev_b32_e32 v247, 1, v247
	v_mul_u32_u24_e32 v247, 0x800, v247
	v_sub_u32_e32 v142, v142, v247
	v_and_b32_e32 v247, 64, v0
	v_mul_u32_u24_e32 v247, 0x100, v247
	v_add_u32_e32 v142, v142, v247
	v_lshlrev_b32_e32 v4, 14, v2
	v_and_b32_e32 v4, 0xffff8000, v4
	v_lshl_add_u32 v4, v12, 11, v4
	v_and_b32_e32 v2, 1, v2
	v_readlane_b32 s20, v243, 43
	s_waitcnt vmcnt(6)
	v_lshl_or_b32 v2, v2, 6, v4
	v_mov_b32_e32 v4, v3
	v_mov_b32_e32 v5, v3
	v_readlane_b32 s21, v243, 44
	s_cmp_gt_i32 s18, 63
	v_lshl_add_u32 v144, v13, 1, v2
	v_lshrrev_b32_e32 v247, 3, v0
	v_xor_b32_e32 v247, v247, v0
	v_and_b32_e32 v247, 7, v247
	v_lshl_add_u32 v144, v247, 4, v144
	v_and_b32_e32 v247, 64, v0
	v_sub_u32_e32 v144, v144, v247
	v_lshrrev_b32_e32 v247, 4, v0
	v_and_b32_e32 v247, 2, v247
	v_xor_b32_e32 v247, v247, v0
	v_and_b32_e32 v247, 3, v247
	v_lshlrev_b32_e32 v247, 4, v247
	v_sub_u32_e32 v144, v144, v247
	v_bfe_u32 v247, v0, 2, 4
	v_add_u32_e32 v247, 1, v247
	v_lshrrev_b32_e32 v247, 1, v247
	v_mul_u32_u24_e32 v247, 0x800, v247
	v_sub_u32_e32 v144, v144, v247
	v_and_b32_e32 v247, 64, v0
	v_mul_u32_u24_e32 v247, 0x100, v247
	v_add_u32_e32 v144, v144, v247
	v_mov_b32_e32 v2, v3
	v_add_u32_e32 v148, 0, v6
	v_bfe_u32 v148, v0, 4, 2
	v_xor_b32_e32 v148, v148, v0
	v_and_b32_e32 v148, 7, v148
	v_lshlrev_b32_e32 v148, 4, v148
	v_and_b32_e32 v247, 15, v0
	v_lshl_or_b32 v148, v247, 7, v148
	v_and_b32_e32 v247, 0x100, v0
	v_lshl_or_b32 v148, v247, 5, v148
	v_mov_b64_e32 v[8:9], v[4:5]
	v_mov_b64_e32 v[12:13], v[4:5]
	v_mov_b64_e32 v[24:25], v[4:5]
	v_mov_b64_e32 v[28:29], v[4:5]
	v_mov_b64_e32 v[40:41], v[4:5]
	v_mov_b64_e32 v[44:45], v[4:5]
	v_mov_b64_e32 v[56:57], v[4:5]
	v_mov_b64_e32 v[60:61], v[4:5]
	v_mov_b64_e32 v[16:17], v[4:5]
	v_mov_b64_e32 v[20:21], v[4:5]
	v_mov_b64_e32 v[32:33], v[4:5]
	v_mov_b64_e32 v[36:37], v[4:5]
	v_mov_b64_e32 v[48:49], v[4:5]
	v_mov_b64_e32 v[52:53], v[4:5]
	v_mov_b64_e32 v[64:65], v[4:5]
	v_mov_b64_e32 v[68:69], v[4:5]
	v_mov_b64_e32 v[72:73], v[4:5]
	v_mov_b64_e32 v[76:77], v[4:5]
	v_mov_b64_e32 v[88:89], v[4:5]
	v_mov_b64_e32 v[92:93], v[4:5]
	v_mov_b64_e32 v[104:105], v[4:5]
	v_mov_b64_e32 v[108:109], v[4:5]
	v_mov_b64_e32 v[120:121], v[4:5]
	v_mov_b64_e32 v[124:125], v[4:5]
	v_mov_b64_e32 v[80:81], v[4:5]
	v_mov_b64_e32 v[84:85], v[4:5]
	v_mov_b64_e32 v[96:97], v[4:5]
	v_mov_b64_e32 v[100:101], v[4:5]
	v_mov_b64_e32 v[112:113], v[4:5]
	v_mov_b64_e32 v[116:117], v[4:5]
	v_mov_b64_e32 v[128:129], v[4:5]
	v_mov_b64_e32 v[132:133], v[4:5]
	s_mov_b32 s4, s20
	v_readlane_b32 s20, v243, 39
	s_cselect_b64 s[18:19], -1, 0
	s_add_i32 s59, s56, -2
	v_mov_b32_e32 v143, v3
	v_mov_b32_e32 v145, v3
	s_mov_b32 s60, 0
	v_mov_b64_e32 v[6:7], v[2:3]
	v_mov_b64_e32 v[10:11], v[2:3]
	v_mov_b64_e32 v[22:23], v[2:3]
	v_mov_b64_e32 v[26:27], v[2:3]
	v_mov_b64_e32 v[38:39], v[2:3]
	v_mov_b64_e32 v[42:43], v[2:3]
	v_mov_b64_e32 v[54:55], v[2:3]
	v_mov_b64_e32 v[58:59], v[2:3]
	v_mov_b64_e32 v[14:15], v[2:3]
	v_mov_b64_e32 v[18:19], v[2:3]
	v_mov_b64_e32 v[30:31], v[2:3]
	v_mov_b64_e32 v[34:35], v[2:3]
	v_mov_b64_e32 v[46:47], v[2:3]
	v_mov_b64_e32 v[50:51], v[2:3]
	v_mov_b64_e32 v[62:63], v[2:3]
	v_mov_b64_e32 v[66:67], v[2:3]
	v_mov_b64_e32 v[70:71], v[2:3]
	v_mov_b64_e32 v[74:75], v[2:3]
	v_mov_b64_e32 v[86:87], v[2:3]
	v_mov_b64_e32 v[90:91], v[2:3]
	v_mov_b64_e32 v[102:103], v[2:3]
	v_mov_b64_e32 v[106:107], v[2:3]
	v_mov_b64_e32 v[118:119], v[2:3]
	v_mov_b64_e32 v[122:123], v[2:3]
	v_mov_b64_e32 v[78:79], v[2:3]
	v_mov_b64_e32 v[82:83], v[2:3]
	v_mov_b64_e32 v[94:95], v[2:3]
	v_mov_b64_e32 v[98:99], v[2:3]
	v_mov_b64_e32 v[110:111], v[2:3]
	v_mov_b64_e32 v[114:115], v[2:3]
	v_mov_b64_e32 v[126:127], v[2:3]
	v_mov_b64_e32 v[130:131], v[2:3]
	s_mov_b32 s61, s20
	s_barrier
	v_readlane_b32 s21, v243, 40
	s_branch .LBB0_1920

; #define PG8_STAGE(bufoff, gbase, voff) do { _Pragma("unroll") for (int _i = 0; _i < 2; ++_i) \
;         __builtin_amdgcn_global_load_lds((const unsigned*)((const char*)(gbase) + (voff)[_i]), (LAS unsigned*)(lds + (bufoff) + ldsw + _i * 8192), 16, 0, 0); } while (0)
; #define PG8_LDA(dst, b, h) do { _Pragma("unroll") for (int m = 0; m < 4; ++m) _Pragma("unroll") for (int k = 0; k < 2; ++k) dst[m][k] = *(const LAS bf16x8*)(lds + PG8_SA(b, h) + aoff + m * 2048 + k * 1024); } while (0)
; #define PG8_LDB(dst, b, h) do { _Pragma("unroll") for (int n = 0; n < 2; ++n) _Pragma("unroll") for (int k = 0; k < 2; ++k) dst[n][k] = *(const LAS bf16x8*)(lds + PG8_SB(b, h) + boff + n * 2048 + k * 1024); } while (0)
; #define PG8_MMA(ai, bj, At, Bt) do { __builtin_amdgcn_s_setprio(1); _Pragma("unroll") for (int m = 0; m < 4; ++m) _Pragma("unroll") for (int n = 0; n < 2; ++n) _Pragma("unroll") for (int k = 0; k < 2; ++k) \
;         acc[ai][bj][m][n] = __builtin_amdgcn_mfma_f32_16x16x32_bf16(Bt[n][k], At[m][k], acc[ai][bj][m][n], 0, 0, 0); __builtin_amdgcn_s_setprio(0); } while (0)
; template <class Epi, bool ALIGN_EPI = true>
; __device__ __forceinline__ void gemm_phase(LAS unsigned char* lds, const Gemm g, const Sched& S, const Epi& E) {
;     ...
;         for (int t = t_lo; t < t_hi; t += 2) {
;             const bool last = (t == nt - 2);
;             const char* a1 = cA + (size_t)(t + 1) * kstep;
;             const char* a2 = last ? nA : cA + (size_t)(t + 2) * kstep; const char* b2 = last ? nB : cB + (size_t)(t + 2) * kstep;
;             const char* a3 = a2 + kstep; const char* b3 = b2 + kstep;
;             const int rflag = __builtin_amdgcn_readfirstlane(t | (int)(ui == 0));
;             PG8_LDB(B0, 0, 0); PG8_LDB(B1, 0, 1); PG8_SCHED; PG8_LDA(At, 0, 0); PG8_STAGE(PG8_SA(1, 1), a1 + hstepA, voffA);
;             if constexpr (Epi::NSTORES > 0) PG8_WAIT_RELAX(rflag, 8 + Epi::NSTORES); else PG8_WAIT_V(8);
;             PG8_WAIT_L(0); PG8_BAR; PG8_MMA(0, 0, At, B0); PG8_MMA(0, 1, At, B1); PG8_BAR; PG8_SCHED;
;             PG8_LDA(At, 0, 1); PG8_STAGE(PG8_SB(0, 0), b2, voffB); PG8_STAGE(PG8_SB(0, 1), b2 + hstepB, voffB); PG8_STAGE(PG8_SA(0, 0), a2, voffA);
;             if constexpr (Epi::NSTORES > 0) PG8_WAIT_RELAX(rflag, 8 + Epi::NSTORES); else PG8_WAIT_V(8);
;             PG8_WAIT_L(0); PG8_BAR; PG8_MMA(1, 0, At, B0); PG8_MMA(1, 1, At, B1); PG8_BAR; PG8_SCHED;
.LBB0_1927:
	s_add_u32 s26, s33, s24
	s_addc_u32 s27, s34, s25
	s_add_u32 s42, s35, s40
	s_addc_u32 s43, s36, s41
	s_andn2_b64 vcc, exec, s[18:19]
	s_cbranch_vccnz .LBB0_1930
	s_and_b64 s[46:47], s[44:45], exec
	s_cselect_b32 s21, s27, s17
	s_cselect_b32 s23, s26, s16
	s_cselect_b32 s63, s43, s15
	s_cselect_b32 s64, s42, s14
	s_add_u32 s46, s16, 0x40080
	s_addc_u32 s47, s17, 0
	s_add_u32 s65, s14, 0x100
	s_addc_u32 s66, s15, 0
	s_mov_b32 s48, 0
	v_xor_b32_e32 v238, 64, v148
	v_xor_b32_e32 v239, 64, v147
.LBB0_1929:
	s_add_i32 s67, s48, 2
	s_add_u32 s49, s46, 0xfffc0080
	s_addc_u32 s50, s47, -1
	s_add_i32 s68, 0, 0x10000
	s_cmp_eq_u32 s59, s48
	s_cselect_b32 s51, s21, s50
	s_cselect_b32 s50, s23, s49
	s_cselect_b32 s49, s63, s66
	s_cselect_b32 s48, s64, s65
	s_add_i32 s70, 0, 0x14000
	ds_read_b128 v[150:153], v147
	ds_read_b128 v[154:157], v239
	ds_read_b128 v[158:161], v147 offset:2048
	ds_read_b128 v[162:165], v239 offset:2048
	ds_read_b128 v[166:169], v147 offset:16384
	ds_read_b128 v[170:173], v239 offset:16384
	ds_read_b128 v[174:177], v147 offset:18432
	ds_read_b128 v[178:181], v239 offset:18432
	s_add_i32 m0, s52, 0xc000
	ds_read_b128 v[182:185], v148
	ds_read_b128 v[186:189], v238
	ds_read_b128 v[190:193], v148 offset:2048
	ds_read_b128 v[194:197], v238 offset:2048
	ds_read_b128 v[206:209], v148 offset:4096
	ds_read_b128 v[224:227], v238 offset:4096
	ds_read_b128 v[228:231], v148 offset:6144
	ds_read_b128 v[232:235], v238 offset:6144
	s_add_u32 s100, s46, 0xfffc0000
	s_addc_u32 s101, s47, -1
	s_mov_b32 m0, s57
	s_nop 0
	global_load_lds_dwordx4 v142, s[100:101]
	s_mov_b32 m0, s58
	s_nop 0
	global_load_lds_dwordx4 v144, s[100:101]
	s_add_i32 m0, s52, 0xc000
	s_nop 0
	global_load_lds_dwordx4 v142, s[46:47]
	s_add_i32 m0, s52, 0xe000
	s_nop 0
	global_load_lds_dwordx4 v144, s[46:47]
	s_waitcnt vmcnt(8)
	s_waitcnt lgkmcnt(0)
	s_barrier
	s_setprio 1
	s_waitcnt lgkmcnt(0)
	v_mfma_f32_16x16x32_bf16 v[130:133], v[150:153], v[182:185], v[130:133]
	v_mfma_f32_16x16x32_bf16 v[126:129], v[158:161], v[182:185], v[126:129]
	v_mfma_f32_16x16x32_bf16 v[114:117], v[150:153], v[190:193], v[114:117]
	v_mfma_f32_16x16x32_bf16 v[110:113], v[158:161], v[190:193], v[110:113]
	v_mfma_f32_16x16x32_bf16 v[98:101], v[150:153], v[206:209], v[98:101]
	v_mfma_f32_16x16x32_bf16 v[94:97], v[158:161], v[206:209], v[94:97]
	v_mfma_f32_16x16x32_bf16 v[82:85], v[150:153], v[228:231], v[82:85]
	v_mfma_f32_16x16x32_bf16 v[78:81], v[158:161], v[228:231], v[78:81]
	v_mfma_f32_16x16x32_bf16 v[130:133], v[154:157], v[186:189], v[130:133]
	v_mfma_f32_16x16x32_bf16 v[126:129], v[162:165], v[186:189], v[126:129]
	v_mfma_f32_16x16x32_bf16 v[114:117], v[154:157], v[194:197], v[114:117]
	v_mfma_f32_16x16x32_bf16 v[110:113], v[162:165], v[194:197], v[110:113]
	v_mfma_f32_16x16x32_bf16 v[98:101], v[154:157], v[224:227], v[98:101]
	v_mfma_f32_16x16x32_bf16 v[94:97], v[162:165], v[224:227], v[94:97]
	v_mfma_f32_16x16x32_bf16 v[82:85], v[154:157], v[232:235], v[82:85]
	v_mfma_f32_16x16x32_bf16 v[78:81], v[162:165], v[232:235], v[78:81]
	s_setprio 0
	s_setprio 1
	v_mfma_f32_16x16x32_bf16 v[122:125], v[166:169], v[182:185], v[122:125]
	v_mfma_f32_16x16x32_bf16 v[118:121], v[174:177], v[182:185], v[118:121]
	v_mfma_f32_16x16x32_bf16 v[106:109], v[166:169], v[190:193], v[106:109]
	v_mfma_f32_16x16x32_bf16 v[102:105], v[174:177], v[190:193], v[102:105]
	v_mfma_f32_16x16x32_bf16 v[90:93], v[166:169], v[206:209], v[90:93]
	v_mfma_f32_16x16x32_bf16 v[86:89], v[174:177], v[206:209], v[86:89]
	v_mfma_f32_16x16x32_bf16 v[74:77], v[166:169], v[228:231], v[74:77]
	v_mfma_f32_16x16x32_bf16 v[70:73], v[174:177], v[228:231], v[70:73]
	v_mfma_f32_16x16x32_bf16 v[122:125], v[170:173], v[186:189], v[122:125]
	v_mfma_f32_16x16x32_bf16 v[118:121], v[178:181], v[186:189], v[118:121]
	v_mfma_f32_16x16x32_bf16 v[106:109], v[170:173], v[194:197], v[106:109]
	v_mfma_f32_16x16x32_bf16 v[102:105], v[178:181], v[194:197], v[102:105]
	v_mfma_f32_16x16x32_bf16 v[90:93], v[170:173], v[224:227], v[90:93]
	v_mfma_f32_16x16x32_bf16 v[86:89], v[178:181], v[224:227], v[86:89]
	v_mfma_f32_16x16x32_bf16 v[74:77], v[170:173], v[232:235], v[74:77]
	v_mfma_f32_16x16x32_bf16 v[70:73], v[178:181], v[232:235], v[70:73]
	s_setprio 0
	s_barrier
	s_add_i32 s68, s68, s37
	s_mov_b32 m0, s68
	ds_read_b128 v[182:185], v148 offset:16384
	ds_read_b128 v[186:189], v238 offset:16384
	ds_read_b128 v[190:193], v148 offset:18432
	ds_read_b128 v[194:197], v238 offset:18432
	ds_read_b128 v[206:209], v148 offset:20480
	ds_read_b128 v[224:227], v238 offset:20480
	ds_read_b128 v[228:231], v148 offset:22528
	ds_read_b128 v[232:235], v238 offset:22528
	global_load_lds_dwordx4 v138, s[48:49]
	s_add_i32 m0, s68, 0x2000
	s_add_u32 s68, s48, 0x40000
	s_addc_u32 s69, s49, 0
	s_add_i32 s70, s70, s37
	global_load_lds_dwordx4 v134, s[48:49]
	s_mov_b32 m0, s70
	s_nop 0
	global_load_lds_dwordx4 v138, s[68:69]
	s_add_i32 m0, s70, 0x2000
	s_nop 0
	global_load_lds_dwordx4 v134, s[68:69]
	s_waitcnt vmcnt(6)
	s_waitcnt lgkmcnt(0)
	s_barrier
; #define PG8_STAGE(bufoff, gbase, voff) do { _Pragma("unroll") for (int _i = 0; _i < 2; ++_i) \
;         __builtin_amdgcn_global_load_lds((const unsigned*)((const char*)(gbase) + (voff)[_i]), (LAS unsigned*)(lds + (bufoff) + ldsw + _i * 8192), 16, 0, 0); } while (0)
; #define PG8_LDA(dst, b, h) do { _Pragma("unroll") for (int m = 0; m < 4; ++m) _Pragma("unroll") for (int k = 0; k < 2; ++k) dst[m][k] = *(const LAS bf16x8*)(lds + PG8_SA(b, h) + aoff + m * 2048 + k * 1024); } while (0)
; #define PG8_LDB(dst, b, h) do { _Pragma("unroll") for (int n = 0; n < 2; ++n) _Pragma("unroll") for (int k = 0; k < 2; ++k) dst[n][k] = *(const LAS bf16x8*)(lds + PG8_SB(b, h) + boff + n * 2048 + k * 1024); } while (0)
; #define PG8_MMA(ai, bj, At, Bt) do { __builtin_amdgcn_s_setprio(1); _Pragma("unroll") for (int m = 0; m < 4; ++m) _Pragma("unroll") for (int n = 0; n < 2; ++n) _Pragma("unroll") for (int k = 0; k < 2; ++k) \
;         acc[ai][bj][m][n] = __builtin_amdgcn_mfma_f32_16x16x32_bf16(Bt[n][k], At[m][k], acc[ai][bj][m][n], 0, 0, 0); __builtin_amdgcn_s_setprio(0); } while (0)
; #define PG8_WAIT_V(n) asm volatile("s_waitcnt vmcnt(" #n ")" ::: "memory")
; #define PG8_WAIT_L(n) asm volatile("s_waitcnt lgkmcnt(" #n ")" ::: "memory")
; #define PG8_BAR __builtin_amdgcn_s_barrier()
; #define PG8_WAIT_RELAX(flag, n) asm volatile("s_cmp_eq_u32 %0, 0\n\ts_cbranch_scc1 .Lrw%=\n\ts_waitcnt vmcnt(8)\n.Lrw%=:\n\ts_waitcnt vmcnt(%1)" :: "s"(flag), "n"(n) : "scc", "memory")
; #define PG8_SCHED __builtin_amdgcn_sched_barrier(0)
; template <class Epi, bool ALIGN_EPI = true>
; __device__ __forceinline__ void gemm_phase(LAS unsigned char* lds, const Gemm g, const Sched& S, const Epi& E) {
;     ...
;             PG8_WAIT_L(0); PG8_BAR; PG8_MMA(0, 0, At, B0); PG8_MMA(0, 1, At, B1); PG8_BAR; PG8_SCHED;
;             PG8_LDA(At, 0, 1); PG8_STAGE(PG8_SB(0, 0), b2, voffB); PG8_STAGE(PG8_SB(0, 1), b2 + hstepB, voffB); PG8_STAGE(PG8_SA(0, 0), a2, voffA);
;             if constexpr (Epi::NSTORES > 0) PG8_WAIT_RELAX(rflag, 8 + Epi::NSTORES); else PG8_WAIT_V(8);
;             PG8_WAIT_L(0); PG8_BAR; PG8_MMA(1, 0, At, B0); PG8_MMA(1, 1, At, B1); PG8_BAR; PG8_SCHED;
;             PG8_LDB(B0, 1, 0); PG8_LDB(B1, 1, 1); PG8_SCHED; PG8_LDA(At, 1, 0); PG8_STAGE(PG8_SA(0, 1), a2 + hstepA, voffA);
;             PG8_WAIT_V(8); PG8_WAIT_L(0); PG8_BAR; PG8_MMA(0, 0, At, B0); PG8_MMA(0, 1, At, B1); PG8_BAR; PG8_SCHED;
	s_setprio 1
	s_waitcnt lgkmcnt(0)
	v_mfma_f32_16x16x32_bf16 v[66:69], v[150:153], v[182:185], v[66:69]
	v_mfma_f32_16x16x32_bf16 v[62:65], v[158:161], v[182:185], v[62:65]
	v_mfma_f32_16x16x32_bf16 v[50:53], v[150:153], v[190:193], v[50:53]
	v_mfma_f32_16x16x32_bf16 v[46:49], v[158:161], v[190:193], v[46:49]
	v_mfma_f32_16x16x32_bf16 v[34:37], v[150:153], v[206:209], v[34:37]
	v_mfma_f32_16x16x32_bf16 v[30:33], v[158:161], v[206:209], v[30:33]
	v_mfma_f32_16x16x32_bf16 v[18:21], v[150:153], v[228:231], v[18:21]
	v_mfma_f32_16x16x32_bf16 v[14:17], v[158:161], v[228:231], v[14:17]
	v_mfma_f32_16x16x32_bf16 v[66:69], v[154:157], v[186:189], v[66:69]
	v_mfma_f32_16x16x32_bf16 v[62:65], v[162:165], v[186:189], v[62:65]
	v_mfma_f32_16x16x32_bf16 v[50:53], v[154:157], v[194:197], v[50:53]
	v_mfma_f32_16x16x32_bf16 v[46:49], v[162:165], v[194:197], v[46:49]
	v_mfma_f32_16x16x32_bf16 v[34:37], v[154:157], v[224:227], v[34:37]
	v_mfma_f32_16x16x32_bf16 v[30:33], v[162:165], v[224:227], v[30:33]
	v_mfma_f32_16x16x32_bf16 v[18:21], v[154:157], v[232:235], v[18:21]
	v_mfma_f32_16x16x32_bf16 v[14:17], v[162:165], v[232:235], v[14:17]
	s_setprio 0
	s_setprio 1
	v_mfma_f32_16x16x32_bf16 v[58:61], v[166:169], v[182:185], v[58:61]
	v_mfma_f32_16x16x32_bf16 v[54:57], v[174:177], v[182:185], v[54:57]
	v_mfma_f32_16x16x32_bf16 v[42:45], v[166:169], v[190:193], v[42:45]
	v_mfma_f32_16x16x32_bf16 v[38:41], v[174:177], v[190:193], v[38:41]
	v_mfma_f32_16x16x32_bf16 v[26:29], v[166:169], v[206:209], v[26:29]
	v_mfma_f32_16x16x32_bf16 v[22:25], v[174:177], v[206:209], v[22:25]
	v_mfma_f32_16x16x32_bf16 v[10:13], v[166:169], v[228:231], v[10:13]
	v_mfma_f32_16x16x32_bf16 v[4:7], v[174:177], v[228:231], v[6:9]
	v_mfma_f32_16x16x32_bf16 v[58:61], v[170:173], v[186:189], v[58:61]
	v_mfma_f32_16x16x32_bf16 v[54:57], v[178:181], v[186:189], v[54:57]
	v_mfma_f32_16x16x32_bf16 v[42:45], v[170:173], v[194:197], v[42:45]
	v_mfma_f32_16x16x32_bf16 v[38:41], v[178:181], v[194:197], v[38:41]
	v_mfma_f32_16x16x32_bf16 v[26:29], v[170:173], v[224:227], v[26:29]
	v_mfma_f32_16x16x32_bf16 v[22:25], v[178:181], v[224:227], v[22:25]
	v_mfma_f32_16x16x32_bf16 v[10:13], v[170:173], v[232:235], v[10:13]
	v_mfma_f32_16x16x32_bf16 v[4:7], v[178:181], v[232:235], v[4:7]
	s_setprio 0
	s_barrier
	s_add_i32 s68, 0, 0x18000
	s_add_i32 s69, 0, 0x1c000
	ds_read_b128 v[150:153], v147 offset:32768
	ds_read_b128 v[154:157], v239 offset:32768
	ds_read_b128 v[158:161], v147 offset:34816
	ds_read_b128 v[162:165], v239 offset:34816
	ds_read_b128 v[166:169], v147 offset:49152
	ds_read_b128 v[170:173], v239 offset:49152
	ds_read_b128 v[174:177], v147 offset:51200
	ds_read_b128 v[178:181], v239 offset:51200
	s_add_u32 s50, s50, 0x40000
	s_addc_u32 s51, s51, 0
	s_mov_b32 m0, s54
	ds_read_b128 v[182:185], v148 offset:32768
	ds_read_b128 v[186:189], v238 offset:32768
	ds_read_b128 v[190:193], v148 offset:34816
	ds_read_b128 v[194:197], v238 offset:34816
	ds_read_b128 v[206:209], v148 offset:36864
	ds_read_b128 v[224:227], v238 offset:36864
	ds_read_b128 v[228:231], v148 offset:38912
	ds_read_b128 v[232:235], v238 offset:38912
	s_add_u32 s100, s50, 0xfffc0000
	s_addc_u32 s101, s51, -1
	s_mov_b32 m0, s52
	s_nop 0
	global_load_lds_dwordx4 v140, s[100:101]
	s_mov_b32 m0, s53
	s_nop 0
	global_load_lds_dwordx4 v136, s[100:101]
	s_mov_b32 m0, s54
	s_nop 0
	global_load_lds_dwordx4 v140, s[50:51]
	s_mov_b32 m0, s55
	s_nop 0
	global_load_lds_dwordx4 v136, s[50:51]
	s_waitcnt vmcnt(8)
	s_waitcnt lgkmcnt(0)
	s_barrier
; #define PG8_STAGE(bufoff, gbase, voff) do { _Pragma("unroll") for (int _i = 0; _i < 2; ++_i) \
;         __builtin_amdgcn_global_load_lds((const unsigned*)((const char*)(gbase) + (voff)[_i]), (LAS unsigned*)(lds + (bufoff) + ldsw + _i * 8192), 16, 0, 0); } while (0)
; #define PG8_LDA(dst, b, h) do { _Pragma("unroll") for (int m = 0; m < 4; ++m) _Pragma("unroll") for (int k = 0; k < 2; ++k) dst[m][k] = *(const LAS bf16x8*)(lds + PG8_SA(b, h) + aoff + m * 2048 + k * 1024); } while (0)
; #define PG8_LDB(dst, b, h) do { _Pragma("unroll") for (int n = 0; n < 2; ++n) _Pragma("unroll") for (int k = 0; k < 2; ++k) dst[n][k] = *(const LAS bf16x8*)(lds + PG8_SB(b, h) + boff + n * 2048 + k * 1024); } while (0)
; #define PG8_MMA(ai, bj, At, Bt) do { __builtin_amdgcn_s_setprio(1); _Pragma("unroll") for (int m = 0; m < 4; ++m) _Pragma("unroll") for (int n = 0; n < 2; ++n) _Pragma("unroll") for (int k = 0; k < 2; ++k) \
;         acc[ai][bj][m][n] = __builtin_amdgcn_mfma_f32_16x16x32_bf16(Bt[n][k], At[m][k], acc[ai][bj][m][n], 0, 0, 0); __builtin_amdgcn_s_setprio(0); } while (0)
; #define PG8_WAIT_V(n) asm volatile("s_waitcnt vmcnt(" #n ")" ::: "memory")
; #define PG8_WAIT_L(n) asm volatile("s_waitcnt lgkmcnt(" #n ")" ::: "memory")
; #define PG8_BAR __builtin_amdgcn_s_barrier()
; #define PG8_SCHED __builtin_amdgcn_sched_barrier(0)
; template <class Epi, bool ALIGN_EPI = true>
; __device__ __forceinline__ void gemm_phase(LAS unsigned char* lds, const Gemm g, const Sched& S, const Epi& E) {
;     ...
;             PG8_LDB(B0, 1, 0); PG8_LDB(B1, 1, 1); PG8_SCHED; PG8_LDA(At, 1, 0); PG8_STAGE(PG8_SA(0, 1), a2 + hstepA, voffA);
;             PG8_WAIT_V(8); PG8_WAIT_L(0); PG8_BAR; PG8_MMA(0, 0, At, B0); PG8_MMA(0, 1, At, B1); PG8_BAR; PG8_SCHED;
;             PG8_LDA(At, 1, 1); PG8_STAGE(PG8_SB(1, 0), b3, voffB); PG8_STAGE(PG8_SB(1, 1), b3 + hstepB, voffB); PG8_STAGE(PG8_SA(1, 0), a3, voffA);
;             PG8_WAIT_V(8); PG8_WAIT_L(0); PG8_BAR; PG8_MMA(1, 0, At, B0); PG8_MMA(1, 1, At, B1); PG8_BAR; PG8_SCHED;
;         }
	s_setprio 1
	s_waitcnt lgkmcnt(0)
	v_mfma_f32_16x16x32_bf16 v[130:133], v[150:153], v[182:185], v[130:133]
	v_mfma_f32_16x16x32_bf16 v[126:129], v[158:161], v[182:185], v[126:129]
	v_mfma_f32_16x16x32_bf16 v[114:117], v[150:153], v[190:193], v[114:117]
	v_mfma_f32_16x16x32_bf16 v[110:113], v[158:161], v[190:193], v[110:113]
	v_mfma_f32_16x16x32_bf16 v[98:101], v[150:153], v[206:209], v[98:101]
	v_mfma_f32_16x16x32_bf16 v[94:97], v[158:161], v[206:209], v[94:97]
	v_mfma_f32_16x16x32_bf16 v[82:85], v[150:153], v[228:231], v[82:85]
	v_mfma_f32_16x16x32_bf16 v[78:81], v[158:161], v[228:231], v[78:81]
	v_mfma_f32_16x16x32_bf16 v[130:133], v[154:157], v[186:189], v[130:133]
	v_mfma_f32_16x16x32_bf16 v[126:129], v[162:165], v[186:189], v[126:129]
	v_mfma_f32_16x16x32_bf16 v[114:117], v[154:157], v[194:197], v[114:117]
	v_mfma_f32_16x16x32_bf16 v[110:113], v[162:165], v[194:197], v[110:113]
	v_mfma_f32_16x16x32_bf16 v[98:101], v[154:157], v[224:227], v[98:101]
	v_mfma_f32_16x16x32_bf16 v[94:97], v[162:165], v[224:227], v[94:97]
	v_mfma_f32_16x16x32_bf16 v[82:85], v[154:157], v[232:235], v[82:85]
	v_mfma_f32_16x16x32_bf16 v[78:81], v[162:165], v[232:235], v[78:81]
	s_setprio 0
	s_setprio 1
	v_mfma_f32_16x16x32_bf16 v[122:125], v[166:169], v[182:185], v[122:125]
	v_mfma_f32_16x16x32_bf16 v[118:121], v[174:177], v[182:185], v[118:121]
	v_mfma_f32_16x16x32_bf16 v[106:109], v[166:169], v[190:193], v[106:109]
	v_mfma_f32_16x16x32_bf16 v[102:105], v[174:177], v[190:193], v[102:105]
	v_mfma_f32_16x16x32_bf16 v[90:93], v[166:169], v[206:209], v[90:93]
	v_mfma_f32_16x16x32_bf16 v[86:89], v[174:177], v[206:209], v[86:89]
	v_mfma_f32_16x16x32_bf16 v[74:77], v[166:169], v[228:231], v[74:77]
	v_mfma_f32_16x16x32_bf16 v[70:73], v[174:177], v[228:231], v[70:73]
	v_mfma_f32_16x16x32_bf16 v[122:125], v[170:173], v[186:189], v[122:125]
	v_mfma_f32_16x16x32_bf16 v[118:121], v[178:181], v[186:189], v[118:121]
	v_mfma_f32_16x16x32_bf16 v[106:109], v[170:173], v[194:197], v[106:109]
	v_mfma_f32_16x16x32_bf16 v[102:105], v[178:181], v[194:197], v[102:105]
	v_mfma_f32_16x16x32_bf16 v[90:93], v[170:173], v[224:227], v[90:93]
	v_mfma_f32_16x16x32_bf16 v[86:89], v[178:181], v[224:227], v[86:89]
	v_mfma_f32_16x16x32_bf16 v[74:77], v[170:173], v[232:235], v[74:77]
	v_mfma_f32_16x16x32_bf16 v[70:73], v[178:181], v[232:235], v[70:73]
	s_setprio 0
	s_barrier
	s_add_u32 s100, s48, 0x80
	s_addc_u32 s101, s49, 0
	s_add_i32 s50, s68, s37
	s_mov_b32 m0, s50
	ds_read_b128 v[182:185], v148 offset:49152
	ds_read_b128 v[186:189], v238 offset:49152
	ds_read_b128 v[190:193], v148 offset:51200
	ds_read_b128 v[194:197], v238 offset:51200
	ds_read_b128 v[206:209], v148 offset:53248
	ds_read_b128 v[224:227], v238 offset:53248
	ds_read_b128 v[228:231], v148 offset:55296
	ds_read_b128 v[232:235], v238 offset:55296
	global_load_lds_dwordx4 v138, s[100:101]
	s_add_i32 m0, s50, 0x2000
	s_add_u32 s48, s48, 0x40080
	s_addc_u32 s49, s49, 0
	s_add_i32 s50, s69, s37
	global_load_lds_dwordx4 v134, s[100:101]
	s_mov_b32 m0, s50
	s_nop 0
	global_load_lds_dwordx4 v138, s[48:49]
	s_add_i32 m0, s50, 0x2000
	s_nop 0
	global_load_lds_dwordx4 v134, s[48:49]
	s_waitcnt vmcnt(6)
	s_waitcnt lgkmcnt(0)
	s_barrier
	s_setprio 1
	s_waitcnt lgkmcnt(0)
	v_mfma_f32_16x16x32_bf16 v[66:69], v[150:153], v[182:185], v[66:69]
	v_mfma_f32_16x16x32_bf16 v[62:65], v[158:161], v[182:185], v[62:65]
	v_mfma_f32_16x16x32_bf16 v[50:53], v[150:153], v[190:193], v[50:53]
	v_mfma_f32_16x16x32_bf16 v[46:49], v[158:161], v[190:193], v[46:49]
	v_mfma_f32_16x16x32_bf16 v[34:37], v[150:153], v[206:209], v[34:37]
	v_mfma_f32_16x16x32_bf16 v[30:33], v[158:161], v[206:209], v[30:33]
	v_mfma_f32_16x16x32_bf16 v[18:21], v[150:153], v[228:231], v[18:21]
	v_mfma_f32_16x16x32_bf16 v[14:17], v[158:161], v[228:231], v[14:17]
	v_mfma_f32_16x16x32_bf16 v[66:69], v[154:157], v[186:189], v[66:69]
	v_mfma_f32_16x16x32_bf16 v[62:65], v[162:165], v[186:189], v[62:65]
	v_mfma_f32_16x16x32_bf16 v[50:53], v[154:157], v[194:197], v[50:53]
	v_mfma_f32_16x16x32_bf16 v[46:49], v[162:165], v[194:197], v[46:49]
	v_mfma_f32_16x16x32_bf16 v[34:37], v[154:157], v[224:227], v[34:37]
	v_mfma_f32_16x16x32_bf16 v[30:33], v[162:165], v[224:227], v[30:33]
	v_mfma_f32_16x16x32_bf16 v[18:21], v[154:157], v[232:235], v[18:21]
	v_mfma_f32_16x16x32_bf16 v[14:17], v[162:165], v[232:235], v[14:17]
	s_setprio 0
	s_setprio 1
	v_mfma_f32_16x16x32_bf16 v[58:61], v[166:169], v[182:185], v[58:61]
	v_mfma_f32_16x16x32_bf16 v[54:57], v[174:177], v[182:185], v[54:57]
	v_mfma_f32_16x16x32_bf16 v[42:45], v[166:169], v[190:193], v[42:45]
	v_mfma_f32_16x16x32_bf16 v[38:41], v[174:177], v[190:193], v[38:41]
	v_mfma_f32_16x16x32_bf16 v[26:29], v[166:169], v[206:209], v[26:29]
	v_mfma_f32_16x16x32_bf16 v[22:25], v[174:177], v[206:209], v[22:25]
	v_mfma_f32_16x16x32_bf16 v[8:11], v[166:169], v[228:231], v[10:13]
	v_mfma_f32_16x16x32_bf16 v[4:7], v[174:177], v[228:231], v[4:7]
	v_mfma_f32_16x16x32_bf16 v[58:61], v[170:173], v[186:189], v[58:61]
	v_mfma_f32_16x16x32_bf16 v[54:57], v[178:181], v[186:189], v[54:57]
	v_mfma_f32_16x16x32_bf16 v[42:45], v[170:173], v[194:197], v[42:45]
	v_mfma_f32_16x16x32_bf16 v[38:41], v[178:181], v[194:197], v[38:41]
	v_mfma_f32_16x16x32_bf16 v[26:29], v[170:173], v[224:227], v[26:29]
	v_mfma_f32_16x16x32_bf16 v[22:25], v[178:181], v[224:227], v[22:25]
	v_mfma_f32_16x16x32_bf16 v[10:13], v[170:173], v[232:235], v[8:11]
	v_mfma_f32_16x16x32_bf16 v[6:9], v[178:181], v[232:235], v[4:7]
	s_setprio 0
	s_barrier
	s_add_u32 s46, s46, 0x100
	s_addc_u32 s47, s47, 0
	s_add_u32 s65, s65, 0x100
	s_addc_u32 s66, s66, 0
	s_cmp_ge_i32 s67, s56
	s_mov_b32 s48, s67
	s_cbranch_scc0 .LBB0_1929

; #define PG8_STAGE(bufoff, gbase, voff) do { _Pragma("unroll") for (int _i = 0; _i < 2; ++_i) \
;         __builtin_amdgcn_global_load_lds((const unsigned*)((const char*)(gbase) + (voff)[_i]), (LAS unsigned*)(lds + (bufoff) + ldsw + _i * 8192), 16, 0, 0); } while (0)
; #define PG8_WAIT_V(n) asm volatile("s_waitcnt vmcnt(" #n ")" ::: "memory")
; #define PG8_BAR __builtin_amdgcn_s_barrier()
; template <class Epi, bool ALIGN_EPI = true>
; __device__ __forceinline__ void gemm_phase(LAS unsigned char* lds, const Gemm g, const Sched& S, const Epi& E) {
;     ...
;     for (int i = 0; i < 2; ++i) { int R, C; stage_rc(tid * 16 + i * 8192, R, C); const int Rb = (R & ~31) + perm32(R & 31);
;         voffA[i] = (unsigned)(R * g.lda + C) * 2u; voffB[i] = (unsigned)(Rb * g.ldb + C) * 2u; }
;     const size_t kstep = (size_t)(BK * 2);
;     const size_t hstepA = (size_t)HALF * g.lda * 2, hstepB = (size_t)HALF * g.ldb * 2;
;     const unsigned ldsw = (unsigned)wid * 1024u;
;     const int aoff = lds_byte(wr * 64 + fr, fq * 8), boff = lds_byte(wc * 32 + fr, fq * 8);
;     ...
;     const char* cA = (const char*)g.A + cur.aoff; const char* cB = (const char*)g.Bt + cur.boff;
;     PG8_STAGE(PG8_SB(0, 0), cB, voffB); PG8_STAGE(PG8_SB(0, 1), cB + hstepB, voffB); PG8_STAGE(PG8_SA(0, 0), cA, voffA); PG8_STAGE(PG8_SA(0, 1), cA + hstepA, voffA);
;     if (wr == 1) PG8_BAR;
;     PG8_WAIT_V(2); PG8_BAR;
.LBB0_2013:
	s_or_b64 exec, exec, s[4:5]
	v_bfe_i32 v5, v12, 27, 1
	v_lshlrev_b32_e32 v4, 4, v12
	v_lshrrev_b32_e32 v5, 22, v5
	v_add_u32_e32 v5, v4, v5
	v_and_b32_e32 v5, 0xfffffc00, v5
	v_sub_u32_e32 v5, v4, v5
	v_lshrrev_b32_e32 v6, 4, v5
	v_ashrrev_i32_e32 v2, 31, v12
	v_bitop3_b32 v5, v6, v5, 32 bitop3:0x6c
	v_lshrrev_b32_e32 v2, 26, v2
	v_ashrrev_i32_e32 v7, 31, v5
	v_add_u32_e32 v2, v12, v2
	v_lshrrev_b32_e32 v7, 26, v7
	v_ashrrev_i32_e32 v2, 6, v2
	v_add_u32_e32 v7, v5, v7
	s_add_u32 s30, s54, s0
	v_lshlrev_b32_e32 v6, 3, v2
	v_ashrrev_i32_e32 v13, 6, v7
	v_and_b32_e32 v7, 0xc0, v7
	s_addc_u32 s31, s55, s1
	v_readlane_b32 s0, v242, 27
	v_and_b32_e32 v6, -16, v6
	v_sub_u32_e32 v5, v5, v7
	s_add_u32 s33, s0, 0x4500000
	v_readlane_b32 s0, v242, 28
	v_add_u32_e32 v6, v13, v6
	v_ashrrev_i16_sdwa v5, v213, sext(v5) dst_sel:DWORD dst_unused:UNUSED_PAD src0_sel:DWORD src1_sel:BYTE_0
	s_addc_u32 s34, s0, 0
	v_lshlrev_b32_e32 v8, 5, v2
	v_bfe_i32 v14, v5, 0, 16
	v_lshlrev_b32_e32 v5, 1, v6
	v_lshrrev_b32_e32 v7, 2, v6
	v_and_b32_e32 v9, 3, v13
	s_mov_b32 s0, 0xfffe0
	v_and_b32_e32 v8, 32, v8
	v_and_b32_e32 v5, 24, v5
	v_and_b32_e32 v7, 4, v7
	v_and_or_b32 v9, v6, s0, v9
	v_or3_b32 v5, v9, v7, v5
	v_add_lshl_u32 v7, v8, v14, 1
	v_add_u32_e32 v4, 0x2000, v4
	v_lshl_add_u32 v136, v5, 12, v7
	v_lshrrev_b32_e32 v247, 3, v0
	v_xor_b32_e32 v247, v247, v0
	v_and_b32_e32 v247, 7, v247
	v_lshl_add_u32 v136, v247, 4, v136
	v_and_b32_e32 v247, 64, v0
	v_sub_u32_e32 v136, v136, v247
	v_lshrrev_b32_e32 v247, 4, v0
	v_and_b32_e32 v247, 2, v247
	v_xor_b32_e32 v247, v247, v0
	v_and_b32_e32 v247, 3, v247
	v_lshlrev_b32_e32 v247, 4, v247
	v_sub_u32_e32 v136, v136, v247
	v_and_b32_e32 v247, 64, v0
	v_mul_u32_u24_e32 v247, 0x400, v247
	v_add_u32_e32 v136, v136, v247
	v_and_b32_e32 v247, 32, v0
	v_mul_u32_u24_e32 v247, 0x400, v247
	v_sub_u32_e32 v136, v136, v247
	v_and_b32_e32 v247, 16, v0
	v_mul_u32_u24_e32 v247, 0x600, v247
	v_sub_u32_e32 v136, v136, v247
	v_and_b32_e32 v247, 8, v0
	v_mul_u32_u24_e32 v247, 0x200, v247
	v_sub_u32_e32 v136, v136, v247
	v_and_b32_e32 v247, 4, v0
	v_mul_u32_u24_e32 v247, 0x400, v247
	v_sub_u32_e32 v136, v136, v247
	v_ashrrev_i32_e32 v5, 31, v4
	v_lshrrev_b32_e32 v5, 22, v5
	v_add_u32_e32 v5, v4, v5
	v_ashrrev_i32_e32 v15, 10, v5
	v_mul_i32_i24_e32 v5, 0x400, v15
	v_sub_u32_e32 v4, v4, v5
	v_lshrrev_b32_e32 v5, 4, v4
	v_bitop3_b32 v4, v5, v4, 32 bitop3:0x6c
	v_lshl_add_u32 v134, v6, 12, v7
	v_lshrrev_b32_e32 v247, 3, v0
	v_xor_b32_e32 v247, v247, v0
	v_and_b32_e32 v247, 7, v247
	v_lshl_add_u32 v134, v247, 4, v134
	v_and_b32_e32 v247, 64, v0
	v_sub_u32_e32 v134, v134, v247
	v_lshrrev_b32_e32 v247, 4, v0
	v_and_b32_e32 v247, 2, v247
	v_xor_b32_e32 v247, v247, v0
	v_and_b32_e32 v247, 3, v247
	v_lshlrev_b32_e32 v247, 4, v247
	v_sub_u32_e32 v134, v134, v247
	v_bfe_u32 v247, v0, 2, 4
	v_add_u32_e32 v247, 1, v247
	v_lshrrev_b32_e32 v247, 1, v247
	v_mul_u32_u24_e32 v247, 0x1000, v247
	v_sub_u32_e32 v134, v134, v247
	v_and_b32_e32 v247, 64, v0
	v_mul_u32_u24_e32 v247, 0x200, v247
	v_add_u32_e32 v134, v134, v247
	v_ashrrev_i32_e32 v6, 31, v4
	v_lshrrev_b32_e32 v6, 26, v6
	v_lshlrev_b32_e32 v5, 3, v15
	v_add_u32_e32 v6, v4, v6
	v_and_b32_e32 v5, -16, v5
	v_ashrrev_i32_e32 v16, 6, v6
	s_ashr_i32 s17, s18, 6
	v_add_u32_e32 v5, v16, v5
	v_and_b32_e32 v6, 0xc0, v6
	v_and_b32_e32 v8, 3, v16
	v_sub_u32_e32 v4, v4, v6
	v_and_or_b32 v8, v5, s0, v8
	s_ashr_i32 s19, s18, 8
	s_lshl_b32 s35, s17, 10
	v_readlane_b32 s0, v243, 57
	v_ashrrev_i16_sdwa v4, v213, sext(v4) dst_sel:DWORD dst_unused:UNUSED_PAD src0_sel:DWORD src1_sel:BYTE_0
	v_readlane_b32 s1, v243, 58
	s_add_u32 s0, s33, s0
	v_lshlrev_b32_e32 v7, 5, v15
	v_bfe_i32 v17, v4, 0, 16
	v_lshlrev_b32_e32 v4, 1, v5
	v_lshrrev_b32_e32 v6, 2, v5
	s_addc_u32 s1, s34, s1
	s_add_i32 s36, s35, 0
	v_and_b32_e32 v7, 32, v7
	v_and_b32_e32 v4, 24, v4
	v_and_b32_e32 v6, 4, v6
	s_waitcnt lgkmcnt(0)
	s_barrier
	s_add_i32 m0, s36, 0x10000
	v_or3_b32 v4, v8, v6, v4
	v_add_lshl_u32 v6, v7, v17, 1
	global_load_lds_dwordx4 v136, s[0:1]
	s_add_i32 m0, s36, 0x12000
	v_lshl_add_u32 v140, v4, 12, v6
	v_lshrrev_b32_e32 v247, 3, v0
	v_xor_b32_e32 v247, v247, v0
	v_and_b32_e32 v247, 7, v247
	v_lshl_add_u32 v140, v247, 4, v140
	v_and_b32_e32 v247, 64, v0
	v_sub_u32_e32 v140, v140, v247
	v_lshrrev_b32_e32 v247, 4, v0
	v_and_b32_e32 v247, 2, v247
	v_xor_b32_e32 v247, v247, v0
	v_and_b32_e32 v247, 3, v247
	v_lshlrev_b32_e32 v247, 4, v247
	v_sub_u32_e32 v140, v140, v247
	v_and_b32_e32 v247, 64, v0
	v_mul_u32_u24_e32 v247, 0x400, v247
	v_add_u32_e32 v140, v140, v247
	v_and_b32_e32 v247, 32, v0
	v_mul_u32_u24_e32 v247, 0x400, v247
	v_sub_u32_e32 v140, v140, v247
	v_and_b32_e32 v247, 16, v0
	v_mul_u32_u24_e32 v247, 0x600, v247
	v_sub_u32_e32 v140, v140, v247
	v_and_b32_e32 v247, 8, v0
	v_mul_u32_u24_e32 v247, 0x200, v247
	v_sub_u32_e32 v140, v140, v247
	v_and_b32_e32 v247, 4, v0
	v_mul_u32_u24_e32 v247, 0x400, v247
	v_sub_u32_e32 v140, v140, v247
	s_add_u32 s4, s0, 0x80000
	global_load_lds_dwordx4 v140, s[0:1]
	s_addc_u32 s5, s1, 0
	s_add_i32 m0, s36, 0x14000
	v_lshl_add_u32 v138, v5, 12, v6
	v_lshrrev_b32_e32 v247, 3, v0
	v_xor_b32_e32 v247, v247, v0
	v_and_b32_e32 v247, 7, v247
	v_lshl_add_u32 v138, v247, 4, v138
	v_and_b32_e32 v247, 64, v0
	v_sub_u32_e32 v138, v138, v247
	v_lshrrev_b32_e32 v247, 4, v0
	v_and_b32_e32 v247, 2, v247
	v_xor_b32_e32 v247, v247, v0
	v_and_b32_e32 v247, 3, v247
	v_lshlrev_b32_e32 v247, 4, v247
	v_sub_u32_e32 v138, v138, v247
	v_bfe_u32 v247, v0, 2, 4
	v_add_u32_e32 v247, 1, v247
	v_lshrrev_b32_e32 v247, 1, v247
	v_mul_u32_u24_e32 v247, 0x1000, v247
	v_sub_u32_e32 v138, v138, v247
	v_and_b32_e32 v247, 64, v0
	v_mul_u32_u24_e32 v247, 0x200, v247
	v_add_u32_e32 v138, v138, v247
	global_load_lds_dwordx4 v136, s[4:5]
	s_add_i32 m0, s36, 0x16000
	v_mov_b32_e32 v137, v3
	global_load_lds_dwordx4 v140, s[4:5]
	v_readlane_b32 s4, v243, 53
	v_readlane_b32 s5, v243, 54
	s_add_u32 s6, s30, s4
	s_addc_u32 s7, s31, s5
	s_add_i32 s37, s36, 0x2000
	s_mov_b32 m0, s36
	s_add_u32 s4, s6, 0x80000
	global_load_lds_dwordx4 v134, s[6:7]
	s_mov_b32 m0, s37
	s_addc_u32 s5, s7, 0
	s_add_i32 s50, s36, 0x4000
	global_load_lds_dwordx4 v138, s[6:7]
	s_mov_b32 m0, s50
	s_add_i32 s51, s36, 0x6000
	global_load_lds_dwordx4 v134, s[4:5]
	s_mov_b32 m0, s51
	v_mov_b32_e32 v141, v3
	global_load_lds_dwordx4 v138, s[4:5]
	v_mov_b32_e32 v135, v3
	v_mov_b32_e32 v139, v3
	s_cmp_eq_u32 s19, 1
	v_lshl_add_u64 v[10:11], s[0:1], 0, v[136:137]
	v_lshl_add_u64 v[8:9], s[0:1], 0, v[140:141]
	v_lshl_add_u64 v[4:5], s[6:7], 0, v[134:135]
	s_cselect_b64 s[4:5], -1, 0
	s_cmp_lg_u32 s19, 1
	v_lshl_add_u64 v[6:7], s[6:7], 0, v[138:139]
	s_cbranch_scc1 .LBB0_2015
	s_barrier
; #define LAS __attribute__((address_space(3)))
; #define PG8_WAIT_V(n) asm volatile("s_waitcnt vmcnt(" #n ")" ::: "memory")
; #define PG8_BAR __builtin_amdgcn_s_barrier()
; template <class Epi, bool ALIGN_EPI = true>
; __device__ __forceinline__ void gemm_phase(LAS unsigned char* lds, const Gemm g, const Sched& S, const Epi& E) {
;     ...
;     for (int i = 0; i < 2; ++i) { int R, C; stage_rc(tid * 16 + i * 8192, R, C); const int Rb = (R & ~31) + perm32(R & 31);
;         voffA[i] = (unsigned)(R * g.lda + C) * 2u; voffB[i] = (unsigned)(Rb * g.ldb + C) * 2u; }
;     const size_t kstep = (size_t)(BK * 2);
;     const size_t hstepA = (size_t)HALF * g.lda * 2, hstepB = (size_t)HALF * g.ldb * 2;
;     const unsigned ldsw = (unsigned)wid * 1024u;
;     const int aoff = lds_byte(wr * 64 + fr, fq * 8), boff = lds_byte(wc * 32 + fr, fq * 8);
;     ...
;     Unit cur, nxt; int ui = 0;
;     if (!S.next(0, cur)) return;
;     if constexpr (Epi::USES_RSTD) {
;         LAS float* T = (LAS float*)(lds + RSTD_OFF);
; #pragma unroll
;         for (int k = 0; k < RSTD_UNITS * 256 / 512; ++k) { const int idx = tid + 512 * k; Unit uu;
;             if (S.next(idx >> 8, uu)) { const float* sp = E.SS + uu.pm * BM + (idx & 255); float ssum = 0.f;
; #pragma unroll
;                 for (int j = 0; j < 8; ++j) ssum += sp[(size_t)j * MROWS];
;                 T[idx] = __builtin_amdgcn_rsqf(ssum * (1.0f / DM) + EPS); } }
;         asm volatile("s_waitcnt lgkmcnt(0)" ::: "memory"); __builtin_amdgcn_s_barrier(); asm volatile("" ::: "memory");
;     }
;     f32x4 acc[2][2][4][2];
; #pragma unroll
;     for (int a = 0; a < 2; ++a)
; #pragma unroll
;         for (int b = 0; b < 2; ++b)
; #pragma unroll
;             for (int m = 0; m < 4; ++m)
; #pragma unroll
;                 for (int n = 0; n < 2; ++n) acc[a][b][m][n] = (f32x4){0.f, 0.f, 0.f, 0.f};
;     bf16x8 At[4][2], B0[2][2], B1[2][2];
;     const char* cA = (const char*)g.A + cur.aoff; const char* cB = (const char*)g.Bt + cur.boff;
;     PG8_STAGE(PG8_SB(0, 0), cB, voffB); PG8_STAGE(PG8_SB(0, 1), cB + hstepB, voffB); PG8_STAGE(PG8_SA(0, 0), cA, voffA); PG8_STAGE(PG8_SA(0, 1), cA + hstepA, voffA);
;     if (wr == 1) PG8_BAR;
;     PG8_WAIT_V(2); PG8_BAR;
;     PG8_STAGE(PG8_SB(1, 0), cB + kstep, voffB); PG8_STAGE(PG8_SA(1, 0), cA + kstep, voffA); PG8_STAGE(PG8_SB(1, 1), cB + hstepB + kstep, voffB);
;     PG8_WAIT_V(6); PG8_BAR;
.LBB0_2015:
	s_add_u32 s52, s54, s14
	s_addc_u32 s53, s55, s15
	s_ashr_i32 s14, s16, 31
	s_lshr_b32 s14, s14, 26
	s_and_b32 s20, s17, 3
	s_add_i32 s14, s16, s14
	s_add_i32 m0, s36, 0x18000
	v_lshl_add_u64 v[10:11], v[10:11], 0, s[8:9]
	s_ashr_i32 s54, s14, 6
	s_lshl_b32 s55, s19, 6
	s_lshl_b32 s17, s19, 13
	s_lshl_b32 s19, s20, 12
	s_waitcnt vmcnt(2)
	s_barrier
	global_load_lds_dwordx4 v[10:11], off
	v_lshl_add_u64 v[8:9], v[8:9], 0, s[8:9]
	s_add_i32 m0, s36, 0x1a000
	s_add_i32 s56, s36, 0x8000
	s_add_i32 s57, s36, 0xa000
	global_load_lds_dwordx4 v[8:9], off
	v_lshl_add_u64 v[4:5], v[4:5], 0, s[8:9]
	s_mov_b32 m0, s56
	s_add_u32 s14, s0, 0x80080
	global_load_lds_dwordx4 v[4:5], off
	v_lshl_add_u64 v[4:5], v[6:7], 0, s[8:9]
	s_mov_b32 m0, s57
	s_addc_u32 s15, s1, 0
	global_load_lds_dwordx4 v[4:5], off
	s_add_i32 m0, s36, 0x1c000
	v_lshl_add_u64 v[4:5], s[14:15], 0, v[136:137]
	global_load_lds_dwordx4 v[4:5], off
	v_lshl_add_u64 v[4:5], s[14:15], 0, v[140:141]
	s_add_i32 m0, s36, 0x1e000
	s_movk_i32 s10, 0x3c0
	global_load_lds_dwordx4 v[4:5], off
	v_and_b32_e32 v4, 48, v12
	v_lshlrev_b32_e32 v5, 6, v12
	v_and_or_b32 v4, v5, s10, v4
	v_lshlrev_b32_e32 v5, 2, v12
	v_and_b32_e32 v5, 32, v5
	v_bitop3_b32 v6, v4, s17, v5 bitop3:0xde
	v_bitop3_b32 v151, v4, s19, v5 bitop3:0xde
	v_bfe_u32 v151, v0, 4, 2
	v_xor_b32_e32 v151, v151, v0
	v_and_b32_e32 v151, 7, v151
	v_lshlrev_b32_e32 v151, 4, v151
	v_and_b32_e32 v247, 15, v0
	v_lshl_or_b32 v151, v247, 7, v151
	v_and_b32_e32 v247, 0xc0, v0
	v_lshl_or_b32 v151, v247, 6, v151
	v_or_b32_e32 v151, 0x10000, v151
	v_lshlrev_b32_e32 v4, 15, v2
	v_and_b32_e32 v4, 0xffff0000, v4
	s_cmp_gt_i32 s16, 63
	v_lshl_add_u32 v4, v13, 12, v4
	v_and_b32_e32 v2, 1, v2
	s_cselect_b64 s[14:15], -1, 0
	s_add_i32 s58, s54, -2
	v_lshl_or_b32 v2, v2, 6, v4
	s_cmpk_lt_u32 s18, 0x100
	v_lshl_add_u32 v142, v14, 1, v2
	v_lshrrev_b32_e32 v247, 3, v0
	v_xor_b32_e32 v247, v247, v0
	v_and_b32_e32 v247, 7, v247
	v_lshl_add_u32 v142, v247, 4, v142
	v_and_b32_e32 v247, 64, v0
	v_sub_u32_e32 v142, v142, v247
	v_lshrrev_b32_e32 v247, 4, v0
	v_and_b32_e32 v247, 2, v247
	v_xor_b32_e32 v247, v247, v0
	v_and_b32_e32 v247, 3, v247
	v_lshlrev_b32_e32 v247, 4, v247
	v_sub_u32_e32 v142, v142, v247
	v_bfe_u32 v247, v0, 2, 4
	v_add_u32_e32 v247, 1, v247
	v_lshrrev_b32_e32 v247, 1, v247
	v_mul_u32_u24_e32 v247, 0x1000, v247
	v_sub_u32_e32 v142, v142, v247
	v_and_b32_e32 v247, 64, v0
	v_mul_u32_u24_e32 v247, 0x200, v247
	v_add_u32_e32 v142, v142, v247
	v_lshlrev_b32_e32 v2, 15, v15
	s_cselect_b64 s[16:17], -1, 0
	s_and_b32 s18, s18, 0xffffff00
	v_and_b32_e32 v2, 0xffff0000, v2
	s_add_i32 s60, s18, 0
	v_lshl_add_u32 v2, v16, 12, v2
	v_and_b32_e32 v4, 1, v15
	v_readlane_b32 s18, v243, 55
	s_waitcnt vmcnt(6)
	v_lshl_or_b32 v2, v4, 6, v2
	v_mov_b32_e32 v4, v3
	v_mov_b32_e32 v5, v3
	v_readlane_b32 s19, v243, 56
	v_and_b32_e32 v150, 63, v12
	v_lshl_add_u32 v144, v17, 1, v2
	v_lshrrev_b32_e32 v247, 3, v0
	v_xor_b32_e32 v247, v247, v0
	v_and_b32_e32 v247, 7, v247
	v_lshl_add_u32 v144, v247, 4, v144
	v_and_b32_e32 v247, 64, v0
	v_sub_u32_e32 v144, v144, v247
	v_lshrrev_b32_e32 v247, 4, v0
	v_and_b32_e32 v247, 2, v247
	v_xor_b32_e32 v247, v247, v0
	v_and_b32_e32 v247, 3, v247
	v_lshlrev_b32_e32 v247, 4, v247
	v_sub_u32_e32 v144, v144, v247
	v_bfe_u32 v247, v0, 2, 4
	v_add_u32_e32 v247, 1, v247
	v_lshrrev_b32_e32 v247, 1, v247
	v_mul_u32_u24_e32 v247, 0x1000, v247
	v_sub_u32_e32 v144, v144, v247
	v_and_b32_e32 v247, 64, v0
	v_mul_u32_u24_e32 v247, 0x200, v247
	v_add_u32_e32 v144, v144, v247
	v_mov_b32_e32 v2, v3
	v_add_u32_e32 v152, 0, v6
	v_bfe_u32 v152, v0, 4, 2
	v_xor_b32_e32 v152, v152, v0
	v_and_b32_e32 v152, 7, v152
	v_lshlrev_b32_e32 v152, 4, v152
	v_and_b32_e32 v247, 15, v0
	v_lshl_or_b32 v152, v247, 7, v152
	v_and_b32_e32 v247, 0x100, v0
	v_lshl_or_b32 v152, v247, 5, v152
	v_mov_b64_e32 v[8:9], v[4:5]
	v_mov_b64_e32 v[12:13], v[4:5]
	v_mov_b64_e32 v[16:17], v[4:5]
	v_mov_b64_e32 v[20:21], v[4:5]
	v_mov_b64_e32 v[24:25], v[4:5]
	v_mov_b64_e32 v[28:29], v[4:5]
	v_mov_b64_e32 v[32:33], v[4:5]
	v_mov_b64_e32 v[36:37], v[4:5]
	v_mov_b64_e32 v[40:41], v[4:5]
	v_mov_b64_e32 v[44:45], v[4:5]
	v_mov_b64_e32 v[48:49], v[4:5]
	v_mov_b64_e32 v[52:53], v[4:5]
	v_mov_b64_e32 v[56:57], v[4:5]
	v_mov_b64_e32 v[60:61], v[4:5]
	v_mov_b64_e32 v[64:65], v[4:5]
	v_mov_b64_e32 v[68:69], v[4:5]
	v_mov_b64_e32 v[72:73], v[4:5]
	v_mov_b64_e32 v[76:77], v[4:5]
	v_mov_b64_e32 v[80:81], v[4:5]
	v_mov_b64_e32 v[84:85], v[4:5]
	v_mov_b64_e32 v[88:89], v[4:5]
	v_mov_b64_e32 v[92:93], v[4:5]
	v_mov_b64_e32 v[96:97], v[4:5]
	v_mov_b64_e32 v[100:101], v[4:5]
	v_mov_b64_e32 v[104:105], v[4:5]
	v_mov_b64_e32 v[108:109], v[4:5]
	v_mov_b64_e32 v[112:113], v[4:5]
	v_mov_b64_e32 v[116:117], v[4:5]
	v_mov_b64_e32 v[120:121], v[4:5]
	v_mov_b64_e32 v[124:125], v[4:5]
	v_mov_b64_e32 v[128:129], v[4:5]
	v_mov_b64_e32 v[132:133], v[4:5]
	s_mov_b32 s62, s18
	v_readlane_b32 s18, v243, 51
	s_lshl_b32 s59, s20, 6
	s_add_i32 s60, s60, 0x20000
	v_mov_b32_e32 v143, v3
	v_mov_b32_e32 v145, v3
	s_mov_b32 s61, 0
	v_mov_b64_e32 v[6:7], v[2:3]
	v_mov_b64_e32 v[10:11], v[2:3]
	v_mov_b64_e32 v[14:15], v[2:3]
	v_mov_b64_e32 v[18:19], v[2:3]
	v_mov_b64_e32 v[22:23], v[2:3]
	v_mov_b64_e32 v[26:27], v[2:3]
	v_mov_b64_e32 v[30:31], v[2:3]
	v_mov_b64_e32 v[34:35], v[2:3]
	v_mov_b64_e32 v[38:39], v[2:3]
	v_mov_b64_e32 v[42:43], v[2:3]
	v_mov_b64_e32 v[46:47], v[2:3]
	v_mov_b64_e32 v[50:51], v[2:3]
	v_mov_b64_e32 v[54:55], v[2:3]
	v_mov_b64_e32 v[58:59], v[2:3]
	v_mov_b64_e32 v[62:63], v[2:3]
	v_mov_b64_e32 v[66:67], v[2:3]
	v_mov_b64_e32 v[70:71], v[2:3]
	v_mov_b64_e32 v[74:75], v[2:3]
	v_mov_b64_e32 v[78:79], v[2:3]
	v_mov_b64_e32 v[82:83], v[2:3]
	v_mov_b64_e32 v[86:87], v[2:3]
	v_mov_b64_e32 v[90:91], v[2:3]
	v_mov_b64_e32 v[94:95], v[2:3]
	v_mov_b64_e32 v[98:99], v[2:3]
	v_mov_b64_e32 v[102:103], v[2:3]
	v_mov_b64_e32 v[106:107], v[2:3]
	v_mov_b64_e32 v[110:111], v[2:3]
	v_mov_b64_e32 v[114:115], v[2:3]
	v_mov_b64_e32 v[118:119], v[2:3]
	v_mov_b64_e32 v[122:123], v[2:3]
	v_mov_b64_e32 v[126:127], v[2:3]
	v_mov_b64_e32 v[130:131], v[2:3]
	s_mov_b32 s63, s18
	s_barrier
	v_readlane_b32 s19, v243, 52
	s_branch .LBB0_2018

; #define PG8_STAGE(bufoff, gbase, voff) do { _Pragma("unroll") for (int _i = 0; _i < 2; ++_i) \
;         __builtin_amdgcn_global_load_lds((const unsigned*)((const char*)(gbase) + (voff)[_i]), (LAS unsigned*)(lds + (bufoff) + ldsw + _i * 8192), 16, 0, 0); } while (0)
; #define PG8_LDA(dst, b, h) do { _Pragma("unroll") for (int m = 0; m < 4; ++m) _Pragma("unroll") for (int k = 0; k < 2; ++k) dst[m][k] = *(const LAS bf16x8*)(lds + PG8_SA(b, h) + aoff + m * 2048 + k * 1024); } while (0)
; #define PG8_LDB(dst, b, h) do { _Pragma("unroll") for (int n = 0; n < 2; ++n) _Pragma("unroll") for (int k = 0; k < 2; ++k) dst[n][k] = *(const LAS bf16x8*)(lds + PG8_SB(b, h) + boff + n * 2048 + k * 1024); } while (0)
; #define PG8_MMA(ai, bj, At, Bt) do { __builtin_amdgcn_s_setprio(1); _Pragma("unroll") for (int m = 0; m < 4; ++m) _Pragma("unroll") for (int n = 0; n < 2; ++n) _Pragma("unroll") for (int k = 0; k < 2; ++k) \
;         acc[ai][bj][m][n] = __builtin_amdgcn_mfma_f32_16x16x32_bf16(Bt[n][k], At[m][k], acc[ai][bj][m][n], 0, 0, 0); __builtin_amdgcn_s_setprio(0); } while (0)
; template <class Epi, bool ALIGN_EPI = true>
; __device__ __forceinline__ void gemm_phase(LAS unsigned char* lds, const Gemm g, const Sched& S, const Epi& E) {
;     ...
;         for (int t = t_lo; t < t_hi; t += 2) {
;             const bool last = (t == nt - 2);
;             const char* a1 = cA + (size_t)(t + 1) * kstep;
;             const char* a2 = last ? nA : cA + (size_t)(t + 2) * kstep; const char* b2 = last ? nB : cB + (size_t)(t + 2) * kstep;
;             const char* a3 = a2 + kstep; const char* b3 = b2 + kstep;
;             const int rflag = __builtin_amdgcn_readfirstlane(t | (int)(ui == 0));
;             PG8_LDB(B0, 0, 0); PG8_LDB(B1, 0, 1); PG8_SCHED; PG8_LDA(At, 0, 0); PG8_STAGE(PG8_SA(1, 1), a1 + hstepA, voffA);
;             if constexpr (Epi::NSTORES > 0) PG8_WAIT_RELAX(rflag, 8 + Epi::NSTORES); else PG8_WAIT_V(8);
;             PG8_WAIT_L(0); PG8_BAR; PG8_MMA(0, 0, At, B0); PG8_MMA(0, 1, At, B1); PG8_BAR; PG8_SCHED;
;             PG8_LDA(At, 0, 1); PG8_STAGE(PG8_SB(0, 0), b2, voffB); PG8_STAGE(PG8_SB(0, 1), b2 + hstepB, voffB); PG8_STAGE(PG8_SA(0, 0), a2, voffA);
;             if constexpr (Epi::NSTORES > 0) PG8_WAIT_RELAX(rflag, 8 + Epi::NSTORES); else PG8_WAIT_V(8);
;             PG8_WAIT_L(0); PG8_BAR; PG8_MMA(1, 0, At, B0); PG8_MMA(1, 1, At, B1); PG8_BAR; PG8_SCHED;
.LBB0_2021:
	s_add_u32 s40, s30, s22
	s_addc_u32 s41, s31, s23
	s_add_u32 s42, s33, s24
	s_addc_u32 s43, s34, s25
	s_andn2_b64 vcc, exec, s[14:15]
	s_cbranch_vccnz .LBB0_2025
	s_and_b64 s[26:27], s[44:45], exec
	s_cselect_b32 s19, s41, s7
	s_cselect_b32 s21, s40, s6
	s_cselect_b32 s65, s43, s1
	s_cselect_b32 s66, s42, s0
	s_cmp_eq_u32 s61, 0
	s_cselect_b64 s[26:27], -1, 0
	v_cndmask_b32_e64 v2, 0, 1, s[26:27]
	s_add_u32 s26, s6, 0x80080
	s_addc_u32 s27, s7, 0
	s_add_u32 s67, s0, 0x100
	s_mov_b32 s46, 0
	s_addc_u32 s68, s1, 0
	v_xor_b32_e32 v238, 64, v152
	v_xor_b32_e32 v239, 64, v151
.LBB0_2023:
	s_add_i32 s69, s46, 2
	s_add_u32 s47, s26, 0xfff80080
	s_addc_u32 s48, s27, -1
	s_add_i32 s70, 0, 0x10000
	s_cmp_eq_u32 s58, s46
	v_add_u32_e32 v153, s46, v2
	s_cselect_b32 s49, s19, s48
	s_cselect_b32 s48, s21, s47
	s_cselect_b32 s47, s65, s68
	s_cselect_b32 s46, s66, s67
	s_add_i32 s72, 0, 0x14000
	ds_read_b128 v[146:149], v151
	ds_read_b128 v[154:157], v239
	ds_read_b128 v[158:161], v151 offset:2048
	ds_read_b128 v[162:165], v239 offset:2048
	ds_read_b128 v[166:169], v151 offset:16384
	ds_read_b128 v[170:173], v239 offset:16384
	ds_read_b128 v[174:177], v151 offset:18432
	ds_read_b128 v[178:181], v239 offset:18432
	s_add_i32 m0, s36, 0xc000
	ds_read_b128 v[182:185], v152
	ds_read_b128 v[186:189], v238
	ds_read_b128 v[190:193], v152 offset:2048
	ds_read_b128 v[194:197], v238 offset:2048
	ds_read_b128 v[206:209], v152 offset:4096
	ds_read_b128 v[224:227], v238 offset:4096
	ds_read_b128 v[228:231], v152 offset:6144
	ds_read_b128 v[232:235], v238 offset:6144
	s_add_u32 s100, s26, 0xfff80000
	s_addc_u32 s101, s27, -1
	s_mov_b32 m0, s56
	s_nop 0
	global_load_lds_dwordx4 v142, s[100:101]
	s_mov_b32 m0, s57
	s_nop 0
	global_load_lds_dwordx4 v144, s[100:101]
	s_add_i32 m0, s36, 0xc000
	s_nop 0
	global_load_lds_dwordx4 v142, s[26:27]
	s_add_i32 m0, s36, 0xe000
	v_readfirstlane_b32 s73, v153
	global_load_lds_dwordx4 v144, s[26:27]
	s_cmp_eq_u32 s73, 0
	s_cbranch_scc1 .Lrw18
	s_waitcnt vmcnt(8)
.Lrw18:
	s_waitcnt vmcnt(16)
	s_waitcnt lgkmcnt(0)
	s_barrier
	s_setprio 1
	s_waitcnt lgkmcnt(0)
	v_mfma_f32_16x16x32_bf16 v[130:133], v[146:149], v[182:185], v[130:133]
	v_mfma_f32_16x16x32_bf16 v[126:129], v[158:161], v[182:185], v[126:129]
	v_mfma_f32_16x16x32_bf16 v[122:125], v[146:149], v[190:193], v[122:125]
	v_mfma_f32_16x16x32_bf16 v[118:121], v[158:161], v[190:193], v[118:121]
	v_mfma_f32_16x16x32_bf16 v[114:117], v[146:149], v[206:209], v[114:117]
	v_mfma_f32_16x16x32_bf16 v[110:113], v[158:161], v[206:209], v[110:113]
	v_mfma_f32_16x16x32_bf16 v[106:109], v[146:149], v[228:231], v[106:109]
	v_mfma_f32_16x16x32_bf16 v[102:105], v[158:161], v[228:231], v[102:105]
	v_mfma_f32_16x16x32_bf16 v[130:133], v[154:157], v[186:189], v[130:133]
	v_mfma_f32_16x16x32_bf16 v[126:129], v[162:165], v[186:189], v[126:129]
	v_mfma_f32_16x16x32_bf16 v[122:125], v[154:157], v[194:197], v[122:125]
	v_mfma_f32_16x16x32_bf16 v[118:121], v[162:165], v[194:197], v[118:121]
	v_mfma_f32_16x16x32_bf16 v[114:117], v[154:157], v[224:227], v[114:117]
	v_mfma_f32_16x16x32_bf16 v[110:113], v[162:165], v[224:227], v[110:113]
	v_mfma_f32_16x16x32_bf16 v[106:109], v[154:157], v[232:235], v[106:109]
	v_mfma_f32_16x16x32_bf16 v[102:105], v[162:165], v[232:235], v[102:105]
	s_setprio 0
	s_setprio 1
	v_mfma_f32_16x16x32_bf16 v[98:101], v[166:169], v[182:185], v[98:101]
	v_mfma_f32_16x16x32_bf16 v[94:97], v[174:177], v[182:185], v[94:97]
	v_mfma_f32_16x16x32_bf16 v[90:93], v[166:169], v[190:193], v[90:93]
	v_mfma_f32_16x16x32_bf16 v[86:89], v[174:177], v[190:193], v[86:89]
	v_mfma_f32_16x16x32_bf16 v[82:85], v[166:169], v[206:209], v[82:85]
	v_mfma_f32_16x16x32_bf16 v[78:81], v[174:177], v[206:209], v[78:81]
	v_mfma_f32_16x16x32_bf16 v[74:77], v[166:169], v[228:231], v[74:77]
	v_mfma_f32_16x16x32_bf16 v[70:73], v[174:177], v[228:231], v[70:73]
	v_mfma_f32_16x16x32_bf16 v[98:101], v[170:173], v[186:189], v[98:101]
	v_mfma_f32_16x16x32_bf16 v[94:97], v[178:181], v[186:189], v[94:97]
	v_mfma_f32_16x16x32_bf16 v[90:93], v[170:173], v[194:197], v[90:93]
	v_mfma_f32_16x16x32_bf16 v[86:89], v[178:181], v[194:197], v[86:89]
	v_mfma_f32_16x16x32_bf16 v[82:85], v[170:173], v[224:227], v[82:85]
	v_mfma_f32_16x16x32_bf16 v[78:81], v[178:181], v[224:227], v[78:81]
	v_mfma_f32_16x16x32_bf16 v[74:77], v[170:173], v[232:235], v[74:77]
	v_mfma_f32_16x16x32_bf16 v[70:73], v[178:181], v[232:235], v[70:73]
	s_setprio 0
	s_barrier
	s_add_i32 s70, s70, s35
	s_mov_b32 m0, s70
	ds_read_b128 v[182:185], v152 offset:16384
	ds_read_b128 v[186:189], v238 offset:16384
	ds_read_b128 v[190:193], v152 offset:18432
	ds_read_b128 v[194:197], v238 offset:18432
	ds_read_b128 v[206:209], v152 offset:20480
	ds_read_b128 v[224:227], v238 offset:20480
	ds_read_b128 v[228:231], v152 offset:22528
	ds_read_b128 v[232:235], v238 offset:22528
	global_load_lds_dwordx4 v136, s[46:47]
	s_add_i32 m0, s70, 0x2000
	s_add_u32 s70, s46, 0x80000
	s_addc_u32 s71, s47, 0
	s_add_i32 s72, s72, s35
	global_load_lds_dwordx4 v140, s[46:47]
	s_mov_b32 m0, s72
	s_nop 0
	global_load_lds_dwordx4 v136, s[70:71]
	s_add_i32 m0, s72, 0x2000
	s_nop 0
	global_load_lds_dwordx4 v140, s[70:71]
	s_cmp_eq_u32 s73, 0
	s_cbranch_scc1 .Lrw19
	s_waitcnt vmcnt(6)
; #define PG8_STAGE(bufoff, gbase, voff) do { _Pragma("unroll") for (int _i = 0; _i < 2; ++_i) \
;         __builtin_amdgcn_global_load_lds((const unsigned*)((const char*)(gbase) + (voff)[_i]), (LAS unsigned*)(lds + (bufoff) + ldsw + _i * 8192), 16, 0, 0); } while (0)
; #define PG8_LDA(dst, b, h) do { _Pragma("unroll") for (int m = 0; m < 4; ++m) _Pragma("unroll") for (int k = 0; k < 2; ++k) dst[m][k] = *(const LAS bf16x8*)(lds + PG8_SA(b, h) + aoff + m * 2048 + k * 1024); } while (0)
; #define PG8_LDB(dst, b, h) do { _Pragma("unroll") for (int n = 0; n < 2; ++n) _Pragma("unroll") for (int k = 0; k < 2; ++k) dst[n][k] = *(const LAS bf16x8*)(lds + PG8_SB(b, h) + boff + n * 2048 + k * 1024); } while (0)
; #define PG8_MMA(ai, bj, At, Bt) do { __builtin_amdgcn_s_setprio(1); _Pragma("unroll") for (int m = 0; m < 4; ++m) _Pragma("unroll") for (int n = 0; n < 2; ++n) _Pragma("unroll") for (int k = 0; k < 2; ++k) \
;         acc[ai][bj][m][n] = __builtin_amdgcn_mfma_f32_16x16x32_bf16(Bt[n][k], At[m][k], acc[ai][bj][m][n], 0, 0, 0); __builtin_amdgcn_s_setprio(0); } while (0)
; #define PG8_WAIT_V(n) asm volatile("s_waitcnt vmcnt(" #n ")" ::: "memory")
; #define PG8_WAIT_L(n) asm volatile("s_waitcnt lgkmcnt(" #n ")" ::: "memory")
; #define PG8_BAR __builtin_amdgcn_s_barrier()
; #define PG8_SCHED __builtin_amdgcn_sched_barrier(0)
; template <class Epi, bool ALIGN_EPI = true>
; __device__ __forceinline__ void gemm_phase(LAS unsigned char* lds, const Gemm g, const Sched& S, const Epi& E) {
;     ...
;             PG8_WAIT_L(0); PG8_BAR; PG8_MMA(1, 0, At, B0); PG8_MMA(1, 1, At, B1); PG8_BAR; PG8_SCHED;
;             PG8_LDB(B0, 1, 0); PG8_LDB(B1, 1, 1); PG8_SCHED; PG8_LDA(At, 1, 0); PG8_STAGE(PG8_SA(0, 1), a2 + hstepA, voffA);
;             PG8_WAIT_V(8); PG8_WAIT_L(0); PG8_BAR; PG8_MMA(0, 0, At, B0); PG8_MMA(0, 1, At, B1); PG8_BAR; PG8_SCHED;
.Lrw19:
	s_waitcnt vmcnt(6)
	s_waitcnt lgkmcnt(0)
	s_barrier
	s_setprio 1
	s_waitcnt lgkmcnt(0)
	v_mfma_f32_16x16x32_bf16 v[66:69], v[146:149], v[182:185], v[66:69]
	v_mfma_f32_16x16x32_bf16 v[62:65], v[158:161], v[182:185], v[62:65]
	v_mfma_f32_16x16x32_bf16 v[58:61], v[146:149], v[190:193], v[58:61]
	v_mfma_f32_16x16x32_bf16 v[54:57], v[158:161], v[190:193], v[54:57]
	v_mfma_f32_16x16x32_bf16 v[50:53], v[146:149], v[206:209], v[50:53]
	v_mfma_f32_16x16x32_bf16 v[46:49], v[158:161], v[206:209], v[46:49]
	v_mfma_f32_16x16x32_bf16 v[42:45], v[146:149], v[228:231], v[42:45]
	v_mfma_f32_16x16x32_bf16 v[38:41], v[158:161], v[228:231], v[38:41]
	v_mfma_f32_16x16x32_bf16 v[66:69], v[154:157], v[186:189], v[66:69]
	v_mfma_f32_16x16x32_bf16 v[62:65], v[162:165], v[186:189], v[62:65]
	v_mfma_f32_16x16x32_bf16 v[58:61], v[154:157], v[194:197], v[58:61]
	v_mfma_f32_16x16x32_bf16 v[54:57], v[162:165], v[194:197], v[54:57]
	v_mfma_f32_16x16x32_bf16 v[50:53], v[154:157], v[224:227], v[50:53]
	v_mfma_f32_16x16x32_bf16 v[46:49], v[162:165], v[224:227], v[46:49]
	v_mfma_f32_16x16x32_bf16 v[42:45], v[154:157], v[232:235], v[42:45]
	v_mfma_f32_16x16x32_bf16 v[38:41], v[162:165], v[232:235], v[38:41]
	s_setprio 0
	s_setprio 1
	v_mfma_f32_16x16x32_bf16 v[34:37], v[166:169], v[182:185], v[34:37]
	v_mfma_f32_16x16x32_bf16 v[30:33], v[174:177], v[182:185], v[30:33]
	v_mfma_f32_16x16x32_bf16 v[26:29], v[166:169], v[190:193], v[26:29]
	v_mfma_f32_16x16x32_bf16 v[22:25], v[174:177], v[190:193], v[22:25]
	v_mfma_f32_16x16x32_bf16 v[18:21], v[166:169], v[206:209], v[18:21]
	v_mfma_f32_16x16x32_bf16 v[14:17], v[174:177], v[206:209], v[14:17]
	v_mfma_f32_16x16x32_bf16 v[10:13], v[166:169], v[228:231], v[10:13]
	v_mfma_f32_16x16x32_bf16 v[4:7], v[174:177], v[228:231], v[6:9]
	v_mfma_f32_16x16x32_bf16 v[34:37], v[170:173], v[186:189], v[34:37]
	v_mfma_f32_16x16x32_bf16 v[30:33], v[178:181], v[186:189], v[30:33]
	v_mfma_f32_16x16x32_bf16 v[26:29], v[170:173], v[194:197], v[26:29]
	v_mfma_f32_16x16x32_bf16 v[22:25], v[178:181], v[194:197], v[22:25]
	v_mfma_f32_16x16x32_bf16 v[18:21], v[170:173], v[224:227], v[18:21]
	v_mfma_f32_16x16x32_bf16 v[14:17], v[178:181], v[224:227], v[14:17]
	v_mfma_f32_16x16x32_bf16 v[10:13], v[170:173], v[232:235], v[10:13]
	v_mfma_f32_16x16x32_bf16 v[4:7], v[178:181], v[232:235], v[4:7]
	s_setprio 0
	s_barrier
	s_add_i32 s70, 0, 0x18000
	s_add_i32 s71, 0, 0x1c000
	ds_read_b128 v[146:149], v151 offset:32768
	ds_read_b128 v[154:157], v239 offset:32768
	ds_read_b128 v[158:161], v151 offset:34816
	ds_read_b128 v[162:165], v239 offset:34816
	ds_read_b128 v[166:169], v151 offset:49152
	ds_read_b128 v[170:173], v239 offset:49152
	ds_read_b128 v[174:177], v151 offset:51200
	ds_read_b128 v[178:181], v239 offset:51200
	s_add_u32 s48, s48, 0x80000
	s_addc_u32 s49, s49, 0
	s_mov_b32 m0, s50
	ds_read_b128 v[182:185], v152 offset:32768
	ds_read_b128 v[186:189], v238 offset:32768
	ds_read_b128 v[190:193], v152 offset:34816
	ds_read_b128 v[194:197], v238 offset:34816
	ds_read_b128 v[206:209], v152 offset:36864
	ds_read_b128 v[224:227], v238 offset:36864
	ds_read_b128 v[228:231], v152 offset:38912
	ds_read_b128 v[232:235], v238 offset:38912
	s_add_u32 s100, s48, 0xfff80000
	s_addc_u32 s101, s49, -1
	s_mov_b32 m0, s36
	s_nop 0
	global_load_lds_dwordx4 v134, s[100:101]
	s_mov_b32 m0, s37
	s_nop 0
	global_load_lds_dwordx4 v138, s[100:101]
	s_mov_b32 m0, s50
	s_nop 0
	global_load_lds_dwordx4 v134, s[48:49]
	s_mov_b32 m0, s51
	s_nop 0
	global_load_lds_dwordx4 v138, s[48:49]
	s_waitcnt vmcnt(8)
	s_waitcnt lgkmcnt(0)
	s_barrier
; #define PG8_STAGE(bufoff, gbase, voff) do { _Pragma("unroll") for (int _i = 0; _i < 2; ++_i) \
;         __builtin_amdgcn_global_load_lds((const unsigned*)((const char*)(gbase) + (voff)[_i]), (LAS unsigned*)(lds + (bufoff) + ldsw + _i * 8192), 16, 0, 0); } while (0)
; #define PG8_LDA(dst, b, h) do { _Pragma("unroll") for (int m = 0; m < 4; ++m) _Pragma("unroll") for (int k = 0; k < 2; ++k) dst[m][k] = *(const LAS bf16x8*)(lds + PG8_SA(b, h) + aoff + m * 2048 + k * 1024); } while (0)
; #define PG8_MMA(ai, bj, At, Bt) do { __builtin_amdgcn_s_setprio(1); _Pragma("unroll") for (int m = 0; m < 4; ++m) _Pragma("unroll") for (int n = 0; n < 2; ++n) _Pragma("unroll") for (int k = 0; k < 2; ++k) \
;         acc[ai][bj][m][n] = __builtin_amdgcn_mfma_f32_16x16x32_bf16(Bt[n][k], At[m][k], acc[ai][bj][m][n], 0, 0, 0); __builtin_amdgcn_s_setprio(0); } while (0)
; #define PG8_WAIT_V(n) asm volatile("s_waitcnt vmcnt(" #n ")" ::: "memory")
; #define PG8_WAIT_L(n) asm volatile("s_waitcnt lgkmcnt(" #n ")" ::: "memory")
; #define PG8_BAR __builtin_amdgcn_s_barrier()
; #define PG8_SCHED __builtin_amdgcn_sched_barrier(0)
; template <class Epi, bool ALIGN_EPI = true>
; __device__ __forceinline__ void gemm_phase(LAS unsigned char* lds, const Gemm g, const Sched& S, const Epi& E) {
;     ...
;             PG8_WAIT_V(8); PG8_WAIT_L(0); PG8_BAR; PG8_MMA(0, 0, At, B0); PG8_MMA(0, 1, At, B1); PG8_BAR; PG8_SCHED;
;             PG8_LDA(At, 1, 1); PG8_STAGE(PG8_SB(1, 0), b3, voffB); PG8_STAGE(PG8_SB(1, 1), b3 + hstepB, voffB); PG8_STAGE(PG8_SA(1, 0), a3, voffA);
;             PG8_WAIT_V(8); PG8_WAIT_L(0); PG8_BAR; PG8_MMA(1, 0, At, B0); PG8_MMA(1, 1, At, B1); PG8_BAR; PG8_SCHED;
;         }
	s_setprio 1
	s_waitcnt lgkmcnt(0)
	v_mfma_f32_16x16x32_bf16 v[130:133], v[146:149], v[182:185], v[130:133]
	v_mfma_f32_16x16x32_bf16 v[126:129], v[158:161], v[182:185], v[126:129]
	v_mfma_f32_16x16x32_bf16 v[122:125], v[146:149], v[190:193], v[122:125]
	v_mfma_f32_16x16x32_bf16 v[118:121], v[158:161], v[190:193], v[118:121]
	v_mfma_f32_16x16x32_bf16 v[114:117], v[146:149], v[206:209], v[114:117]
	v_mfma_f32_16x16x32_bf16 v[110:113], v[158:161], v[206:209], v[110:113]
	v_mfma_f32_16x16x32_bf16 v[106:109], v[146:149], v[228:231], v[106:109]
	v_mfma_f32_16x16x32_bf16 v[102:105], v[158:161], v[228:231], v[102:105]
	v_mfma_f32_16x16x32_bf16 v[130:133], v[154:157], v[186:189], v[130:133]
	v_mfma_f32_16x16x32_bf16 v[126:129], v[162:165], v[186:189], v[126:129]
	v_mfma_f32_16x16x32_bf16 v[122:125], v[154:157], v[194:197], v[122:125]
	v_mfma_f32_16x16x32_bf16 v[118:121], v[162:165], v[194:197], v[118:121]
	v_mfma_f32_16x16x32_bf16 v[114:117], v[154:157], v[224:227], v[114:117]
	v_mfma_f32_16x16x32_bf16 v[110:113], v[162:165], v[224:227], v[110:113]
	v_mfma_f32_16x16x32_bf16 v[106:109], v[154:157], v[232:235], v[106:109]
	v_mfma_f32_16x16x32_bf16 v[102:105], v[162:165], v[232:235], v[102:105]
	s_setprio 0
	s_setprio 1
	v_mfma_f32_16x16x32_bf16 v[98:101], v[166:169], v[182:185], v[98:101]
	v_mfma_f32_16x16x32_bf16 v[94:97], v[174:177], v[182:185], v[94:97]
	v_mfma_f32_16x16x32_bf16 v[90:93], v[166:169], v[190:193], v[90:93]
	v_mfma_f32_16x16x32_bf16 v[86:89], v[174:177], v[190:193], v[86:89]
	v_mfma_f32_16x16x32_bf16 v[82:85], v[166:169], v[206:209], v[82:85]
	v_mfma_f32_16x16x32_bf16 v[78:81], v[174:177], v[206:209], v[78:81]
	v_mfma_f32_16x16x32_bf16 v[74:77], v[166:169], v[228:231], v[74:77]
	v_mfma_f32_16x16x32_bf16 v[70:73], v[174:177], v[228:231], v[70:73]
	v_mfma_f32_16x16x32_bf16 v[98:101], v[170:173], v[186:189], v[98:101]
	v_mfma_f32_16x16x32_bf16 v[94:97], v[178:181], v[186:189], v[94:97]
	v_mfma_f32_16x16x32_bf16 v[90:93], v[170:173], v[194:197], v[90:93]
	v_mfma_f32_16x16x32_bf16 v[86:89], v[178:181], v[194:197], v[86:89]
	v_mfma_f32_16x16x32_bf16 v[82:85], v[170:173], v[224:227], v[82:85]
	v_mfma_f32_16x16x32_bf16 v[78:81], v[178:181], v[224:227], v[78:81]
	v_mfma_f32_16x16x32_bf16 v[74:77], v[170:173], v[232:235], v[74:77]
	v_mfma_f32_16x16x32_bf16 v[70:73], v[178:181], v[232:235], v[70:73]
	s_setprio 0
	s_barrier
	s_add_u32 s100, s46, 0x80
	s_addc_u32 s101, s47, 0
	s_add_i32 s48, s70, s35
	s_mov_b32 m0, s48
	ds_read_b128 v[182:185], v152 offset:49152
	ds_read_b128 v[186:189], v238 offset:49152
	ds_read_b128 v[190:193], v152 offset:51200
	ds_read_b128 v[194:197], v238 offset:51200
	ds_read_b128 v[206:209], v152 offset:53248
	ds_read_b128 v[224:227], v238 offset:53248
	ds_read_b128 v[228:231], v152 offset:55296
	ds_read_b128 v[232:235], v238 offset:55296
	global_load_lds_dwordx4 v136, s[100:101]
	s_add_i32 m0, s48, 0x2000
	s_add_u32 s46, s46, 0x80080
	s_addc_u32 s47, s47, 0
	s_add_i32 s48, s71, s35
	global_load_lds_dwordx4 v140, s[100:101]
	s_mov_b32 m0, s48
	s_nop 0
	global_load_lds_dwordx4 v136, s[46:47]
	s_add_i32 m0, s48, 0x2000
	s_nop 0
	global_load_lds_dwordx4 v140, s[46:47]
	s_waitcnt vmcnt(6)
	s_waitcnt lgkmcnt(0)
	s_barrier
	s_setprio 1
	s_waitcnt lgkmcnt(0)
	v_mfma_f32_16x16x32_bf16 v[66:69], v[146:149], v[182:185], v[66:69]
	v_mfma_f32_16x16x32_bf16 v[62:65], v[158:161], v[182:185], v[62:65]
	v_mfma_f32_16x16x32_bf16 v[58:61], v[146:149], v[190:193], v[58:61]
	v_mfma_f32_16x16x32_bf16 v[54:57], v[158:161], v[190:193], v[54:57]
	v_mfma_f32_16x16x32_bf16 v[50:53], v[146:149], v[206:209], v[50:53]
	v_mfma_f32_16x16x32_bf16 v[46:49], v[158:161], v[206:209], v[46:49]
	v_mfma_f32_16x16x32_bf16 v[42:45], v[146:149], v[228:231], v[42:45]
	v_mfma_f32_16x16x32_bf16 v[38:41], v[158:161], v[228:231], v[38:41]
	v_mfma_f32_16x16x32_bf16 v[66:69], v[154:157], v[186:189], v[66:69]
	v_mfma_f32_16x16x32_bf16 v[62:65], v[162:165], v[186:189], v[62:65]
	v_mfma_f32_16x16x32_bf16 v[58:61], v[154:157], v[194:197], v[58:61]
	v_mfma_f32_16x16x32_bf16 v[54:57], v[162:165], v[194:197], v[54:57]
	v_mfma_f32_16x16x32_bf16 v[50:53], v[154:157], v[224:227], v[50:53]
	v_mfma_f32_16x16x32_bf16 v[46:49], v[162:165], v[224:227], v[46:49]
	v_mfma_f32_16x16x32_bf16 v[42:45], v[154:157], v[232:235], v[42:45]
	v_mfma_f32_16x16x32_bf16 v[38:41], v[162:165], v[232:235], v[38:41]
	s_setprio 0
	s_setprio 1
	v_mfma_f32_16x16x32_bf16 v[34:37], v[166:169], v[182:185], v[34:37]
	v_mfma_f32_16x16x32_bf16 v[30:33], v[174:177], v[182:185], v[30:33]
	v_mfma_f32_16x16x32_bf16 v[26:29], v[166:169], v[190:193], v[26:29]
	v_mfma_f32_16x16x32_bf16 v[22:25], v[174:177], v[190:193], v[22:25]
	v_mfma_f32_16x16x32_bf16 v[18:21], v[166:169], v[206:209], v[18:21]
	v_mfma_f32_16x16x32_bf16 v[14:17], v[174:177], v[206:209], v[14:17]
	v_mfma_f32_16x16x32_bf16 v[8:11], v[166:169], v[228:231], v[10:13]
	v_mfma_f32_16x16x32_bf16 v[4:7], v[174:177], v[228:231], v[4:7]
	v_mfma_f32_16x16x32_bf16 v[34:37], v[170:173], v[186:189], v[34:37]
	v_mfma_f32_16x16x32_bf16 v[30:33], v[178:181], v[186:189], v[30:33]
	v_mfma_f32_16x16x32_bf16 v[26:29], v[170:173], v[194:197], v[26:29]
	v_mfma_f32_16x16x32_bf16 v[22:25], v[178:181], v[194:197], v[22:25]
	v_mfma_f32_16x16x32_bf16 v[18:21], v[170:173], v[224:227], v[18:21]
	v_mfma_f32_16x16x32_bf16 v[14:17], v[178:181], v[224:227], v[14:17]
	v_mfma_f32_16x16x32_bf16 v[10:13], v[170:173], v[232:235], v[8:11]
	v_mfma_f32_16x16x32_bf16 v[6:9], v[178:181], v[232:235], v[4:7]
	s_setprio 0
	s_barrier
	s_add_u32 s26, s26, 0x100
	s_addc_u32 s27, s27, 0
	s_add_u32 s67, s67, 0x100
	s_addc_u32 s68, s68, 0
	s_cmp_ge_i32 s69, s54
	s_mov_b32 s46, s69
	s_cbranch_scc0 .LBB0_2023
	s_mov_b32 s72, 0x8000

; template <class Epi, bool ALIGN_EPI = true>
; __device__ __forceinline__ void gemm_phase(LAS unsigned char* lds, const Gemm g, const Sched& S, const Epi& E) {
;     ...
;     for (int i = 0; i < 2; ++i) { int R, C; stage_rc(tid * 16 + i * 8192, R, C); const int Rb = (R & ~31) + perm32(R & 31);
;         voffA[i] = (unsigned)(R * g.lda + C) * 2u; voffB[i] = (unsigned)(Rb * g.ldb + C) * 2u; }
.LBB0_2273:
	v_readlane_b32 s14, v244, 0
	s_mov_b64 s[4:5], 0x3a000000
	s_mov_b64 s[6:7], 0x26000000
	s_mov_b64 s[0:1], 0x120000
	v_mov_b32_e32 v146, v0
	v_readlane_b32 s15, v244, 1
	s_movk_i32 s18, 0x1600
	v_readfirstlane_b32 s30, v146
	s_andn2_b64 vcc, exec, s[14:15]
	s_cbranch_vccnz .LBB0_2311
	v_lshlrev_b32_e32 v2, 4, v146
	s_waitcnt vmcnt(0) lgkmcnt(0)
	v_add_u32_e32 v4, 0x2000, v2
	v_ashrrev_i32_e32 v5, 31, v4
	v_lshrrev_b32_e32 v5, 22, v5
	v_add_u32_e32 v5, v4, v5
	v_ashrrev_i32_e32 v12, 10, v5
	v_mul_i32_i24_e32 v5, 0x400, v12
	v_sub_u32_e32 v4, v4, v5
	v_lshrrev_b32_e32 v5, 4, v4
	v_bitop3_b32 v4, v5, v4, 32 bitop3:0x6c
	v_ashrrev_i32_e32 v5, 31, v4
	v_lshrrev_b32_e32 v5, 26, v5
	v_add_u32_e32 v5, v4, v5
	v_lshlrev_b32_e32 v6, 3, v12
	v_ashrrev_i32_e32 v13, 6, v5
	v_and_b32_e32 v6, -16, v6
	v_add_u32_e32 v6, v13, v6
	v_and_b32_e32 v7, 3, v13
	s_mov_b32 s10, 0x7fffe0
	v_lshrrev_b32_e32 v8, 2, v6
	v_lshlrev_b32_e32 v9, 1, v6
	v_and_b32_e32 v5, 0xc0, v5
	v_and_or_b32 v7, v6, s10, v7
	v_and_b32_e32 v8, 4, v8
	v_and_b32_e32 v9, 24, v9
	v_sub_u32_e32 v4, v4, v5
	v_or3_b32 v7, v7, v8, v9
	v_lshlrev_b32_e32 v8, 5, v12
	v_ashrrev_i16_sdwa v4, v213, sext(v4) dst_sel:DWORD dst_unused:UNUSED_PAD src0_sel:DWORD src1_sel:BYTE_0
	v_and_b32_e32 v14, 32, v8
	v_bfe_i32 v15, v4, 0, 16
	s_movk_i32 s14, 0x1600
	v_mul_u32_u24_e32 v7, 0x1600, v7
	v_add_u32_e32 v4, v14, v15
	v_mul_lo_u32 v5, v6, s14
	v_add_lshl_u32 v134, v7, v4, 1
	v_lshrrev_b32_e32 v247, 3, v0
	v_xor_b32_e32 v247, v247, v0
	v_and_b32_e32 v247, 7, v247
	v_lshl_add_u32 v134, v247, 4, v134
	v_and_b32_e32 v247, 64, v0
	v_sub_u32_e32 v134, v134, v247
	v_lshrrev_b32_e32 v247, 4, v0
	v_and_b32_e32 v247, 2, v247
	v_xor_b32_e32 v247, v247, v0
	v_and_b32_e32 v247, 3, v247
	v_lshlrev_b32_e32 v247, 4, v247
	v_sub_u32_e32 v134, v134, v247
	v_and_b32_e32 v247, 64, v0
	v_mul_u32_u24_e32 v247, 0xb00, v247
	v_add_u32_e32 v134, v134, v247
	v_and_b32_e32 v247, 32, v0
	v_mul_u32_u24_e32 v247, 0xb00, v247
	v_sub_u32_e32 v134, v134, v247
	v_and_b32_e32 v247, 16, v0
	v_mul_u32_u24_e32 v247, 0x1080, v247
	v_sub_u32_e32 v134, v134, v247
	v_and_b32_e32 v247, 8, v0
	v_mul_u32_u24_e32 v247, 0x580, v247
	v_sub_u32_e32 v134, v134, v247
	v_and_b32_e32 v247, 4, v0
	v_mul_u32_u24_e32 v247, 0xb00, v247
	v_sub_u32_e32 v134, v134, v247
	v_add_lshl_u32 v136, v4, v5, 1
	v_lshrrev_b32_e32 v247, 3, v0
	v_xor_b32_e32 v247, v247, v0
	v_and_b32_e32 v247, 7, v247
	v_lshl_add_u32 v136, v247, 4, v136
	v_and_b32_e32 v247, 64, v0
	v_sub_u32_e32 v136, v136, v247
	v_lshrrev_b32_e32 v247, 4, v0
	v_and_b32_e32 v247, 2, v247
	v_xor_b32_e32 v247, v247, v0
	v_and_b32_e32 v247, 3, v247
	v_lshlrev_b32_e32 v247, 4, v247
	v_sub_u32_e32 v136, v136, v247
	v_bfe_u32 v247, v0, 2, 4
	v_add_u32_e32 v247, 1, v247
	v_lshrrev_b32_e32 v247, 1, v247
	v_mul_u32_u24_e32 v247, 0x2c00, v247
	v_sub_u32_e32 v136, v136, v247
	v_and_b32_e32 v247, 64, v0
	v_mul_u32_u24_e32 v247, 0x580, v247
	v_add_u32_e32 v136, v136, v247
	v_bfe_i32 v4, v146, 27, 1
	v_lshrrev_b32_e32 v4, 22, v4
	v_add_u32_e32 v4, v2, v4
	v_and_b32_e32 v4, 0xfffffc00, v4
	v_sub_u32_e32 v2, v2, v4
	v_lshrrev_b32_e32 v4, 4, v2
	v_ashrrev_i32_e32 v6, 31, v146
	v_bitop3_b32 v4, v4, v2, 32 bitop3:0x6c
	v_lshrrev_b32_e32 v6, 26, v6
	v_ashrrev_i32_e32 v2, 31, v4
	v_add_u32_e32 v6, v146, v6
	v_lshrrev_b32_e32 v2, 26, v2
	v_ashrrev_i32_e32 v16, 6, v6
	v_add_u32_e32 v5, v4, v2
	v_lshlrev_b32_e32 v6, 3, v16
	s_add_u32 s33, s54, s4
	v_ashrrev_i32_e32 v2, 6, v5
	v_and_b32_e32 v6, -16, v6
	s_addc_u32 s34, s55, s5
	v_readlane_b32 s4, v242, 27
	v_add_u32_e32 v6, v2, v6
	s_add_u32 s35, s4, 0x7100000
	v_readlane_b32 s4, v242, 28
	v_and_b32_e32 v7, 3, v2
	v_lshrrev_b32_e32 v8, 2, v6
	v_lshlrev_b32_e32 v9, 1, v6
	v_and_b32_e32 v5, 0xc0, v5
	s_addc_u32 s36, s4, 0
	s_ashr_i32 s5, s30, 6
	v_and_or_b32 v7, v6, s10, v7
	v_and_b32_e32 v8, 4, v8
	v_and_b32_e32 v9, 24, v9
	v_sub_u32_e32 v4, v4, v5
	v_mul_lo_u32 v5, v6, s14
	v_readlane_b32 s14, v243, 43
	s_ashr_i32 s4, s30, 8
	s_lshl_b32 s37, s5, 10
	v_or3_b32 v7, v7, v8, v9
	v_lshlrev_b32_e32 v8, 5, v16
	v_ashrrev_i16_sdwa v4, v213, sext(v4) dst_sel:DWORD dst_unused:UNUSED_PAD src0_sel:DWORD src1_sel:BYTE_0
	v_readlane_b32 s15, v243, 44
	s_mov_b32 s10, s14
	s_mul_i32 s14, s14, 0x2c0000
	v_and_b32_e32 v17, 32, v8
	v_bfe_i32 v18, v4, 0, 16
	s_add_u32 s14, s35, s14
	s_mul_hi_i32 s15, s10, 0x2c0000
	v_mul_u32_u24_e32 v7, 0x1600, v7
	v_add_u32_e32 v4, v17, v18
	s_addc_u32 s15, s36, s15
	s_add_i32 s50, s37, 0
	v_add_lshl_u32 v138, v7, v4, 1
	v_lshrrev_b32_e32 v247, 3, v0
	v_xor_b32_e32 v247, v247, v0
	v_and_b32_e32 v247, 7, v247
	v_lshl_add_u32 v138, v247, 4, v138
	v_and_b32_e32 v247, 64, v0
	v_sub_u32_e32 v138, v138, v247
	v_lshrrev_b32_e32 v247, 4, v0
	v_and_b32_e32 v247, 2, v247
	v_xor_b32_e32 v247, v247, v0
	v_and_b32_e32 v247, 3, v247
	v_lshlrev_b32_e32 v247, 4, v247
	v_sub_u32_e32 v138, v138, v247
	v_and_b32_e32 v247, 64, v0
	v_mul_u32_u24_e32 v247, 0xb00, v247
	v_add_u32_e32 v138, v138, v247
	v_and_b32_e32 v247, 32, v0
	v_mul_u32_u24_e32 v247, 0xb00, v247
	v_sub_u32_e32 v138, v138, v247
	v_and_b32_e32 v247, 16, v0
	v_mul_u32_u24_e32 v247, 0x1080, v247
	v_sub_u32_e32 v138, v138, v247
	v_and_b32_e32 v247, 8, v0
	v_mul_u32_u24_e32 v247, 0x580, v247
	v_sub_u32_e32 v138, v138, v247
	v_and_b32_e32 v247, 4, v0
	v_mul_u32_u24_e32 v247, 0xb00, v247
	v_sub_u32_e32 v138, v138, v247
	s_add_i32 m0, s50, 0x10000
	v_add_lshl_u32 v140, v4, v5, 1
	v_lshrrev_b32_e32 v247, 3, v0
	v_xor_b32_e32 v247, v247, v0
	v_and_b32_e32 v247, 7, v247
	v_lshl_add_u32 v140, v247, 4, v140
	v_and_b32_e32 v247, 64, v0
	v_sub_u32_e32 v140, v140, v247
	v_lshrrev_b32_e32 v247, 4, v0
	v_and_b32_e32 v247, 2, v247
; #define PG8_STAGE(bufoff, gbase, voff) do { _Pragma("unroll") for (int _i = 0; _i < 2; ++_i) \
;         __builtin_amdgcn_global_load_lds((const unsigned*)((const char*)(gbase) + (voff)[_i]), (LAS unsigned*)(lds + (bufoff) + ldsw + _i * 8192), 16, 0, 0); } while (0)
; #define PG8_WAIT_V(n) asm volatile("s_waitcnt vmcnt(" #n ")" ::: "memory")
; #define PG8_BAR __builtin_amdgcn_s_barrier()
; template <class Epi, bool ALIGN_EPI = true>
; __device__ __forceinline__ void gemm_phase(LAS unsigned char* lds, const Gemm g, const Sched& S, const Epi& E) {
;     ...
;     PG8_STAGE(PG8_SB(0, 0), cB, voffB); PG8_STAGE(PG8_SB(0, 1), cB + hstepB, voffB); PG8_STAGE(PG8_SA(0, 0), cA, voffA); PG8_STAGE(PG8_SA(0, 1), cA + hstepA, voffA);
;     if (wr == 1) PG8_BAR;
;     PG8_WAIT_V(2); PG8_BAR;
	v_xor_b32_e32 v247, v247, v0
	v_and_b32_e32 v247, 3, v247
	v_lshlrev_b32_e32 v247, 4, v247
	v_sub_u32_e32 v140, v140, v247
	v_bfe_u32 v247, v0, 2, 4
	v_add_u32_e32 v247, 1, v247
	v_lshrrev_b32_e32 v247, 1, v247
	v_mul_u32_u24_e32 v247, 0x2c00, v247
	v_sub_u32_e32 v140, v140, v247
	v_and_b32_e32 v247, 64, v0
	v_mul_u32_u24_e32 v247, 0x580, v247
	v_add_u32_e32 v140, v140, v247
	global_load_lds_dwordx4 v138, s[14:15]
	s_add_i32 m0, s50, 0x12000
	s_add_u32 s16, s14, 0x160000
	global_load_lds_dwordx4 v134, s[14:15]
	s_addc_u32 s17, s15, 0
	s_add_i32 m0, s50, 0x14000
	v_mov_b32_e32 v139, v3
	global_load_lds_dwordx4 v138, s[16:17]
	s_add_i32 m0, s50, 0x16000
	v_mov_b32_e32 v135, v3
	global_load_lds_dwordx4 v134, s[16:17]
	v_readlane_b32 s16, v243, 39
	v_readlane_b32 s17, v243, 40
	s_mov_b32 s10, s16
	s_mul_i32 s16, s16, 0x2c0000
	s_add_u32 s16, s33, s16
	s_mul_hi_i32 s17, s10, 0x2c0000
	s_addc_u32 s17, s34, s17
	s_add_i32 s51, s50, 0x2000
	s_mov_b32 m0, s50
	s_add_u32 s20, s16, 0x160000
	global_load_lds_dwordx4 v140, s[16:17]
	s_mov_b32 m0, s51
	s_addc_u32 s21, s17, 0
	s_add_i32 s52, s50, 0x4000
	global_load_lds_dwordx4 v136, s[16:17]
	s_mov_b32 m0, s52
	s_add_i32 s53, s50, 0x6000
	global_load_lds_dwordx4 v140, s[20:21]
	s_mov_b32 m0, s53
	v_mov_b32_e32 v141, v3
	global_load_lds_dwordx4 v136, s[20:21]
	v_mov_b32_e32 v137, v3
	v_lshl_add_u64 v[10:11], s[14:15], 0, v[138:139]
	v_lshl_add_u64 v[8:9], s[14:15], 0, v[134:135]
	v_lshl_add_u64 v[6:7], s[16:17], 0, v[140:141]
	s_cmp_lg_u32 s4, 1
	v_lshl_add_u64 v[4:5], s[16:17], 0, v[136:137]
	s_cbranch_scc1 .LBB0_2276
	s_barrier
; #define LAS __attribute__((address_space(3)))
; #define PG8_WAIT_V(n) asm volatile("s_waitcnt vmcnt(" #n ")" ::: "memory")
; #define PG8_BAR __builtin_amdgcn_s_barrier()
; template <class Epi, bool ALIGN_EPI = true>
; __device__ __forceinline__ void gemm_phase(LAS unsigned char* lds, const Gemm g, const Sched& S, const Epi& E) {
;     ...
;     for (int i = 0; i < 2; ++i) { int R, C; stage_rc(tid * 16 + i * 8192, R, C); const int Rb = (R & ~31) + perm32(R & 31);
;         voffA[i] = (unsigned)(R * g.lda + C) * 2u; voffB[i] = (unsigned)(Rb * g.ldb + C) * 2u; }
;     const size_t kstep = (size_t)(BK * 2);
;     const size_t hstepA = (size_t)HALF * g.lda * 2, hstepB = (size_t)HALF * g.ldb * 2;
;     const unsigned ldsw = (unsigned)wid * 1024u;
;     const int aoff = lds_byte(wr * 64 + fr, fq * 8), boff = lds_byte(wc * 32 + fr, fq * 8);
;     ...
;     Unit cur, nxt; int ui = 0;
;     if (!S.next(0, cur)) return;
;     if constexpr (Epi::USES_RSTD) {
;         LAS float* T = (LAS float*)(lds + RSTD_OFF);
; #pragma unroll
;         for (int k = 0; k < RSTD_UNITS * 256 / 512; ++k) { const int idx = tid + 512 * k; Unit uu;
;             if (S.next(idx >> 8, uu)) { const float* sp = E.SS + uu.pm * BM + (idx & 255); float ssum = 0.f;
; #pragma unroll
;                 for (int j = 0; j < 8; ++j) ssum += sp[(size_t)j * MROWS];
;                 T[idx] = __builtin_amdgcn_rsqf(ssum * (1.0f / DM) + EPS); } }
;         asm volatile("s_waitcnt lgkmcnt(0)" ::: "memory"); __builtin_amdgcn_s_barrier(); asm volatile("" ::: "memory");
;     }
;     f32x4 acc[2][2][4][2];
; #pragma unroll
;     for (int a = 0; a < 2; ++a)
; #pragma unroll
;         for (int b = 0; b < 2; ++b)
; #pragma unroll
;             for (int m = 0; m < 4; ++m)
; #pragma unroll
;                 for (int n = 0; n < 2; ++n) acc[a][b][m][n] = (f32x4){0.f, 0.f, 0.f, 0.f};
;     bf16x8 At[4][2], B0[2][2], B1[2][2];
;     const char* cA = (const char*)g.A + cur.aoff; const char* cB = (const char*)g.Bt + cur.boff;
;     PG8_STAGE(PG8_SB(0, 0), cB, voffB); PG8_STAGE(PG8_SB(0, 1), cB + hstepB, voffB); PG8_STAGE(PG8_SA(0, 0), cA, voffA); PG8_STAGE(PG8_SA(0, 1), cA + hstepA, voffA);
;     if (wr == 1) PG8_BAR;
;     PG8_WAIT_V(2); PG8_BAR;
;     PG8_STAGE(PG8_SB(1, 0), cB + kstep, voffB); PG8_STAGE(PG8_SA(1, 0), cA + kstep, voffA); PG8_STAGE(PG8_SB(1, 1), cB + hstepB + kstep, voffB);
;     PG8_WAIT_V(6); PG8_BAR;
.LBB0_2276:
	s_ashr_i32 s19, s18, 31
	s_lshr_b32 s19, s19, 26
	s_and_b32 s5, s5, 3
	s_add_i32 s19, s18, s19
	s_add_i32 m0, s50, 0x18000
	v_lshl_add_u64 v[10:11], v[10:11], 0, s[8:9]
	s_ashr_i32 s54, s19, 6
	s_lshl_b32 s31, s4, 6
	s_lshl_b32 s4, s4, 13
	s_lshl_b32 s19, s5, 12
	s_waitcnt vmcnt(2)
	s_barrier
	global_load_lds_dwordx4 v[10:11], off
	v_lshl_add_u64 v[8:9], v[8:9], 0, s[8:9]
	s_add_i32 m0, s50, 0x1a000
	s_add_i32 s55, s50, 0x8000
	s_add_i32 s56, s50, 0xa000
	global_load_lds_dwordx4 v[8:9], off
	v_lshl_add_u64 v[6:7], v[6:7], 0, s[8:9]
	s_mov_b32 m0, s55
	s_add_u32 s20, s14, 0x160080
	global_load_lds_dwordx4 v[6:7], off
	v_lshl_add_u64 v[4:5], v[4:5], 0, s[8:9]
	s_mov_b32 m0, s56
	s_addc_u32 s21, s15, 0
	global_load_lds_dwordx4 v[4:5], off
	s_add_i32 m0, s50, 0x1c000
	v_lshl_add_u64 v[4:5], s[20:21], 0, v[138:139]
	global_load_lds_dwordx4 v[4:5], off
	v_lshl_add_u64 v[4:5], s[20:21], 0, v[134:135]
	s_add_i32 m0, s50, 0x1e000
	s_movk_i32 s10, 0x3c0
	global_load_lds_dwordx4 v[4:5], off
	v_and_b32_e32 v4, 48, v146
	v_lshlrev_b32_e32 v5, 6, v146
	v_and_or_b32 v4, v5, s10, v4
	v_lshlrev_b32_e32 v5, 2, v146
	v_and_b32_e32 v5, 32, v5
	s_movk_i32 s10, 0x1600
	v_bitop3_b32 v6, v4, s4, v5 bitop3:0xde
	v_bitop3_b32 v147, v4, s19, v5 bitop3:0xde
	v_bfe_u32 v147, v0, 4, 2
	v_xor_b32_e32 v147, v147, v0
	v_and_b32_e32 v147, 7, v147
	v_lshlrev_b32_e32 v147, 4, v147
	v_and_b32_e32 v247, 15, v0
	v_lshl_or_b32 v147, v247, 7, v147
	v_and_b32_e32 v247, 0xc0, v0
	v_lshl_or_b32 v147, v247, 6, v147
	v_or_b32_e32 v147, 0x10000, v147
	v_lshrrev_b32_e32 v4, 1, v16
	v_mul_lo_u32 v2, v2, s10
	s_mov_b32 s4, 0x16000
	v_mad_u64_u32 v[4:5], s[20:21], v4, s4, v[2:3]
	v_or_b32_e32 v2, v4, v17
	v_add_lshl_u32 v2, v2, v18, 1
	s_mov_b64 s[22:23], 0x160080
	v_lshl_add_u64 v[142:143], v[2:3], 0, s[22:23]
	v_lshrrev_b32_e32 v247, 3, v0
	v_xor_b32_e32 v247, v247, v0
	v_and_b32_e32 v247, 7, v247
	v_lshl_add_u32 v142, v247, 4, v142
	v_and_b32_e32 v247, 64, v0
	v_sub_u32_e32 v142, v142, v247
	v_lshrrev_b32_e32 v247, 4, v0
	v_and_b32_e32 v247, 2, v247
	v_xor_b32_e32 v247, v247, v0
	v_and_b32_e32 v247, 3, v247
	v_lshlrev_b32_e32 v247, 4, v247
	v_sub_u32_e32 v142, v142, v247
	v_bfe_u32 v247, v0, 2, 4
	v_add_u32_e32 v247, 1, v247
	v_lshrrev_b32_e32 v247, 1, v247
	v_mul_u32_u24_e32 v247, 0x2c00, v247
	v_sub_u32_e32 v142, v142, v247
	v_and_b32_e32 v247, 64, v0
	v_mul_u32_u24_e32 v247, 0x580, v247
	v_add_u32_e32 v142, v142, v247
	v_lshrrev_b32_e32 v4, 1, v12
	v_mul_lo_u32 v2, v13, s10
	v_mad_u64_u32 v[4:5], s[20:21], v4, s4, v[2:3]
	v_or_b32_e32 v2, v4, v14
	v_readlane_b32 s20, v243, 43
	s_waitcnt vmcnt(6)
	v_add_lshl_u32 v2, v2, v15, 1
	v_mov_b32_e32 v4, v3
	v_mov_b32_e32 v5, v3
	v_readlane_b32 s21, v243, 44
	s_cmp_gt_i32 s18, 63
	v_lshl_add_u64 v[144:145], v[2:3], 0, s[22:23]
	v_lshrrev_b32_e32 v247, 3, v0
	v_xor_b32_e32 v247, v247, v0
	v_and_b32_e32 v247, 7, v247
	v_lshl_add_u32 v144, v247, 4, v144
	v_and_b32_e32 v247, 64, v0
	v_sub_u32_e32 v144, v144, v247
	v_lshrrev_b32_e32 v247, 4, v0
	v_and_b32_e32 v247, 2, v247
	v_xor_b32_e32 v247, v247, v0
	v_and_b32_e32 v247, 3, v247
	v_lshlrev_b32_e32 v247, 4, v247
	v_sub_u32_e32 v144, v144, v247
	v_bfe_u32 v247, v0, 2, 4
	v_add_u32_e32 v247, 1, v247
	v_lshrrev_b32_e32 v247, 1, v247
	v_mul_u32_u24_e32 v247, 0x2c00, v247
	v_sub_u32_e32 v144, v144, v247
	v_and_b32_e32 v247, 64, v0
	v_mul_u32_u24_e32 v247, 0x580, v247
	v_add_u32_e32 v144, v144, v247
	v_mov_b32_e32 v2, v3
	v_add_u32_e32 v148, 0, v6
	v_bfe_u32 v148, v0, 4, 2
	v_xor_b32_e32 v148, v148, v0
	v_and_b32_e32 v148, 7, v148
	v_lshlrev_b32_e32 v148, 4, v148
	v_and_b32_e32 v247, 15, v0
	v_lshl_or_b32 v148, v247, 7, v148
	v_and_b32_e32 v247, 0x100, v0
	v_lshl_or_b32 v148, v247, 5, v148
	v_mov_b64_e32 v[8:9], v[4:5]
	v_mov_b64_e32 v[12:13], v[4:5]
	v_mov_b64_e32 v[24:25], v[4:5]
	v_mov_b64_e32 v[28:29], v[4:5]
	v_mov_b64_e32 v[40:41], v[4:5]
	v_mov_b64_e32 v[44:45], v[4:5]
	v_mov_b64_e32 v[56:57], v[4:5]
	v_mov_b64_e32 v[60:61], v[4:5]
	v_mov_b64_e32 v[16:17], v[4:5]
	v_mov_b64_e32 v[20:21], v[4:5]
	v_mov_b64_e32 v[32:33], v[4:5]
	v_mov_b64_e32 v[36:37], v[4:5]
	v_mov_b64_e32 v[48:49], v[4:5]
	v_mov_b64_e32 v[52:53], v[4:5]
	v_mov_b64_e32 v[64:65], v[4:5]
	v_mov_b64_e32 v[68:69], v[4:5]
	v_mov_b64_e32 v[72:73], v[4:5]
	v_mov_b64_e32 v[76:77], v[4:5]
	v_mov_b64_e32 v[88:89], v[4:5]
	v_mov_b64_e32 v[92:93], v[4:5]
	v_mov_b64_e32 v[104:105], v[4:5]
	v_mov_b64_e32 v[108:109], v[4:5]
	v_mov_b64_e32 v[120:121], v[4:5]
	v_mov_b64_e32 v[124:125], v[4:5]
	v_mov_b64_e32 v[80:81], v[4:5]
	v_mov_b64_e32 v[84:85], v[4:5]
	v_mov_b64_e32 v[96:97], v[4:5]
	v_mov_b64_e32 v[100:101], v[4:5]
	v_mov_b64_e32 v[112:113], v[4:5]
	v_mov_b64_e32 v[116:117], v[4:5]
	v_mov_b64_e32 v[128:129], v[4:5]
	v_mov_b64_e32 v[132:133], v[4:5]
	s_mov_b32 s4, s20
	v_readlane_b32 s20, v243, 39
	s_cselect_b64 s[18:19], -1, 0
	s_add_i32 s57, s54, -2
	s_mov_b32 s58, 0
	v_mov_b64_e32 v[6:7], v[2:3]
	v_mov_b64_e32 v[10:11], v[2:3]
	v_mov_b64_e32 v[22:23], v[2:3]
	v_mov_b64_e32 v[26:27], v[2:3]
	v_mov_b64_e32 v[38:39], v[2:3]
	v_mov_b64_e32 v[42:43], v[2:3]
	v_mov_b64_e32 v[54:55], v[2:3]
	v_mov_b64_e32 v[58:59], v[2:3]
	v_mov_b64_e32 v[14:15], v[2:3]
	v_mov_b64_e32 v[18:19], v[2:3]
	v_mov_b64_e32 v[30:31], v[2:3]
	v_mov_b64_e32 v[34:35], v[2:3]
	v_mov_b64_e32 v[46:47], v[2:3]
	v_mov_b64_e32 v[50:51], v[2:3]
	v_mov_b64_e32 v[62:63], v[2:3]
	v_mov_b64_e32 v[66:67], v[2:3]
	v_mov_b64_e32 v[70:71], v[2:3]
	v_mov_b64_e32 v[74:75], v[2:3]
	v_mov_b64_e32 v[86:87], v[2:3]
	v_mov_b64_e32 v[90:91], v[2:3]
	v_mov_b64_e32 v[102:103], v[2:3]
	v_mov_b64_e32 v[106:107], v[2:3]
	v_mov_b64_e32 v[118:119], v[2:3]
	v_mov_b64_e32 v[122:123], v[2:3]
	v_mov_b64_e32 v[78:79], v[2:3]
	v_mov_b64_e32 v[82:83], v[2:3]
	v_mov_b64_e32 v[94:95], v[2:3]
	v_mov_b64_e32 v[98:99], v[2:3]
	v_mov_b64_e32 v[110:111], v[2:3]
	v_mov_b64_e32 v[114:115], v[2:3]
	v_mov_b64_e32 v[126:127], v[2:3]
	v_mov_b64_e32 v[130:131], v[2:3]
	v_readlane_b32 s21, v243, 40
	s_mov_b32 s59, s20
	s_barrier
	s_branch .LBB0_2278

; #define PG8_STAGE(bufoff, gbase, voff) do { _Pragma("unroll") for (int _i = 0; _i < 2; ++_i) \
;         __builtin_amdgcn_global_load_lds((const unsigned*)((const char*)(gbase) + (voff)[_i]), (LAS unsigned*)(lds + (bufoff) + ldsw + _i * 8192), 16, 0, 0); } while (0)
; #define PG8_LDA(dst, b, h) do { _Pragma("unroll") for (int m = 0; m < 4; ++m) _Pragma("unroll") for (int k = 0; k < 2; ++k) dst[m][k] = *(const LAS bf16x8*)(lds + PG8_SA(b, h) + aoff + m * 2048 + k * 1024); } while (0)
; #define PG8_LDB(dst, b, h) do { _Pragma("unroll") for (int n = 0; n < 2; ++n) _Pragma("unroll") for (int k = 0; k < 2; ++k) dst[n][k] = *(const LAS bf16x8*)(lds + PG8_SB(b, h) + boff + n * 2048 + k * 1024); } while (0)
; #define PG8_MMA(ai, bj, At, Bt) do { __builtin_amdgcn_s_setprio(1); _Pragma("unroll") for (int m = 0; m < 4; ++m) _Pragma("unroll") for (int n = 0; n < 2; ++n) _Pragma("unroll") for (int k = 0; k < 2; ++k) \
;         acc[ai][bj][m][n] = __builtin_amdgcn_mfma_f32_16x16x32_bf16(Bt[n][k], At[m][k], acc[ai][bj][m][n], 0, 0, 0); __builtin_amdgcn_s_setprio(0); } while (0)
; template <class Epi, bool ALIGN_EPI = true>
; __device__ __forceinline__ void gemm_phase(LAS unsigned char* lds, const Gemm g, const Sched& S, const Epi& E) {
;     ...
;         for (int t = t_lo; t < t_hi; t += 2) {
;             const bool last = (t == nt - 2);
;             const char* a1 = cA + (size_t)(t + 1) * kstep;
;             const char* a2 = last ? nA : cA + (size_t)(t + 2) * kstep; const char* b2 = last ? nB : cB + (size_t)(t + 2) * kstep;
;             const char* a3 = a2 + kstep; const char* b3 = b2 + kstep;
;             const int rflag = __builtin_amdgcn_readfirstlane(t | (int)(ui == 0));
;             PG8_LDB(B0, 0, 0); PG8_LDB(B1, 0, 1); PG8_SCHED; PG8_LDA(At, 0, 0); PG8_STAGE(PG8_SA(1, 1), a1 + hstepA, voffA);
;             if constexpr (Epi::NSTORES > 0) PG8_WAIT_RELAX(rflag, 8 + Epi::NSTORES); else PG8_WAIT_V(8);
;             PG8_WAIT_L(0); PG8_BAR; PG8_MMA(0, 0, At, B0); PG8_MMA(0, 1, At, B1); PG8_BAR; PG8_SCHED;
;             PG8_LDA(At, 0, 1); PG8_STAGE(PG8_SB(0, 0), b2, voffB); PG8_STAGE(PG8_SB(0, 1), b2 + hstepB, voffB); PG8_STAGE(PG8_SA(0, 0), a2, voffA);
;             if constexpr (Epi::NSTORES > 0) PG8_WAIT_RELAX(rflag, 8 + Epi::NSTORES); else PG8_WAIT_V(8);
;             PG8_WAIT_L(0); PG8_BAR; PG8_MMA(1, 0, At, B0); PG8_MMA(1, 1, At, B1); PG8_BAR; PG8_SCHED;
.LBB0_2285:
	s_add_u32 s24, s33, s20
	s_addc_u32 s25, s34, s21
	s_add_u32 s26, s35, s22
	s_addc_u32 s27, s36, s23
	s_andn2_b64 vcc, exec, s[18:19]
	s_cbranch_vccnz .LBB0_2288
	s_and_b64 s[42:43], s[40:41], exec
	s_cselect_b32 s63, s25, s17
	s_cselect_b32 s64, s24, s16
	s_cselect_b32 s65, s27, s15
	s_cselect_b32 s66, s26, s14
	s_add_u32 s67, s14, 0x100
	s_addc_u32 s68, s15, 0
	s_mov_b32 s44, 0
	s_mov_b64 s[48:49], s[16:17]
	v_xor_b32_e32 v238, 64, v148
	v_xor_b32_e32 v239, 64, v147
.LBB0_2287:
	s_add_i32 s69, s44, 2
	s_add_u32 s42, s48, 0x100
	s_addc_u32 s43, s49, 0
	s_add_i32 s70, 0, 0x10000
	s_cmp_eq_u32 s57, s44
	s_cselect_b32 s47, s63, s43
	s_cselect_b32 s46, s64, s42
	s_cselect_b32 s45, s65, s68
	s_cselect_b32 s44, s66, s67
	s_add_i32 s71, 0, 0x14000
	ds_read_b128 v[150:153], v147
	ds_read_b128 v[154:157], v239
	ds_read_b128 v[158:161], v147 offset:2048
	ds_read_b128 v[162:165], v239 offset:2048
	ds_read_b128 v[166:169], v147 offset:16384
	ds_read_b128 v[170:173], v239 offset:16384
	ds_read_b128 v[174:177], v147 offset:18432
	ds_read_b128 v[178:181], v239 offset:18432
	s_add_i32 m0, s50, 0xc000
	ds_read_b128 v[182:185], v148
	ds_read_b128 v[186:189], v238
	ds_read_b128 v[190:193], v148 offset:2048
	ds_read_b128 v[194:197], v238 offset:2048
	ds_read_b128 v[206:209], v148 offset:4096
	ds_read_b128 v[224:227], v238 offset:4096
	ds_read_b128 v[228:231], v148 offset:6144
	ds_read_b128 v[232:235], v238 offset:6144
	s_add_u32 s100, s48, 0xffea0000
	s_addc_u32 s101, s49, -1
	s_mov_b32 m0, s55
	s_nop 0
	global_load_lds_dwordx4 v142, s[100:101]
	s_mov_b32 m0, s56
	s_nop 0
	global_load_lds_dwordx4 v144, s[100:101]
	s_add_i32 m0, s50, 0xc000
	s_nop 0
	global_load_lds_dwordx4 v142, s[48:49]
	s_add_i32 m0, s50, 0xe000
	s_nop 0
	global_load_lds_dwordx4 v144, s[48:49]
	s_waitcnt vmcnt(8)
	s_waitcnt lgkmcnt(0)
	s_barrier
	s_setprio 1
	s_waitcnt lgkmcnt(0)
	v_mfma_f32_16x16x32_bf16 v[130:133], v[150:153], v[182:185], v[130:133]
	v_mfma_f32_16x16x32_bf16 v[126:129], v[158:161], v[182:185], v[126:129]
	v_mfma_f32_16x16x32_bf16 v[114:117], v[150:153], v[190:193], v[114:117]
	v_mfma_f32_16x16x32_bf16 v[110:113], v[158:161], v[190:193], v[110:113]
	v_mfma_f32_16x16x32_bf16 v[98:101], v[150:153], v[206:209], v[98:101]
	v_mfma_f32_16x16x32_bf16 v[94:97], v[158:161], v[206:209], v[94:97]
	v_mfma_f32_16x16x32_bf16 v[82:85], v[150:153], v[228:231], v[82:85]
	v_mfma_f32_16x16x32_bf16 v[78:81], v[158:161], v[228:231], v[78:81]
	v_mfma_f32_16x16x32_bf16 v[130:133], v[154:157], v[186:189], v[130:133]
	v_mfma_f32_16x16x32_bf16 v[126:129], v[162:165], v[186:189], v[126:129]
	v_mfma_f32_16x16x32_bf16 v[114:117], v[154:157], v[194:197], v[114:117]
	v_mfma_f32_16x16x32_bf16 v[110:113], v[162:165], v[194:197], v[110:113]
	v_mfma_f32_16x16x32_bf16 v[98:101], v[154:157], v[224:227], v[98:101]
	v_mfma_f32_16x16x32_bf16 v[94:97], v[162:165], v[224:227], v[94:97]
	v_mfma_f32_16x16x32_bf16 v[82:85], v[154:157], v[232:235], v[82:85]
	v_mfma_f32_16x16x32_bf16 v[78:81], v[162:165], v[232:235], v[78:81]
	s_setprio 0
	s_setprio 1
	v_mfma_f32_16x16x32_bf16 v[122:125], v[166:169], v[182:185], v[122:125]
	v_mfma_f32_16x16x32_bf16 v[118:121], v[174:177], v[182:185], v[118:121]
	v_mfma_f32_16x16x32_bf16 v[106:109], v[166:169], v[190:193], v[106:109]
	v_mfma_f32_16x16x32_bf16 v[102:105], v[174:177], v[190:193], v[102:105]
	v_mfma_f32_16x16x32_bf16 v[90:93], v[166:169], v[206:209], v[90:93]
	v_mfma_f32_16x16x32_bf16 v[86:89], v[174:177], v[206:209], v[86:89]
	v_mfma_f32_16x16x32_bf16 v[74:77], v[166:169], v[228:231], v[74:77]
	v_mfma_f32_16x16x32_bf16 v[70:73], v[174:177], v[228:231], v[70:73]
	v_mfma_f32_16x16x32_bf16 v[122:125], v[170:173], v[186:189], v[122:125]
	v_mfma_f32_16x16x32_bf16 v[118:121], v[178:181], v[186:189], v[118:121]
	v_mfma_f32_16x16x32_bf16 v[106:109], v[170:173], v[194:197], v[106:109]
	v_mfma_f32_16x16x32_bf16 v[102:105], v[178:181], v[194:197], v[102:105]
	v_mfma_f32_16x16x32_bf16 v[90:93], v[170:173], v[224:227], v[90:93]
	v_mfma_f32_16x16x32_bf16 v[86:89], v[178:181], v[224:227], v[86:89]
	v_mfma_f32_16x16x32_bf16 v[74:77], v[170:173], v[232:235], v[74:77]
	v_mfma_f32_16x16x32_bf16 v[70:73], v[178:181], v[232:235], v[70:73]
	s_setprio 0
	s_barrier
	s_add_i32 s48, s70, s37
	s_mov_b32 m0, s48
	ds_read_b128 v[182:185], v148 offset:16384
	ds_read_b128 v[186:189], v238 offset:16384
	ds_read_b128 v[190:193], v148 offset:18432
	ds_read_b128 v[194:197], v238 offset:18432
	ds_read_b128 v[206:209], v148 offset:20480
	ds_read_b128 v[224:227], v238 offset:20480
	ds_read_b128 v[228:231], v148 offset:22528
	ds_read_b128 v[232:235], v238 offset:22528
	global_load_lds_dwordx4 v138, s[44:45]
	s_add_i32 m0, s48, 0x2000
	s_add_u32 s48, s44, 0x160000
	s_addc_u32 s49, s45, 0
	s_add_i32 s70, s71, s37
	global_load_lds_dwordx4 v134, s[44:45]
	s_mov_b32 m0, s70
	s_nop 0
	global_load_lds_dwordx4 v138, s[48:49]
	s_add_i32 m0, s70, 0x2000
	s_nop 0
	global_load_lds_dwordx4 v134, s[48:49]
	s_waitcnt vmcnt(6)
	s_waitcnt lgkmcnt(0)
	s_barrier
; #define PG8_STAGE(bufoff, gbase, voff) do { _Pragma("unroll") for (int _i = 0; _i < 2; ++_i) \
;         __builtin_amdgcn_global_load_lds((const unsigned*)((const char*)(gbase) + (voff)[_i]), (LAS unsigned*)(lds + (bufoff) + ldsw + _i * 8192), 16, 0, 0); } while (0)
; #define PG8_LDA(dst, b, h) do { _Pragma("unroll") for (int m = 0; m < 4; ++m) _Pragma("unroll") for (int k = 0; k < 2; ++k) dst[m][k] = *(const LAS bf16x8*)(lds + PG8_SA(b, h) + aoff + m * 2048 + k * 1024); } while (0)
; #define PG8_LDB(dst, b, h) do { _Pragma("unroll") for (int n = 0; n < 2; ++n) _Pragma("unroll") for (int k = 0; k < 2; ++k) dst[n][k] = *(const LAS bf16x8*)(lds + PG8_SB(b, h) + boff + n * 2048 + k * 1024); } while (0)
; #define PG8_MMA(ai, bj, At, Bt) do { __builtin_amdgcn_s_setprio(1); _Pragma("unroll") for (int m = 0; m < 4; ++m) _Pragma("unroll") for (int n = 0; n < 2; ++n) _Pragma("unroll") for (int k = 0; k < 2; ++k) \
;         acc[ai][bj][m][n] = __builtin_amdgcn_mfma_f32_16x16x32_bf16(Bt[n][k], At[m][k], acc[ai][bj][m][n], 0, 0, 0); __builtin_amdgcn_s_setprio(0); } while (0)
; #define PG8_WAIT_V(n) asm volatile("s_waitcnt vmcnt(" #n ")" ::: "memory")
; #define PG8_WAIT_L(n) asm volatile("s_waitcnt lgkmcnt(" #n ")" ::: "memory")
; #define PG8_BAR __builtin_amdgcn_s_barrier()
; #define PG8_SCHED __builtin_amdgcn_sched_barrier(0)
; template <class Epi, bool ALIGN_EPI = true>
; __device__ __forceinline__ void gemm_phase(LAS unsigned char* lds, const Gemm g, const Sched& S, const Epi& E) {
;     ...
;             PG8_WAIT_L(0); PG8_BAR; PG8_MMA(1, 0, At, B0); PG8_MMA(1, 1, At, B1); PG8_BAR; PG8_SCHED;
;             PG8_LDB(B0, 1, 0); PG8_LDB(B1, 1, 1); PG8_SCHED; PG8_LDA(At, 1, 0); PG8_STAGE(PG8_SA(0, 1), a2 + hstepA, voffA);
;             PG8_WAIT_V(8); PG8_WAIT_L(0); PG8_BAR; PG8_MMA(0, 0, At, B0); PG8_MMA(0, 1, At, B1); PG8_BAR; PG8_SCHED;
	s_setprio 1
	s_waitcnt lgkmcnt(0)
	v_mfma_f32_16x16x32_bf16 v[66:69], v[150:153], v[182:185], v[66:69]
	v_mfma_f32_16x16x32_bf16 v[62:65], v[158:161], v[182:185], v[62:65]
	v_mfma_f32_16x16x32_bf16 v[50:53], v[150:153], v[190:193], v[50:53]
	v_mfma_f32_16x16x32_bf16 v[46:49], v[158:161], v[190:193], v[46:49]
	v_mfma_f32_16x16x32_bf16 v[34:37], v[150:153], v[206:209], v[34:37]
	v_mfma_f32_16x16x32_bf16 v[30:33], v[158:161], v[206:209], v[30:33]
	v_mfma_f32_16x16x32_bf16 v[18:21], v[150:153], v[228:231], v[18:21]
	v_mfma_f32_16x16x32_bf16 v[14:17], v[158:161], v[228:231], v[14:17]
	v_mfma_f32_16x16x32_bf16 v[66:69], v[154:157], v[186:189], v[66:69]
	v_mfma_f32_16x16x32_bf16 v[62:65], v[162:165], v[186:189], v[62:65]
	v_mfma_f32_16x16x32_bf16 v[50:53], v[154:157], v[194:197], v[50:53]
	v_mfma_f32_16x16x32_bf16 v[46:49], v[162:165], v[194:197], v[46:49]
	v_mfma_f32_16x16x32_bf16 v[34:37], v[154:157], v[224:227], v[34:37]
	v_mfma_f32_16x16x32_bf16 v[30:33], v[162:165], v[224:227], v[30:33]
	v_mfma_f32_16x16x32_bf16 v[18:21], v[154:157], v[232:235], v[18:21]
	v_mfma_f32_16x16x32_bf16 v[14:17], v[162:165], v[232:235], v[14:17]
	s_setprio 0
	s_setprio 1
	v_mfma_f32_16x16x32_bf16 v[58:61], v[166:169], v[182:185], v[58:61]
	v_mfma_f32_16x16x32_bf16 v[54:57], v[174:177], v[182:185], v[54:57]
	v_mfma_f32_16x16x32_bf16 v[42:45], v[166:169], v[190:193], v[42:45]
	v_mfma_f32_16x16x32_bf16 v[38:41], v[174:177], v[190:193], v[38:41]
	v_mfma_f32_16x16x32_bf16 v[26:29], v[166:169], v[206:209], v[26:29]
	v_mfma_f32_16x16x32_bf16 v[22:25], v[174:177], v[206:209], v[22:25]
	v_mfma_f32_16x16x32_bf16 v[10:13], v[166:169], v[228:231], v[10:13]
	v_mfma_f32_16x16x32_bf16 v[4:7], v[174:177], v[228:231], v[6:9]
	v_mfma_f32_16x16x32_bf16 v[58:61], v[170:173], v[186:189], v[58:61]
	v_mfma_f32_16x16x32_bf16 v[54:57], v[178:181], v[186:189], v[54:57]
	v_mfma_f32_16x16x32_bf16 v[42:45], v[170:173], v[194:197], v[42:45]
	v_mfma_f32_16x16x32_bf16 v[38:41], v[178:181], v[194:197], v[38:41]
	v_mfma_f32_16x16x32_bf16 v[26:29], v[170:173], v[224:227], v[26:29]
	v_mfma_f32_16x16x32_bf16 v[22:25], v[178:181], v[224:227], v[22:25]
	v_mfma_f32_16x16x32_bf16 v[10:13], v[170:173], v[232:235], v[10:13]
	v_mfma_f32_16x16x32_bf16 v[4:7], v[178:181], v[232:235], v[4:7]
	s_setprio 0
	s_barrier
	s_add_i32 s48, 0, 0x18000
	s_add_i32 s49, 0, 0x1c000
	ds_read_b128 v[150:153], v147 offset:32768
	ds_read_b128 v[154:157], v239 offset:32768
	ds_read_b128 v[158:161], v147 offset:34816
	ds_read_b128 v[162:165], v239 offset:34816
	ds_read_b128 v[166:169], v147 offset:49152
	ds_read_b128 v[170:173], v239 offset:49152
	ds_read_b128 v[174:177], v147 offset:51200
	ds_read_b128 v[178:181], v239 offset:51200
	s_add_u32 s46, s46, 0x160000
	s_addc_u32 s47, s47, 0
	s_mov_b32 m0, s52
	ds_read_b128 v[182:185], v148 offset:32768
	ds_read_b128 v[186:189], v238 offset:32768
	ds_read_b128 v[190:193], v148 offset:34816
	ds_read_b128 v[194:197], v238 offset:34816
	ds_read_b128 v[206:209], v148 offset:36864
	ds_read_b128 v[224:227], v238 offset:36864
	ds_read_b128 v[228:231], v148 offset:38912
	ds_read_b128 v[232:235], v238 offset:38912
	s_add_u32 s100, s46, 0xffea0000
	s_addc_u32 s101, s47, -1
	s_mov_b32 m0, s50
	s_nop 0
	global_load_lds_dwordx4 v140, s[100:101]
	s_mov_b32 m0, s51
	s_nop 0
	global_load_lds_dwordx4 v136, s[100:101]
	s_mov_b32 m0, s52
	s_nop 0
	global_load_lds_dwordx4 v140, s[46:47]
	s_mov_b32 m0, s53
	s_nop 0
	global_load_lds_dwordx4 v136, s[46:47]
	s_waitcnt vmcnt(8)
	s_waitcnt lgkmcnt(0)
	s_barrier
; #define PG8_STAGE(bufoff, gbase, voff) do { _Pragma("unroll") for (int _i = 0; _i < 2; ++_i) \
;         __builtin_amdgcn_global_load_lds((const unsigned*)((const char*)(gbase) + (voff)[_i]), (LAS unsigned*)(lds + (bufoff) + ldsw + _i * 8192), 16, 0, 0); } while (0)
; #define PG8_LDA(dst, b, h) do { _Pragma("unroll") for (int m = 0; m < 4; ++m) _Pragma("unroll") for (int k = 0; k < 2; ++k) dst[m][k] = *(const LAS bf16x8*)(lds + PG8_SA(b, h) + aoff + m * 2048 + k * 1024); } while (0)
; #define PG8_MMA(ai, bj, At, Bt) do { __builtin_amdgcn_s_setprio(1); _Pragma("unroll") for (int m = 0; m < 4; ++m) _Pragma("unroll") for (int n = 0; n < 2; ++n) _Pragma("unroll") for (int k = 0; k < 2; ++k) \
;         acc[ai][bj][m][n] = __builtin_amdgcn_mfma_f32_16x16x32_bf16(Bt[n][k], At[m][k], acc[ai][bj][m][n], 0, 0, 0); __builtin_amdgcn_s_setprio(0); } while (0)
; #define PG8_WAIT_V(n) asm volatile("s_waitcnt vmcnt(" #n ")" ::: "memory")
; #define PG8_WAIT_L(n) asm volatile("s_waitcnt lgkmcnt(" #n ")" ::: "memory")
; #define PG8_BAR __builtin_amdgcn_s_barrier()
; #define PG8_SCHED __builtin_amdgcn_sched_barrier(0)
; template <class Epi, bool ALIGN_EPI = true>
; __device__ __forceinline__ void gemm_phase(LAS unsigned char* lds, const Gemm g, const Sched& S, const Epi& E) {
;     ...
;             PG8_WAIT_V(8); PG8_WAIT_L(0); PG8_BAR; PG8_MMA(0, 0, At, B0); PG8_MMA(0, 1, At, B1); PG8_BAR; PG8_SCHED;
;             PG8_LDA(At, 1, 1); PG8_STAGE(PG8_SB(1, 0), b3, voffB); PG8_STAGE(PG8_SB(1, 1), b3 + hstepB, voffB); PG8_STAGE(PG8_SA(1, 0), a3, voffA);
;             PG8_WAIT_V(8); PG8_WAIT_L(0); PG8_BAR; PG8_MMA(1, 0, At, B0); PG8_MMA(1, 1, At, B1); PG8_BAR; PG8_SCHED;
;         }
	s_setprio 1
	s_waitcnt lgkmcnt(0)
	v_mfma_f32_16x16x32_bf16 v[130:133], v[150:153], v[182:185], v[130:133]
	v_mfma_f32_16x16x32_bf16 v[126:129], v[158:161], v[182:185], v[126:129]
	v_mfma_f32_16x16x32_bf16 v[114:117], v[150:153], v[190:193], v[114:117]
	v_mfma_f32_16x16x32_bf16 v[110:113], v[158:161], v[190:193], v[110:113]
	v_mfma_f32_16x16x32_bf16 v[98:101], v[150:153], v[206:209], v[98:101]
	v_mfma_f32_16x16x32_bf16 v[94:97], v[158:161], v[206:209], v[94:97]
	v_mfma_f32_16x16x32_bf16 v[82:85], v[150:153], v[228:231], v[82:85]
	v_mfma_f32_16x16x32_bf16 v[78:81], v[158:161], v[228:231], v[78:81]
	v_mfma_f32_16x16x32_bf16 v[130:133], v[154:157], v[186:189], v[130:133]
	v_mfma_f32_16x16x32_bf16 v[126:129], v[162:165], v[186:189], v[126:129]
	v_mfma_f32_16x16x32_bf16 v[114:117], v[154:157], v[194:197], v[114:117]
	v_mfma_f32_16x16x32_bf16 v[110:113], v[162:165], v[194:197], v[110:113]
	v_mfma_f32_16x16x32_bf16 v[98:101], v[154:157], v[224:227], v[98:101]
	v_mfma_f32_16x16x32_bf16 v[94:97], v[162:165], v[224:227], v[94:97]
	v_mfma_f32_16x16x32_bf16 v[82:85], v[154:157], v[232:235], v[82:85]
	v_mfma_f32_16x16x32_bf16 v[78:81], v[162:165], v[232:235], v[78:81]
	s_setprio 0
	s_setprio 1
	v_mfma_f32_16x16x32_bf16 v[122:125], v[166:169], v[182:185], v[122:125]
	v_mfma_f32_16x16x32_bf16 v[118:121], v[174:177], v[182:185], v[118:121]
	v_mfma_f32_16x16x32_bf16 v[106:109], v[166:169], v[190:193], v[106:109]
	v_mfma_f32_16x16x32_bf16 v[102:105], v[174:177], v[190:193], v[102:105]
	v_mfma_f32_16x16x32_bf16 v[90:93], v[166:169], v[206:209], v[90:93]
	v_mfma_f32_16x16x32_bf16 v[86:89], v[174:177], v[206:209], v[86:89]
	v_mfma_f32_16x16x32_bf16 v[74:77], v[166:169], v[228:231], v[74:77]
	v_mfma_f32_16x16x32_bf16 v[70:73], v[174:177], v[228:231], v[70:73]
	v_mfma_f32_16x16x32_bf16 v[122:125], v[170:173], v[186:189], v[122:125]
	v_mfma_f32_16x16x32_bf16 v[118:121], v[178:181], v[186:189], v[118:121]
	v_mfma_f32_16x16x32_bf16 v[106:109], v[170:173], v[194:197], v[106:109]
	v_mfma_f32_16x16x32_bf16 v[102:105], v[178:181], v[194:197], v[102:105]
	v_mfma_f32_16x16x32_bf16 v[90:93], v[170:173], v[224:227], v[90:93]
	v_mfma_f32_16x16x32_bf16 v[86:89], v[178:181], v[224:227], v[86:89]
	v_mfma_f32_16x16x32_bf16 v[74:77], v[170:173], v[232:235], v[74:77]
	v_mfma_f32_16x16x32_bf16 v[70:73], v[178:181], v[232:235], v[70:73]
	s_setprio 0
	s_barrier
	s_add_u32 s100, s44, 0x80
	s_addc_u32 s101, s45, 0
	s_add_i32 s46, s48, s37
	s_mov_b32 m0, s46
	ds_read_b128 v[182:185], v148 offset:49152
	ds_read_b128 v[186:189], v238 offset:49152
	ds_read_b128 v[190:193], v148 offset:51200
	ds_read_b128 v[194:197], v238 offset:51200
	ds_read_b128 v[206:209], v148 offset:53248
	ds_read_b128 v[224:227], v238 offset:53248
	ds_read_b128 v[228:231], v148 offset:55296
	ds_read_b128 v[232:235], v238 offset:55296
	global_load_lds_dwordx4 v138, s[100:101]
	s_add_i32 m0, s46, 0x2000
	s_add_u32 s44, s44, 0x160080
	s_addc_u32 s45, s45, 0
	s_add_i32 s46, s49, s37
	global_load_lds_dwordx4 v134, s[100:101]
	s_mov_b32 m0, s46
	s_nop 0
	global_load_lds_dwordx4 v138, s[44:45]
	s_add_i32 m0, s46, 0x2000
	s_nop 0
	global_load_lds_dwordx4 v134, s[44:45]
	s_waitcnt vmcnt(6)
	s_waitcnt lgkmcnt(0)
	s_barrier
	s_setprio 1
	s_waitcnt lgkmcnt(0)
	v_mfma_f32_16x16x32_bf16 v[66:69], v[150:153], v[182:185], v[66:69]
	v_mfma_f32_16x16x32_bf16 v[62:65], v[158:161], v[182:185], v[62:65]
	v_mfma_f32_16x16x32_bf16 v[50:53], v[150:153], v[190:193], v[50:53]
	v_mfma_f32_16x16x32_bf16 v[46:49], v[158:161], v[190:193], v[46:49]
	v_mfma_f32_16x16x32_bf16 v[34:37], v[150:153], v[206:209], v[34:37]
	v_mfma_f32_16x16x32_bf16 v[30:33], v[158:161], v[206:209], v[30:33]
	v_mfma_f32_16x16x32_bf16 v[18:21], v[150:153], v[228:231], v[18:21]
	v_mfma_f32_16x16x32_bf16 v[14:17], v[158:161], v[228:231], v[14:17]
	v_mfma_f32_16x16x32_bf16 v[66:69], v[154:157], v[186:189], v[66:69]
	v_mfma_f32_16x16x32_bf16 v[62:65], v[162:165], v[186:189], v[62:65]
	v_mfma_f32_16x16x32_bf16 v[50:53], v[154:157], v[194:197], v[50:53]
	v_mfma_f32_16x16x32_bf16 v[46:49], v[162:165], v[194:197], v[46:49]
	v_mfma_f32_16x16x32_bf16 v[34:37], v[154:157], v[224:227], v[34:37]
	v_mfma_f32_16x16x32_bf16 v[30:33], v[162:165], v[224:227], v[30:33]
	v_mfma_f32_16x16x32_bf16 v[18:21], v[154:157], v[232:235], v[18:21]
	v_mfma_f32_16x16x32_bf16 v[14:17], v[162:165], v[232:235], v[14:17]
	s_setprio 0
	s_setprio 1
	v_mfma_f32_16x16x32_bf16 v[58:61], v[166:169], v[182:185], v[58:61]
	v_mfma_f32_16x16x32_bf16 v[54:57], v[174:177], v[182:185], v[54:57]
	v_mfma_f32_16x16x32_bf16 v[42:45], v[166:169], v[190:193], v[42:45]
	v_mfma_f32_16x16x32_bf16 v[38:41], v[174:177], v[190:193], v[38:41]
	v_mfma_f32_16x16x32_bf16 v[26:29], v[166:169], v[206:209], v[26:29]
	v_mfma_f32_16x16x32_bf16 v[22:25], v[174:177], v[206:209], v[22:25]
	v_mfma_f32_16x16x32_bf16 v[8:11], v[166:169], v[228:231], v[10:13]
	v_mfma_f32_16x16x32_bf16 v[4:7], v[174:177], v[228:231], v[4:7]
	v_mfma_f32_16x16x32_bf16 v[58:61], v[170:173], v[186:189], v[58:61]
	v_mfma_f32_16x16x32_bf16 v[54:57], v[178:181], v[186:189], v[54:57]
	v_mfma_f32_16x16x32_bf16 v[42:45], v[170:173], v[194:197], v[42:45]
	v_mfma_f32_16x16x32_bf16 v[38:41], v[178:181], v[194:197], v[38:41]
	v_mfma_f32_16x16x32_bf16 v[26:29], v[170:173], v[224:227], v[26:29]
	v_mfma_f32_16x16x32_bf16 v[22:25], v[178:181], v[224:227], v[22:25]
	v_mfma_f32_16x16x32_bf16 v[10:13], v[170:173], v[232:235], v[8:11]
	v_mfma_f32_16x16x32_bf16 v[6:9], v[178:181], v[232:235], v[4:7]
	s_setprio 0
	s_barrier
	s_add_u32 s67, s67, 0x100
	s_addc_u32 s68, s68, 0
	s_cmp_ge_i32 s69, s54
	s_mov_b64 s[48:49], s[42:43]
	s_mov_b32 s44, s69
	s_cbranch_scc0 .LBB0_2287

; __global__ void __launch_bounds__(NWAVES * 64, 2) mk_fwd(Args args) {
	.amdhsa_kernel _Z6mk_fwd4Args
		.amdhsa_group_segment_fixed_size 0
		.amdhsa_private_segment_fixed_size 0
		.amdhsa_kernarg_size 440
		.amdhsa_user_sgpr_count 2
		.amdhsa_user_sgpr_dispatch_ptr 0
		.amdhsa_user_sgpr_queue_ptr 0
		.amdhsa_user_sgpr_kernarg_segment_ptr 1
		.amdhsa_user_sgpr_dispatch_id 0
		.amdhsa_user_sgpr_kernarg_preload_length 0
		.amdhsa_user_sgpr_kernarg_preload_offset 0
		.amdhsa_user_sgpr_private_segment_size 0
		.amdhsa_uses_dynamic_stack 0
		.amdhsa_enable_private_segment 0
		.amdhsa_system_sgpr_workgroup_id_x 1
		.amdhsa_system_sgpr_workgroup_id_y 0
		.amdhsa_system_sgpr_workgroup_id_z 0
		.amdhsa_system_sgpr_workgroup_info 0
		.amdhsa_system_vgpr_workitem_id 0
		.amdhsa_next_free_vgpr 248
		.amdhsa_next_free_sgpr 102
		.amdhsa_accum_offset 248
		.amdhsa_reserve_vcc 1
		.amdhsa_float_round_mode_32 0
		.amdhsa_float_round_mode_16_64 0
		.amdhsa_float_denorm_mode_32 3
		.amdhsa_float_denorm_mode_16_64 3
		.amdhsa_dx10_clamp 1
		.amdhsa_ieee_mode 1
		.amdhsa_fp16_overflow 0
		.amdhsa_tg_split 0
		.amdhsa_exception_fp_ieee_invalid_op 0
		.amdhsa_exception_fp_denorm_src 0
		.amdhsa_exception_fp_ieee_div_zero 0
		.amdhsa_exception_fp_ieee_overflow 0
		.amdhsa_exception_fp_ieee_underflow 0
		.amdhsa_exception_fp_ieee_inexact 0
		.amdhsa_exception_int_div_zero 0
	.end_amdhsa_kernel

; __global__ void __launch_bounds__(NWAVES * 64, 2) mk_fwd(Args args) {
amdhsa.kernels:
  - .agpr_count:     0
    .args:
      - .offset:         0
        .size:           184
        .value_kind:     by_value
      - .offset:         184
        .size:           4
        .value_kind:     hidden_block_count_x
      - .offset:         188
        .size:           4
        .value_kind:     hidden_block_count_y
      - .offset:         192
        .size:           4
        .value_kind:     hidden_block_count_z
      - .offset:         196
        .size:           2
        .value_kind:     hidden_group_size_x
      - .offset:         198
        .size:           2
        .value_kind:     hidden_group_size_y
      - .offset:         200
        .size:           2
        .value_kind:     hidden_group_size_z
      - .offset:         202
        .size:           2
        .value_kind:     hidden_remainder_x
      - .offset:         204
        .size:           2
        .value_kind:     hidden_remainder_y
      - .offset:         206
        .size:           2
        .value_kind:     hidden_remainder_z
      - .offset:         224
        .size:           8
        .value_kind:     hidden_global_offset_x
      - .offset:         232
        .size:           8
        .value_kind:     hidden_global_offset_y
      - .offset:         240
        .size:           8
        .value_kind:     hidden_global_offset_z
      - .offset:         248
        .size:           2
        .value_kind:     hidden_grid_dims
      - .offset:         304
        .size:           4
        .value_kind:     hidden_dynamic_lds_size
    .group_segment_fixed_size: 0
    .kernarg_segment_align: 8
    .kernarg_segment_size: 440
    .language:       OpenCL C
    .language_version:
      - 2
      - 0
    .max_flat_workgroup_size: 512
    .name:           _Z6mk_fwd4Args
    .private_segment_fixed_size: 0
    .sgpr_count:     108
    .sgpr_spill_count: 351
    .symbol:         _Z6mk_fwd4Args.kd
    .uniform_work_group_size: 1
    .uses_dynamic_stack: false
    .vgpr_count:     248
    .vgpr_spill_count: 0
    .wavefront_size: 64
